# K-loops: s_setprio 0 of the load group issued after the segment's last ds_read (priority held through the LDS read issue) in P2/P3/P4
# speedup vs baseline: 1.0040x; 1.0011x over previous
; #define PG8_STAGE(bufoff, gbase, voff) do { _Pragma("unroll") for (int _i = 0; _i < 2; ++_i) \
;         __builtin_amdgcn_global_load_lds((const unsigned*)((const char*)(gbase) + (voff)[_i]), (PG8_LAS unsigned*)(lds + (bufoff) + ldsw + _i * 8192), 16, 0, 0); } while (0)
; #define PG8_LDA(dst, b, h) do { _Pragma("unroll") for (int m = 0; m < 4; ++m) _Pragma("unroll") for (int k = 0; k < 2; ++k) dst[m][k] = *(const PG8_LAS bf16x8*)(lds + PG8_SA(b, h) + aoff + m * 2048 + k * 1024); } while (0)
; #define PG8_BAR __builtin_amdgcn_s_barrier()
; template <class Epi, class Sched, bool ALIGN_EPI = false, bool SP2 = false, bool I8 = false>
; __device__ __forceinline__ void gemm_phase(PG8_LAS unsigned char* lds, const Gemm g, const Sched& S, const Epi& E) {
;     ...
;         const char* nA = has_next ? (const char*)g.A + (size_t)nxt.pm * tstep : cA; const char* nB = has_next ? (const char*)g.Bt + (size_t)nxt.pn * tstep : cB;
;         for (int t = 0; t < nt; t += 2) {
;             const bool last = (t == nt - 2);
;             const char* a1 = cA + (size_t)(t + 1) * kstep;
;             const char* a2 = last ? nA : cA + (size_t)(t + 2) * kstep; const char* b2 = last ? nB : cB + (size_t)(t + 2) * kstep;
;             const char* a3 = a2 + kstep; const char* b3 = b2 + kstep;
;             if (last && has_next) S.a_ready(nxt);
;             if constexpr (SP2) {
;             PG8_LDB(B0, 0, 0); PG8_LDB(B1, 0, 1); PG8_SCHED; PG8_LDA(At, 0, 0); PG8_STAGE(PG8_SA(1, 1), a1 + hstep, voffA);
;             PG8_WAIT_V(8); PG8_WAIT_L(0); PG8_BAR; PG8_MMA(0, 0, At, B0); PG8_MMA(0, 1, At, B1); PG8_BAR; PG8_SCHED;
;             PG8_LDA(At, 0, 1); PG8_STAGE(PG8_SB(0, 0), b2, voffB); PG8_STAGE(PG8_SB(0, 1), b2 + hstep, voffB); PG8_STAGE(PG8_SA(0, 0), a2, voffA);
;             PG8_WAIT_V(8); PG8_WAIT_L(0); PG8_BAR; PG8_MMA(1, 0, At, B0); PG8_MMA(1, 1, At, B1); PG8_BAR; PG8_SCHED;
;             PG8_LDB(B0, 1, 0); PG8_LDB(B1, 1, 1); PG8_SCHED; PG8_LDA(At, 1, 0); PG8_STAGE(PG8_SA(0, 1), a2 + hstep, voffA);
;             PG8_WAIT_V(8); PG8_WAIT_L(0); PG8_BAR; PG8_MMA(0, 0, At, B0); PG8_MMA(0, 1, At, B1); PG8_BAR; PG8_SCHED;
;             PG8_LDA(At, 1, 1); PG8_STAGE(PG8_SB(1, 0), b3, voffB); PG8_STAGE(PG8_SB(1, 1), b3 + hstep, voffB); PG8_STAGE(PG8_SA(1, 0), a3, voffA);
;             PG8_WAIT_V(8); PG8_WAIT_L(0); PG8_BAR; PG8_MMA(1, 0, At, B0); PG8_MMA(1, 1, At, B1); PG8_BAR; PG8_SCHED;
.LBB0_207:
	s_ashr_i32 s19, s18, 31
	s_lshl_b64 s[22:23], s[18:19], 20
	s_add_u32 s22, s28, s22
	s_addc_u32 s23, s34, s23
	s_and_b64 s[24:25], s[6:7], exec
	s_cselect_b32 s19, s23, s27
	s_cselect_b32 s64, s22, s26
	s_ashr_i32 s17, s16, 31
	s_lshl_b64 s[24:25], s[16:17], 20
	s_add_u32 s24, s35, s24
	s_addc_u32 s25, s42, s25
	s_and_b64 s[40:41], s[6:7], exec
	s_cselect_b32 s17, s25, s37
	s_cselect_b32 s65, s24, s36
	s_add_u32 s26, s26, 0x80080
	s_addc_u32 s27, s27, 0
	s_add_u32 s72, s36, 0x100
	s_addc_u32 s73, s37, 0
	s_mov_b32 s76, -2
	s_add_u32 s36, s26, 0xfff80080
	s_addc_u32 s37, s27, -1
	s_add_i32 s50, 0, 0x10000
	s_cmp_eq_u32 s76, 28
	s_cselect_b32 s41, s19, s37
	s_cselect_b32 s40, s64, s36
	s_cselect_b32 s37, s17, s73
	s_cselect_b32 s36, s65, s72
	s_add_i32 s56, 0, 0x14000
	v_add_u32_e32 v136, s50, v175
	v_add_u32_e32 v172, s56, v175
	ds_read_b128 v[116:119], v136
	ds_read_b128 v[182:185], v177
	ds_read_b128 v[124:127], v136 offset:1024
	ds_read_b128 v[186:189], v177 offset:1024
	ds_read_b128 v[208:211], v177 offset:3072
	ds_read_b128 v[204:207], v177 offset:2048
	ds_read_b128 v[212:215], v177 offset:4096
	ds_read_b128 v[216:219], v177 offset:5120
	s_add_i32 m0, s44, 0xc000
	ds_read_b128 v[224:227], v177 offset:7168
	ds_read_b128 v[220:223], v177 offset:6144
	ds_read_b128 v[132:135], v136 offset:2048
	ds_read_b128 v[136:139], v136 offset:3072
	ds_read_b128 v[160:163], v172
	ds_read_b128 v[164:167], v172 offset:1024
	ds_read_b128 v[168:171], v172 offset:2048
	ds_read_b128 v[178:181], v172 offset:3072
	global_load_lds_dwordx4 v156, s[26:27]
	s_add_i32 m0, s44, 0xe000
	s_nop 0
	global_load_lds_dwordx4 v158, s[26:27]
	s_waitcnt vmcnt(8)
	s_waitcnt lgkmcnt(14)
	s_setprio 1
	s_barrier
	v_mfma_i32_16x16x64_i8 v[144:147], v[116:119], v[182:185], 0
	s_waitcnt lgkmcnt(12)
	v_mfma_i32_16x16x64_i8 v[144:147], v[124:127], v[186:189], v[144:147]
	s_waitcnt lgkmcnt(11)
	v_mfma_i32_16x16x64_i8 v[112:115], v[124:127], v[208:211], 0
	s_waitcnt lgkmcnt(10)
	v_mfma_i32_16x16x64_i8 v[112:115], v[116:119], v[204:207], v[112:115]
	s_waitcnt lgkmcnt(9)
	v_mfma_i32_16x16x64_i8 v[96:99], v[116:119], v[212:215], 0
	s_waitcnt lgkmcnt(8)
	v_mfma_i32_16x16x64_i8 v[96:99], v[124:127], v[216:219], v[96:99]
	s_waitcnt lgkmcnt(7)
	v_mfma_i32_16x16x64_i8 v[80:83], v[124:127], v[224:227], 0
	s_waitcnt lgkmcnt(6)
	v_mfma_i32_16x16x64_i8 v[80:83], v[116:119], v[220:223], v[80:83]
	s_waitcnt lgkmcnt(5)
	v_mfma_i32_16x16x64_i8 v[76:79], v[132:135], v[220:223], 0
	s_waitcnt lgkmcnt(4)
	v_mfma_i32_16x16x64_i8 v[76:79], v[136:139], v[224:227], v[76:79]
	v_mfma_i32_16x16x64_i8 v[92:95], v[136:139], v[216:219], 0
	v_mfma_i32_16x16x64_i8 v[92:95], v[132:135], v[212:215], v[92:95]
	v_mfma_i32_16x16x64_i8 v[108:111], v[132:135], v[204:207], 0
	v_mfma_i32_16x16x64_i8 v[108:111], v[136:139], v[208:211], v[108:111]
	v_mfma_i32_16x16x64_i8 v[140:143], v[136:139], v[186:189], 0
	v_mfma_i32_16x16x64_i8 v[140:143], v[132:135], v[182:185], v[140:143]
	s_waitcnt lgkmcnt(3)
	v_mfma_i32_16x16x64_i8 v[128:131], v[160:163], v[182:185], 0
	s_waitcnt lgkmcnt(2)
	v_mfma_i32_16x16x64_i8 v[128:131], v[164:167], v[186:189], v[128:131]
	v_mfma_i32_16x16x64_i8 v[104:107], v[164:167], v[208:211], 0
	v_mfma_i32_16x16x64_i8 v[104:107], v[160:163], v[204:207], v[104:107]
	v_mfma_i32_16x16x64_i8 v[88:91], v[160:163], v[212:215], 0
	v_mfma_i32_16x16x64_i8 v[88:91], v[164:167], v[216:219], v[88:91]
	v_mfma_i32_16x16x64_i8 v[72:75], v[164:167], v[224:227], 0
	v_mfma_i32_16x16x64_i8 v[72:75], v[160:163], v[220:223], v[72:75]
	s_waitcnt lgkmcnt(1)
	v_mfma_i32_16x16x64_i8 v[68:71], v[168:171], v[220:223], 0
	s_waitcnt lgkmcnt(0)
	v_mfma_i32_16x16x64_i8 v[68:71], v[178:181], v[224:227], v[68:71]
	v_mfma_i32_16x16x64_i8 v[84:87], v[178:181], v[216:219], 0
	v_mfma_i32_16x16x64_i8 v[84:87], v[168:171], v[212:215], v[84:87]
	v_mfma_i32_16x16x64_i8 v[100:103], v[168:171], v[204:207], 0
	v_mfma_i32_16x16x64_i8 v[100:103], v[178:181], v[208:211], v[100:103]
	v_mfma_i32_16x16x64_i8 v[120:123], v[178:181], v[186:189], 0
	v_mfma_i32_16x16x64_i8 v[120:123], v[168:171], v[182:185], v[120:123]
	s_barrier
	s_add_i32 s50, s50, s43
	v_lshl_add_u64 v[172:173], s[36:37], 0, v[2:3]
	s_mov_b32 m0, s50
	ds_read_b128 v[182:185], v177 offset:16384
	ds_read_b128 v[186:189], v177 offset:17408
	ds_read_b128 v[208:211], v177 offset:19456
	ds_read_b128 v[204:207], v177 offset:18432
	ds_read_b128 v[212:215], v177 offset:20480
	ds_read_b128 v[216:219], v177 offset:21504
	ds_read_b128 v[224:227], v177 offset:23552
	ds_read_b128 v[220:223], v177 offset:22528
	s_setprio 0
	global_load_lds_dwordx4 v[172:173], off
	s_add_i32 m0, s50, 0x2000
	s_add_u32 s50, s36, 0x80000
	v_lshl_add_u64 v[190:191], s[36:37], 0, v[148:149]
	s_addc_u32 s51, s37, 0
	s_add_i32 s56, s56, s43
	global_load_lds_dwordx4 v[190:191], off
	s_mov_b32 m0, s56
	v_lshl_add_u64 v[240:241], s[40:41], 0, v[150:151]
	global_load_lds_dwordx4 v2, s[50:51]
	s_add_i32 m0, s56, 0x2000
	s_nop 0
	global_load_lds_dwordx4 v148, s[50:51]
	v_lshl_add_u64 v[228:229], s[40:41], 0, v[152:153]
	s_waitcnt vmcnt(6)
	s_waitcnt lgkmcnt(7)
	s_setprio 1
	s_barrier
; #define PG8_STAGE(bufoff, gbase, voff) do { _Pragma("unroll") for (int _i = 0; _i < 2; ++_i) \
;         __builtin_amdgcn_global_load_lds((const unsigned*)((const char*)(gbase) + (voff)[_i]), (PG8_LAS unsigned*)(lds + (bufoff) + ldsw + _i * 8192), 16, 0, 0); } while (0)
; #define PG8_LDA(dst, b, h) do { _Pragma("unroll") for (int m = 0; m < 4; ++m) _Pragma("unroll") for (int k = 0; k < 2; ++k) dst[m][k] = *(const PG8_LAS bf16x8*)(lds + PG8_SA(b, h) + aoff + m * 2048 + k * 1024); } while (0)
; #define PG8_LDB(dst, b, h) do { _Pragma("unroll") for (int n = 0; n < 2; ++n) _Pragma("unroll") for (int k = 0; k < 2; ++k) dst[n][k] = *(const PG8_LAS bf16x8*)(lds + PG8_SB(b, h) + boff + n * 2048 + k * 1024); } while (0)
; #define PG8_WAIT_V(n) asm volatile("s_waitcnt vmcnt(" #n ")" ::: "memory")
; #define PG8_WAIT_L(n) asm volatile("s_waitcnt lgkmcnt(" #n ")" ::: "memory")
; #define PG8_BAR __builtin_amdgcn_s_barrier()
; #define PG8_SCHED __builtin_amdgcn_sched_barrier(0)
; template <class Epi, class Sched, bool ALIGN_EPI = false, bool SP2 = false, bool I8 = false>
; __device__ __forceinline__ void gemm_phase(PG8_LAS unsigned char* lds, const Gemm g, const Sched& S, const Epi& E) {
;     ...
;             if constexpr (SP2) {
;             PG8_LDB(B0, 0, 0); PG8_LDB(B1, 0, 1); PG8_SCHED; PG8_LDA(At, 0, 0); PG8_STAGE(PG8_SA(1, 1), a1 + hstep, voffA);
;             PG8_WAIT_V(8); PG8_WAIT_L(0); PG8_BAR; PG8_MMA(0, 0, At, B0); PG8_MMA(0, 1, At, B1); PG8_BAR; PG8_SCHED;
;             PG8_LDA(At, 0, 1); PG8_STAGE(PG8_SB(0, 0), b2, voffB); PG8_STAGE(PG8_SB(0, 1), b2 + hstep, voffB); PG8_STAGE(PG8_SA(0, 0), a2, voffA);
;             PG8_WAIT_V(8); PG8_WAIT_L(0); PG8_BAR; PG8_MMA(1, 0, At, B0); PG8_MMA(1, 1, At, B1); PG8_BAR; PG8_SCHED;
;             PG8_LDB(B0, 1, 0); PG8_LDB(B1, 1, 1); PG8_SCHED; PG8_LDA(At, 1, 0); PG8_STAGE(PG8_SA(0, 1), a2 + hstep, voffA);
;             PG8_WAIT_V(8); PG8_WAIT_L(0); PG8_BAR; PG8_MMA(0, 0, At, B0); PG8_MMA(0, 1, At, B1); PG8_BAR; PG8_SCHED;
;             PG8_LDA(At, 1, 1); PG8_STAGE(PG8_SB(1, 0), b3, voffB); PG8_STAGE(PG8_SB(1, 1), b3 + hstep, voffB); PG8_STAGE(PG8_SA(1, 0), a3, voffA);
;             PG8_WAIT_V(8); PG8_WAIT_L(0); PG8_BAR; PG8_MMA(1, 0, At, B0); PG8_MMA(1, 1, At, B1); PG8_BAR; PG8_SCHED;
	v_mfma_i32_16x16x64_i8 v[64:67], v[116:119], v[182:185], 0
	s_waitcnt lgkmcnt(6)
	v_mfma_i32_16x16x64_i8 v[64:67], v[124:127], v[186:189], v[64:67]
	s_waitcnt lgkmcnt(5)
	v_mfma_i32_16x16x64_i8 v[48:51], v[124:127], v[208:211], 0
	s_waitcnt lgkmcnt(4)
	v_mfma_i32_16x16x64_i8 v[48:51], v[116:119], v[204:207], v[48:51]
	s_waitcnt lgkmcnt(3)
	v_mfma_i32_16x16x64_i8 v[32:35], v[116:119], v[212:215], 0
	s_waitcnt lgkmcnt(2)
	v_mfma_i32_16x16x64_i8 v[32:35], v[124:127], v[216:219], v[32:35]
	s_waitcnt lgkmcnt(1)
	v_mfma_i32_16x16x64_i8 v[16:19], v[124:127], v[224:227], 0
	s_waitcnt lgkmcnt(0)
	v_mfma_i32_16x16x64_i8 v[16:19], v[116:119], v[220:223], v[16:19]
	v_mfma_i32_16x16x64_i8 v[12:15], v[132:135], v[220:223], 0
	v_mfma_i32_16x16x64_i8 v[12:15], v[136:139], v[224:227], v[12:15]
	v_mfma_i32_16x16x64_i8 v[28:31], v[136:139], v[216:219], 0
	v_mfma_i32_16x16x64_i8 v[28:31], v[132:135], v[212:215], v[28:31]
	v_mfma_i32_16x16x64_i8 v[44:47], v[132:135], v[204:207], 0
	v_mfma_i32_16x16x64_i8 v[44:47], v[136:139], v[208:211], v[44:47]
	v_mfma_i32_16x16x64_i8 v[60:63], v[136:139], v[186:189], 0
	v_mfma_i32_16x16x64_i8 v[60:63], v[132:135], v[182:185], v[60:63]
	v_mfma_i32_16x16x64_i8 v[56:59], v[160:163], v[182:185], 0
	v_mfma_i32_16x16x64_i8 v[56:59], v[164:167], v[186:189], v[56:59]
	v_mfma_i32_16x16x64_i8 v[40:43], v[164:167], v[208:211], 0
	v_mfma_i32_16x16x64_i8 v[40:43], v[160:163], v[204:207], v[40:43]
	v_mfma_i32_16x16x64_i8 v[24:27], v[160:163], v[212:215], 0
	v_mfma_i32_16x16x64_i8 v[24:27], v[164:167], v[216:219], v[24:27]
	v_mfma_i32_16x16x64_i8 v[8:11], v[164:167], v[224:227], 0
	v_mfma_i32_16x16x64_i8 v[8:11], v[160:163], v[220:223], v[8:11]
	v_mfma_i32_16x16x64_i8 v[4:7], v[168:171], v[220:223], 0
	v_mfma_i32_16x16x64_i8 v[4:7], v[178:181], v[224:227], v[4:7]
	v_mfma_i32_16x16x64_i8 v[20:23], v[178:181], v[216:219], 0
	v_mfma_i32_16x16x64_i8 v[20:23], v[168:171], v[212:215], v[20:23]
	v_mfma_i32_16x16x64_i8 v[36:39], v[168:171], v[204:207], 0
	v_mfma_i32_16x16x64_i8 v[36:39], v[178:181], v[208:211], v[36:39]
	v_mfma_i32_16x16x64_i8 v[52:55], v[178:181], v[186:189], 0
	v_mfma_i32_16x16x64_i8 v[52:55], v[168:171], v[182:185], v[52:55]
	s_barrier
	s_mov_b32 m0, s44
	s_nop 0
	global_load_lds_dwordx4 v[228:229], off
	s_mov_b32 m0, s45
	s_nop 0
	global_load_lds_dwordx4 v[240:241], off
	s_add_i32 s50, 0, 0x18000
	s_add_i32 s51, 0, 0x1c000
	v_add_u32_e32 v136, s50, v175
	v_add_u32_e32 v178, s51, v175
	ds_read_b128 v[116:119], v136
	ds_read_b128 v[182:185], v177 offset:32768
	ds_read_b128 v[124:127], v136 offset:1024
	ds_read_b128 v[186:189], v177 offset:33792
	ds_read_b128 v[208:211], v177 offset:35840
	ds_read_b128 v[204:207], v177 offset:34816
	ds_read_b128 v[212:215], v177 offset:36864
	ds_read_b128 v[216:219], v177 offset:37888
	s_add_u32 s40, s40, 0x80000
	s_addc_u32 s41, s41, 0
	s_mov_b32 m0, s46
	ds_read_b128 v[224:227], v177 offset:39936
	ds_read_b128 v[220:223], v177 offset:38912
	ds_read_b128 v[132:135], v136 offset:2048
	ds_read_b128 v[136:139], v136 offset:3072
	ds_read_b128 v[160:163], v178
	ds_read_b128 v[164:167], v178 offset:1024
	ds_read_b128 v[168:171], v178 offset:2048
	ds_read_b128 v[178:181], v178 offset:3072
	s_setprio 0
	global_load_lds_dwordx4 v152, s[40:41]
	s_mov_b32 m0, s47
	s_nop 0
	global_load_lds_dwordx4 v150, s[40:41]
	s_waitcnt vmcnt(8)
	s_waitcnt lgkmcnt(14)
	s_setprio 1
	s_barrier
	v_mfma_i32_16x16x64_i8 v[144:147], v[116:119], v[182:185], v[144:147]
	s_waitcnt lgkmcnt(12)
	v_mfma_i32_16x16x64_i8 v[144:147], v[124:127], v[186:189], v[144:147]
	s_waitcnt lgkmcnt(11)
	v_mfma_i32_16x16x64_i8 v[112:115], v[124:127], v[208:211], v[112:115]
	s_waitcnt lgkmcnt(10)
	v_mfma_i32_16x16x64_i8 v[112:115], v[116:119], v[204:207], v[112:115]
	s_waitcnt lgkmcnt(9)
	v_mfma_i32_16x16x64_i8 v[96:99], v[116:119], v[212:215], v[96:99]
	s_waitcnt lgkmcnt(8)
	v_mfma_i32_16x16x64_i8 v[96:99], v[124:127], v[216:219], v[96:99]
	s_waitcnt lgkmcnt(7)
	v_mfma_i32_16x16x64_i8 v[80:83], v[124:127], v[224:227], v[80:83]
	s_waitcnt lgkmcnt(6)
	v_mfma_i32_16x16x64_i8 v[80:83], v[116:119], v[220:223], v[80:83]
	s_waitcnt lgkmcnt(5)
	v_mfma_i32_16x16x64_i8 v[76:79], v[132:135], v[220:223], v[76:79]
	s_waitcnt lgkmcnt(4)
	v_mfma_i32_16x16x64_i8 v[76:79], v[136:139], v[224:227], v[76:79]
	v_mfma_i32_16x16x64_i8 v[92:95], v[136:139], v[216:219], v[92:95]
	v_mfma_i32_16x16x64_i8 v[92:95], v[132:135], v[212:215], v[92:95]
	v_mfma_i32_16x16x64_i8 v[108:111], v[132:135], v[204:207], v[108:111]
	v_mfma_i32_16x16x64_i8 v[108:111], v[136:139], v[208:211], v[108:111]
	v_mfma_i32_16x16x64_i8 v[140:143], v[136:139], v[186:189], v[140:143]
	v_mfma_i32_16x16x64_i8 v[140:143], v[132:135], v[182:185], v[140:143]
	s_waitcnt lgkmcnt(3)
	v_mfma_i32_16x16x64_i8 v[128:131], v[160:163], v[182:185], v[128:131]
	s_waitcnt lgkmcnt(2)
	v_mfma_i32_16x16x64_i8 v[128:131], v[164:167], v[186:189], v[128:131]
	v_mfma_i32_16x16x64_i8 v[104:107], v[164:167], v[208:211], v[104:107]
	v_mfma_i32_16x16x64_i8 v[104:107], v[160:163], v[204:207], v[104:107]
	v_mfma_i32_16x16x64_i8 v[88:91], v[160:163], v[212:215], v[88:91]
	v_mfma_i32_16x16x64_i8 v[88:91], v[164:167], v[216:219], v[88:91]
	v_mfma_i32_16x16x64_i8 v[72:75], v[164:167], v[224:227], v[72:75]
	v_mfma_i32_16x16x64_i8 v[72:75], v[160:163], v[220:223], v[72:75]
	s_waitcnt lgkmcnt(1)
	v_mfma_i32_16x16x64_i8 v[68:71], v[168:171], v[220:223], v[68:71]
	s_waitcnt lgkmcnt(0)
	v_mfma_i32_16x16x64_i8 v[68:71], v[178:181], v[224:227], v[68:71]
	v_mfma_i32_16x16x64_i8 v[84:87], v[178:181], v[216:219], v[84:87]
	v_mfma_i32_16x16x64_i8 v[84:87], v[168:171], v[212:215], v[84:87]
	v_mfma_i32_16x16x64_i8 v[100:103], v[168:171], v[204:207], v[100:103]
	v_mfma_i32_16x16x64_i8 v[100:103], v[178:181], v[208:211], v[100:103]
	v_mfma_i32_16x16x64_i8 v[120:123], v[178:181], v[186:189], v[120:123]
	v_mfma_i32_16x16x64_i8 v[120:123], v[168:171], v[182:185], v[120:123]
	s_barrier
	s_add_i32 s40, s50, s43
	v_lshl_add_u64 v[172:173], v[172:173], 0, s[84:85]
	s_mov_b32 m0, s40
	ds_read_b128 v[182:185], v177 offset:49152
	ds_read_b128 v[186:189], v177 offset:50176
	ds_read_b128 v[208:211], v177 offset:52224
	ds_read_b128 v[204:207], v177 offset:51200
	ds_read_b128 v[212:215], v177 offset:53248
	ds_read_b128 v[216:219], v177 offset:54272
	ds_read_b128 v[224:227], v177 offset:56320
	ds_read_b128 v[220:223], v177 offset:55296
	s_setprio 0
	global_load_lds_dwordx4 v[172:173], off
	s_add_i32 m0, s40, 0x2000
	s_add_u32 s36, s36, 0x80080
	v_lshl_add_u64 v[172:173], v[190:191], 0, s[84:85]
	s_addc_u32 s37, s37, 0
	s_add_i32 s40, s51, s43
	global_load_lds_dwordx4 v[172:173], off
	s_mov_b32 m0, s40
	s_nop 0
	global_load_lds_dwordx4 v2, s[36:37]
	s_add_i32 m0, s40, 0x2000
	s_nop 0
	global_load_lds_dwordx4 v148, s[36:37]
	s_cmp_eq_u32 s76, 28
	s_cbranch_scc0 .Ldefer_208_peel
	v_lshl_add_u64 v[172:173], v[228:229], 0, s[84:85]
	s_mov_b32 m0, s52
	s_nop 0
	global_load_lds_dwordx4 v[172:173], off
	v_lshl_add_u64 v[172:173], v[240:241], 0, s[84:85]
	s_mov_b32 m0, s53
	s_nop 0
	global_load_lds_dwordx4 v[172:173], off

; #define PG8_STAGE(bufoff, gbase, voff) do { _Pragma("unroll") for (int _i = 0; _i < 2; ++_i) \
;         __builtin_amdgcn_global_load_lds((const unsigned*)((const char*)(gbase) + (voff)[_i]), (PG8_LAS unsigned*)(lds + (bufoff) + ldsw + _i * 8192), 16, 0, 0); } while (0)
; #define PG8_LDA(dst, b, h) do { _Pragma("unroll") for (int m = 0; m < 4; ++m) _Pragma("unroll") for (int k = 0; k < 2; ++k) dst[m][k] = *(const PG8_LAS bf16x8*)(lds + PG8_SA(b, h) + aoff + m * 2048 + k * 1024); } while (0)
; #define PG8_WAIT_V(n) asm volatile("s_waitcnt vmcnt(" #n ")" ::: "memory")
; #define PG8_WAIT_L(n) asm volatile("s_waitcnt lgkmcnt(" #n ")" ::: "memory")
; #define PG8_BAR __builtin_amdgcn_s_barrier()
; template <class Epi, class Sched, bool ALIGN_EPI = false, bool SP2 = false, bool I8 = false>
; __device__ __forceinline__ void gemm_phase(PG8_LAS unsigned char* lds, const Gemm g, const Sched& S, const Epi& E) {
;     ...
;         for (int t = 0; t < nt; t += 2) {
;             const bool last = (t == nt - 2);
;             const char* a1 = cA + (size_t)(t + 1) * kstep;
;             const char* a2 = last ? nA : cA + (size_t)(t + 2) * kstep; const char* b2 = last ? nB : cB + (size_t)(t + 2) * kstep;
;             const char* a3 = a2 + kstep; const char* b3 = b2 + kstep;
;             if (last && has_next) S.a_ready(nxt);
;             if constexpr (SP2) {
;             PG8_LDB(B0, 0, 0); PG8_LDB(B1, 0, 1); PG8_SCHED; PG8_LDA(At, 0, 0); PG8_STAGE(PG8_SA(1, 1), a1 + hstep, voffA);
;             PG8_WAIT_V(8); PG8_WAIT_L(0); PG8_BAR; PG8_MMA(0, 0, At, B0); PG8_MMA(0, 1, At, B1); PG8_BAR; PG8_SCHED;
;             PG8_LDA(At, 0, 1); PG8_STAGE(PG8_SB(0, 0), b2, voffB); PG8_STAGE(PG8_SB(0, 1), b2 + hstep, voffB); PG8_STAGE(PG8_SA(0, 0), a2, voffA);
;             PG8_WAIT_V(8); PG8_WAIT_L(0); PG8_BAR; PG8_MMA(1, 0, At, B0); PG8_MMA(1, 1, At, B1); PG8_BAR; PG8_SCHED;
;             PG8_LDB(B0, 1, 0); PG8_LDB(B1, 1, 1); PG8_SCHED; PG8_LDA(At, 1, 0); PG8_STAGE(PG8_SA(0, 1), a2 + hstep, voffA);
;             PG8_WAIT_V(8); PG8_WAIT_L(0); PG8_BAR; PG8_MMA(0, 0, At, B0); PG8_MMA(0, 1, At, B1); PG8_BAR; PG8_SCHED;
;             PG8_LDA(At, 1, 1); PG8_STAGE(PG8_SB(1, 0), b3, voffB); PG8_STAGE(PG8_SB(1, 1), b3 + hstep, voffB); PG8_STAGE(PG8_SA(1, 0), a3, voffA);
;             PG8_WAIT_V(8); PG8_WAIT_L(0); PG8_BAR; PG8_MMA(1, 0, At, B0); PG8_MMA(1, 1, At, B1); PG8_BAR; PG8_SCHED;
.LBB0_208:
	s_add_u32 s36, s26, 0xfff80080
	s_addc_u32 s37, s27, -1
	s_add_i32 s50, 0, 0x10000
	s_cmp_eq_u32 s76, 28
	s_cselect_b32 s41, s19, s37
	s_cselect_b32 s40, s64, s36
	s_cselect_b32 s37, s17, s73
	s_cselect_b32 s36, s65, s72
	s_add_i32 s56, 0, 0x14000
	v_add_u32_e32 v136, s50, v175
	v_add_u32_e32 v172, s56, v175
	ds_read_b128 v[116:119], v136
	ds_read_b128 v[124:127], v136 offset:1024
	ds_read_b128 v[132:135], v136 offset:2048
	ds_read_b128 v[136:139], v136 offset:3072
	ds_read_b128 v[160:163], v172
	ds_read_b128 v[164:167], v172 offset:1024
	ds_read_b128 v[168:171], v172 offset:2048
	ds_read_b128 v[178:181], v172 offset:3072
	v_lshl_add_u64 v[172:173], v[228:229], 0, s[84:85]
	s_mov_b32 m0, s52
	s_nop 0
	global_load_lds_dwordx4 v[172:173], off
	v_lshl_add_u64 v[172:173], v[240:241], 0, s[84:85]
	s_mov_b32 m0, s53
	s_nop 0
	global_load_lds_dwordx4 v[172:173], off
	s_add_i32 m0, s44, 0xc000
	ds_read_b128 v[182:185], v177
	ds_read_b128 v[186:189], v177 offset:1024
	ds_read_b128 v[204:207], v177 offset:2048
	ds_read_b128 v[208:211], v177 offset:3072
	ds_read_b128 v[212:215], v177 offset:4096
	ds_read_b128 v[216:219], v177 offset:5120
	ds_read_b128 v[220:223], v177 offset:6144
	ds_read_b128 v[224:227], v177 offset:7168
	global_load_lds_dwordx4 v156, s[26:27]
	s_add_i32 m0, s44, 0xe000
	s_nop 0
	global_load_lds_dwordx4 v158, s[26:27]
	s_waitcnt vmcnt(8)
	s_waitcnt lgkmcnt(7)
	s_setprio 1
	s_barrier
	v_mfma_i32_16x16x64_i8 v[144:147], v[116:119], v[182:185], v[144:147]
	s_waitcnt lgkmcnt(6)
	v_mfma_i32_16x16x64_i8 v[144:147], v[124:127], v[186:189], v[144:147]
	s_waitcnt lgkmcnt(4)
	v_mfma_i32_16x16x64_i8 v[112:115], v[124:127], v[208:211], v[112:115]
	v_mfma_i32_16x16x64_i8 v[112:115], v[116:119], v[204:207], v[112:115]
	s_waitcnt lgkmcnt(3)
	v_mfma_i32_16x16x64_i8 v[96:99], v[116:119], v[212:215], v[96:99]
	s_waitcnt lgkmcnt(2)
	v_mfma_i32_16x16x64_i8 v[96:99], v[124:127], v[216:219], v[96:99]
	s_waitcnt lgkmcnt(0)
	v_mfma_i32_16x16x64_i8 v[80:83], v[124:127], v[224:227], v[80:83]
	v_mfma_i32_16x16x64_i8 v[80:83], v[116:119], v[220:223], v[80:83]
	v_mfma_i32_16x16x64_i8 v[76:79], v[132:135], v[220:223], v[76:79]
	v_mfma_i32_16x16x64_i8 v[76:79], v[136:139], v[224:227], v[76:79]
	v_mfma_i32_16x16x64_i8 v[92:95], v[136:139], v[216:219], v[92:95]
	v_mfma_i32_16x16x64_i8 v[92:95], v[132:135], v[212:215], v[92:95]
	v_mfma_i32_16x16x64_i8 v[108:111], v[132:135], v[204:207], v[108:111]
	v_mfma_i32_16x16x64_i8 v[108:111], v[136:139], v[208:211], v[108:111]
	v_mfma_i32_16x16x64_i8 v[140:143], v[136:139], v[186:189], v[140:143]
	v_mfma_i32_16x16x64_i8 v[140:143], v[132:135], v[182:185], v[140:143]
	v_mfma_i32_16x16x64_i8 v[128:131], v[160:163], v[182:185], v[128:131]
	v_mfma_i32_16x16x64_i8 v[128:131], v[164:167], v[186:189], v[128:131]
	v_mfma_i32_16x16x64_i8 v[104:107], v[164:167], v[208:211], v[104:107]
	v_mfma_i32_16x16x64_i8 v[104:107], v[160:163], v[204:207], v[104:107]
	v_mfma_i32_16x16x64_i8 v[88:91], v[160:163], v[212:215], v[88:91]
	v_mfma_i32_16x16x64_i8 v[88:91], v[164:167], v[216:219], v[88:91]
	v_mfma_i32_16x16x64_i8 v[72:75], v[164:167], v[224:227], v[72:75]
	v_mfma_i32_16x16x64_i8 v[72:75], v[160:163], v[220:223], v[72:75]
	v_mfma_i32_16x16x64_i8 v[68:71], v[168:171], v[220:223], v[68:71]
	v_mfma_i32_16x16x64_i8 v[68:71], v[178:181], v[224:227], v[68:71]
	v_mfma_i32_16x16x64_i8 v[84:87], v[178:181], v[216:219], v[84:87]
	v_mfma_i32_16x16x64_i8 v[84:87], v[168:171], v[212:215], v[84:87]
	v_mfma_i32_16x16x64_i8 v[100:103], v[168:171], v[204:207], v[100:103]
	v_mfma_i32_16x16x64_i8 v[100:103], v[178:181], v[208:211], v[100:103]
	v_mfma_i32_16x16x64_i8 v[120:123], v[178:181], v[186:189], v[120:123]
	v_mfma_i32_16x16x64_i8 v[120:123], v[168:171], v[182:185], v[120:123]
	s_barrier
	s_add_i32 s50, s50, s43
	v_lshl_add_u64 v[172:173], s[36:37], 0, v[2:3]
	s_mov_b32 m0, s50
	ds_read_b128 v[182:185], v177 offset:16384
	ds_read_b128 v[186:189], v177 offset:17408
	ds_read_b128 v[208:211], v177 offset:19456
	ds_read_b128 v[204:207], v177 offset:18432
	ds_read_b128 v[212:215], v177 offset:20480
	ds_read_b128 v[216:219], v177 offset:21504
	ds_read_b128 v[224:227], v177 offset:23552
	ds_read_b128 v[220:223], v177 offset:22528
	s_setprio 0
	global_load_lds_dwordx4 v[172:173], off
	s_add_i32 m0, s50, 0x2000
	s_add_u32 s50, s36, 0x80000
	v_lshl_add_u64 v[190:191], s[36:37], 0, v[148:149]
	s_addc_u32 s51, s37, 0
	s_add_i32 s56, s56, s43
	global_load_lds_dwordx4 v[190:191], off
	s_mov_b32 m0, s56
	v_lshl_add_u64 v[240:241], s[40:41], 0, v[150:151]
	global_load_lds_dwordx4 v2, s[50:51]
	s_add_i32 m0, s56, 0x2000
	s_nop 0
	global_load_lds_dwordx4 v148, s[50:51]
	v_lshl_add_u64 v[228:229], s[40:41], 0, v[152:153]
	s_waitcnt vmcnt(6)
	s_waitcnt lgkmcnt(7)
	s_setprio 1
	s_barrier
; #define PG8_STAGE(bufoff, gbase, voff) do { _Pragma("unroll") for (int _i = 0; _i < 2; ++_i) \
;         __builtin_amdgcn_global_load_lds((const unsigned*)((const char*)(gbase) + (voff)[_i]), (PG8_LAS unsigned*)(lds + (bufoff) + ldsw + _i * 8192), 16, 0, 0); } while (0)
; #define PG8_LDA(dst, b, h) do { _Pragma("unroll") for (int m = 0; m < 4; ++m) _Pragma("unroll") for (int k = 0; k < 2; ++k) dst[m][k] = *(const PG8_LAS bf16x8*)(lds + PG8_SA(b, h) + aoff + m * 2048 + k * 1024); } while (0)
; #define PG8_LDB(dst, b, h) do { _Pragma("unroll") for (int n = 0; n < 2; ++n) _Pragma("unroll") for (int k = 0; k < 2; ++k) dst[n][k] = *(const PG8_LAS bf16x8*)(lds + PG8_SB(b, h) + boff + n * 2048 + k * 1024); } while (0)
; #define PG8_WAIT_V(n) asm volatile("s_waitcnt vmcnt(" #n ")" ::: "memory")
; #define PG8_WAIT_L(n) asm volatile("s_waitcnt lgkmcnt(" #n ")" ::: "memory")
; #define PG8_BAR __builtin_amdgcn_s_barrier()
; #define PG8_SCHED __builtin_amdgcn_sched_barrier(0)
; template <class Epi, class Sched, bool ALIGN_EPI = false, bool SP2 = false, bool I8 = false>
; __device__ __forceinline__ void gemm_phase(PG8_LAS unsigned char* lds, const Gemm g, const Sched& S, const Epi& E) {
;     ...
;             PG8_WAIT_V(8); PG8_WAIT_L(0); PG8_BAR; PG8_MMA(0, 0, At, B0); PG8_MMA(0, 1, At, B1); PG8_BAR; PG8_SCHED;
;             PG8_LDA(At, 0, 1); PG8_STAGE(PG8_SB(0, 0), b2, voffB); PG8_STAGE(PG8_SB(0, 1), b2 + hstep, voffB); PG8_STAGE(PG8_SA(0, 0), a2, voffA);
;             PG8_WAIT_V(8); PG8_WAIT_L(0); PG8_BAR; PG8_MMA(1, 0, At, B0); PG8_MMA(1, 1, At, B1); PG8_BAR; PG8_SCHED;
;             PG8_LDB(B0, 1, 0); PG8_LDB(B1, 1, 1); PG8_SCHED; PG8_LDA(At, 1, 0); PG8_STAGE(PG8_SA(0, 1), a2 + hstep, voffA);
;             PG8_WAIT_V(8); PG8_WAIT_L(0); PG8_BAR; PG8_MMA(0, 0, At, B0); PG8_MMA(0, 1, At, B1); PG8_BAR; PG8_SCHED;
;             PG8_LDA(At, 1, 1); PG8_STAGE(PG8_SB(1, 0), b3, voffB); PG8_STAGE(PG8_SB(1, 1), b3 + hstep, voffB); PG8_STAGE(PG8_SA(1, 0), a3, voffA);
;             PG8_WAIT_V(8); PG8_WAIT_L(0); PG8_BAR; PG8_MMA(1, 0, At, B0); PG8_MMA(1, 1, At, B1); PG8_BAR; PG8_SCHED;
	v_mfma_i32_16x16x64_i8 v[64:67], v[116:119], v[182:185], v[64:67]
	s_waitcnt lgkmcnt(6)
	v_mfma_i32_16x16x64_i8 v[64:67], v[124:127], v[186:189], v[64:67]
	s_waitcnt lgkmcnt(5)
	v_mfma_i32_16x16x64_i8 v[48:51], v[124:127], v[208:211], v[48:51]
	s_waitcnt lgkmcnt(4)
	v_mfma_i32_16x16x64_i8 v[48:51], v[116:119], v[204:207], v[48:51]
	s_waitcnt lgkmcnt(3)
	v_mfma_i32_16x16x64_i8 v[32:35], v[116:119], v[212:215], v[32:35]
	s_waitcnt lgkmcnt(2)
	v_mfma_i32_16x16x64_i8 v[32:35], v[124:127], v[216:219], v[32:35]
	s_waitcnt lgkmcnt(1)
	v_mfma_i32_16x16x64_i8 v[16:19], v[124:127], v[224:227], v[16:19]
	s_waitcnt lgkmcnt(0)
	v_mfma_i32_16x16x64_i8 v[16:19], v[116:119], v[220:223], v[16:19]
	v_mfma_i32_16x16x64_i8 v[12:15], v[132:135], v[220:223], v[12:15]
	v_mfma_i32_16x16x64_i8 v[12:15], v[136:139], v[224:227], v[12:15]
	v_mfma_i32_16x16x64_i8 v[28:31], v[136:139], v[216:219], v[28:31]
	v_mfma_i32_16x16x64_i8 v[28:31], v[132:135], v[212:215], v[28:31]
	v_mfma_i32_16x16x64_i8 v[44:47], v[132:135], v[204:207], v[44:47]
	v_mfma_i32_16x16x64_i8 v[44:47], v[136:139], v[208:211], v[44:47]
	v_mfma_i32_16x16x64_i8 v[60:63], v[136:139], v[186:189], v[60:63]
	v_mfma_i32_16x16x64_i8 v[60:63], v[132:135], v[182:185], v[60:63]
	v_mfma_i32_16x16x64_i8 v[56:59], v[160:163], v[182:185], v[56:59]
	v_mfma_i32_16x16x64_i8 v[56:59], v[164:167], v[186:189], v[56:59]
	v_mfma_i32_16x16x64_i8 v[40:43], v[164:167], v[208:211], v[40:43]
	v_mfma_i32_16x16x64_i8 v[40:43], v[160:163], v[204:207], v[40:43]
	v_mfma_i32_16x16x64_i8 v[24:27], v[160:163], v[212:215], v[24:27]
	v_mfma_i32_16x16x64_i8 v[24:27], v[164:167], v[216:219], v[24:27]
	v_mfma_i32_16x16x64_i8 v[8:11], v[164:167], v[224:227], v[8:11]
	v_mfma_i32_16x16x64_i8 v[8:11], v[160:163], v[220:223], v[8:11]
	v_mfma_i32_16x16x64_i8 v[4:7], v[168:171], v[220:223], v[4:7]
	v_mfma_i32_16x16x64_i8 v[4:7], v[178:181], v[224:227], v[4:7]
	v_mfma_i32_16x16x64_i8 v[20:23], v[178:181], v[216:219], v[20:23]
	v_mfma_i32_16x16x64_i8 v[20:23], v[168:171], v[212:215], v[20:23]
	v_mfma_i32_16x16x64_i8 v[36:39], v[168:171], v[204:207], v[36:39]
	v_mfma_i32_16x16x64_i8 v[36:39], v[178:181], v[208:211], v[36:39]
	v_mfma_i32_16x16x64_i8 v[52:55], v[178:181], v[186:189], v[52:55]
	v_mfma_i32_16x16x64_i8 v[52:55], v[168:171], v[182:185], v[52:55]
	s_barrier
	s_mov_b32 m0, s44
	s_nop 0
	global_load_lds_dwordx4 v[228:229], off
	s_mov_b32 m0, s45
	s_nop 0
	global_load_lds_dwordx4 v[240:241], off
	s_add_i32 s50, 0, 0x18000
	s_add_i32 s51, 0, 0x1c000
	v_add_u32_e32 v136, s50, v175
	v_add_u32_e32 v178, s51, v175
	ds_read_b128 v[116:119], v136
	ds_read_b128 v[182:185], v177 offset:32768
	ds_read_b128 v[124:127], v136 offset:1024
	ds_read_b128 v[186:189], v177 offset:33792
	ds_read_b128 v[208:211], v177 offset:35840
	ds_read_b128 v[204:207], v177 offset:34816
	ds_read_b128 v[212:215], v177 offset:36864
	ds_read_b128 v[216:219], v177 offset:37888
	s_add_u32 s40, s40, 0x80000
	s_addc_u32 s41, s41, 0
	s_mov_b32 m0, s46
	ds_read_b128 v[224:227], v177 offset:39936
	ds_read_b128 v[220:223], v177 offset:38912
	ds_read_b128 v[132:135], v136 offset:2048
	ds_read_b128 v[136:139], v136 offset:3072
	ds_read_b128 v[160:163], v178
	ds_read_b128 v[164:167], v178 offset:1024
	ds_read_b128 v[168:171], v178 offset:2048
	ds_read_b128 v[178:181], v178 offset:3072
	s_setprio 0
	global_load_lds_dwordx4 v152, s[40:41]
	s_mov_b32 m0, s47
	s_nop 0
	global_load_lds_dwordx4 v150, s[40:41]
	s_waitcnt vmcnt(8)
	s_waitcnt lgkmcnt(14)
	s_setprio 1
	s_barrier
; #define PG8_STAGE(bufoff, gbase, voff) do { _Pragma("unroll") for (int _i = 0; _i < 2; ++_i) \
;         __builtin_amdgcn_global_load_lds((const unsigned*)((const char*)(gbase) + (voff)[_i]), (PG8_LAS unsigned*)(lds + (bufoff) + ldsw + _i * 8192), 16, 0, 0); } while (0)
; #define PG8_LDA(dst, b, h) do { _Pragma("unroll") for (int m = 0; m < 4; ++m) _Pragma("unroll") for (int k = 0; k < 2; ++k) dst[m][k] = *(const PG8_LAS bf16x8*)(lds + PG8_SA(b, h) + aoff + m * 2048 + k * 1024); } while (0)
; #define PG8_LDB(dst, b, h) do { _Pragma("unroll") for (int n = 0; n < 2; ++n) _Pragma("unroll") for (int k = 0; k < 2; ++k) dst[n][k] = *(const PG8_LAS bf16x8*)(lds + PG8_SB(b, h) + boff + n * 2048 + k * 1024); } while (0)
; #define PG8_WAIT_V(n) asm volatile("s_waitcnt vmcnt(" #n ")" ::: "memory")
; #define PG8_WAIT_L(n) asm volatile("s_waitcnt lgkmcnt(" #n ")" ::: "memory")
; #define PG8_BAR __builtin_amdgcn_s_barrier()
; #define PG8_SCHED __builtin_amdgcn_sched_barrier(0)
; template <class Epi, class Sched, bool ALIGN_EPI = false, bool SP2 = false, bool I8 = false>
; __device__ __forceinline__ void gemm_phase(PG8_LAS unsigned char* lds, const Gemm g, const Sched& S, const Epi& E) {
;     ...
;             PG8_WAIT_V(8); PG8_WAIT_L(0); PG8_BAR; PG8_MMA(0, 0, At, B0); PG8_MMA(0, 1, At, B1); PG8_BAR; PG8_SCHED;
;             PG8_LDA(At, 0, 1); PG8_STAGE(PG8_SB(0, 0), b2, voffB); PG8_STAGE(PG8_SB(0, 1), b2 + hstep, voffB); PG8_STAGE(PG8_SA(0, 0), a2, voffA);
;             PG8_WAIT_V(8); PG8_WAIT_L(0); PG8_BAR; PG8_MMA(1, 0, At, B0); PG8_MMA(1, 1, At, B1); PG8_BAR; PG8_SCHED;
;             PG8_LDB(B0, 1, 0); PG8_LDB(B1, 1, 1); PG8_SCHED; PG8_LDA(At, 1, 0); PG8_STAGE(PG8_SA(0, 1), a2 + hstep, voffA);
;             PG8_WAIT_V(8); PG8_WAIT_L(0); PG8_BAR; PG8_MMA(0, 0, At, B0); PG8_MMA(0, 1, At, B1); PG8_BAR; PG8_SCHED;
;             PG8_LDA(At, 1, 1); PG8_STAGE(PG8_SB(1, 0), b3, voffB); PG8_STAGE(PG8_SB(1, 1), b3 + hstep, voffB); PG8_STAGE(PG8_SA(1, 0), a3, voffA);
;             PG8_WAIT_V(8); PG8_WAIT_L(0); PG8_BAR; PG8_MMA(1, 0, At, B0); PG8_MMA(1, 1, At, B1); PG8_BAR; PG8_SCHED;
	v_mfma_i32_16x16x64_i8 v[144:147], v[116:119], v[182:185], v[144:147]
	s_waitcnt lgkmcnt(12)
	v_mfma_i32_16x16x64_i8 v[144:147], v[124:127], v[186:189], v[144:147]
	s_waitcnt lgkmcnt(11)
	v_mfma_i32_16x16x64_i8 v[112:115], v[124:127], v[208:211], v[112:115]
	s_waitcnt lgkmcnt(10)
	v_mfma_i32_16x16x64_i8 v[112:115], v[116:119], v[204:207], v[112:115]
	s_waitcnt lgkmcnt(9)
	v_mfma_i32_16x16x64_i8 v[96:99], v[116:119], v[212:215], v[96:99]
	s_waitcnt lgkmcnt(8)
	v_mfma_i32_16x16x64_i8 v[96:99], v[124:127], v[216:219], v[96:99]
	s_waitcnt lgkmcnt(7)
	v_mfma_i32_16x16x64_i8 v[80:83], v[124:127], v[224:227], v[80:83]
	s_waitcnt lgkmcnt(6)
	v_mfma_i32_16x16x64_i8 v[80:83], v[116:119], v[220:223], v[80:83]
	s_waitcnt lgkmcnt(5)
	v_mfma_i32_16x16x64_i8 v[76:79], v[132:135], v[220:223], v[76:79]
	s_waitcnt lgkmcnt(4)
	v_mfma_i32_16x16x64_i8 v[76:79], v[136:139], v[224:227], v[76:79]
	v_mfma_i32_16x16x64_i8 v[92:95], v[136:139], v[216:219], v[92:95]
	v_mfma_i32_16x16x64_i8 v[92:95], v[132:135], v[212:215], v[92:95]
	v_mfma_i32_16x16x64_i8 v[108:111], v[132:135], v[204:207], v[108:111]
	v_mfma_i32_16x16x64_i8 v[108:111], v[136:139], v[208:211], v[108:111]
	v_mfma_i32_16x16x64_i8 v[140:143], v[136:139], v[186:189], v[140:143]
	v_mfma_i32_16x16x64_i8 v[140:143], v[132:135], v[182:185], v[140:143]
	s_waitcnt lgkmcnt(3)
	v_mfma_i32_16x16x64_i8 v[128:131], v[160:163], v[182:185], v[128:131]
	s_waitcnt lgkmcnt(2)
	v_mfma_i32_16x16x64_i8 v[128:131], v[164:167], v[186:189], v[128:131]
	v_mfma_i32_16x16x64_i8 v[104:107], v[164:167], v[208:211], v[104:107]
	v_mfma_i32_16x16x64_i8 v[104:107], v[160:163], v[204:207], v[104:107]
	v_mfma_i32_16x16x64_i8 v[88:91], v[160:163], v[212:215], v[88:91]
	v_mfma_i32_16x16x64_i8 v[88:91], v[164:167], v[216:219], v[88:91]
	v_mfma_i32_16x16x64_i8 v[72:75], v[164:167], v[224:227], v[72:75]
	v_mfma_i32_16x16x64_i8 v[72:75], v[160:163], v[220:223], v[72:75]
	s_waitcnt lgkmcnt(1)
	v_mfma_i32_16x16x64_i8 v[68:71], v[168:171], v[220:223], v[68:71]
	s_waitcnt lgkmcnt(0)
	v_mfma_i32_16x16x64_i8 v[68:71], v[178:181], v[224:227], v[68:71]
	v_mfma_i32_16x16x64_i8 v[84:87], v[178:181], v[216:219], v[84:87]
	v_mfma_i32_16x16x64_i8 v[84:87], v[168:171], v[212:215], v[84:87]
	v_mfma_i32_16x16x64_i8 v[100:103], v[168:171], v[204:207], v[100:103]
	v_mfma_i32_16x16x64_i8 v[100:103], v[178:181], v[208:211], v[100:103]
	v_mfma_i32_16x16x64_i8 v[120:123], v[178:181], v[186:189], v[120:123]
	v_mfma_i32_16x16x64_i8 v[120:123], v[168:171], v[182:185], v[120:123]
	s_barrier
	s_add_i32 s40, s50, s43
	v_lshl_add_u64 v[172:173], v[172:173], 0, s[84:85]
	s_mov_b32 m0, s40
	ds_read_b128 v[182:185], v177 offset:49152
	ds_read_b128 v[186:189], v177 offset:50176
	ds_read_b128 v[208:211], v177 offset:52224
	ds_read_b128 v[204:207], v177 offset:51200
	ds_read_b128 v[212:215], v177 offset:53248
	ds_read_b128 v[216:219], v177 offset:54272
	ds_read_b128 v[224:227], v177 offset:56320
	ds_read_b128 v[220:223], v177 offset:55296
	s_setprio 0
	global_load_lds_dwordx4 v[172:173], off
	s_add_i32 m0, s40, 0x2000
	s_add_u32 s36, s36, 0x80080
	v_lshl_add_u64 v[172:173], v[190:191], 0, s[84:85]
	s_addc_u32 s37, s37, 0
	s_add_i32 s40, s51, s43
	global_load_lds_dwordx4 v[172:173], off
	s_mov_b32 m0, s40
	s_nop 0
	global_load_lds_dwordx4 v2, s[36:37]
	s_add_i32 m0, s40, 0x2000
	s_nop 0
	global_load_lds_dwordx4 v148, s[36:37]
	s_cmp_eq_u32 s76, 28
	s_cbranch_scc0 .Ldefer_208_body
	v_lshl_add_u64 v[172:173], v[228:229], 0, s[84:85]
	s_mov_b32 m0, s52
	s_nop 0
	global_load_lds_dwordx4 v[172:173], off
	v_lshl_add_u64 v[172:173], v[240:241], 0, s[84:85]
	s_mov_b32 m0, s53
	s_nop 0
	global_load_lds_dwordx4 v[172:173], off

; #define PG8_STAGE(bufoff, gbase, voff) do { _Pragma("unroll") for (int _i = 0; _i < 2; ++_i) \
;         __builtin_amdgcn_global_load_lds((const unsigned*)((const char*)(gbase) + (voff)[_i]), (PG8_LAS unsigned*)(lds + (bufoff) + ldsw + _i * 8192), 16, 0, 0); } while (0)
; #define PG8_LDA(dst, b, h) do { _Pragma("unroll") for (int m = 0; m < 4; ++m) _Pragma("unroll") for (int k = 0; k < 2; ++k) dst[m][k] = *(const PG8_LAS bf16x8*)(lds + PG8_SA(b, h) + aoff + m * 2048 + k * 1024); } while (0)
; #define PG8_BAR __builtin_amdgcn_s_barrier()
; template <class Epi, class Sched, bool ALIGN_EPI = false, bool SP2 = false, bool I8 = false>
; __device__ __forceinline__ void gemm_phase(PG8_LAS unsigned char* lds, const Gemm g, const Sched& S, const Epi& E) {
;     ...
;         const char* nA = has_next ? (const char*)g.A + (size_t)nxt.pm * tstep : cA; const char* nB = has_next ? (const char*)g.Bt + (size_t)nxt.pn * tstep : cB;
;         for (int t = 0; t < nt; t += 2) {
;             const bool last = (t == nt - 2);
;             const char* a1 = cA + (size_t)(t + 1) * kstep;
;             const char* a2 = last ? nA : cA + (size_t)(t + 2) * kstep; const char* b2 = last ? nB : cB + (size_t)(t + 2) * kstep;
;             const char* a3 = a2 + kstep; const char* b3 = b2 + kstep;
;             if (last && has_next) S.a_ready(nxt);
;             if constexpr (SP2) {
;             PG8_LDB(B0, 0, 0); PG8_LDB(B1, 0, 1); PG8_SCHED; PG8_LDA(At, 0, 0); PG8_STAGE(PG8_SA(1, 1), a1 + hstep, voffA);
;             PG8_WAIT_V(8); PG8_WAIT_L(0); PG8_BAR; PG8_MMA(0, 0, At, B0); PG8_MMA(0, 1, At, B1); PG8_BAR; PG8_SCHED;
;             PG8_LDA(At, 0, 1); PG8_STAGE(PG8_SB(0, 0), b2, voffB); PG8_STAGE(PG8_SB(0, 1), b2 + hstep, voffB); PG8_STAGE(PG8_SA(0, 0), a2, voffA);
;             PG8_WAIT_V(8); PG8_WAIT_L(0); PG8_BAR; PG8_MMA(1, 0, At, B0); PG8_MMA(1, 1, At, B1); PG8_BAR; PG8_SCHED;
;             PG8_LDB(B0, 1, 0); PG8_LDB(B1, 1, 1); PG8_SCHED; PG8_LDA(At, 1, 0); PG8_STAGE(PG8_SA(0, 1), a2 + hstep, voffA);
;             PG8_WAIT_V(8); PG8_WAIT_L(0); PG8_BAR; PG8_MMA(0, 0, At, B0); PG8_MMA(0, 1, At, B1); PG8_BAR; PG8_SCHED;
;             PG8_LDA(At, 1, 1); PG8_STAGE(PG8_SB(1, 0), b3, voffB); PG8_STAGE(PG8_SB(1, 1), b3 + hstep, voffB); PG8_STAGE(PG8_SA(1, 0), a3, voffA);
;             PG8_WAIT_V(8); PG8_WAIT_L(0); PG8_BAR; PG8_MMA(1, 0, At, B0); PG8_MMA(1, 1, At, B1); PG8_BAR; PG8_SCHED;
.LBB0_229:
	s_ashr_i32 s37, s36, 31
	s_lshl_b64 s[34:35], s[36:37], 21
	s_add_u32 s40, s42, s34
	s_addc_u32 s41, s43, s35
	s_and_b64 s[34:35], s[8:9], exec
	s_cselect_b32 s11, s41, s13
	s_cselect_b32 s34, s40, s12
	s_ashr_i32 s27, s26, 31
	s_lshl_b64 s[50:51], s[26:27], 21
	s_add_u32 s54, s44, s50
	s_addc_u32 s55, s45, s51
	s_and_b64 s[50:51], s[8:9], exec
	s_cselect_b32 s27, s55, s73
	s_cselect_b32 s35, s54, s72
	s_add_u32 s12, s12, 0x100080
	s_addc_u32 s13, s13, 0
	s_add_u32 s37, s72, 0x100
	s_addc_u32 s61, s73, 0
	s_mov_b32 s97, -2
	s_add_u32 s50, s12, 0xfff00080
	s_addc_u32 s51, s13, -1
	s_add_i32 s56, 0, 0x10000
	s_cmp_eq_u32 s97, 60
	s_cselect_b32 s77, s11, s51
	s_cselect_b32 s76, s34, s50
	s_cselect_b32 s73, s27, s61
	s_cselect_b32 s72, s35, s37
	s_add_i32 s57, 0, 0x14000
	v_add_u32_e32 v156, s56, v171
	v_add_u32_e32 v168, s57, v171
	s_waitcnt vmcnt(0)
	ds_read_b128 v[112:115], v156
	ds_read_b128 v[184:187], v173
	ds_read_b128 v[120:123], v156 offset:1024
	ds_read_b128 v[188:191], v173 offset:1024
	ds_read_b128 v[208:211], v173 offset:3072
	ds_read_b128 v[204:207], v173 offset:2048
	s_waitcnt lgkmcnt(0)
	ds_read_b128 v[212:215], v173 offset:4096
	ds_read_b128 v[216:219], v173 offset:5120
	s_add_i32 m0, s47, 0xc000
	ds_read_b128 v[224:227], v173 offset:7168
	ds_read_b128 v[220:223], v173 offset:6144
	ds_read_b128 v[152:155], v156 offset:2048
	ds_read_b128 v[156:159], v156 offset:3072
	ds_read_b128 v[160:163], v168
	ds_read_b128 v[164:167], v168 offset:1024
	ds_read_b128 v[176:179], v168 offset:2048
	ds_read_b128 v[180:183], v168 offset:3072
	global_load_lds_dwordx4 v148, s[12:13]
	s_add_i32 m0, s47, 0xe000
	s_nop 0
	global_load_lds_dwordx4 v150, s[12:13]
	s_waitcnt vmcnt(8)
	s_waitcnt lgkmcnt(14)
	s_setprio 1
	s_barrier
	v_mfma_f32_16x16x32_bf16 v[136:139], v[112:115], v[184:187], 0
	s_waitcnt lgkmcnt(12)
	v_mfma_f32_16x16x32_bf16 v[136:139], v[120:123], v[188:191], v[136:139]
	s_waitcnt lgkmcnt(11)
	v_mfma_f32_16x16x32_bf16 v[116:119], v[120:123], v[208:211], 0
	s_waitcnt lgkmcnt(10)
	v_mfma_f32_16x16x32_bf16 v[116:119], v[112:115], v[204:207], v[116:119]
	s_waitcnt lgkmcnt(9)
	v_mfma_f32_16x16x32_bf16 v[96:99], v[112:115], v[212:215], 0
	s_waitcnt lgkmcnt(8)
	v_mfma_f32_16x16x32_bf16 v[96:99], v[120:123], v[216:219], v[96:99]
	s_waitcnt lgkmcnt(7)
	v_mfma_f32_16x16x32_bf16 v[80:83], v[120:123], v[224:227], 0
	s_waitcnt lgkmcnt(6)
	v_mfma_f32_16x16x32_bf16 v[80:83], v[112:115], v[220:223], v[80:83]
	s_waitcnt lgkmcnt(5)
	v_mfma_f32_16x16x32_bf16 v[76:79], v[152:155], v[220:223], 0
	s_waitcnt lgkmcnt(4)
	v_mfma_f32_16x16x32_bf16 v[76:79], v[156:159], v[224:227], v[76:79]
	v_mfma_f32_16x16x32_bf16 v[92:95], v[156:159], v[216:219], 0
	v_mfma_f32_16x16x32_bf16 v[92:95], v[152:155], v[212:215], v[92:95]
	v_mfma_f32_16x16x32_bf16 v[108:111], v[152:155], v[204:207], 0
	v_mfma_f32_16x16x32_bf16 v[108:111], v[156:159], v[208:211], v[108:111]
	v_mfma_f32_16x16x32_bf16 v[132:135], v[156:159], v[188:191], 0
	v_mfma_f32_16x16x32_bf16 v[132:135], v[152:155], v[184:187], v[132:135]
	s_waitcnt lgkmcnt(3)
	v_mfma_f32_16x16x32_bf16 v[128:131], v[160:163], v[184:187], 0
	s_waitcnt lgkmcnt(2)
	v_mfma_f32_16x16x32_bf16 v[128:131], v[164:167], v[188:191], v[128:131]
	v_mfma_f32_16x16x32_bf16 v[104:107], v[164:167], v[208:211], 0
	v_mfma_f32_16x16x32_bf16 v[104:107], v[160:163], v[204:207], v[104:107]
	v_mfma_f32_16x16x32_bf16 v[88:91], v[160:163], v[212:215], 0
	v_mfma_f32_16x16x32_bf16 v[88:91], v[164:167], v[216:219], v[88:91]
	v_mfma_f32_16x16x32_bf16 v[72:75], v[164:167], v[224:227], 0
	v_mfma_f32_16x16x32_bf16 v[72:75], v[160:163], v[220:223], v[72:75]
	s_waitcnt lgkmcnt(1)
	v_mfma_f32_16x16x32_bf16 v[68:71], v[176:179], v[220:223], 0
	s_waitcnt lgkmcnt(0)
	v_mfma_f32_16x16x32_bf16 v[68:71], v[180:183], v[224:227], v[68:71]
	v_mfma_f32_16x16x32_bf16 v[84:87], v[180:183], v[216:219], 0
	v_mfma_f32_16x16x32_bf16 v[84:87], v[176:179], v[212:215], v[84:87]
	v_mfma_f32_16x16x32_bf16 v[100:103], v[176:179], v[204:207], 0
	v_mfma_f32_16x16x32_bf16 v[100:103], v[180:183], v[208:211], v[100:103]
	v_mfma_f32_16x16x32_bf16 v[124:127], v[180:183], v[188:191], 0
	v_mfma_f32_16x16x32_bf16 v[124:127], v[176:179], v[184:187], v[124:127]
	s_barrier
	s_add_i32 s50, s56, s46
	v_lshl_add_u64 v[168:169], s[72:73], 0, v[2:3]
	s_mov_b32 m0, s50
	ds_read_b128 v[184:187], v173 offset:16384
	ds_read_b128 v[188:191], v173 offset:17408
	ds_read_b128 v[208:211], v173 offset:19456
	ds_read_b128 v[204:207], v173 offset:18432
	ds_read_b128 v[212:215], v173 offset:20480
	ds_read_b128 v[216:219], v173 offset:21504
	ds_read_b128 v[224:227], v173 offset:23552
	ds_read_b128 v[220:223], v173 offset:22528
	s_setprio 0
	global_load_lds_dwordx4 v[168:169], off
	s_add_i32 m0, s50, 0x2000
	s_add_u32 s50, s72, 0x100000
	v_lshl_add_u64 v[228:229], s[72:73], 0, v[144:145]
	s_addc_u32 s51, s73, 0
	s_add_i32 s56, s57, s46
	global_load_lds_dwordx4 v[228:229], off
	s_mov_b32 m0, s56
	v_lshl_add_u64 v[242:243], s[76:77], 0, v[142:143]
	global_load_lds_dwordx4 v2, s[50:51]
	s_add_i32 m0, s56, 0x2000
	s_nop 0
	global_load_lds_dwordx4 v144, s[50:51]
	v_lshl_add_u64 v[240:241], s[76:77], 0, v[140:141]
	s_waitcnt vmcnt(6)
	s_waitcnt lgkmcnt(7)
	s_setprio 1
	s_barrier
; #define PG8_STAGE(bufoff, gbase, voff) do { _Pragma("unroll") for (int _i = 0; _i < 2; ++_i) \
;         __builtin_amdgcn_global_load_lds((const unsigned*)((const char*)(gbase) + (voff)[_i]), (PG8_LAS unsigned*)(lds + (bufoff) + ldsw + _i * 8192), 16, 0, 0); } while (0)
; #define PG8_LDA(dst, b, h) do { _Pragma("unroll") for (int m = 0; m < 4; ++m) _Pragma("unroll") for (int k = 0; k < 2; ++k) dst[m][k] = *(const PG8_LAS bf16x8*)(lds + PG8_SA(b, h) + aoff + m * 2048 + k * 1024); } while (0)
; #define PG8_LDB(dst, b, h) do { _Pragma("unroll") for (int n = 0; n < 2; ++n) _Pragma("unroll") for (int k = 0; k < 2; ++k) dst[n][k] = *(const PG8_LAS bf16x8*)(lds + PG8_SB(b, h) + boff + n * 2048 + k * 1024); } while (0)
; #define PG8_WAIT_V(n) asm volatile("s_waitcnt vmcnt(" #n ")" ::: "memory")
; #define PG8_WAIT_L(n) asm volatile("s_waitcnt lgkmcnt(" #n ")" ::: "memory")
; #define PG8_BAR __builtin_amdgcn_s_barrier()
; #define PG8_SCHED __builtin_amdgcn_sched_barrier(0)
; template <class Epi, class Sched, bool ALIGN_EPI = false, bool SP2 = false, bool I8 = false>
; __device__ __forceinline__ void gemm_phase(PG8_LAS unsigned char* lds, const Gemm g, const Sched& S, const Epi& E) {
;     ...
;             PG8_WAIT_V(8); PG8_WAIT_L(0); PG8_BAR; PG8_MMA(0, 0, At, B0); PG8_MMA(0, 1, At, B1); PG8_BAR; PG8_SCHED;
;             PG8_LDA(At, 0, 1); PG8_STAGE(PG8_SB(0, 0), b2, voffB); PG8_STAGE(PG8_SB(0, 1), b2 + hstep, voffB); PG8_STAGE(PG8_SA(0, 0), a2, voffA);
;             PG8_WAIT_V(8); PG8_WAIT_L(0); PG8_BAR; PG8_MMA(1, 0, At, B0); PG8_MMA(1, 1, At, B1); PG8_BAR; PG8_SCHED;
;             PG8_LDB(B0, 1, 0); PG8_LDB(B1, 1, 1); PG8_SCHED; PG8_LDA(At, 1, 0); PG8_STAGE(PG8_SA(0, 1), a2 + hstep, voffA);
;             PG8_WAIT_V(8); PG8_WAIT_L(0); PG8_BAR; PG8_MMA(0, 0, At, B0); PG8_MMA(0, 1, At, B1); PG8_BAR; PG8_SCHED;
;             PG8_LDA(At, 1, 1); PG8_STAGE(PG8_SB(1, 0), b3, voffB); PG8_STAGE(PG8_SB(1, 1), b3 + hstep, voffB); PG8_STAGE(PG8_SA(1, 0), a3, voffA);
;             PG8_WAIT_V(8); PG8_WAIT_L(0); PG8_BAR; PG8_MMA(1, 0, At, B0); PG8_MMA(1, 1, At, B1); PG8_BAR; PG8_SCHED;
	v_mfma_f32_16x16x32_bf16 v[64:67], v[112:115], v[184:187], 0
	s_waitcnt lgkmcnt(6)
	v_mfma_f32_16x16x32_bf16 v[64:67], v[120:123], v[188:191], v[64:67]
	s_waitcnt lgkmcnt(5)
	v_mfma_f32_16x16x32_bf16 v[48:51], v[120:123], v[208:211], 0
	s_waitcnt lgkmcnt(4)
	v_mfma_f32_16x16x32_bf16 v[48:51], v[112:115], v[204:207], v[48:51]
	s_waitcnt lgkmcnt(3)
	v_mfma_f32_16x16x32_bf16 v[32:35], v[112:115], v[212:215], 0
	s_waitcnt lgkmcnt(2)
	v_mfma_f32_16x16x32_bf16 v[32:35], v[120:123], v[216:219], v[32:35]
	s_waitcnt lgkmcnt(1)
	v_mfma_f32_16x16x32_bf16 v[16:19], v[120:123], v[224:227], 0
	s_waitcnt lgkmcnt(0)
	v_mfma_f32_16x16x32_bf16 v[16:19], v[112:115], v[220:223], v[16:19]
	v_mfma_f32_16x16x32_bf16 v[12:15], v[152:155], v[220:223], 0
	v_mfma_f32_16x16x32_bf16 v[12:15], v[156:159], v[224:227], v[12:15]
	v_mfma_f32_16x16x32_bf16 v[28:31], v[156:159], v[216:219], 0
	v_mfma_f32_16x16x32_bf16 v[28:31], v[152:155], v[212:215], v[28:31]
	v_mfma_f32_16x16x32_bf16 v[44:47], v[152:155], v[204:207], 0
	v_mfma_f32_16x16x32_bf16 v[44:47], v[156:159], v[208:211], v[44:47]
	v_mfma_f32_16x16x32_bf16 v[60:63], v[156:159], v[188:191], 0
	v_mfma_f32_16x16x32_bf16 v[60:63], v[152:155], v[184:187], v[60:63]
	v_mfma_f32_16x16x32_bf16 v[56:59], v[160:163], v[184:187], 0
	v_mfma_f32_16x16x32_bf16 v[56:59], v[164:167], v[188:191], v[56:59]
	v_mfma_f32_16x16x32_bf16 v[40:43], v[164:167], v[208:211], 0
	v_mfma_f32_16x16x32_bf16 v[40:43], v[160:163], v[204:207], v[40:43]
	v_mfma_f32_16x16x32_bf16 v[24:27], v[160:163], v[212:215], 0
	v_mfma_f32_16x16x32_bf16 v[24:27], v[164:167], v[216:219], v[24:27]
	v_mfma_f32_16x16x32_bf16 v[8:11], v[164:167], v[224:227], 0
	v_mfma_f32_16x16x32_bf16 v[8:11], v[160:163], v[220:223], v[8:11]
	v_mfma_f32_16x16x32_bf16 v[4:7], v[176:179], v[220:223], 0
	v_mfma_f32_16x16x32_bf16 v[4:7], v[180:183], v[224:227], v[4:7]
	v_mfma_f32_16x16x32_bf16 v[20:23], v[180:183], v[216:219], 0
	v_mfma_f32_16x16x32_bf16 v[20:23], v[176:179], v[212:215], v[20:23]
	v_mfma_f32_16x16x32_bf16 v[36:39], v[176:179], v[204:207], 0
	v_mfma_f32_16x16x32_bf16 v[36:39], v[180:183], v[208:211], v[36:39]
	v_mfma_f32_16x16x32_bf16 v[52:55], v[180:183], v[188:191], 0
	v_mfma_f32_16x16x32_bf16 v[52:55], v[176:179], v[184:187], v[52:55]
	s_barrier
	s_mov_b32 m0, s47
	s_nop 0
	global_load_lds_dwordx4 v[240:241], off
	s_mov_b32 m0, s52
	s_nop 0
	global_load_lds_dwordx4 v[242:243], off
	s_add_i32 s56, 0, 0x18000
	s_add_i32 s57, 0, 0x1c000
	v_add_u32_e32 v156, s56, v171
	v_add_u32_e32 v175, s57, v171
	ds_read_b128 v[112:115], v156
	ds_read_b128 v[184:187], v173 offset:32768
	ds_read_b128 v[120:123], v156 offset:1024
	ds_read_b128 v[188:191], v173 offset:33792
	ds_read_b128 v[208:211], v173 offset:35840
	ds_read_b128 v[204:207], v173 offset:34816
	ds_read_b128 v[212:215], v173 offset:36864
	ds_read_b128 v[216:219], v173 offset:37888
	s_add_u32 s50, s76, 0x100000
	s_addc_u32 s51, s77, 0
	s_mov_b32 m0, s53
	ds_read_b128 v[224:227], v173 offset:39936
	ds_read_b128 v[220:223], v173 offset:38912
	ds_read_b128 v[152:155], v156 offset:2048
	ds_read_b128 v[156:159], v156 offset:3072
	ds_read_b128 v[160:163], v175
	ds_read_b128 v[164:167], v175 offset:1024
	ds_read_b128 v[176:179], v175 offset:2048
	ds_read_b128 v[180:183], v175 offset:3072
	s_setprio 0
	global_load_lds_dwordx4 v140, s[50:51]
	s_mov_b32 m0, s64
	s_nop 0
	global_load_lds_dwordx4 v142, s[50:51]
	s_waitcnt vmcnt(8)
	s_waitcnt lgkmcnt(14)
	s_setprio 1
	s_barrier
; #define PG8_STAGE(bufoff, gbase, voff) do { _Pragma("unroll") for (int _i = 0; _i < 2; ++_i) \
;         __builtin_amdgcn_global_load_lds((const unsigned*)((const char*)(gbase) + (voff)[_i]), (PG8_LAS unsigned*)(lds + (bufoff) + ldsw + _i * 8192), 16, 0, 0); } while (0)
; #define PG8_LDA(dst, b, h) do { _Pragma("unroll") for (int m = 0; m < 4; ++m) _Pragma("unroll") for (int k = 0; k < 2; ++k) dst[m][k] = *(const PG8_LAS bf16x8*)(lds + PG8_SA(b, h) + aoff + m * 2048 + k * 1024); } while (0)
; #define PG8_LDB(dst, b, h) do { _Pragma("unroll") for (int n = 0; n < 2; ++n) _Pragma("unroll") for (int k = 0; k < 2; ++k) dst[n][k] = *(const PG8_LAS bf16x8*)(lds + PG8_SB(b, h) + boff + n * 2048 + k * 1024); } while (0)
; #define PG8_WAIT_V(n) asm volatile("s_waitcnt vmcnt(" #n ")" ::: "memory")
; #define PG8_WAIT_L(n) asm volatile("s_waitcnt lgkmcnt(" #n ")" ::: "memory")
; #define PG8_BAR __builtin_amdgcn_s_barrier()
; #define PG8_SCHED __builtin_amdgcn_sched_barrier(0)
; template <class Epi, class Sched, bool ALIGN_EPI = false, bool SP2 = false, bool I8 = false>
; __device__ __forceinline__ void gemm_phase(PG8_LAS unsigned char* lds, const Gemm g, const Sched& S, const Epi& E) {
;     ...
;             if constexpr (SP2) {
;             PG8_LDB(B0, 0, 0); PG8_LDB(B1, 0, 1); PG8_SCHED; PG8_LDA(At, 0, 0); PG8_STAGE(PG8_SA(1, 1), a1 + hstep, voffA);
;             PG8_WAIT_V(8); PG8_WAIT_L(0); PG8_BAR; PG8_MMA(0, 0, At, B0); PG8_MMA(0, 1, At, B1); PG8_BAR; PG8_SCHED;
;             PG8_LDA(At, 0, 1); PG8_STAGE(PG8_SB(0, 0), b2, voffB); PG8_STAGE(PG8_SB(0, 1), b2 + hstep, voffB); PG8_STAGE(PG8_SA(0, 0), a2, voffA);
;             PG8_WAIT_V(8); PG8_WAIT_L(0); PG8_BAR; PG8_MMA(1, 0, At, B0); PG8_MMA(1, 1, At, B1); PG8_BAR; PG8_SCHED;
;             PG8_LDB(B0, 1, 0); PG8_LDB(B1, 1, 1); PG8_SCHED; PG8_LDA(At, 1, 0); PG8_STAGE(PG8_SA(0, 1), a2 + hstep, voffA);
;             PG8_WAIT_V(8); PG8_WAIT_L(0); PG8_BAR; PG8_MMA(0, 0, At, B0); PG8_MMA(0, 1, At, B1); PG8_BAR; PG8_SCHED;
;             PG8_LDA(At, 1, 1); PG8_STAGE(PG8_SB(1, 0), b3, voffB); PG8_STAGE(PG8_SB(1, 1), b3 + hstep, voffB); PG8_STAGE(PG8_SA(1, 0), a3, voffA);
;             PG8_WAIT_V(8); PG8_WAIT_L(0); PG8_BAR; PG8_MMA(1, 0, At, B0); PG8_MMA(1, 1, At, B1); PG8_BAR; PG8_SCHED;
	v_mfma_f32_16x16x32_bf16 v[136:139], v[112:115], v[184:187], v[136:139]
	s_waitcnt lgkmcnt(12)
	v_mfma_f32_16x16x32_bf16 v[136:139], v[120:123], v[188:191], v[136:139]
	s_waitcnt lgkmcnt(11)
	v_mfma_f32_16x16x32_bf16 v[116:119], v[120:123], v[208:211], v[116:119]
	s_waitcnt lgkmcnt(10)
	v_mfma_f32_16x16x32_bf16 v[116:119], v[112:115], v[204:207], v[116:119]
	s_waitcnt lgkmcnt(9)
	v_mfma_f32_16x16x32_bf16 v[96:99], v[112:115], v[212:215], v[96:99]
	s_waitcnt lgkmcnt(8)
	v_mfma_f32_16x16x32_bf16 v[96:99], v[120:123], v[216:219], v[96:99]
	s_waitcnt lgkmcnt(7)
	v_mfma_f32_16x16x32_bf16 v[80:83], v[120:123], v[224:227], v[80:83]
	s_waitcnt lgkmcnt(6)
	v_mfma_f32_16x16x32_bf16 v[80:83], v[112:115], v[220:223], v[80:83]
	s_waitcnt lgkmcnt(5)
	v_mfma_f32_16x16x32_bf16 v[76:79], v[152:155], v[220:223], v[76:79]
	s_waitcnt lgkmcnt(4)
	v_mfma_f32_16x16x32_bf16 v[76:79], v[156:159], v[224:227], v[76:79]
	v_mfma_f32_16x16x32_bf16 v[92:95], v[156:159], v[216:219], v[92:95]
	v_mfma_f32_16x16x32_bf16 v[92:95], v[152:155], v[212:215], v[92:95]
	v_mfma_f32_16x16x32_bf16 v[108:111], v[152:155], v[204:207], v[108:111]
	v_mfma_f32_16x16x32_bf16 v[108:111], v[156:159], v[208:211], v[108:111]
	v_mfma_f32_16x16x32_bf16 v[132:135], v[156:159], v[188:191], v[132:135]
	v_mfma_f32_16x16x32_bf16 v[132:135], v[152:155], v[184:187], v[132:135]
	s_waitcnt lgkmcnt(3)
	v_mfma_f32_16x16x32_bf16 v[128:131], v[160:163], v[184:187], v[128:131]
	s_waitcnt lgkmcnt(2)
	v_mfma_f32_16x16x32_bf16 v[128:131], v[164:167], v[188:191], v[128:131]
	v_mfma_f32_16x16x32_bf16 v[104:107], v[164:167], v[208:211], v[104:107]
	v_mfma_f32_16x16x32_bf16 v[104:107], v[160:163], v[204:207], v[104:107]
	v_mfma_f32_16x16x32_bf16 v[88:91], v[160:163], v[212:215], v[88:91]
	v_mfma_f32_16x16x32_bf16 v[88:91], v[164:167], v[216:219], v[88:91]
	v_mfma_f32_16x16x32_bf16 v[72:75], v[164:167], v[224:227], v[72:75]
	v_mfma_f32_16x16x32_bf16 v[72:75], v[160:163], v[220:223], v[72:75]
	s_waitcnt lgkmcnt(1)
	v_mfma_f32_16x16x32_bf16 v[68:71], v[176:179], v[220:223], v[68:71]
	s_waitcnt lgkmcnt(0)
	v_mfma_f32_16x16x32_bf16 v[68:71], v[180:183], v[224:227], v[68:71]
	v_mfma_f32_16x16x32_bf16 v[84:87], v[180:183], v[216:219], v[84:87]
	v_mfma_f32_16x16x32_bf16 v[84:87], v[176:179], v[212:215], v[84:87]
	v_mfma_f32_16x16x32_bf16 v[100:103], v[176:179], v[204:207], v[100:103]
	v_mfma_f32_16x16x32_bf16 v[100:103], v[180:183], v[208:211], v[100:103]
	v_mfma_f32_16x16x32_bf16 v[124:127], v[180:183], v[188:191], v[124:127]
	v_mfma_f32_16x16x32_bf16 v[124:127], v[176:179], v[184:187], v[124:127]
	s_barrier
	s_add_i32 s50, s56, s46
	v_lshl_add_u64 v[168:169], v[168:169], 0, s[84:85]
	s_mov_b32 m0, s50
	ds_read_b128 v[184:187], v173 offset:49152
	ds_read_b128 v[188:191], v173 offset:50176
	ds_read_b128 v[208:211], v173 offset:52224
	ds_read_b128 v[204:207], v173 offset:51200
	ds_read_b128 v[212:215], v173 offset:53248
	ds_read_b128 v[216:219], v173 offset:54272
	ds_read_b128 v[224:227], v173 offset:56320
	ds_read_b128 v[220:223], v173 offset:55296
	s_setprio 0
	global_load_lds_dwordx4 v[168:169], off
	s_add_i32 m0, s50, 0x2000
	s_add_u32 s50, s72, 0x100080
	v_lshl_add_u64 v[168:169], v[228:229], 0, s[84:85]
	s_addc_u32 s51, s73, 0
	s_add_i32 s56, s57, s46
	global_load_lds_dwordx4 v[168:169], off
	s_mov_b32 m0, s56
	s_nop 0
	global_load_lds_dwordx4 v2, s[50:51]
	s_add_i32 m0, s56, 0x2000
	s_nop 0
	global_load_lds_dwordx4 v144, s[50:51]
	s_cmp_eq_u32 s97, 60
	s_cbranch_scc0 .Ldefer_230_peel
	v_lshl_add_u64 v[168:169], v[240:241], 0, s[84:85]
	s_mov_b32 m0, s28
	s_nop 0
	global_load_lds_dwordx4 v[168:169], off
	v_lshl_add_u64 v[168:169], v[242:243], 0, s[84:85]
	s_mov_b32 m0, s65
	s_nop 0
	global_load_lds_dwordx4 v[168:169], off

; #define PG8_STAGE(bufoff, gbase, voff) do { _Pragma("unroll") for (int _i = 0; _i < 2; ++_i) \
;         __builtin_amdgcn_global_load_lds((const unsigned*)((const char*)(gbase) + (voff)[_i]), (PG8_LAS unsigned*)(lds + (bufoff) + ldsw + _i * 8192), 16, 0, 0); } while (0)
; #define PG8_LDA(dst, b, h) do { _Pragma("unroll") for (int m = 0; m < 4; ++m) _Pragma("unroll") for (int k = 0; k < 2; ++k) dst[m][k] = *(const PG8_LAS bf16x8*)(lds + PG8_SA(b, h) + aoff + m * 2048 + k * 1024); } while (0)
; #define PG8_WAIT_V(n) asm volatile("s_waitcnt vmcnt(" #n ")" ::: "memory")
; #define PG8_WAIT_L(n) asm volatile("s_waitcnt lgkmcnt(" #n ")" ::: "memory")
; #define PG8_BAR __builtin_amdgcn_s_barrier()
; template <class Epi, class Sched, bool ALIGN_EPI = false, bool SP2 = false, bool I8 = false>
; __device__ __forceinline__ void gemm_phase(PG8_LAS unsigned char* lds, const Gemm g, const Sched& S, const Epi& E) {
;     ...
;         for (int t = 0; t < nt; t += 2) {
;             const bool last = (t == nt - 2);
;             const char* a1 = cA + (size_t)(t + 1) * kstep;
;             const char* a2 = last ? nA : cA + (size_t)(t + 2) * kstep; const char* b2 = last ? nB : cB + (size_t)(t + 2) * kstep;
;             const char* a3 = a2 + kstep; const char* b3 = b2 + kstep;
;             if (last && has_next) S.a_ready(nxt);
;             if constexpr (SP2) {
;             PG8_LDB(B0, 0, 0); PG8_LDB(B1, 0, 1); PG8_SCHED; PG8_LDA(At, 0, 0); PG8_STAGE(PG8_SA(1, 1), a1 + hstep, voffA);
;             PG8_WAIT_V(8); PG8_WAIT_L(0); PG8_BAR; PG8_MMA(0, 0, At, B0); PG8_MMA(0, 1, At, B1); PG8_BAR; PG8_SCHED;
;             PG8_LDA(At, 0, 1); PG8_STAGE(PG8_SB(0, 0), b2, voffB); PG8_STAGE(PG8_SB(0, 1), b2 + hstep, voffB); PG8_STAGE(PG8_SA(0, 0), a2, voffA);
;             PG8_WAIT_V(8); PG8_WAIT_L(0); PG8_BAR; PG8_MMA(1, 0, At, B0); PG8_MMA(1, 1, At, B1); PG8_BAR; PG8_SCHED;
;             PG8_LDB(B0, 1, 0); PG8_LDB(B1, 1, 1); PG8_SCHED; PG8_LDA(At, 1, 0); PG8_STAGE(PG8_SA(0, 1), a2 + hstep, voffA);
;             PG8_WAIT_V(8); PG8_WAIT_L(0); PG8_BAR; PG8_MMA(0, 0, At, B0); PG8_MMA(0, 1, At, B1); PG8_BAR; PG8_SCHED;
;             PG8_LDA(At, 1, 1); PG8_STAGE(PG8_SB(1, 0), b3, voffB); PG8_STAGE(PG8_SB(1, 1), b3 + hstep, voffB); PG8_STAGE(PG8_SA(1, 0), a3, voffA);
;             PG8_WAIT_V(8); PG8_WAIT_L(0); PG8_BAR; PG8_MMA(1, 0, At, B0); PG8_MMA(1, 1, At, B1); PG8_BAR; PG8_SCHED;
.LBB0_230:
	s_add_u32 s50, s12, 0xfff00080
	s_addc_u32 s51, s13, -1
	s_add_i32 s56, 0, 0x10000
	s_cmp_eq_u32 s97, 60
	s_cselect_b32 s77, s11, s51
	s_cselect_b32 s76, s34, s50
	s_cselect_b32 s73, s27, s61
	s_cselect_b32 s72, s35, s37
	s_add_i32 s57, 0, 0x14000
	v_add_u32_e32 v156, s56, v171
	v_add_u32_e32 v168, s57, v171
	ds_read_b128 v[112:115], v156
	ds_read_b128 v[120:123], v156 offset:1024
	ds_read_b128 v[152:155], v156 offset:2048
	ds_read_b128 v[156:159], v156 offset:3072
	ds_read_b128 v[160:163], v168
	ds_read_b128 v[164:167], v168 offset:1024
	ds_read_b128 v[176:179], v168 offset:2048
	ds_read_b128 v[180:183], v168 offset:3072
	v_lshl_add_u64 v[168:169], v[240:241], 0, s[84:85]
	s_mov_b32 m0, s28
	s_nop 0
	global_load_lds_dwordx4 v[168:169], off
	v_lshl_add_u64 v[168:169], v[242:243], 0, s[84:85]
	s_mov_b32 m0, s65
	s_nop 0
	global_load_lds_dwordx4 v[168:169], off
	s_add_i32 m0, s47, 0xc000
	ds_read_b128 v[184:187], v173
	ds_read_b128 v[188:191], v173 offset:1024
	ds_read_b128 v[204:207], v173 offset:2048
	ds_read_b128 v[208:211], v173 offset:3072
	ds_read_b128 v[212:215], v173 offset:4096
	ds_read_b128 v[216:219], v173 offset:5120
	ds_read_b128 v[220:223], v173 offset:6144
	ds_read_b128 v[224:227], v173 offset:7168
	global_load_lds_dwordx4 v148, s[12:13]
	s_add_i32 m0, s47, 0xe000
	s_nop 0
	global_load_lds_dwordx4 v150, s[12:13]
	s_waitcnt vmcnt(8)
	s_waitcnt lgkmcnt(7)
	s_setprio 1
	s_barrier
	v_mfma_f32_16x16x32_bf16 v[136:139], v[112:115], v[184:187], v[136:139]
	s_waitcnt lgkmcnt(6)
	v_mfma_f32_16x16x32_bf16 v[136:139], v[120:123], v[188:191], v[136:139]
	s_waitcnt lgkmcnt(4)
	v_mfma_f32_16x16x32_bf16 v[116:119], v[120:123], v[208:211], v[116:119]
	v_mfma_f32_16x16x32_bf16 v[116:119], v[112:115], v[204:207], v[116:119]
	s_waitcnt lgkmcnt(3)
	v_mfma_f32_16x16x32_bf16 v[96:99], v[112:115], v[212:215], v[96:99]
	s_waitcnt lgkmcnt(2)
	v_mfma_f32_16x16x32_bf16 v[96:99], v[120:123], v[216:219], v[96:99]
	s_waitcnt lgkmcnt(0)
	v_mfma_f32_16x16x32_bf16 v[80:83], v[120:123], v[224:227], v[80:83]
	v_mfma_f32_16x16x32_bf16 v[80:83], v[112:115], v[220:223], v[80:83]
	v_mfma_f32_16x16x32_bf16 v[76:79], v[152:155], v[220:223], v[76:79]
	v_mfma_f32_16x16x32_bf16 v[76:79], v[156:159], v[224:227], v[76:79]
	v_mfma_f32_16x16x32_bf16 v[92:95], v[156:159], v[216:219], v[92:95]
	v_mfma_f32_16x16x32_bf16 v[92:95], v[152:155], v[212:215], v[92:95]
	v_mfma_f32_16x16x32_bf16 v[108:111], v[152:155], v[204:207], v[108:111]
	v_mfma_f32_16x16x32_bf16 v[108:111], v[156:159], v[208:211], v[108:111]
	v_mfma_f32_16x16x32_bf16 v[132:135], v[156:159], v[188:191], v[132:135]
	v_mfma_f32_16x16x32_bf16 v[132:135], v[152:155], v[184:187], v[132:135]
	v_mfma_f32_16x16x32_bf16 v[128:131], v[160:163], v[184:187], v[128:131]
	v_mfma_f32_16x16x32_bf16 v[128:131], v[164:167], v[188:191], v[128:131]
	v_mfma_f32_16x16x32_bf16 v[104:107], v[164:167], v[208:211], v[104:107]
	v_mfma_f32_16x16x32_bf16 v[104:107], v[160:163], v[204:207], v[104:107]
	v_mfma_f32_16x16x32_bf16 v[88:91], v[160:163], v[212:215], v[88:91]
	v_mfma_f32_16x16x32_bf16 v[88:91], v[164:167], v[216:219], v[88:91]
	v_mfma_f32_16x16x32_bf16 v[72:75], v[164:167], v[224:227], v[72:75]
	v_mfma_f32_16x16x32_bf16 v[72:75], v[160:163], v[220:223], v[72:75]
	v_mfma_f32_16x16x32_bf16 v[68:71], v[176:179], v[220:223], v[68:71]
	v_mfma_f32_16x16x32_bf16 v[68:71], v[180:183], v[224:227], v[68:71]
	v_mfma_f32_16x16x32_bf16 v[84:87], v[180:183], v[216:219], v[84:87]
	v_mfma_f32_16x16x32_bf16 v[84:87], v[176:179], v[212:215], v[84:87]
	v_mfma_f32_16x16x32_bf16 v[100:103], v[176:179], v[204:207], v[100:103]
	v_mfma_f32_16x16x32_bf16 v[100:103], v[180:183], v[208:211], v[100:103]
	v_mfma_f32_16x16x32_bf16 v[124:127], v[180:183], v[188:191], v[124:127]
	v_mfma_f32_16x16x32_bf16 v[124:127], v[176:179], v[184:187], v[124:127]
	s_barrier
	s_add_i32 s50, s56, s46
	v_lshl_add_u64 v[168:169], s[72:73], 0, v[2:3]
	s_mov_b32 m0, s50
	ds_read_b128 v[184:187], v173 offset:16384
	ds_read_b128 v[188:191], v173 offset:17408
	ds_read_b128 v[208:211], v173 offset:19456
	ds_read_b128 v[204:207], v173 offset:18432
	ds_read_b128 v[212:215], v173 offset:20480
	ds_read_b128 v[216:219], v173 offset:21504
	ds_read_b128 v[224:227], v173 offset:23552
	ds_read_b128 v[220:223], v173 offset:22528
	s_setprio 0
	global_load_lds_dwordx4 v[168:169], off
	s_add_i32 m0, s50, 0x2000
	s_add_u32 s50, s72, 0x100000
	v_lshl_add_u64 v[228:229], s[72:73], 0, v[144:145]
	s_addc_u32 s51, s73, 0
	s_add_i32 s56, s57, s46
	global_load_lds_dwordx4 v[228:229], off
	s_mov_b32 m0, s56
	v_lshl_add_u64 v[242:243], s[76:77], 0, v[142:143]
	global_load_lds_dwordx4 v2, s[50:51]
	s_add_i32 m0, s56, 0x2000
	s_nop 0
	global_load_lds_dwordx4 v144, s[50:51]
	v_lshl_add_u64 v[240:241], s[76:77], 0, v[140:141]
	s_waitcnt vmcnt(6)
	s_waitcnt lgkmcnt(7)
	s_setprio 1
	s_barrier
; #define PG8_STAGE(bufoff, gbase, voff) do { _Pragma("unroll") for (int _i = 0; _i < 2; ++_i) \
;         __builtin_amdgcn_global_load_lds((const unsigned*)((const char*)(gbase) + (voff)[_i]), (PG8_LAS unsigned*)(lds + (bufoff) + ldsw + _i * 8192), 16, 0, 0); } while (0)
; #define PG8_LDA(dst, b, h) do { _Pragma("unroll") for (int m = 0; m < 4; ++m) _Pragma("unroll") for (int k = 0; k < 2; ++k) dst[m][k] = *(const PG8_LAS bf16x8*)(lds + PG8_SA(b, h) + aoff + m * 2048 + k * 1024); } while (0)
; #define PG8_LDB(dst, b, h) do { _Pragma("unroll") for (int n = 0; n < 2; ++n) _Pragma("unroll") for (int k = 0; k < 2; ++k) dst[n][k] = *(const PG8_LAS bf16x8*)(lds + PG8_SB(b, h) + boff + n * 2048 + k * 1024); } while (0)
; #define PG8_WAIT_V(n) asm volatile("s_waitcnt vmcnt(" #n ")" ::: "memory")
; #define PG8_WAIT_L(n) asm volatile("s_waitcnt lgkmcnt(" #n ")" ::: "memory")
; #define PG8_BAR __builtin_amdgcn_s_barrier()
; #define PG8_SCHED __builtin_amdgcn_sched_barrier(0)
; template <class Epi, class Sched, bool ALIGN_EPI = false, bool SP2 = false, bool I8 = false>
; __device__ __forceinline__ void gemm_phase(PG8_LAS unsigned char* lds, const Gemm g, const Sched& S, const Epi& E) {
;     ...
;             PG8_WAIT_V(8); PG8_WAIT_L(0); PG8_BAR; PG8_MMA(0, 0, At, B0); PG8_MMA(0, 1, At, B1); PG8_BAR; PG8_SCHED;
;             PG8_LDA(At, 0, 1); PG8_STAGE(PG8_SB(0, 0), b2, voffB); PG8_STAGE(PG8_SB(0, 1), b2 + hstep, voffB); PG8_STAGE(PG8_SA(0, 0), a2, voffA);
;             PG8_WAIT_V(8); PG8_WAIT_L(0); PG8_BAR; PG8_MMA(1, 0, At, B0); PG8_MMA(1, 1, At, B1); PG8_BAR; PG8_SCHED;
;             PG8_LDB(B0, 1, 0); PG8_LDB(B1, 1, 1); PG8_SCHED; PG8_LDA(At, 1, 0); PG8_STAGE(PG8_SA(0, 1), a2 + hstep, voffA);
;             PG8_WAIT_V(8); PG8_WAIT_L(0); PG8_BAR; PG8_MMA(0, 0, At, B0); PG8_MMA(0, 1, At, B1); PG8_BAR; PG8_SCHED;
;             PG8_LDA(At, 1, 1); PG8_STAGE(PG8_SB(1, 0), b3, voffB); PG8_STAGE(PG8_SB(1, 1), b3 + hstep, voffB); PG8_STAGE(PG8_SA(1, 0), a3, voffA);
;             PG8_WAIT_V(8); PG8_WAIT_L(0); PG8_BAR; PG8_MMA(1, 0, At, B0); PG8_MMA(1, 1, At, B1); PG8_BAR; PG8_SCHED;
	v_mfma_f32_16x16x32_bf16 v[64:67], v[112:115], v[184:187], v[64:67]
	s_waitcnt lgkmcnt(6)
	v_mfma_f32_16x16x32_bf16 v[64:67], v[120:123], v[188:191], v[64:67]
	s_waitcnt lgkmcnt(5)
	v_mfma_f32_16x16x32_bf16 v[48:51], v[120:123], v[208:211], v[48:51]
	s_waitcnt lgkmcnt(4)
	v_mfma_f32_16x16x32_bf16 v[48:51], v[112:115], v[204:207], v[48:51]
	s_waitcnt lgkmcnt(3)
	v_mfma_f32_16x16x32_bf16 v[32:35], v[112:115], v[212:215], v[32:35]
	s_waitcnt lgkmcnt(2)
	v_mfma_f32_16x16x32_bf16 v[32:35], v[120:123], v[216:219], v[32:35]
	s_waitcnt lgkmcnt(1)
	v_mfma_f32_16x16x32_bf16 v[16:19], v[120:123], v[224:227], v[16:19]
	s_waitcnt lgkmcnt(0)
	v_mfma_f32_16x16x32_bf16 v[16:19], v[112:115], v[220:223], v[16:19]
	v_mfma_f32_16x16x32_bf16 v[12:15], v[152:155], v[220:223], v[12:15]
	v_mfma_f32_16x16x32_bf16 v[12:15], v[156:159], v[224:227], v[12:15]
	v_mfma_f32_16x16x32_bf16 v[28:31], v[156:159], v[216:219], v[28:31]
	v_mfma_f32_16x16x32_bf16 v[28:31], v[152:155], v[212:215], v[28:31]
	v_mfma_f32_16x16x32_bf16 v[44:47], v[152:155], v[204:207], v[44:47]
	v_mfma_f32_16x16x32_bf16 v[44:47], v[156:159], v[208:211], v[44:47]
	v_mfma_f32_16x16x32_bf16 v[60:63], v[156:159], v[188:191], v[60:63]
	v_mfma_f32_16x16x32_bf16 v[60:63], v[152:155], v[184:187], v[60:63]
	v_mfma_f32_16x16x32_bf16 v[56:59], v[160:163], v[184:187], v[56:59]
	v_mfma_f32_16x16x32_bf16 v[56:59], v[164:167], v[188:191], v[56:59]
	v_mfma_f32_16x16x32_bf16 v[40:43], v[164:167], v[208:211], v[40:43]
	v_mfma_f32_16x16x32_bf16 v[40:43], v[160:163], v[204:207], v[40:43]
	v_mfma_f32_16x16x32_bf16 v[24:27], v[160:163], v[212:215], v[24:27]
	v_mfma_f32_16x16x32_bf16 v[24:27], v[164:167], v[216:219], v[24:27]
	v_mfma_f32_16x16x32_bf16 v[8:11], v[164:167], v[224:227], v[8:11]
	v_mfma_f32_16x16x32_bf16 v[8:11], v[160:163], v[220:223], v[8:11]
	v_mfma_f32_16x16x32_bf16 v[4:7], v[176:179], v[220:223], v[4:7]
	v_mfma_f32_16x16x32_bf16 v[4:7], v[180:183], v[224:227], v[4:7]
	v_mfma_f32_16x16x32_bf16 v[20:23], v[180:183], v[216:219], v[20:23]
	v_mfma_f32_16x16x32_bf16 v[20:23], v[176:179], v[212:215], v[20:23]
	v_mfma_f32_16x16x32_bf16 v[36:39], v[176:179], v[204:207], v[36:39]
	v_mfma_f32_16x16x32_bf16 v[36:39], v[180:183], v[208:211], v[36:39]
	v_mfma_f32_16x16x32_bf16 v[52:55], v[180:183], v[188:191], v[52:55]
	v_mfma_f32_16x16x32_bf16 v[52:55], v[176:179], v[184:187], v[52:55]
	s_barrier
	s_mov_b32 m0, s47
	s_nop 0
	global_load_lds_dwordx4 v[240:241], off
	s_mov_b32 m0, s52
	s_nop 0
	global_load_lds_dwordx4 v[242:243], off
	s_add_i32 s56, 0, 0x18000
	s_add_i32 s57, 0, 0x1c000
	v_add_u32_e32 v156, s56, v171
	v_add_u32_e32 v175, s57, v171
	ds_read_b128 v[112:115], v156
	ds_read_b128 v[184:187], v173 offset:32768
	ds_read_b128 v[120:123], v156 offset:1024
	ds_read_b128 v[188:191], v173 offset:33792
	ds_read_b128 v[208:211], v173 offset:35840
	ds_read_b128 v[204:207], v173 offset:34816
	ds_read_b128 v[212:215], v173 offset:36864
	ds_read_b128 v[216:219], v173 offset:37888
	s_add_u32 s50, s76, 0x100000
	s_addc_u32 s51, s77, 0
	s_mov_b32 m0, s53
	ds_read_b128 v[224:227], v173 offset:39936
	ds_read_b128 v[220:223], v173 offset:38912
	ds_read_b128 v[152:155], v156 offset:2048
	ds_read_b128 v[156:159], v156 offset:3072
	ds_read_b128 v[160:163], v175
	ds_read_b128 v[164:167], v175 offset:1024
	ds_read_b128 v[176:179], v175 offset:2048
	ds_read_b128 v[180:183], v175 offset:3072
	s_setprio 0
	global_load_lds_dwordx4 v140, s[50:51]
	s_mov_b32 m0, s64
	s_nop 0
	global_load_lds_dwordx4 v142, s[50:51]
	s_waitcnt vmcnt(8)
	s_waitcnt lgkmcnt(14)
	s_setprio 1
	s_barrier
; #define PG8_STAGE(bufoff, gbase, voff) do { _Pragma("unroll") for (int _i = 0; _i < 2; ++_i) \
;         __builtin_amdgcn_global_load_lds((const unsigned*)((const char*)(gbase) + (voff)[_i]), (PG8_LAS unsigned*)(lds + (bufoff) + ldsw + _i * 8192), 16, 0, 0); } while (0)
; #define PG8_LDA(dst, b, h) do { _Pragma("unroll") for (int m = 0; m < 4; ++m) _Pragma("unroll") for (int k = 0; k < 2; ++k) dst[m][k] = *(const PG8_LAS bf16x8*)(lds + PG8_SA(b, h) + aoff + m * 2048 + k * 1024); } while (0)
; #define PG8_LDB(dst, b, h) do { _Pragma("unroll") for (int n = 0; n < 2; ++n) _Pragma("unroll") for (int k = 0; k < 2; ++k) dst[n][k] = *(const PG8_LAS bf16x8*)(lds + PG8_SB(b, h) + boff + n * 2048 + k * 1024); } while (0)
; #define PG8_WAIT_V(n) asm volatile("s_waitcnt vmcnt(" #n ")" ::: "memory")
; #define PG8_WAIT_L(n) asm volatile("s_waitcnt lgkmcnt(" #n ")" ::: "memory")
; #define PG8_BAR __builtin_amdgcn_s_barrier()
; #define PG8_SCHED __builtin_amdgcn_sched_barrier(0)
; template <class Epi, class Sched, bool ALIGN_EPI = false, bool SP2 = false, bool I8 = false>
; __device__ __forceinline__ void gemm_phase(PG8_LAS unsigned char* lds, const Gemm g, const Sched& S, const Epi& E) {
;     ...
;             PG8_WAIT_V(8); PG8_WAIT_L(0); PG8_BAR; PG8_MMA(0, 0, At, B0); PG8_MMA(0, 1, At, B1); PG8_BAR; PG8_SCHED;
;             PG8_LDA(At, 0, 1); PG8_STAGE(PG8_SB(0, 0), b2, voffB); PG8_STAGE(PG8_SB(0, 1), b2 + hstep, voffB); PG8_STAGE(PG8_SA(0, 0), a2, voffA);
;             PG8_WAIT_V(8); PG8_WAIT_L(0); PG8_BAR; PG8_MMA(1, 0, At, B0); PG8_MMA(1, 1, At, B1); PG8_BAR; PG8_SCHED;
;             PG8_LDB(B0, 1, 0); PG8_LDB(B1, 1, 1); PG8_SCHED; PG8_LDA(At, 1, 0); PG8_STAGE(PG8_SA(0, 1), a2 + hstep, voffA);
;             PG8_WAIT_V(8); PG8_WAIT_L(0); PG8_BAR; PG8_MMA(0, 0, At, B0); PG8_MMA(0, 1, At, B1); PG8_BAR; PG8_SCHED;
;             PG8_LDA(At, 1, 1); PG8_STAGE(PG8_SB(1, 0), b3, voffB); PG8_STAGE(PG8_SB(1, 1), b3 + hstep, voffB); PG8_STAGE(PG8_SA(1, 0), a3, voffA);
;             PG8_WAIT_V(8); PG8_WAIT_L(0); PG8_BAR; PG8_MMA(1, 0, At, B0); PG8_MMA(1, 1, At, B1); PG8_BAR; PG8_SCHED;
	v_mfma_f32_16x16x32_bf16 v[136:139], v[112:115], v[184:187], v[136:139]
	s_waitcnt lgkmcnt(12)
	v_mfma_f32_16x16x32_bf16 v[136:139], v[120:123], v[188:191], v[136:139]
	s_waitcnt lgkmcnt(11)
	v_mfma_f32_16x16x32_bf16 v[116:119], v[120:123], v[208:211], v[116:119]
	s_waitcnt lgkmcnt(10)
	v_mfma_f32_16x16x32_bf16 v[116:119], v[112:115], v[204:207], v[116:119]
	s_waitcnt lgkmcnt(9)
	v_mfma_f32_16x16x32_bf16 v[96:99], v[112:115], v[212:215], v[96:99]
	s_waitcnt lgkmcnt(8)
	v_mfma_f32_16x16x32_bf16 v[96:99], v[120:123], v[216:219], v[96:99]
	s_waitcnt lgkmcnt(7)
	v_mfma_f32_16x16x32_bf16 v[80:83], v[120:123], v[224:227], v[80:83]
	s_waitcnt lgkmcnt(6)
	v_mfma_f32_16x16x32_bf16 v[80:83], v[112:115], v[220:223], v[80:83]
	s_waitcnt lgkmcnt(5)
	v_mfma_f32_16x16x32_bf16 v[76:79], v[152:155], v[220:223], v[76:79]
	s_waitcnt lgkmcnt(4)
	v_mfma_f32_16x16x32_bf16 v[76:79], v[156:159], v[224:227], v[76:79]
	v_mfma_f32_16x16x32_bf16 v[92:95], v[156:159], v[216:219], v[92:95]
	v_mfma_f32_16x16x32_bf16 v[92:95], v[152:155], v[212:215], v[92:95]
	v_mfma_f32_16x16x32_bf16 v[108:111], v[152:155], v[204:207], v[108:111]
	v_mfma_f32_16x16x32_bf16 v[108:111], v[156:159], v[208:211], v[108:111]
	v_mfma_f32_16x16x32_bf16 v[132:135], v[156:159], v[188:191], v[132:135]
	v_mfma_f32_16x16x32_bf16 v[132:135], v[152:155], v[184:187], v[132:135]
	s_waitcnt lgkmcnt(3)
	v_mfma_f32_16x16x32_bf16 v[128:131], v[160:163], v[184:187], v[128:131]
	s_waitcnt lgkmcnt(2)
	v_mfma_f32_16x16x32_bf16 v[128:131], v[164:167], v[188:191], v[128:131]
	v_mfma_f32_16x16x32_bf16 v[104:107], v[164:167], v[208:211], v[104:107]
	v_mfma_f32_16x16x32_bf16 v[104:107], v[160:163], v[204:207], v[104:107]
	v_mfma_f32_16x16x32_bf16 v[88:91], v[160:163], v[212:215], v[88:91]
	v_mfma_f32_16x16x32_bf16 v[88:91], v[164:167], v[216:219], v[88:91]
	v_mfma_f32_16x16x32_bf16 v[72:75], v[164:167], v[224:227], v[72:75]
	v_mfma_f32_16x16x32_bf16 v[72:75], v[160:163], v[220:223], v[72:75]
	s_waitcnt lgkmcnt(1)
	v_mfma_f32_16x16x32_bf16 v[68:71], v[176:179], v[220:223], v[68:71]
	s_waitcnt lgkmcnt(0)
	v_mfma_f32_16x16x32_bf16 v[68:71], v[180:183], v[224:227], v[68:71]
	v_mfma_f32_16x16x32_bf16 v[84:87], v[180:183], v[216:219], v[84:87]
	v_mfma_f32_16x16x32_bf16 v[84:87], v[176:179], v[212:215], v[84:87]
	v_mfma_f32_16x16x32_bf16 v[100:103], v[176:179], v[204:207], v[100:103]
	v_mfma_f32_16x16x32_bf16 v[100:103], v[180:183], v[208:211], v[100:103]
	v_mfma_f32_16x16x32_bf16 v[124:127], v[180:183], v[188:191], v[124:127]
	v_mfma_f32_16x16x32_bf16 v[124:127], v[176:179], v[184:187], v[124:127]
	s_barrier
	s_add_i32 s50, s56, s46
	v_lshl_add_u64 v[168:169], v[168:169], 0, s[84:85]
	s_mov_b32 m0, s50
	ds_read_b128 v[184:187], v173 offset:49152
	ds_read_b128 v[188:191], v173 offset:50176
	ds_read_b128 v[208:211], v173 offset:52224
	ds_read_b128 v[204:207], v173 offset:51200
	ds_read_b128 v[212:215], v173 offset:53248
	ds_read_b128 v[216:219], v173 offset:54272
	ds_read_b128 v[224:227], v173 offset:56320
	ds_read_b128 v[220:223], v173 offset:55296
	s_setprio 0
	global_load_lds_dwordx4 v[168:169], off
	s_add_i32 m0, s50, 0x2000
	s_add_u32 s50, s72, 0x100080
	v_lshl_add_u64 v[168:169], v[228:229], 0, s[84:85]
	s_addc_u32 s51, s73, 0
	s_add_i32 s56, s57, s46
	global_load_lds_dwordx4 v[168:169], off
	s_mov_b32 m0, s56
	s_nop 0
	global_load_lds_dwordx4 v2, s[50:51]
	s_add_i32 m0, s56, 0x2000
	s_nop 0
	global_load_lds_dwordx4 v144, s[50:51]
	s_cmp_eq_u32 s97, 60
	s_cbranch_scc0 .Ldefer_230_body
	v_lshl_add_u64 v[168:169], v[240:241], 0, s[84:85]
	s_mov_b32 m0, s28
	s_nop 0
	global_load_lds_dwordx4 v[168:169], off
	v_lshl_add_u64 v[168:169], v[242:243], 0, s[84:85]
	s_mov_b32 m0, s65
	s_nop 0
	global_load_lds_dwordx4 v[168:169], off

; #define PG8_STAGE(bufoff, gbase, voff) do { _Pragma("unroll") for (int _i = 0; _i < 2; ++_i) \
;         __builtin_amdgcn_global_load_lds((const unsigned*)((const char*)(gbase) + (voff)[_i]), (PG8_LAS unsigned*)(lds + (bufoff) + ldsw + _i * 8192), 16, 0, 0); } while (0)
; #define PG8_LDA(dst, b, h) do { _Pragma("unroll") for (int m = 0; m < 4; ++m) _Pragma("unroll") for (int k = 0; k < 2; ++k) dst[m][k] = *(const PG8_LAS bf16x8*)(lds + PG8_SA(b, h) + aoff + m * 2048 + k * 1024); } while (0)
; #define PG8_BAR __builtin_amdgcn_s_barrier()
; template <class Epi, class Sched, bool ALIGN_EPI = false, bool SP2 = false, bool I8 = false>
; __device__ __forceinline__ void gemm_phase(PG8_LAS unsigned char* lds, const Gemm g, const Sched& S, const Epi& E) {
;     ...
;         const char* nA = has_next ? (const char*)g.A + (size_t)nxt.pm * tstep : cA; const char* nB = has_next ? (const char*)g.Bt + (size_t)nxt.pn * tstep : cB;
;         for (int t = 0; t < nt; t += 2) {
;             const bool last = (t == nt - 2);
;             const char* a1 = cA + (size_t)(t + 1) * kstep;
;             const char* a2 = last ? nA : cA + (size_t)(t + 2) * kstep; const char* b2 = last ? nB : cB + (size_t)(t + 2) * kstep;
;             const char* a3 = a2 + kstep; const char* b3 = b2 + kstep;
;             if (last && has_next) S.a_ready(nxt);
;             if constexpr (SP2) {
;             PG8_LDB(B0, 0, 0); PG8_LDB(B1, 0, 1); PG8_SCHED; PG8_LDA(At, 0, 0); PG8_STAGE(PG8_SA(1, 1), a1 + hstep, voffA);
;             PG8_WAIT_V(8); PG8_WAIT_L(0); PG8_BAR; PG8_MMA(0, 0, At, B0); PG8_MMA(0, 1, At, B1); PG8_BAR; PG8_SCHED;
;             PG8_LDA(At, 0, 1); PG8_STAGE(PG8_SB(0, 0), b2, voffB); PG8_STAGE(PG8_SB(0, 1), b2 + hstep, voffB); PG8_STAGE(PG8_SA(0, 0), a2, voffA);
;             PG8_WAIT_V(8); PG8_WAIT_L(0); PG8_BAR; PG8_MMA(1, 0, At, B0); PG8_MMA(1, 1, At, B1); PG8_BAR; PG8_SCHED;
;             PG8_LDB(B0, 1, 0); PG8_LDB(B1, 1, 1); PG8_SCHED; PG8_LDA(At, 1, 0); PG8_STAGE(PG8_SA(0, 1), a2 + hstep, voffA);
;             PG8_WAIT_V(8); PG8_WAIT_L(0); PG8_BAR; PG8_MMA(0, 0, At, B0); PG8_MMA(0, 1, At, B1); PG8_BAR; PG8_SCHED;
;             PG8_LDA(At, 1, 1); PG8_STAGE(PG8_SB(1, 0), b3, voffB); PG8_STAGE(PG8_SB(1, 1), b3 + hstep, voffB); PG8_STAGE(PG8_SA(1, 0), a3, voffA);
;             PG8_WAIT_V(8); PG8_WAIT_L(0); PG8_BAR; PG8_MMA(1, 0, At, B0); PG8_MMA(1, 1, At, B1); PG8_BAR; PG8_SCHED;
.LBB0_1455:
	s_ashr_i32 s17, s16, 31
	s_lshl_b64 s[20:21], s[16:17], 21
	s_add_u32 s20, s28, s20
	s_addc_u32 s21, s34, s21
	s_and_b64 s[22:23], s[8:9], exec
	s_cselect_b32 s17, s21, s25
	s_cselect_b32 s51, s20, s24
	s_ashr_i32 s19, s18, 31
	s_lshl_b64 s[22:23], s[18:19], 21
	s_add_u32 s22, s35, s22
	s_addc_u32 s23, s39, s23
	s_and_b64 s[36:37], s[8:9], exec
	s_cselect_b32 s19, s23, s27
	s_cselect_b32 s52, s22, s26
	s_add_u32 s24, s24, 0x100080
	s_addc_u32 s25, s25, 0
	s_add_u32 s53, s26, 0x100
	s_addc_u32 s54, s27, 0
	s_mov_b32 s55, -2
	s_waitcnt vmcnt(0)
	s_add_u32 s26, s24, 0xfff00080
	s_addc_u32 s27, s25, -1
	s_add_i32 s56, 0, 0x10000
	s_cmp_eq_u32 s55, 60
	s_cselect_b32 s37, s17, s27
	s_cselect_b32 s36, s51, s26
	s_cselect_b32 s27, s19, s54
	s_cselect_b32 s26, s52, s53
	s_add_i32 s58, 0, 0x14000
	v_add_u32_e32 v144, s56, v240
	v_add_u32_e32 v160, s58, v240
	ds_read_b128 v[124:127], v144
	ds_read_b128 v[164:167], v242
	ds_read_b128 v[128:131], v144 offset:1024
	ds_read_b128 v[168:171], v242 offset:1024
	ds_read_b128 v[176:179], v242 offset:3072
	ds_read_b128 v[172:175], v242 offset:2048
	ds_read_b128 v[180:183], v242 offset:4096
	ds_read_b128 v[184:187], v242 offset:5120
	s_add_i32 m0, s41, 0xc000
	ds_read_b128 v[214:217], v242 offset:7168
	ds_read_b128 v[188:191], v242 offset:6144
	ds_read_b128 v[132:135], v144 offset:2048
	ds_read_b128 v[144:147], v144 offset:3072
	ds_read_b128 v[148:151], v160
	ds_read_b128 v[152:155], v160 offset:1024
	ds_read_b128 v[156:159], v160 offset:2048
	ds_read_b128 v[160:163], v160 offset:3072
	global_load_lds_dwordx4 v210, s[24:25]
	s_add_i32 m0, s41, 0xe000
	s_nop 0
	global_load_lds_dwordx4 v212, s[24:25]
	s_waitcnt vmcnt(8)
	s_waitcnt lgkmcnt(14)
	s_setprio 1
	s_barrier
	v_mfma_f32_16x16x32_bf16 v[140:143], v[124:127], v[164:167], 0
	s_waitcnt lgkmcnt(12)
	v_mfma_f32_16x16x32_bf16 v[140:143], v[128:131], v[168:171], v[140:143]
	s_waitcnt lgkmcnt(11)
	v_mfma_f32_16x16x32_bf16 v[112:115], v[128:131], v[176:179], 0
	s_waitcnt lgkmcnt(10)
	v_mfma_f32_16x16x32_bf16 v[112:115], v[124:127], v[172:175], v[112:115]
	s_waitcnt lgkmcnt(9)
	v_mfma_f32_16x16x32_bf16 v[96:99], v[124:127], v[180:183], 0
	s_waitcnt lgkmcnt(8)
	v_mfma_f32_16x16x32_bf16 v[96:99], v[128:131], v[184:187], v[96:99]
	s_waitcnt lgkmcnt(7)
	v_mfma_f32_16x16x32_bf16 v[80:83], v[128:131], v[214:217], 0
	s_waitcnt lgkmcnt(6)
	v_mfma_f32_16x16x32_bf16 v[80:83], v[124:127], v[188:191], v[80:83]
	s_waitcnt lgkmcnt(5)
	v_mfma_f32_16x16x32_bf16 v[76:79], v[132:135], v[188:191], 0
	s_waitcnt lgkmcnt(4)
	v_mfma_f32_16x16x32_bf16 v[76:79], v[144:147], v[214:217], v[76:79]
	v_mfma_f32_16x16x32_bf16 v[92:95], v[144:147], v[184:187], 0
	v_mfma_f32_16x16x32_bf16 v[92:95], v[132:135], v[180:183], v[92:95]
	v_mfma_f32_16x16x32_bf16 v[108:111], v[132:135], v[172:175], 0
	v_mfma_f32_16x16x32_bf16 v[108:111], v[144:147], v[176:179], v[108:111]
	v_mfma_f32_16x16x32_bf16 v[136:139], v[144:147], v[168:171], 0
	v_mfma_f32_16x16x32_bf16 v[136:139], v[132:135], v[164:167], v[136:139]
	s_waitcnt lgkmcnt(3)
	v_mfma_f32_16x16x32_bf16 v[120:123], v[148:151], v[164:167], 0
	s_waitcnt lgkmcnt(2)
	v_mfma_f32_16x16x32_bf16 v[120:123], v[152:155], v[168:171], v[120:123]
	v_mfma_f32_16x16x32_bf16 v[104:107], v[152:155], v[176:179], 0
	v_mfma_f32_16x16x32_bf16 v[104:107], v[148:151], v[172:175], v[104:107]
	v_mfma_f32_16x16x32_bf16 v[88:91], v[148:151], v[180:183], 0
	v_mfma_f32_16x16x32_bf16 v[88:91], v[152:155], v[184:187], v[88:91]
	v_mfma_f32_16x16x32_bf16 v[72:75], v[152:155], v[214:217], 0
	v_mfma_f32_16x16x32_bf16 v[72:75], v[148:151], v[188:191], v[72:75]
	s_waitcnt lgkmcnt(1)
	v_mfma_f32_16x16x32_bf16 v[68:71], v[156:159], v[188:191], 0
	s_waitcnt lgkmcnt(0)
	v_mfma_f32_16x16x32_bf16 v[68:71], v[160:163], v[214:217], v[68:71]
	v_mfma_f32_16x16x32_bf16 v[84:87], v[160:163], v[184:187], 0
	v_mfma_f32_16x16x32_bf16 v[84:87], v[156:159], v[180:183], v[84:87]
	v_mfma_f32_16x16x32_bf16 v[100:103], v[156:159], v[172:175], 0
	v_mfma_f32_16x16x32_bf16 v[100:103], v[160:163], v[176:179], v[100:103]
	v_mfma_f32_16x16x32_bf16 v[116:119], v[160:163], v[168:171], 0
	v_mfma_f32_16x16x32_bf16 v[116:119], v[156:159], v[164:167], v[116:119]
	s_barrier
	s_add_i32 s56, s56, s40
	v_lshl_add_u64 v[218:219], s[26:27], 0, v[2:3]
	s_mov_b32 m0, s56
	ds_read_b128 v[164:167], v242 offset:16384
	ds_read_b128 v[168:171], v242 offset:17408
	ds_read_b128 v[176:179], v242 offset:19456
	ds_read_b128 v[172:175], v242 offset:18432
	ds_read_b128 v[180:183], v242 offset:20480
	ds_read_b128 v[184:187], v242 offset:21504
	ds_read_b128 v[214:217], v242 offset:23552
	ds_read_b128 v[188:191], v242 offset:22528
	s_setprio 0
	global_load_lds_dwordx4 v[218:219], off
	s_add_i32 m0, s56, 0x2000
	s_add_u32 s56, s26, 0x100000
	v_lshl_add_u64 v[220:221], s[26:27], 0, v[204:205]
	s_addc_u32 s57, s27, 0
	s_add_i32 s58, s58, s40
	global_load_lds_dwordx4 v[220:221], off
	s_mov_b32 m0, s58
	v_lshl_add_u64 v[224:225], s[36:37], 0, v[206:207]
	global_load_lds_dwordx4 v2, s[56:57]
	s_add_i32 m0, s58, 0x2000
	s_nop 0
	global_load_lds_dwordx4 v204, s[56:57]
	v_lshl_add_u64 v[222:223], s[36:37], 0, v[208:209]
	s_waitcnt vmcnt(6)
	s_waitcnt lgkmcnt(7)
	s_setprio 1
	s_barrier
; #define PG8_STAGE(bufoff, gbase, voff) do { _Pragma("unroll") for (int _i = 0; _i < 2; ++_i) \
;         __builtin_amdgcn_global_load_lds((const unsigned*)((const char*)(gbase) + (voff)[_i]), (PG8_LAS unsigned*)(lds + (bufoff) + ldsw + _i * 8192), 16, 0, 0); } while (0)
; #define PG8_LDA(dst, b, h) do { _Pragma("unroll") for (int m = 0; m < 4; ++m) _Pragma("unroll") for (int k = 0; k < 2; ++k) dst[m][k] = *(const PG8_LAS bf16x8*)(lds + PG8_SA(b, h) + aoff + m * 2048 + k * 1024); } while (0)
; #define PG8_LDB(dst, b, h) do { _Pragma("unroll") for (int n = 0; n < 2; ++n) _Pragma("unroll") for (int k = 0; k < 2; ++k) dst[n][k] = *(const PG8_LAS bf16x8*)(lds + PG8_SB(b, h) + boff + n * 2048 + k * 1024); } while (0)
; #define PG8_WAIT_V(n) asm volatile("s_waitcnt vmcnt(" #n ")" ::: "memory")
; #define PG8_WAIT_L(n) asm volatile("s_waitcnt lgkmcnt(" #n ")" ::: "memory")
; #define PG8_BAR __builtin_amdgcn_s_barrier()
; #define PG8_SCHED __builtin_amdgcn_sched_barrier(0)
; template <class Epi, class Sched, bool ALIGN_EPI = false, bool SP2 = false, bool I8 = false>
; __device__ __forceinline__ void gemm_phase(PG8_LAS unsigned char* lds, const Gemm g, const Sched& S, const Epi& E) {
;     ...
;             PG8_WAIT_V(8); PG8_WAIT_L(0); PG8_BAR; PG8_MMA(0, 0, At, B0); PG8_MMA(0, 1, At, B1); PG8_BAR; PG8_SCHED;
;             PG8_LDA(At, 0, 1); PG8_STAGE(PG8_SB(0, 0), b2, voffB); PG8_STAGE(PG8_SB(0, 1), b2 + hstep, voffB); PG8_STAGE(PG8_SA(0, 0), a2, voffA);
;             PG8_WAIT_V(8); PG8_WAIT_L(0); PG8_BAR; PG8_MMA(1, 0, At, B0); PG8_MMA(1, 1, At, B1); PG8_BAR; PG8_SCHED;
;             PG8_LDB(B0, 1, 0); PG8_LDB(B1, 1, 1); PG8_SCHED; PG8_LDA(At, 1, 0); PG8_STAGE(PG8_SA(0, 1), a2 + hstep, voffA);
;             PG8_WAIT_V(8); PG8_WAIT_L(0); PG8_BAR; PG8_MMA(0, 0, At, B0); PG8_MMA(0, 1, At, B1); PG8_BAR; PG8_SCHED;
;             PG8_LDA(At, 1, 1); PG8_STAGE(PG8_SB(1, 0), b3, voffB); PG8_STAGE(PG8_SB(1, 1), b3 + hstep, voffB); PG8_STAGE(PG8_SA(1, 0), a3, voffA);
;             PG8_WAIT_V(8); PG8_WAIT_L(0); PG8_BAR; PG8_MMA(1, 0, At, B0); PG8_MMA(1, 1, At, B1); PG8_BAR; PG8_SCHED;
	v_mfma_f32_16x16x32_bf16 v[64:67], v[124:127], v[164:167], 0
	s_waitcnt lgkmcnt(6)
	v_mfma_f32_16x16x32_bf16 v[64:67], v[128:131], v[168:171], v[64:67]
	s_waitcnt lgkmcnt(5)
	v_mfma_f32_16x16x32_bf16 v[48:51], v[128:131], v[176:179], 0
	s_waitcnt lgkmcnt(4)
	v_mfma_f32_16x16x32_bf16 v[48:51], v[124:127], v[172:175], v[48:51]
	s_waitcnt lgkmcnt(3)
	v_mfma_f32_16x16x32_bf16 v[32:35], v[124:127], v[180:183], 0
	s_waitcnt lgkmcnt(2)
	v_mfma_f32_16x16x32_bf16 v[32:35], v[128:131], v[184:187], v[32:35]
	s_waitcnt lgkmcnt(1)
	v_mfma_f32_16x16x32_bf16 v[16:19], v[128:131], v[214:217], 0
	s_waitcnt lgkmcnt(0)
	v_mfma_f32_16x16x32_bf16 v[16:19], v[124:127], v[188:191], v[16:19]
	v_mfma_f32_16x16x32_bf16 v[12:15], v[132:135], v[188:191], 0
	v_mfma_f32_16x16x32_bf16 v[12:15], v[144:147], v[214:217], v[12:15]
	v_mfma_f32_16x16x32_bf16 v[28:31], v[144:147], v[184:187], 0
	v_mfma_f32_16x16x32_bf16 v[28:31], v[132:135], v[180:183], v[28:31]
	v_mfma_f32_16x16x32_bf16 v[44:47], v[132:135], v[172:175], 0
	v_mfma_f32_16x16x32_bf16 v[44:47], v[144:147], v[176:179], v[44:47]
	v_mfma_f32_16x16x32_bf16 v[60:63], v[144:147], v[168:171], 0
	v_mfma_f32_16x16x32_bf16 v[60:63], v[132:135], v[164:167], v[60:63]
	v_mfma_f32_16x16x32_bf16 v[56:59], v[148:151], v[164:167], 0
	v_mfma_f32_16x16x32_bf16 v[56:59], v[152:155], v[168:171], v[56:59]
	v_mfma_f32_16x16x32_bf16 v[40:43], v[152:155], v[176:179], 0
	v_mfma_f32_16x16x32_bf16 v[40:43], v[148:151], v[172:175], v[40:43]
	v_mfma_f32_16x16x32_bf16 v[24:27], v[148:151], v[180:183], 0
	v_mfma_f32_16x16x32_bf16 v[24:27], v[152:155], v[184:187], v[24:27]
	v_mfma_f32_16x16x32_bf16 v[8:11], v[152:155], v[214:217], 0
	v_mfma_f32_16x16x32_bf16 v[8:11], v[148:151], v[188:191], v[8:11]
	v_mfma_f32_16x16x32_bf16 v[4:7], v[156:159], v[188:191], 0
	v_mfma_f32_16x16x32_bf16 v[4:7], v[160:163], v[214:217], v[4:7]
	v_mfma_f32_16x16x32_bf16 v[20:23], v[160:163], v[184:187], 0
	v_mfma_f32_16x16x32_bf16 v[20:23], v[156:159], v[180:183], v[20:23]
	v_mfma_f32_16x16x32_bf16 v[36:39], v[156:159], v[172:175], 0
	v_mfma_f32_16x16x32_bf16 v[36:39], v[160:163], v[176:179], v[36:39]
	v_mfma_f32_16x16x32_bf16 v[52:55], v[160:163], v[168:171], 0
	v_mfma_f32_16x16x32_bf16 v[52:55], v[156:159], v[164:167], v[52:55]
	s_barrier
	s_mov_b32 m0, s41
	s_nop 0
	global_load_lds_dwordx4 v[222:223], off
	s_mov_b32 m0, s42
	s_nop 0
	global_load_lds_dwordx4 v[224:225], off
	s_add_i32 s56, 0, 0x18000
	s_add_i32 s57, 0, 0x1c000
	v_add_u32_e32 v144, s56, v240
	v_add_u32_e32 v160, s57, v240
	ds_read_b128 v[124:127], v144
	ds_read_b128 v[164:167], v242 offset:32768
	ds_read_b128 v[128:131], v144 offset:1024
	ds_read_b128 v[168:171], v242 offset:33792
	ds_read_b128 v[176:179], v242 offset:35840
	ds_read_b128 v[172:175], v242 offset:34816
	ds_read_b128 v[180:183], v242 offset:36864
	ds_read_b128 v[184:187], v242 offset:37888
	s_add_u32 s36, s36, 0x100000
	s_addc_u32 s37, s37, 0
	s_mov_b32 m0, s43
	ds_read_b128 v[214:217], v242 offset:39936
	ds_read_b128 v[188:191], v242 offset:38912
	ds_read_b128 v[132:135], v144 offset:2048
	ds_read_b128 v[144:147], v144 offset:3072
	ds_read_b128 v[148:151], v160
	ds_read_b128 v[152:155], v160 offset:1024
	ds_read_b128 v[156:159], v160 offset:2048
	ds_read_b128 v[160:163], v160 offset:3072
	s_setprio 0
	global_load_lds_dwordx4 v208, s[36:37]
	s_mov_b32 m0, s44
	s_nop 0
	global_load_lds_dwordx4 v206, s[36:37]
	s_waitcnt vmcnt(8)
	s_waitcnt lgkmcnt(14)
	s_setprio 1
	s_barrier
; #define PG8_STAGE(bufoff, gbase, voff) do { _Pragma("unroll") for (int _i = 0; _i < 2; ++_i) \
;         __builtin_amdgcn_global_load_lds((const unsigned*)((const char*)(gbase) + (voff)[_i]), (PG8_LAS unsigned*)(lds + (bufoff) + ldsw + _i * 8192), 16, 0, 0); } while (0)
; #define PG8_LDA(dst, b, h) do { _Pragma("unroll") for (int m = 0; m < 4; ++m) _Pragma("unroll") for (int k = 0; k < 2; ++k) dst[m][k] = *(const PG8_LAS bf16x8*)(lds + PG8_SA(b, h) + aoff + m * 2048 + k * 1024); } while (0)
; #define PG8_LDB(dst, b, h) do { _Pragma("unroll") for (int n = 0; n < 2; ++n) _Pragma("unroll") for (int k = 0; k < 2; ++k) dst[n][k] = *(const PG8_LAS bf16x8*)(lds + PG8_SB(b, h) + boff + n * 2048 + k * 1024); } while (0)
; #define PG8_WAIT_V(n) asm volatile("s_waitcnt vmcnt(" #n ")" ::: "memory")
; #define PG8_WAIT_L(n) asm volatile("s_waitcnt lgkmcnt(" #n ")" ::: "memory")
; #define PG8_BAR __builtin_amdgcn_s_barrier()
; #define PG8_SCHED __builtin_amdgcn_sched_barrier(0)
; template <class Epi, class Sched, bool ALIGN_EPI = false, bool SP2 = false, bool I8 = false>
; __device__ __forceinline__ void gemm_phase(PG8_LAS unsigned char* lds, const Gemm g, const Sched& S, const Epi& E) {
;     ...
;             if constexpr (SP2) {
;             PG8_LDB(B0, 0, 0); PG8_LDB(B1, 0, 1); PG8_SCHED; PG8_LDA(At, 0, 0); PG8_STAGE(PG8_SA(1, 1), a1 + hstep, voffA);
;             PG8_WAIT_V(8); PG8_WAIT_L(0); PG8_BAR; PG8_MMA(0, 0, At, B0); PG8_MMA(0, 1, At, B1); PG8_BAR; PG8_SCHED;
;             PG8_LDA(At, 0, 1); PG8_STAGE(PG8_SB(0, 0), b2, voffB); PG8_STAGE(PG8_SB(0, 1), b2 + hstep, voffB); PG8_STAGE(PG8_SA(0, 0), a2, voffA);
;             PG8_WAIT_V(8); PG8_WAIT_L(0); PG8_BAR; PG8_MMA(1, 0, At, B0); PG8_MMA(1, 1, At, B1); PG8_BAR; PG8_SCHED;
;             PG8_LDB(B0, 1, 0); PG8_LDB(B1, 1, 1); PG8_SCHED; PG8_LDA(At, 1, 0); PG8_STAGE(PG8_SA(0, 1), a2 + hstep, voffA);
;             PG8_WAIT_V(8); PG8_WAIT_L(0); PG8_BAR; PG8_MMA(0, 0, At, B0); PG8_MMA(0, 1, At, B1); PG8_BAR; PG8_SCHED;
;             PG8_LDA(At, 1, 1); PG8_STAGE(PG8_SB(1, 0), b3, voffB); PG8_STAGE(PG8_SB(1, 1), b3 + hstep, voffB); PG8_STAGE(PG8_SA(1, 0), a3, voffA);
;             PG8_WAIT_V(8); PG8_WAIT_L(0); PG8_BAR; PG8_MMA(1, 0, At, B0); PG8_MMA(1, 1, At, B1); PG8_BAR; PG8_SCHED;
	v_mfma_f32_16x16x32_bf16 v[140:143], v[124:127], v[164:167], v[140:143]
	s_waitcnt lgkmcnt(12)
	v_mfma_f32_16x16x32_bf16 v[140:143], v[128:131], v[168:171], v[140:143]
	s_waitcnt lgkmcnt(11)
	v_mfma_f32_16x16x32_bf16 v[112:115], v[128:131], v[176:179], v[112:115]
	s_waitcnt lgkmcnt(10)
	v_mfma_f32_16x16x32_bf16 v[112:115], v[124:127], v[172:175], v[112:115]
	s_waitcnt lgkmcnt(9)
	v_mfma_f32_16x16x32_bf16 v[96:99], v[124:127], v[180:183], v[96:99]
	s_waitcnt lgkmcnt(8)
	v_mfma_f32_16x16x32_bf16 v[96:99], v[128:131], v[184:187], v[96:99]
	s_waitcnt lgkmcnt(7)
	v_mfma_f32_16x16x32_bf16 v[80:83], v[128:131], v[214:217], v[80:83]
	s_waitcnt lgkmcnt(6)
	v_mfma_f32_16x16x32_bf16 v[80:83], v[124:127], v[188:191], v[80:83]
	s_waitcnt lgkmcnt(5)
	v_mfma_f32_16x16x32_bf16 v[76:79], v[132:135], v[188:191], v[76:79]
	s_waitcnt lgkmcnt(4)
	v_mfma_f32_16x16x32_bf16 v[76:79], v[144:147], v[214:217], v[76:79]
	v_mfma_f32_16x16x32_bf16 v[92:95], v[144:147], v[184:187], v[92:95]
	v_mfma_f32_16x16x32_bf16 v[92:95], v[132:135], v[180:183], v[92:95]
	v_mfma_f32_16x16x32_bf16 v[108:111], v[132:135], v[172:175], v[108:111]
	v_mfma_f32_16x16x32_bf16 v[108:111], v[144:147], v[176:179], v[108:111]
	v_mfma_f32_16x16x32_bf16 v[136:139], v[144:147], v[168:171], v[136:139]
	v_mfma_f32_16x16x32_bf16 v[136:139], v[132:135], v[164:167], v[136:139]
	s_waitcnt lgkmcnt(3)
	v_mfma_f32_16x16x32_bf16 v[120:123], v[148:151], v[164:167], v[120:123]
	s_waitcnt lgkmcnt(2)
	v_mfma_f32_16x16x32_bf16 v[120:123], v[152:155], v[168:171], v[120:123]
	v_mfma_f32_16x16x32_bf16 v[104:107], v[152:155], v[176:179], v[104:107]
	v_mfma_f32_16x16x32_bf16 v[104:107], v[148:151], v[172:175], v[104:107]
	v_mfma_f32_16x16x32_bf16 v[88:91], v[148:151], v[180:183], v[88:91]
	v_mfma_f32_16x16x32_bf16 v[88:91], v[152:155], v[184:187], v[88:91]
	v_mfma_f32_16x16x32_bf16 v[72:75], v[152:155], v[214:217], v[72:75]
	v_mfma_f32_16x16x32_bf16 v[72:75], v[148:151], v[188:191], v[72:75]
	s_waitcnt lgkmcnt(1)
	v_mfma_f32_16x16x32_bf16 v[68:71], v[156:159], v[188:191], v[68:71]
	s_waitcnt lgkmcnt(0)
	v_mfma_f32_16x16x32_bf16 v[68:71], v[160:163], v[214:217], v[68:71]
	v_mfma_f32_16x16x32_bf16 v[84:87], v[160:163], v[184:187], v[84:87]
	v_mfma_f32_16x16x32_bf16 v[84:87], v[156:159], v[180:183], v[84:87]
	v_mfma_f32_16x16x32_bf16 v[100:103], v[156:159], v[172:175], v[100:103]
	v_mfma_f32_16x16x32_bf16 v[100:103], v[160:163], v[176:179], v[100:103]
	v_mfma_f32_16x16x32_bf16 v[116:119], v[160:163], v[168:171], v[116:119]
	v_mfma_f32_16x16x32_bf16 v[116:119], v[156:159], v[164:167], v[116:119]
	s_barrier
	s_add_i32 s36, s56, s40
	v_lshl_add_u64 v[218:219], v[218:219], 0, s[84:85]
	s_mov_b32 m0, s36
	ds_read_b128 v[164:167], v242 offset:49152
	ds_read_b128 v[168:171], v242 offset:50176
	ds_read_b128 v[176:179], v242 offset:52224
	ds_read_b128 v[172:175], v242 offset:51200
	ds_read_b128 v[180:183], v242 offset:53248
	ds_read_b128 v[184:187], v242 offset:54272
	ds_read_b128 v[214:217], v242 offset:56320
	ds_read_b128 v[188:191], v242 offset:55296
	s_setprio 0
	global_load_lds_dwordx4 v[218:219], off
	s_add_i32 m0, s36, 0x2000
	s_add_u32 s26, s26, 0x100080
	v_lshl_add_u64 v[218:219], v[220:221], 0, s[84:85]
	s_addc_u32 s27, s27, 0
	s_add_i32 s36, s57, s40
	global_load_lds_dwordx4 v[218:219], off
	s_mov_b32 m0, s36
	s_nop 0
	global_load_lds_dwordx4 v2, s[26:27]
	s_add_i32 m0, s36, 0x2000
	s_nop 0
	global_load_lds_dwordx4 v204, s[26:27]
	s_cmp_eq_u32 s55, 60
	s_cbranch_scc0 .Ldefer_1456_peel
	v_lshl_add_u64 v[218:219], v[222:223], 0, s[84:85]
	s_mov_b32 m0, s45
	s_nop 0
	global_load_lds_dwordx4 v[218:219], off
	v_lshl_add_u64 v[218:219], v[224:225], 0, s[84:85]
	s_mov_b32 m0, s46
	s_nop 0
	global_load_lds_dwordx4 v[218:219], off

; #define PG8_STAGE(bufoff, gbase, voff) do { _Pragma("unroll") for (int _i = 0; _i < 2; ++_i) \
;         __builtin_amdgcn_global_load_lds((const unsigned*)((const char*)(gbase) + (voff)[_i]), (PG8_LAS unsigned*)(lds + (bufoff) + ldsw + _i * 8192), 16, 0, 0); } while (0)
; #define PG8_LDA(dst, b, h) do { _Pragma("unroll") for (int m = 0; m < 4; ++m) _Pragma("unroll") for (int k = 0; k < 2; ++k) dst[m][k] = *(const PG8_LAS bf16x8*)(lds + PG8_SA(b, h) + aoff + m * 2048 + k * 1024); } while (0)
; #define PG8_WAIT_V(n) asm volatile("s_waitcnt vmcnt(" #n ")" ::: "memory")
; #define PG8_WAIT_L(n) asm volatile("s_waitcnt lgkmcnt(" #n ")" ::: "memory")
; #define PG8_BAR __builtin_amdgcn_s_barrier()
; template <class Epi, class Sched, bool ALIGN_EPI = false, bool SP2 = false, bool I8 = false>
; __device__ __forceinline__ void gemm_phase(PG8_LAS unsigned char* lds, const Gemm g, const Sched& S, const Epi& E) {
;     ...
;         for (int t = 0; t < nt; t += 2) {
;             const bool last = (t == nt - 2);
;             const char* a1 = cA + (size_t)(t + 1) * kstep;
;             const char* a2 = last ? nA : cA + (size_t)(t + 2) * kstep; const char* b2 = last ? nB : cB + (size_t)(t + 2) * kstep;
;             const char* a3 = a2 + kstep; const char* b3 = b2 + kstep;
;             if (last && has_next) S.a_ready(nxt);
;             if constexpr (SP2) {
;             PG8_LDB(B0, 0, 0); PG8_LDB(B1, 0, 1); PG8_SCHED; PG8_LDA(At, 0, 0); PG8_STAGE(PG8_SA(1, 1), a1 + hstep, voffA);
;             PG8_WAIT_V(8); PG8_WAIT_L(0); PG8_BAR; PG8_MMA(0, 0, At, B0); PG8_MMA(0, 1, At, B1); PG8_BAR; PG8_SCHED;
;             PG8_LDA(At, 0, 1); PG8_STAGE(PG8_SB(0, 0), b2, voffB); PG8_STAGE(PG8_SB(0, 1), b2 + hstep, voffB); PG8_STAGE(PG8_SA(0, 0), a2, voffA);
;             PG8_WAIT_V(8); PG8_WAIT_L(0); PG8_BAR; PG8_MMA(1, 0, At, B0); PG8_MMA(1, 1, At, B1); PG8_BAR; PG8_SCHED;
;             PG8_LDB(B0, 1, 0); PG8_LDB(B1, 1, 1); PG8_SCHED; PG8_LDA(At, 1, 0); PG8_STAGE(PG8_SA(0, 1), a2 + hstep, voffA);
;             PG8_WAIT_V(8); PG8_WAIT_L(0); PG8_BAR; PG8_MMA(0, 0, At, B0); PG8_MMA(0, 1, At, B1); PG8_BAR; PG8_SCHED;
;             PG8_LDA(At, 1, 1); PG8_STAGE(PG8_SB(1, 0), b3, voffB); PG8_STAGE(PG8_SB(1, 1), b3 + hstep, voffB); PG8_STAGE(PG8_SA(1, 0), a3, voffA);
;             PG8_WAIT_V(8); PG8_WAIT_L(0); PG8_BAR; PG8_MMA(1, 0, At, B0); PG8_MMA(1, 1, At, B1); PG8_BAR; PG8_SCHED;
.LBB0_1456:
	s_add_u32 s26, s24, 0xfff00080
	s_addc_u32 s27, s25, -1
	s_add_i32 s56, 0, 0x10000
	s_cmp_eq_u32 s55, 60
	s_cselect_b32 s37, s17, s27
	s_cselect_b32 s36, s51, s26
	s_cselect_b32 s27, s19, s54
	s_cselect_b32 s26, s52, s53
	s_add_i32 s58, 0, 0x14000
	v_add_u32_e32 v144, s56, v240
	v_add_u32_e32 v160, s58, v240
	ds_read_b128 v[124:127], v144
	ds_read_b128 v[164:167], v242
	ds_read_b128 v[128:131], v144 offset:1024
	ds_read_b128 v[168:171], v242 offset:1024
	ds_read_b128 v[176:179], v242 offset:3072
	ds_read_b128 v[172:175], v242 offset:2048
	ds_read_b128 v[180:183], v242 offset:4096
	ds_read_b128 v[184:187], v242 offset:5120
	v_lshl_add_u64 v[218:219], v[222:223], 0, s[84:85]
	s_mov_b32 m0, s45
	s_nop 0
	global_load_lds_dwordx4 v[218:219], off
	v_lshl_add_u64 v[218:219], v[224:225], 0, s[84:85]
	s_mov_b32 m0, s46
	s_nop 0
	global_load_lds_dwordx4 v[218:219], off
	s_add_i32 m0, s41, 0xc000
	ds_read_b128 v[214:217], v242 offset:7168
	ds_read_b128 v[188:191], v242 offset:6144
	ds_read_b128 v[132:135], v144 offset:2048
	ds_read_b128 v[144:147], v144 offset:3072
	ds_read_b128 v[148:151], v160
	ds_read_b128 v[152:155], v160 offset:1024
	ds_read_b128 v[156:159], v160 offset:2048
	ds_read_b128 v[160:163], v160 offset:3072
	global_load_lds_dwordx4 v210, s[24:25]
	s_add_i32 m0, s41, 0xe000
	s_nop 0
	global_load_lds_dwordx4 v212, s[24:25]
	s_waitcnt vmcnt(8)
	s_waitcnt lgkmcnt(14)
	s_setprio 1
	s_barrier
	v_mfma_f32_16x16x32_bf16 v[140:143], v[124:127], v[164:167], v[140:143]
	s_waitcnt lgkmcnt(12)
	v_mfma_f32_16x16x32_bf16 v[140:143], v[128:131], v[168:171], v[140:143]
	s_waitcnt lgkmcnt(11)
	v_mfma_f32_16x16x32_bf16 v[112:115], v[128:131], v[176:179], v[112:115]
	s_waitcnt lgkmcnt(10)
	v_mfma_f32_16x16x32_bf16 v[112:115], v[124:127], v[172:175], v[112:115]
	s_waitcnt lgkmcnt(9)
	v_mfma_f32_16x16x32_bf16 v[96:99], v[124:127], v[180:183], v[96:99]
	s_waitcnt lgkmcnt(8)
	v_mfma_f32_16x16x32_bf16 v[96:99], v[128:131], v[184:187], v[96:99]
	s_waitcnt lgkmcnt(7)
	v_mfma_f32_16x16x32_bf16 v[80:83], v[128:131], v[214:217], v[80:83]
	s_waitcnt lgkmcnt(6)
	v_mfma_f32_16x16x32_bf16 v[80:83], v[124:127], v[188:191], v[80:83]
	s_waitcnt lgkmcnt(5)
	v_mfma_f32_16x16x32_bf16 v[76:79], v[132:135], v[188:191], v[76:79]
	s_waitcnt lgkmcnt(4)
	v_mfma_f32_16x16x32_bf16 v[76:79], v[144:147], v[214:217], v[76:79]
	v_mfma_f32_16x16x32_bf16 v[92:95], v[144:147], v[184:187], v[92:95]
	v_mfma_f32_16x16x32_bf16 v[92:95], v[132:135], v[180:183], v[92:95]
	v_mfma_f32_16x16x32_bf16 v[108:111], v[132:135], v[172:175], v[108:111]
	v_mfma_f32_16x16x32_bf16 v[108:111], v[144:147], v[176:179], v[108:111]
	v_mfma_f32_16x16x32_bf16 v[136:139], v[144:147], v[168:171], v[136:139]
	v_mfma_f32_16x16x32_bf16 v[136:139], v[132:135], v[164:167], v[136:139]
	s_waitcnt lgkmcnt(3)
	v_mfma_f32_16x16x32_bf16 v[120:123], v[148:151], v[164:167], v[120:123]
	s_waitcnt lgkmcnt(2)
	v_mfma_f32_16x16x32_bf16 v[120:123], v[152:155], v[168:171], v[120:123]
	v_mfma_f32_16x16x32_bf16 v[104:107], v[152:155], v[176:179], v[104:107]
	v_mfma_f32_16x16x32_bf16 v[104:107], v[148:151], v[172:175], v[104:107]
	v_mfma_f32_16x16x32_bf16 v[88:91], v[148:151], v[180:183], v[88:91]
	v_mfma_f32_16x16x32_bf16 v[88:91], v[152:155], v[184:187], v[88:91]
	v_mfma_f32_16x16x32_bf16 v[72:75], v[152:155], v[214:217], v[72:75]
	v_mfma_f32_16x16x32_bf16 v[72:75], v[148:151], v[188:191], v[72:75]
	s_waitcnt lgkmcnt(1)
	v_mfma_f32_16x16x32_bf16 v[68:71], v[156:159], v[188:191], v[68:71]
	s_waitcnt lgkmcnt(0)
	v_mfma_f32_16x16x32_bf16 v[68:71], v[160:163], v[214:217], v[68:71]
	v_mfma_f32_16x16x32_bf16 v[84:87], v[160:163], v[184:187], v[84:87]
	v_mfma_f32_16x16x32_bf16 v[84:87], v[156:159], v[180:183], v[84:87]
	v_mfma_f32_16x16x32_bf16 v[100:103], v[156:159], v[172:175], v[100:103]
	v_mfma_f32_16x16x32_bf16 v[100:103], v[160:163], v[176:179], v[100:103]
	v_mfma_f32_16x16x32_bf16 v[116:119], v[160:163], v[168:171], v[116:119]
	v_mfma_f32_16x16x32_bf16 v[116:119], v[156:159], v[164:167], v[116:119]
	s_barrier
	s_add_i32 s56, s56, s40
	v_lshl_add_u64 v[218:219], s[26:27], 0, v[2:3]
	s_mov_b32 m0, s56
	ds_read_b128 v[164:167], v242 offset:16384
	ds_read_b128 v[168:171], v242 offset:17408
	ds_read_b128 v[176:179], v242 offset:19456
	ds_read_b128 v[172:175], v242 offset:18432
	ds_read_b128 v[180:183], v242 offset:20480
	ds_read_b128 v[184:187], v242 offset:21504
	ds_read_b128 v[214:217], v242 offset:23552
	ds_read_b128 v[188:191], v242 offset:22528
	s_setprio 0
	global_load_lds_dwordx4 v[218:219], off
	s_add_i32 m0, s56, 0x2000
	s_add_u32 s56, s26, 0x100000
	v_lshl_add_u64 v[220:221], s[26:27], 0, v[204:205]
	s_addc_u32 s57, s27, 0
	s_add_i32 s58, s58, s40
	global_load_lds_dwordx4 v[220:221], off
	s_mov_b32 m0, s58
	v_lshl_add_u64 v[224:225], s[36:37], 0, v[206:207]
	global_load_lds_dwordx4 v2, s[56:57]
	s_add_i32 m0, s58, 0x2000
	s_nop 0
	global_load_lds_dwordx4 v204, s[56:57]
	v_lshl_add_u64 v[222:223], s[36:37], 0, v[208:209]
	s_waitcnt vmcnt(6)
	s_waitcnt lgkmcnt(7)
	s_setprio 1
	s_barrier
; #define PG8_STAGE(bufoff, gbase, voff) do { _Pragma("unroll") for (int _i = 0; _i < 2; ++_i) \
;         __builtin_amdgcn_global_load_lds((const unsigned*)((const char*)(gbase) + (voff)[_i]), (PG8_LAS unsigned*)(lds + (bufoff) + ldsw + _i * 8192), 16, 0, 0); } while (0)
; #define PG8_LDA(dst, b, h) do { _Pragma("unroll") for (int m = 0; m < 4; ++m) _Pragma("unroll") for (int k = 0; k < 2; ++k) dst[m][k] = *(const PG8_LAS bf16x8*)(lds + PG8_SA(b, h) + aoff + m * 2048 + k * 1024); } while (0)
; #define PG8_LDB(dst, b, h) do { _Pragma("unroll") for (int n = 0; n < 2; ++n) _Pragma("unroll") for (int k = 0; k < 2; ++k) dst[n][k] = *(const PG8_LAS bf16x8*)(lds + PG8_SB(b, h) + boff + n * 2048 + k * 1024); } while (0)
; #define PG8_WAIT_V(n) asm volatile("s_waitcnt vmcnt(" #n ")" ::: "memory")
; #define PG8_WAIT_L(n) asm volatile("s_waitcnt lgkmcnt(" #n ")" ::: "memory")
; #define PG8_BAR __builtin_amdgcn_s_barrier()
; #define PG8_SCHED __builtin_amdgcn_sched_barrier(0)
; template <class Epi, class Sched, bool ALIGN_EPI = false, bool SP2 = false, bool I8 = false>
; __device__ __forceinline__ void gemm_phase(PG8_LAS unsigned char* lds, const Gemm g, const Sched& S, const Epi& E) {
;     ...
;             if constexpr (SP2) {
;             PG8_LDB(B0, 0, 0); PG8_LDB(B1, 0, 1); PG8_SCHED; PG8_LDA(At, 0, 0); PG8_STAGE(PG8_SA(1, 1), a1 + hstep, voffA);
;             PG8_WAIT_V(8); PG8_WAIT_L(0); PG8_BAR; PG8_MMA(0, 0, At, B0); PG8_MMA(0, 1, At, B1); PG8_BAR; PG8_SCHED;
;             PG8_LDA(At, 0, 1); PG8_STAGE(PG8_SB(0, 0), b2, voffB); PG8_STAGE(PG8_SB(0, 1), b2 + hstep, voffB); PG8_STAGE(PG8_SA(0, 0), a2, voffA);
;             PG8_WAIT_V(8); PG8_WAIT_L(0); PG8_BAR; PG8_MMA(1, 0, At, B0); PG8_MMA(1, 1, At, B1); PG8_BAR; PG8_SCHED;
;             PG8_LDB(B0, 1, 0); PG8_LDB(B1, 1, 1); PG8_SCHED; PG8_LDA(At, 1, 0); PG8_STAGE(PG8_SA(0, 1), a2 + hstep, voffA);
;             PG8_WAIT_V(8); PG8_WAIT_L(0); PG8_BAR; PG8_MMA(0, 0, At, B0); PG8_MMA(0, 1, At, B1); PG8_BAR; PG8_SCHED;
;             PG8_LDA(At, 1, 1); PG8_STAGE(PG8_SB(1, 0), b3, voffB); PG8_STAGE(PG8_SB(1, 1), b3 + hstep, voffB); PG8_STAGE(PG8_SA(1, 0), a3, voffA);
;             PG8_WAIT_V(8); PG8_WAIT_L(0); PG8_BAR; PG8_MMA(1, 0, At, B0); PG8_MMA(1, 1, At, B1); PG8_BAR; PG8_SCHED;
	v_mfma_f32_16x16x32_bf16 v[64:67], v[124:127], v[164:167], v[64:67]
	s_waitcnt lgkmcnt(6)
	v_mfma_f32_16x16x32_bf16 v[64:67], v[128:131], v[168:171], v[64:67]
	s_waitcnt lgkmcnt(5)
	v_mfma_f32_16x16x32_bf16 v[48:51], v[128:131], v[176:179], v[48:51]
	s_waitcnt lgkmcnt(4)
	v_mfma_f32_16x16x32_bf16 v[48:51], v[124:127], v[172:175], v[48:51]
	s_waitcnt lgkmcnt(3)
	v_mfma_f32_16x16x32_bf16 v[32:35], v[124:127], v[180:183], v[32:35]
	s_waitcnt lgkmcnt(2)
	v_mfma_f32_16x16x32_bf16 v[32:35], v[128:131], v[184:187], v[32:35]
	s_waitcnt lgkmcnt(1)
	v_mfma_f32_16x16x32_bf16 v[16:19], v[128:131], v[214:217], v[16:19]
	s_waitcnt lgkmcnt(0)
	v_mfma_f32_16x16x32_bf16 v[16:19], v[124:127], v[188:191], v[16:19]
	v_mfma_f32_16x16x32_bf16 v[12:15], v[132:135], v[188:191], v[12:15]
	v_mfma_f32_16x16x32_bf16 v[12:15], v[144:147], v[214:217], v[12:15]
	v_mfma_f32_16x16x32_bf16 v[28:31], v[144:147], v[184:187], v[28:31]
	v_mfma_f32_16x16x32_bf16 v[28:31], v[132:135], v[180:183], v[28:31]
	v_mfma_f32_16x16x32_bf16 v[44:47], v[132:135], v[172:175], v[44:47]
	v_mfma_f32_16x16x32_bf16 v[44:47], v[144:147], v[176:179], v[44:47]
	v_mfma_f32_16x16x32_bf16 v[60:63], v[144:147], v[168:171], v[60:63]
	v_mfma_f32_16x16x32_bf16 v[60:63], v[132:135], v[164:167], v[60:63]
	v_mfma_f32_16x16x32_bf16 v[56:59], v[148:151], v[164:167], v[56:59]
	v_mfma_f32_16x16x32_bf16 v[56:59], v[152:155], v[168:171], v[56:59]
	v_mfma_f32_16x16x32_bf16 v[40:43], v[152:155], v[176:179], v[40:43]
	v_mfma_f32_16x16x32_bf16 v[40:43], v[148:151], v[172:175], v[40:43]
	v_mfma_f32_16x16x32_bf16 v[24:27], v[148:151], v[180:183], v[24:27]
	v_mfma_f32_16x16x32_bf16 v[24:27], v[152:155], v[184:187], v[24:27]
	v_mfma_f32_16x16x32_bf16 v[8:11], v[152:155], v[214:217], v[8:11]
	v_mfma_f32_16x16x32_bf16 v[8:11], v[148:151], v[188:191], v[8:11]
	v_mfma_f32_16x16x32_bf16 v[4:7], v[156:159], v[188:191], v[4:7]
	v_mfma_f32_16x16x32_bf16 v[4:7], v[160:163], v[214:217], v[4:7]
	v_mfma_f32_16x16x32_bf16 v[20:23], v[160:163], v[184:187], v[20:23]
	v_mfma_f32_16x16x32_bf16 v[20:23], v[156:159], v[180:183], v[20:23]
	v_mfma_f32_16x16x32_bf16 v[36:39], v[156:159], v[172:175], v[36:39]
	v_mfma_f32_16x16x32_bf16 v[36:39], v[160:163], v[176:179], v[36:39]
	v_mfma_f32_16x16x32_bf16 v[52:55], v[160:163], v[168:171], v[52:55]
	v_mfma_f32_16x16x32_bf16 v[52:55], v[156:159], v[164:167], v[52:55]
	s_barrier
	s_mov_b32 m0, s41
	s_nop 0
	global_load_lds_dwordx4 v[222:223], off
	s_mov_b32 m0, s42
	s_nop 0
	global_load_lds_dwordx4 v[224:225], off
	s_add_i32 s56, 0, 0x18000
	s_add_i32 s57, 0, 0x1c000
	v_add_u32_e32 v144, s56, v240
	v_add_u32_e32 v160, s57, v240
	ds_read_b128 v[124:127], v144
	ds_read_b128 v[164:167], v242 offset:32768
	ds_read_b128 v[128:131], v144 offset:1024
	ds_read_b128 v[168:171], v242 offset:33792
	ds_read_b128 v[176:179], v242 offset:35840
	ds_read_b128 v[172:175], v242 offset:34816
	ds_read_b128 v[180:183], v242 offset:36864
	ds_read_b128 v[184:187], v242 offset:37888
	s_add_u32 s36, s36, 0x100000
	s_addc_u32 s37, s37, 0
	s_mov_b32 m0, s43
	ds_read_b128 v[214:217], v242 offset:39936
	ds_read_b128 v[188:191], v242 offset:38912
	ds_read_b128 v[132:135], v144 offset:2048
	ds_read_b128 v[144:147], v144 offset:3072
	ds_read_b128 v[148:151], v160
	ds_read_b128 v[152:155], v160 offset:1024
	ds_read_b128 v[156:159], v160 offset:2048
	ds_read_b128 v[160:163], v160 offset:3072
	s_setprio 0
	global_load_lds_dwordx4 v208, s[36:37]
	s_mov_b32 m0, s44
	s_nop 0
	global_load_lds_dwordx4 v206, s[36:37]
	s_waitcnt vmcnt(8)
	s_waitcnt lgkmcnt(14)
	s_setprio 1
	s_barrier
; #define PG8_STAGE(bufoff, gbase, voff) do { _Pragma("unroll") for (int _i = 0; _i < 2; ++_i) \
;         __builtin_amdgcn_global_load_lds((const unsigned*)((const char*)(gbase) + (voff)[_i]), (PG8_LAS unsigned*)(lds + (bufoff) + ldsw + _i * 8192), 16, 0, 0); } while (0)
; #define PG8_LDA(dst, b, h) do { _Pragma("unroll") for (int m = 0; m < 4; ++m) _Pragma("unroll") for (int k = 0; k < 2; ++k) dst[m][k] = *(const PG8_LAS bf16x8*)(lds + PG8_SA(b, h) + aoff + m * 2048 + k * 1024); } while (0)
; #define PG8_LDB(dst, b, h) do { _Pragma("unroll") for (int n = 0; n < 2; ++n) _Pragma("unroll") for (int k = 0; k < 2; ++k) dst[n][k] = *(const PG8_LAS bf16x8*)(lds + PG8_SB(b, h) + boff + n * 2048 + k * 1024); } while (0)
; template <class Epi, class Sched, bool ALIGN_EPI = false, bool SP2 = false, bool I8 = false>
; __device__ __forceinline__ void gemm_phase(PG8_LAS unsigned char* lds, const Gemm g, const Sched& S, const Epi& E) {
;     ...
;             const bool last = (t == nt - 2);
;             const char* a1 = cA + (size_t)(t + 1) * kstep;
;             const char* a2 = last ? nA : cA + (size_t)(t + 2) * kstep; const char* b2 = last ? nB : cB + (size_t)(t + 2) * kstep;
;             const char* a3 = a2 + kstep; const char* b3 = b2 + kstep;
;             if (last && has_next) S.a_ready(nxt);
;             if constexpr (SP2) {
;             PG8_LDB(B0, 0, 0); PG8_LDB(B1, 0, 1); PG8_SCHED; PG8_LDA(At, 0, 0); PG8_STAGE(PG8_SA(1, 1), a1 + hstep, voffA);
;             PG8_WAIT_V(8); PG8_WAIT_L(0); PG8_BAR; PG8_MMA(0, 0, At, B0); PG8_MMA(0, 1, At, B1); PG8_BAR; PG8_SCHED;
;             PG8_LDA(At, 0, 1); PG8_STAGE(PG8_SB(0, 0), b2, voffB); PG8_STAGE(PG8_SB(0, 1), b2 + hstep, voffB); PG8_STAGE(PG8_SA(0, 0), a2, voffA);
;             PG8_WAIT_V(8); PG8_WAIT_L(0); PG8_BAR; PG8_MMA(1, 0, At, B0); PG8_MMA(1, 1, At, B1); PG8_BAR; PG8_SCHED;
;             PG8_LDB(B0, 1, 0); PG8_LDB(B1, 1, 1); PG8_SCHED; PG8_LDA(At, 1, 0); PG8_STAGE(PG8_SA(0, 1), a2 + hstep, voffA);
;             PG8_WAIT_V(8); PG8_WAIT_L(0); PG8_BAR; PG8_MMA(0, 0, At, B0); PG8_MMA(0, 1, At, B1); PG8_BAR; PG8_SCHED;
;             PG8_LDA(At, 1, 1); PG8_STAGE(PG8_SB(1, 0), b3, voffB); PG8_STAGE(PG8_SB(1, 1), b3 + hstep, voffB); PG8_STAGE(PG8_SA(1, 0), a3, voffA);
;             PG8_WAIT_V(8); PG8_WAIT_L(0); PG8_BAR; PG8_MMA(1, 0, At, B0); PG8_MMA(1, 1, At, B1); PG8_BAR; PG8_SCHED;
	v_mfma_f32_16x16x32_bf16 v[140:143], v[124:127], v[164:167], v[140:143]
	s_waitcnt lgkmcnt(12)
	v_mfma_f32_16x16x32_bf16 v[140:143], v[128:131], v[168:171], v[140:143]
	s_waitcnt lgkmcnt(11)
	v_mfma_f32_16x16x32_bf16 v[112:115], v[128:131], v[176:179], v[112:115]
	s_waitcnt lgkmcnt(10)
	v_mfma_f32_16x16x32_bf16 v[112:115], v[124:127], v[172:175], v[112:115]
	s_waitcnt lgkmcnt(9)
	v_mfma_f32_16x16x32_bf16 v[96:99], v[124:127], v[180:183], v[96:99]
	s_waitcnt lgkmcnt(8)
	v_mfma_f32_16x16x32_bf16 v[96:99], v[128:131], v[184:187], v[96:99]
	s_waitcnt lgkmcnt(7)
	v_mfma_f32_16x16x32_bf16 v[80:83], v[128:131], v[214:217], v[80:83]
	s_waitcnt lgkmcnt(6)
	v_mfma_f32_16x16x32_bf16 v[80:83], v[124:127], v[188:191], v[80:83]
	s_waitcnt lgkmcnt(5)
	v_mfma_f32_16x16x32_bf16 v[76:79], v[132:135], v[188:191], v[76:79]
	s_waitcnt lgkmcnt(4)
	v_mfma_f32_16x16x32_bf16 v[76:79], v[144:147], v[214:217], v[76:79]
	v_mfma_f32_16x16x32_bf16 v[92:95], v[144:147], v[184:187], v[92:95]
	v_mfma_f32_16x16x32_bf16 v[92:95], v[132:135], v[180:183], v[92:95]
	v_mfma_f32_16x16x32_bf16 v[108:111], v[132:135], v[172:175], v[108:111]
	v_mfma_f32_16x16x32_bf16 v[108:111], v[144:147], v[176:179], v[108:111]
	v_mfma_f32_16x16x32_bf16 v[136:139], v[144:147], v[168:171], v[136:139]
	v_mfma_f32_16x16x32_bf16 v[136:139], v[132:135], v[164:167], v[136:139]
	s_waitcnt lgkmcnt(3)
	v_mfma_f32_16x16x32_bf16 v[120:123], v[148:151], v[164:167], v[120:123]
	s_waitcnt lgkmcnt(2)
	v_mfma_f32_16x16x32_bf16 v[120:123], v[152:155], v[168:171], v[120:123]
	v_mfma_f32_16x16x32_bf16 v[104:107], v[152:155], v[176:179], v[104:107]
	v_mfma_f32_16x16x32_bf16 v[104:107], v[148:151], v[172:175], v[104:107]
	v_mfma_f32_16x16x32_bf16 v[88:91], v[148:151], v[180:183], v[88:91]
	v_mfma_f32_16x16x32_bf16 v[88:91], v[152:155], v[184:187], v[88:91]
	v_mfma_f32_16x16x32_bf16 v[72:75], v[152:155], v[214:217], v[72:75]
	v_mfma_f32_16x16x32_bf16 v[72:75], v[148:151], v[188:191], v[72:75]
	s_waitcnt lgkmcnt(1)
	v_mfma_f32_16x16x32_bf16 v[68:71], v[156:159], v[188:191], v[68:71]
	s_waitcnt lgkmcnt(0)
	v_mfma_f32_16x16x32_bf16 v[68:71], v[160:163], v[214:217], v[68:71]
	v_mfma_f32_16x16x32_bf16 v[84:87], v[160:163], v[184:187], v[84:87]
	v_mfma_f32_16x16x32_bf16 v[84:87], v[156:159], v[180:183], v[84:87]
	v_mfma_f32_16x16x32_bf16 v[100:103], v[156:159], v[172:175], v[100:103]
	v_mfma_f32_16x16x32_bf16 v[100:103], v[160:163], v[176:179], v[100:103]
	v_mfma_f32_16x16x32_bf16 v[116:119], v[160:163], v[168:171], v[116:119]
	v_mfma_f32_16x16x32_bf16 v[116:119], v[156:159], v[164:167], v[116:119]
	s_barrier
	s_add_i32 s36, s56, s40
	v_lshl_add_u64 v[218:219], v[218:219], 0, s[84:85]
	s_mov_b32 m0, s36
	ds_read_b128 v[164:167], v242 offset:49152
	ds_read_b128 v[168:171], v242 offset:50176
	ds_read_b128 v[176:179], v242 offset:52224
	ds_read_b128 v[172:175], v242 offset:51200
	ds_read_b128 v[180:183], v242 offset:53248
	ds_read_b128 v[184:187], v242 offset:54272
	ds_read_b128 v[214:217], v242 offset:56320
	ds_read_b128 v[188:191], v242 offset:55296
	s_setprio 0
	global_load_lds_dwordx4 v[218:219], off
	s_add_i32 m0, s36, 0x2000
	s_add_u32 s26, s26, 0x100080
	v_lshl_add_u64 v[218:219], v[220:221], 0, s[84:85]
	s_addc_u32 s27, s27, 0
	s_add_i32 s36, s57, s40
	global_load_lds_dwordx4 v[218:219], off
	s_mov_b32 m0, s36
	s_nop 0
	global_load_lds_dwordx4 v2, s[26:27]
	s_add_i32 m0, s36, 0x2000
	s_nop 0
	global_load_lds_dwordx4 v204, s[26:27]
	s_cmp_eq_u32 s55, 60
	s_cbranch_scc0 .Ldefer_1456_body
	v_lshl_add_u64 v[218:219], v[222:223], 0, s[84:85]
	s_mov_b32 m0, s45
	s_nop 0
	global_load_lds_dwordx4 v[218:219], off
	v_lshl_add_u64 v[218:219], v[224:225], 0, s[84:85]
	s_mov_b32 m0, s46
	s_nop 0
	global_load_lds_dwordx4 v[218:219], off

; #define PG8_STAGE(bufoff, gbase, voff) do { _Pragma("unroll") for (int _i = 0; _i < 2; ++_i) \
;         __builtin_amdgcn_global_load_lds((const unsigned*)((const char*)(gbase) + (voff)[_i]), (PG8_LAS unsigned*)(lds + (bufoff) + ldsw + _i * 8192), 16, 0, 0); } while (0)
; #define PG8_LDA(dst, b, h) do { _Pragma("unroll") for (int m = 0; m < 4; ++m) _Pragma("unroll") for (int k = 0; k < 2; ++k) dst[m][k] = *(const PG8_LAS bf16x8*)(lds + PG8_SA(b, h) + aoff + m * 2048 + k * 1024); } while (0)
; template <class Epi, class Sched, bool ALIGN_EPI = false, bool SP2 = false, bool I8 = false>
; __device__ __forceinline__ void gemm_phase(PG8_LAS unsigned char* lds, const Gemm g, const Sched& S, const Epi& E) {
;     ...
;         const bool has_next = S.next(ui + 1, nxt);
;         const char* nA = has_next ? (const char*)g.A + (size_t)nxt.pm * tstep : cA; const char* nB = has_next ? (const char*)g.Bt + (size_t)nxt.pn * tstep : cB;
;         for (int t = 0; t < nt; t += 2) {
;             const bool last = (t == nt - 2);
;             const char* a1 = cA + (size_t)(t + 1) * kstep;
;             const char* a2 = last ? nA : cA + (size_t)(t + 2) * kstep; const char* b2 = last ? nB : cB + (size_t)(t + 2) * kstep;
;             const char* a3 = a2 + kstep; const char* b3 = b2 + kstep;
;             if (last && has_next) S.a_ready(nxt);
;             if constexpr (SP2) {
;             PG8_LDB(B0, 0, 0); PG8_LDB(B1, 0, 1); PG8_SCHED; PG8_LDA(At, 0, 0); PG8_STAGE(PG8_SA(1, 1), a1 + hstep, voffA);
;             PG8_WAIT_V(8); PG8_WAIT_L(0); PG8_BAR; PG8_MMA(0, 0, At, B0); PG8_MMA(0, 1, At, B1); PG8_BAR; PG8_SCHED;
;             PG8_LDA(At, 0, 1); PG8_STAGE(PG8_SB(0, 0), b2, voffB); PG8_STAGE(PG8_SB(0, 1), b2 + hstep, voffB); PG8_STAGE(PG8_SA(0, 0), a2, voffA);
;             PG8_WAIT_V(8); PG8_WAIT_L(0); PG8_BAR; PG8_MMA(1, 0, At, B0); PG8_MMA(1, 1, At, B1); PG8_BAR; PG8_SCHED;
;             PG8_LDB(B0, 1, 0); PG8_LDB(B1, 1, 1); PG8_SCHED; PG8_LDA(At, 1, 0); PG8_STAGE(PG8_SA(0, 1), a2 + hstep, voffA);
;             PG8_WAIT_V(8); PG8_WAIT_L(0); PG8_BAR; PG8_MMA(0, 0, At, B0); PG8_MMA(0, 1, At, B1); PG8_BAR; PG8_SCHED;
;             PG8_LDA(At, 1, 1); PG8_STAGE(PG8_SB(1, 0), b3, voffB); PG8_STAGE(PG8_SB(1, 1), b3 + hstep, voffB); PG8_STAGE(PG8_SA(1, 0), a3, voffA);
;             PG8_WAIT_V(8); PG8_WAIT_L(0); PG8_BAR; PG8_MMA(1, 0, At, B0); PG8_MMA(1, 1, At, B1); PG8_BAR; PG8_SCHED;
.LBB0_1590:
	s_ashr_i32 s25, s24, 31
	s_lshl_b64 s[26:27], s[24:25], 20
	s_add_u32 s26, s28, s26
	s_addc_u32 s27, s42, s27
	s_and_b64 s[36:37], s[10:11], exec
	s_cselect_b32 s25, s27, s41
	s_cselect_b32 s57, s26, s40
	s_ashr_i32 s23, s22, 31
	s_lshl_b64 s[36:37], s[22:23], 20
	s_add_u32 s36, s43, s36
	s_addc_u32 s37, s46, s37
	s_and_b64 s[48:49], s[10:11], exec
	s_cselect_b32 s23, s37, s45
	s_cselect_b32 s58, s36, s44
	s_add_u32 s40, s40, 0x80080
	s_addc_u32 s41, s41, 0
	s_add_u32 s59, s44, 0x100
	s_addc_u32 s60, s45, 0
	s_mov_b32 s61, -2
	s_add_u32 s44, s40, 0xfff80080
	s_addc_u32 s45, s41, -1
	s_add_i32 s64, 0, 0x10000
	s_cmp_eq_u32 s61, 28
	s_cselect_b32 s49, s25, s45
	s_cselect_b32 s48, s57, s44
	s_cselect_b32 s45, s23, s60
	s_cselect_b32 s44, s58, s59
	s_add_i32 s67, 0, 0x14000
	v_add_u32_e32 v144, s64, v167
	v_add_u32_e32 v158, s67, v167
	ds_read_b128 v[36:39], v144
	ds_read_b128 v[184:187], v171
	ds_read_b128 v[44:47], v144 offset:1024
	ds_read_b128 v[188:191], v171 offset:1024
	ds_read_b128 v[208:211], v171 offset:3072
	ds_read_b128 v[204:207], v171 offset:2048
	ds_read_b128 v[212:215], v171 offset:4096
	ds_read_b128 v[216:219], v171 offset:5120
	s_add_i32 m0, s50, 0xc000
	ds_read_b128 v[224:227], v171 offset:7168
	ds_read_b128 v[220:223], v171 offset:6144
	ds_read_b128 v[140:143], v144 offset:2048
	ds_read_b128 v[144:147], v144 offset:3072
	ds_read_b128 v[160:163], v158
	ds_read_b128 v[172:175], v158 offset:1024
	ds_read_b128 v[176:179], v158 offset:2048
	ds_read_b128 v[180:183], v158 offset:3072
	global_load_lds_dwordx4 v154, s[40:41]
	s_add_i32 m0, s50, 0xe000
	s_nop 0
	global_load_lds_dwordx4 v156, s[40:41]
	s_waitcnt vmcnt(8)
	s_waitcnt lgkmcnt(14)
	s_setprio 1
	s_barrier
	v_mfma_i32_16x16x64_i8 v[136:139], v[36:39], v[184:187], 0
	s_waitcnt lgkmcnt(12)
	v_mfma_i32_16x16x64_i8 v[136:139], v[44:47], v[188:191], v[136:139]
	s_waitcnt lgkmcnt(11)
	v_mfma_i32_16x16x64_i8 v[120:123], v[44:47], v[208:211], 0
	s_waitcnt lgkmcnt(10)
	v_mfma_i32_16x16x64_i8 v[120:123], v[36:39], v[204:207], v[120:123]
	s_waitcnt lgkmcnt(9)
	v_mfma_i32_16x16x64_i8 v[104:107], v[36:39], v[212:215], 0
	s_waitcnt lgkmcnt(8)
	v_mfma_i32_16x16x64_i8 v[104:107], v[44:47], v[216:219], v[104:107]
	s_waitcnt lgkmcnt(7)
	v_mfma_i32_16x16x64_i8 v[88:91], v[44:47], v[224:227], 0
	s_waitcnt lgkmcnt(6)
	v_mfma_i32_16x16x64_i8 v[88:91], v[36:39], v[220:223], v[88:91]
	s_waitcnt lgkmcnt(5)
	v_mfma_i32_16x16x64_i8 v[80:83], v[140:143], v[220:223], 0
	s_waitcnt lgkmcnt(4)
	v_mfma_i32_16x16x64_i8 v[80:83], v[144:147], v[224:227], v[80:83]
	v_mfma_i32_16x16x64_i8 v[96:99], v[144:147], v[216:219], 0
	v_mfma_i32_16x16x64_i8 v[96:99], v[140:143], v[212:215], v[96:99]
	v_mfma_i32_16x16x64_i8 v[112:115], v[140:143], v[204:207], 0
	v_mfma_i32_16x16x64_i8 v[112:115], v[144:147], v[208:211], v[112:115]
	v_mfma_i32_16x16x64_i8 v[128:131], v[144:147], v[188:191], 0
	v_mfma_i32_16x16x64_i8 v[128:131], v[140:143], v[184:187], v[128:131]
	s_waitcnt lgkmcnt(3)
	v_mfma_i32_16x16x64_i8 v[132:135], v[160:163], v[184:187], 0
	s_waitcnt lgkmcnt(2)
	v_mfma_i32_16x16x64_i8 v[132:135], v[172:175], v[188:191], v[132:135]
	v_mfma_i32_16x16x64_i8 v[116:119], v[172:175], v[208:211], 0
	v_mfma_i32_16x16x64_i8 v[116:119], v[160:163], v[204:207], v[116:119]
	v_mfma_i32_16x16x64_i8 v[100:103], v[160:163], v[212:215], 0
	v_mfma_i32_16x16x64_i8 v[100:103], v[172:175], v[216:219], v[100:103]
	v_mfma_i32_16x16x64_i8 v[84:87], v[172:175], v[224:227], 0
	v_mfma_i32_16x16x64_i8 v[84:87], v[160:163], v[220:223], v[84:87]
	s_waitcnt lgkmcnt(1)
	v_mfma_i32_16x16x64_i8 v[76:79], v[176:179], v[220:223], 0
	s_waitcnt lgkmcnt(0)
	v_mfma_i32_16x16x64_i8 v[76:79], v[180:183], v[224:227], v[76:79]
	v_mfma_i32_16x16x64_i8 v[92:95], v[180:183], v[216:219], 0
	v_mfma_i32_16x16x64_i8 v[92:95], v[176:179], v[212:215], v[92:95]
	v_mfma_i32_16x16x64_i8 v[108:111], v[176:179], v[204:207], 0
	v_mfma_i32_16x16x64_i8 v[108:111], v[180:183], v[208:211], v[108:111]
	v_mfma_i32_16x16x64_i8 v[124:127], v[180:183], v[188:191], 0
	v_mfma_i32_16x16x64_i8 v[124:127], v[176:179], v[184:187], v[124:127]
	s_barrier
	s_add_i32 s64, s64, s47
	v_lshl_add_u64 v[164:165], s[44:45], 0, v[2:3]
	s_mov_b32 m0, s64
	ds_read_b128 v[184:187], v171 offset:16384
	ds_read_b128 v[188:191], v171 offset:17408
	ds_read_b128 v[208:211], v171 offset:19456
	ds_read_b128 v[204:207], v171 offset:18432
	ds_read_b128 v[212:215], v171 offset:20480
	ds_read_b128 v[216:219], v171 offset:21504
	ds_read_b128 v[224:227], v171 offset:23552
	ds_read_b128 v[220:223], v171 offset:22528
	s_setprio 0
	global_load_lds_dwordx4 v[164:165], off
	s_add_i32 m0, s64, 0x2000
	s_add_u32 s64, s44, 0x80000
	v_lshl_add_u64 v[228:229], s[44:45], 0, v[148:149]
	s_addc_u32 s65, s45, 0
	s_add_i32 s67, s67, s47
	global_load_lds_dwordx4 v[228:229], off
	s_mov_b32 m0, s67
	v_lshl_add_u64 v[242:243], s[48:49], 0, v[150:151]
	global_load_lds_dwordx4 v2, s[64:65]
	s_add_i32 m0, s67, 0x2000
	s_nop 0
	global_load_lds_dwordx4 v148, s[64:65]
	v_lshl_add_u64 v[240:241], s[48:49], 0, v[152:153]
	s_waitcnt vmcnt(6)
	s_waitcnt lgkmcnt(7)
	s_setprio 1
	s_barrier
; #define PG8_STAGE(bufoff, gbase, voff) do { _Pragma("unroll") for (int _i = 0; _i < 2; ++_i) \
;         __builtin_amdgcn_global_load_lds((const unsigned*)((const char*)(gbase) + (voff)[_i]), (PG8_LAS unsigned*)(lds + (bufoff) + ldsw + _i * 8192), 16, 0, 0); } while (0)
; #define PG8_LDA(dst, b, h) do { _Pragma("unroll") for (int m = 0; m < 4; ++m) _Pragma("unroll") for (int k = 0; k < 2; ++k) dst[m][k] = *(const PG8_LAS bf16x8*)(lds + PG8_SA(b, h) + aoff + m * 2048 + k * 1024); } while (0)
; #define PG8_LDB(dst, b, h) do { _Pragma("unroll") for (int n = 0; n < 2; ++n) _Pragma("unroll") for (int k = 0; k < 2; ++k) dst[n][k] = *(const PG8_LAS bf16x8*)(lds + PG8_SB(b, h) + boff + n * 2048 + k * 1024); } while (0)
; #define PG8_WAIT_V(n) asm volatile("s_waitcnt vmcnt(" #n ")" ::: "memory")
; #define PG8_WAIT_L(n) asm volatile("s_waitcnt lgkmcnt(" #n ")" ::: "memory")
; #define PG8_BAR __builtin_amdgcn_s_barrier()
; #define PG8_SCHED __builtin_amdgcn_sched_barrier(0)
; template <class Epi, class Sched, bool ALIGN_EPI = false, bool SP2 = false, bool I8 = false>
; __device__ __forceinline__ void gemm_phase(PG8_LAS unsigned char* lds, const Gemm g, const Sched& S, const Epi& E) {
;     ...
;             if constexpr (SP2) {
;             PG8_LDB(B0, 0, 0); PG8_LDB(B1, 0, 1); PG8_SCHED; PG8_LDA(At, 0, 0); PG8_STAGE(PG8_SA(1, 1), a1 + hstep, voffA);
;             PG8_WAIT_V(8); PG8_WAIT_L(0); PG8_BAR; PG8_MMA(0, 0, At, B0); PG8_MMA(0, 1, At, B1); PG8_BAR; PG8_SCHED;
;             PG8_LDA(At, 0, 1); PG8_STAGE(PG8_SB(0, 0), b2, voffB); PG8_STAGE(PG8_SB(0, 1), b2 + hstep, voffB); PG8_STAGE(PG8_SA(0, 0), a2, voffA);
;             PG8_WAIT_V(8); PG8_WAIT_L(0); PG8_BAR; PG8_MMA(1, 0, At, B0); PG8_MMA(1, 1, At, B1); PG8_BAR; PG8_SCHED;
;             PG8_LDB(B0, 1, 0); PG8_LDB(B1, 1, 1); PG8_SCHED; PG8_LDA(At, 1, 0); PG8_STAGE(PG8_SA(0, 1), a2 + hstep, voffA);
;             PG8_WAIT_V(8); PG8_WAIT_L(0); PG8_BAR; PG8_MMA(0, 0, At, B0); PG8_MMA(0, 1, At, B1); PG8_BAR; PG8_SCHED;
;             PG8_LDA(At, 1, 1); PG8_STAGE(PG8_SB(1, 0), b3, voffB); PG8_STAGE(PG8_SB(1, 1), b3 + hstep, voffB); PG8_STAGE(PG8_SA(1, 0), a3, voffA);
;             PG8_WAIT_V(8); PG8_WAIT_L(0); PG8_BAR; PG8_MMA(1, 0, At, B0); PG8_MMA(1, 1, At, B1); PG8_BAR; PG8_SCHED;
	v_mfma_i32_16x16x64_i8 v[72:75], v[36:39], v[184:187], 0
	s_waitcnt lgkmcnt(6)
	v_mfma_i32_16x16x64_i8 v[72:75], v[44:47], v[188:191], v[72:75]
	s_waitcnt lgkmcnt(5)
	v_mfma_i32_16x16x64_i8 v[56:59], v[44:47], v[208:211], 0
	s_waitcnt lgkmcnt(4)
	v_mfma_i32_16x16x64_i8 v[56:59], v[36:39], v[204:207], v[56:59]
	s_waitcnt lgkmcnt(3)
	v_mfma_i32_16x16x64_i8 v[32:35], v[36:39], v[212:215], 0
	s_waitcnt lgkmcnt(2)
	v_mfma_i32_16x16x64_i8 v[32:35], v[44:47], v[216:219], v[32:35]
	s_waitcnt lgkmcnt(1)
	v_mfma_i32_16x16x64_i8 v[16:19], v[44:47], v[224:227], 0
	s_waitcnt lgkmcnt(0)
	v_mfma_i32_16x16x64_i8 v[16:19], v[36:39], v[220:223], v[16:19]
	v_mfma_i32_16x16x64_i8 v[8:11], v[140:143], v[220:223], 0
	v_mfma_i32_16x16x64_i8 v[8:11], v[144:147], v[224:227], v[8:11]
	v_mfma_i32_16x16x64_i8 v[24:27], v[144:147], v[216:219], 0
	v_mfma_i32_16x16x64_i8 v[24:27], v[140:143], v[212:215], v[24:27]
	v_mfma_i32_16x16x64_i8 v[48:51], v[140:143], v[204:207], 0
	v_mfma_i32_16x16x64_i8 v[48:51], v[144:147], v[208:211], v[48:51]
	v_mfma_i32_16x16x64_i8 v[64:67], v[144:147], v[188:191], 0
	v_mfma_i32_16x16x64_i8 v[64:67], v[140:143], v[184:187], v[64:67]
	v_mfma_i32_16x16x64_i8 v[36:39], v[160:163], v[184:187], 0
	v_mfma_i32_16x16x64_i8 v[36:39], v[172:175], v[188:191], v[36:39]
	v_mfma_i32_16x16x64_i8 v[52:55], v[172:175], v[208:211], 0
	v_mfma_i32_16x16x64_i8 v[52:55], v[160:163], v[204:207], v[52:55]
	v_mfma_i32_16x16x64_i8 v[28:31], v[160:163], v[212:215], 0
	v_mfma_i32_16x16x64_i8 v[28:31], v[172:175], v[216:219], v[28:31]
	v_mfma_i32_16x16x64_i8 v[12:15], v[172:175], v[224:227], 0
	v_mfma_i32_16x16x64_i8 v[12:15], v[160:163], v[220:223], v[12:15]
	v_mfma_i32_16x16x64_i8 v[4:7], v[176:179], v[220:223], 0
	v_mfma_i32_16x16x64_i8 v[4:7], v[180:183], v[224:227], v[4:7]
	v_mfma_i32_16x16x64_i8 v[20:23], v[180:183], v[216:219], 0
	v_mfma_i32_16x16x64_i8 v[20:23], v[176:179], v[212:215], v[20:23]
	v_mfma_i32_16x16x64_i8 v[40:43], v[176:179], v[204:207], 0
	v_mfma_i32_16x16x64_i8 v[40:43], v[180:183], v[208:211], v[40:43]
	v_mfma_i32_16x16x64_i8 v[44:47], v[180:183], v[188:191], 0
	v_mfma_i32_16x16x64_i8 v[44:47], v[176:179], v[184:187], v[44:47]
	s_barrier
	s_mov_b32 m0, s50
	s_nop 0
	global_load_lds_dwordx4 v[240:241], off
	s_mov_b32 m0, s51
	s_nop 0
	global_load_lds_dwordx4 v[242:243], off
	s_add_i32 s64, 0, 0x18000
	s_add_i32 s65, 0, 0x1c000
	v_add_u32_e32 v144, s64, v167
	v_add_u32_e32 v158, s65, v167
	ds_read_b128 v[60:63], v144
	ds_read_b128 v[184:187], v171 offset:32768
	ds_read_b128 v[68:71], v144 offset:1024
	ds_read_b128 v[188:191], v171 offset:33792
	ds_read_b128 v[208:211], v171 offset:35840
	ds_read_b128 v[204:207], v171 offset:34816
	ds_read_b128 v[212:215], v171 offset:36864
	ds_read_b128 v[216:219], v171 offset:37888
	s_add_u32 s48, s48, 0x80000
	s_addc_u32 s49, s49, 0
	s_mov_b32 m0, s52
	ds_read_b128 v[224:227], v171 offset:39936
	ds_read_b128 v[220:223], v171 offset:38912
	ds_read_b128 v[140:143], v144 offset:2048
	ds_read_b128 v[144:147], v144 offset:3072
	ds_read_b128 v[160:163], v158
	ds_read_b128 v[172:175], v158 offset:1024
	ds_read_b128 v[176:179], v158 offset:2048
	ds_read_b128 v[180:183], v158 offset:3072
	s_setprio 0
	global_load_lds_dwordx4 v152, s[48:49]
	s_mov_b32 m0, s53
	s_nop 0
	global_load_lds_dwordx4 v150, s[48:49]
	s_waitcnt vmcnt(8)
	s_waitcnt lgkmcnt(14)
	s_setprio 1
	s_barrier
	v_mfma_i32_16x16x64_i8 v[136:139], v[60:63], v[184:187], v[136:139]
	s_waitcnt lgkmcnt(12)
	v_mfma_i32_16x16x64_i8 v[136:139], v[68:71], v[188:191], v[136:139]
	s_waitcnt lgkmcnt(11)
	v_mfma_i32_16x16x64_i8 v[120:123], v[68:71], v[208:211], v[120:123]
	s_waitcnt lgkmcnt(10)
	v_mfma_i32_16x16x64_i8 v[120:123], v[60:63], v[204:207], v[120:123]
	s_waitcnt lgkmcnt(9)
	v_mfma_i32_16x16x64_i8 v[104:107], v[60:63], v[212:215], v[104:107]
	s_waitcnt lgkmcnt(8)
	v_mfma_i32_16x16x64_i8 v[104:107], v[68:71], v[216:219], v[104:107]
	s_waitcnt lgkmcnt(7)
	v_mfma_i32_16x16x64_i8 v[88:91], v[68:71], v[224:227], v[88:91]
	s_waitcnt lgkmcnt(6)
	v_mfma_i32_16x16x64_i8 v[88:91], v[60:63], v[220:223], v[88:91]
	s_waitcnt lgkmcnt(5)
	v_mfma_i32_16x16x64_i8 v[80:83], v[140:143], v[220:223], v[80:83]
	s_waitcnt lgkmcnt(4)
	v_mfma_i32_16x16x64_i8 v[80:83], v[144:147], v[224:227], v[80:83]
	v_mfma_i32_16x16x64_i8 v[96:99], v[144:147], v[216:219], v[96:99]
	v_mfma_i32_16x16x64_i8 v[96:99], v[140:143], v[212:215], v[96:99]
	v_mfma_i32_16x16x64_i8 v[112:115], v[140:143], v[204:207], v[112:115]
	v_mfma_i32_16x16x64_i8 v[112:115], v[144:147], v[208:211], v[112:115]
	v_mfma_i32_16x16x64_i8 v[128:131], v[144:147], v[188:191], v[128:131]
	v_mfma_i32_16x16x64_i8 v[128:131], v[140:143], v[184:187], v[128:131]
	s_waitcnt lgkmcnt(3)
	v_mfma_i32_16x16x64_i8 v[132:135], v[160:163], v[184:187], v[132:135]
	s_waitcnt lgkmcnt(2)
	v_mfma_i32_16x16x64_i8 v[132:135], v[172:175], v[188:191], v[132:135]
	v_mfma_i32_16x16x64_i8 v[116:119], v[172:175], v[208:211], v[116:119]
	v_mfma_i32_16x16x64_i8 v[116:119], v[160:163], v[204:207], v[116:119]
	v_mfma_i32_16x16x64_i8 v[100:103], v[160:163], v[212:215], v[100:103]
	v_mfma_i32_16x16x64_i8 v[100:103], v[172:175], v[216:219], v[100:103]
	v_mfma_i32_16x16x64_i8 v[84:87], v[172:175], v[224:227], v[84:87]
	v_mfma_i32_16x16x64_i8 v[84:87], v[160:163], v[220:223], v[84:87]
	s_waitcnt lgkmcnt(1)
	v_mfma_i32_16x16x64_i8 v[76:79], v[176:179], v[220:223], v[76:79]
	s_waitcnt lgkmcnt(0)
	v_mfma_i32_16x16x64_i8 v[76:79], v[180:183], v[224:227], v[76:79]
	v_mfma_i32_16x16x64_i8 v[92:95], v[180:183], v[216:219], v[92:95]
	v_mfma_i32_16x16x64_i8 v[92:95], v[176:179], v[212:215], v[92:95]
	v_mfma_i32_16x16x64_i8 v[108:111], v[176:179], v[204:207], v[108:111]
	v_mfma_i32_16x16x64_i8 v[108:111], v[180:183], v[208:211], v[108:111]
	v_mfma_i32_16x16x64_i8 v[124:127], v[180:183], v[188:191], v[124:127]
	v_mfma_i32_16x16x64_i8 v[124:127], v[176:179], v[184:187], v[124:127]
	s_barrier
	s_add_i32 s48, s64, s47
	v_lshl_add_u64 v[164:165], v[164:165], 0, s[84:85]
	s_mov_b32 m0, s48
	ds_read_b128 v[184:187], v171 offset:49152
	ds_read_b128 v[188:191], v171 offset:50176
	ds_read_b128 v[208:211], v171 offset:52224
	ds_read_b128 v[204:207], v171 offset:51200
	ds_read_b128 v[212:215], v171 offset:53248
	ds_read_b128 v[216:219], v171 offset:54272
	ds_read_b128 v[224:227], v171 offset:56320
	ds_read_b128 v[220:223], v171 offset:55296
	s_setprio 0
	global_load_lds_dwordx4 v[164:165], off
	s_add_i32 m0, s48, 0x2000
	s_add_u32 s44, s44, 0x80080
	v_lshl_add_u64 v[164:165], v[228:229], 0, s[84:85]
	s_addc_u32 s45, s45, 0
	s_add_i32 s48, s65, s47
	global_load_lds_dwordx4 v[164:165], off
	s_mov_b32 m0, s48
	s_nop 0
	global_load_lds_dwordx4 v2, s[44:45]
	s_add_i32 m0, s48, 0x2000
	s_nop 0
	global_load_lds_dwordx4 v148, s[44:45]
	s_cmp_eq_u32 s61, 28
	s_cbranch_scc0 .Ldefer_1591_peel
	v_lshl_add_u64 v[164:165], v[240:241], 0, s[84:85]
	s_mov_b32 m0, s54
	s_nop 0
	global_load_lds_dwordx4 v[164:165], off
	v_lshl_add_u64 v[164:165], v[242:243], 0, s[84:85]
	s_mov_b32 m0, s55
	s_nop 0
	global_load_lds_dwordx4 v[164:165], off

; #define PG8_STAGE(bufoff, gbase, voff) do { _Pragma("unroll") for (int _i = 0; _i < 2; ++_i) \
;         __builtin_amdgcn_global_load_lds((const unsigned*)((const char*)(gbase) + (voff)[_i]), (PG8_LAS unsigned*)(lds + (bufoff) + ldsw + _i * 8192), 16, 0, 0); } while (0)
; #define PG8_LDA(dst, b, h) do { _Pragma("unroll") for (int m = 0; m < 4; ++m) _Pragma("unroll") for (int k = 0; k < 2; ++k) dst[m][k] = *(const PG8_LAS bf16x8*)(lds + PG8_SA(b, h) + aoff + m * 2048 + k * 1024); } while (0)
; #define PG8_LDB(dst, b, h) do { _Pragma("unroll") for (int n = 0; n < 2; ++n) _Pragma("unroll") for (int k = 0; k < 2; ++k) dst[n][k] = *(const PG8_LAS bf16x8*)(lds + PG8_SB(b, h) + boff + n * 2048 + k * 1024); } while (0)
; #define PG8_WAIT_V(n) asm volatile("s_waitcnt vmcnt(" #n ")" ::: "memory")
; #define PG8_WAIT_L(n) asm volatile("s_waitcnt lgkmcnt(" #n ")" ::: "memory")
; #define PG8_BAR __builtin_amdgcn_s_barrier()
; #define PG8_SCHED __builtin_amdgcn_sched_barrier(0)
; template <class Epi, class Sched, bool ALIGN_EPI = false, bool SP2 = false, bool I8 = false>
; __device__ __forceinline__ void gemm_phase(PG8_LAS unsigned char* lds, const Gemm g, const Sched& S, const Epi& E) {
;     ...
;             if constexpr (SP2) {
;             PG8_LDB(B0, 0, 0); PG8_LDB(B1, 0, 1); PG8_SCHED; PG8_LDA(At, 0, 0); PG8_STAGE(PG8_SA(1, 1), a1 + hstep, voffA);
;             PG8_WAIT_V(8); PG8_WAIT_L(0); PG8_BAR; PG8_MMA(0, 0, At, B0); PG8_MMA(0, 1, At, B1); PG8_BAR; PG8_SCHED;
;             PG8_LDA(At, 0, 1); PG8_STAGE(PG8_SB(0, 0), b2, voffB); PG8_STAGE(PG8_SB(0, 1), b2 + hstep, voffB); PG8_STAGE(PG8_SA(0, 0), a2, voffA);
;             PG8_WAIT_V(8); PG8_WAIT_L(0); PG8_BAR; PG8_MMA(1, 0, At, B0); PG8_MMA(1, 1, At, B1); PG8_BAR; PG8_SCHED;
;             PG8_LDB(B0, 1, 0); PG8_LDB(B1, 1, 1); PG8_SCHED; PG8_LDA(At, 1, 0); PG8_STAGE(PG8_SA(0, 1), a2 + hstep, voffA);
;             PG8_WAIT_V(8); PG8_WAIT_L(0); PG8_BAR; PG8_MMA(0, 0, At, B0); PG8_MMA(0, 1, At, B1); PG8_BAR; PG8_SCHED;
;             PG8_LDA(At, 1, 1); PG8_STAGE(PG8_SB(1, 0), b3, voffB); PG8_STAGE(PG8_SB(1, 1), b3 + hstep, voffB); PG8_STAGE(PG8_SA(1, 0), a3, voffA);
;             PG8_WAIT_V(8); PG8_WAIT_L(0); PG8_BAR; PG8_MMA(1, 0, At, B0); PG8_MMA(1, 1, At, B1); PG8_BAR; PG8_SCHED;
.LBB0_1591:
	s_add_u32 s44, s40, 0xfff80080
	s_addc_u32 s45, s41, -1
	s_add_i32 s64, 0, 0x10000
	s_cmp_eq_u32 s61, 28
	s_cselect_b32 s49, s25, s45
	s_cselect_b32 s48, s57, s44
	s_cselect_b32 s45, s23, s60
	s_cselect_b32 s44, s58, s59
	s_add_i32 s67, 0, 0x14000
	v_add_u32_e32 v144, s64, v167
	v_add_u32_e32 v158, s67, v167
	ds_read_b128 v[36:39], v144
	ds_read_b128 v[184:187], v171
	ds_read_b128 v[44:47], v144 offset:1024
	ds_read_b128 v[188:191], v171 offset:1024
	ds_read_b128 v[208:211], v171 offset:3072
	ds_read_b128 v[204:207], v171 offset:2048
	ds_read_b128 v[212:215], v171 offset:4096
	ds_read_b128 v[216:219], v171 offset:5120
	v_lshl_add_u64 v[164:165], v[240:241], 0, s[84:85]
	s_mov_b32 m0, s54
	s_nop 0
	global_load_lds_dwordx4 v[164:165], off
	v_lshl_add_u64 v[164:165], v[242:243], 0, s[84:85]
	s_mov_b32 m0, s55
	s_nop 0
	global_load_lds_dwordx4 v[164:165], off
	s_add_i32 m0, s50, 0xc000
	ds_read_b128 v[224:227], v171 offset:7168
	ds_read_b128 v[220:223], v171 offset:6144
	ds_read_b128 v[140:143], v144 offset:2048
	ds_read_b128 v[144:147], v144 offset:3072
	ds_read_b128 v[160:163], v158
	ds_read_b128 v[172:175], v158 offset:1024
	ds_read_b128 v[176:179], v158 offset:2048
	ds_read_b128 v[180:183], v158 offset:3072
	global_load_lds_dwordx4 v154, s[40:41]
	s_add_i32 m0, s50, 0xe000
	s_nop 0
	global_load_lds_dwordx4 v156, s[40:41]
	s_waitcnt vmcnt(8)
	s_waitcnt lgkmcnt(14)
	s_setprio 1
	s_barrier
	v_mfma_i32_16x16x64_i8 v[136:139], v[36:39], v[184:187], v[136:139]
	s_waitcnt lgkmcnt(12)
	v_mfma_i32_16x16x64_i8 v[136:139], v[44:47], v[188:191], v[136:139]
	s_waitcnt lgkmcnt(11)
	v_mfma_i32_16x16x64_i8 v[120:123], v[44:47], v[208:211], v[120:123]
	s_waitcnt lgkmcnt(10)
	v_mfma_i32_16x16x64_i8 v[120:123], v[36:39], v[204:207], v[120:123]
	s_waitcnt lgkmcnt(9)
	v_mfma_i32_16x16x64_i8 v[104:107], v[36:39], v[212:215], v[104:107]
	s_waitcnt lgkmcnt(8)
	v_mfma_i32_16x16x64_i8 v[104:107], v[44:47], v[216:219], v[104:107]
	s_waitcnt lgkmcnt(7)
	v_mfma_i32_16x16x64_i8 v[88:91], v[44:47], v[224:227], v[88:91]
	s_waitcnt lgkmcnt(6)
	v_mfma_i32_16x16x64_i8 v[88:91], v[36:39], v[220:223], v[88:91]
	s_waitcnt lgkmcnt(5)
	v_mfma_i32_16x16x64_i8 v[80:83], v[140:143], v[220:223], v[80:83]
	s_waitcnt lgkmcnt(4)
	v_mfma_i32_16x16x64_i8 v[80:83], v[144:147], v[224:227], v[80:83]
	v_mfma_i32_16x16x64_i8 v[96:99], v[144:147], v[216:219], v[96:99]
	v_mfma_i32_16x16x64_i8 v[96:99], v[140:143], v[212:215], v[96:99]
	v_mfma_i32_16x16x64_i8 v[112:115], v[140:143], v[204:207], v[112:115]
	v_mfma_i32_16x16x64_i8 v[112:115], v[144:147], v[208:211], v[112:115]
	v_mfma_i32_16x16x64_i8 v[128:131], v[144:147], v[188:191], v[128:131]
	v_mfma_i32_16x16x64_i8 v[128:131], v[140:143], v[184:187], v[128:131]
	s_waitcnt lgkmcnt(3)
	v_mfma_i32_16x16x64_i8 v[132:135], v[160:163], v[184:187], v[132:135]
	s_waitcnt lgkmcnt(2)
	v_mfma_i32_16x16x64_i8 v[132:135], v[172:175], v[188:191], v[132:135]
	v_mfma_i32_16x16x64_i8 v[116:119], v[172:175], v[208:211], v[116:119]
	v_mfma_i32_16x16x64_i8 v[116:119], v[160:163], v[204:207], v[116:119]
	v_mfma_i32_16x16x64_i8 v[100:103], v[160:163], v[212:215], v[100:103]
	v_mfma_i32_16x16x64_i8 v[100:103], v[172:175], v[216:219], v[100:103]
	v_mfma_i32_16x16x64_i8 v[84:87], v[172:175], v[224:227], v[84:87]
	v_mfma_i32_16x16x64_i8 v[84:87], v[160:163], v[220:223], v[84:87]
	s_waitcnt lgkmcnt(1)
	v_mfma_i32_16x16x64_i8 v[76:79], v[176:179], v[220:223], v[76:79]
	s_waitcnt lgkmcnt(0)
	v_mfma_i32_16x16x64_i8 v[76:79], v[180:183], v[224:227], v[76:79]
	v_mfma_i32_16x16x64_i8 v[92:95], v[180:183], v[216:219], v[92:95]
	v_mfma_i32_16x16x64_i8 v[92:95], v[176:179], v[212:215], v[92:95]
	v_mfma_i32_16x16x64_i8 v[108:111], v[176:179], v[204:207], v[108:111]
	v_mfma_i32_16x16x64_i8 v[108:111], v[180:183], v[208:211], v[108:111]
	v_mfma_i32_16x16x64_i8 v[124:127], v[180:183], v[188:191], v[124:127]
	v_mfma_i32_16x16x64_i8 v[124:127], v[176:179], v[184:187], v[124:127]
	s_barrier
	s_add_i32 s64, s64, s47
	v_lshl_add_u64 v[164:165], s[44:45], 0, v[2:3]
	s_mov_b32 m0, s64
	ds_read_b128 v[184:187], v171 offset:16384
	ds_read_b128 v[188:191], v171 offset:17408
	ds_read_b128 v[208:211], v171 offset:19456
	ds_read_b128 v[204:207], v171 offset:18432
	ds_read_b128 v[212:215], v171 offset:20480
	ds_read_b128 v[216:219], v171 offset:21504
	ds_read_b128 v[224:227], v171 offset:23552
	ds_read_b128 v[220:223], v171 offset:22528
	s_setprio 0
	global_load_lds_dwordx4 v[164:165], off
	s_add_i32 m0, s64, 0x2000
	s_add_u32 s64, s44, 0x80000
	v_lshl_add_u64 v[228:229], s[44:45], 0, v[148:149]
	s_addc_u32 s65, s45, 0
	s_add_i32 s67, s67, s47
	global_load_lds_dwordx4 v[228:229], off
	s_mov_b32 m0, s67
	v_lshl_add_u64 v[242:243], s[48:49], 0, v[150:151]
	global_load_lds_dwordx4 v2, s[64:65]
	s_add_i32 m0, s67, 0x2000
	s_nop 0
	global_load_lds_dwordx4 v148, s[64:65]
	v_lshl_add_u64 v[240:241], s[48:49], 0, v[152:153]
	s_waitcnt vmcnt(6)
	s_waitcnt lgkmcnt(7)
	s_setprio 1
	s_barrier
; #define PG8_STAGE(bufoff, gbase, voff) do { _Pragma("unroll") for (int _i = 0; _i < 2; ++_i) \
;         __builtin_amdgcn_global_load_lds((const unsigned*)((const char*)(gbase) + (voff)[_i]), (PG8_LAS unsigned*)(lds + (bufoff) + ldsw + _i * 8192), 16, 0, 0); } while (0)
; #define PG8_LDA(dst, b, h) do { _Pragma("unroll") for (int m = 0; m < 4; ++m) _Pragma("unroll") for (int k = 0; k < 2; ++k) dst[m][k] = *(const PG8_LAS bf16x8*)(lds + PG8_SA(b, h) + aoff + m * 2048 + k * 1024); } while (0)
; #define PG8_LDB(dst, b, h) do { _Pragma("unroll") for (int n = 0; n < 2; ++n) _Pragma("unroll") for (int k = 0; k < 2; ++k) dst[n][k] = *(const PG8_LAS bf16x8*)(lds + PG8_SB(b, h) + boff + n * 2048 + k * 1024); } while (0)
; #define PG8_WAIT_V(n) asm volatile("s_waitcnt vmcnt(" #n ")" ::: "memory")
; #define PG8_WAIT_L(n) asm volatile("s_waitcnt lgkmcnt(" #n ")" ::: "memory")
; #define PG8_BAR __builtin_amdgcn_s_barrier()
; #define PG8_SCHED __builtin_amdgcn_sched_barrier(0)
; template <class Epi, class Sched, bool ALIGN_EPI = false, bool SP2 = false, bool I8 = false>
; __device__ __forceinline__ void gemm_phase(PG8_LAS unsigned char* lds, const Gemm g, const Sched& S, const Epi& E) {
;     ...
;             if constexpr (SP2) {
;             PG8_LDB(B0, 0, 0); PG8_LDB(B1, 0, 1); PG8_SCHED; PG8_LDA(At, 0, 0); PG8_STAGE(PG8_SA(1, 1), a1 + hstep, voffA);
;             PG8_WAIT_V(8); PG8_WAIT_L(0); PG8_BAR; PG8_MMA(0, 0, At, B0); PG8_MMA(0, 1, At, B1); PG8_BAR; PG8_SCHED;
;             PG8_LDA(At, 0, 1); PG8_STAGE(PG8_SB(0, 0), b2, voffB); PG8_STAGE(PG8_SB(0, 1), b2 + hstep, voffB); PG8_STAGE(PG8_SA(0, 0), a2, voffA);
;             PG8_WAIT_V(8); PG8_WAIT_L(0); PG8_BAR; PG8_MMA(1, 0, At, B0); PG8_MMA(1, 1, At, B1); PG8_BAR; PG8_SCHED;
;             PG8_LDB(B0, 1, 0); PG8_LDB(B1, 1, 1); PG8_SCHED; PG8_LDA(At, 1, 0); PG8_STAGE(PG8_SA(0, 1), a2 + hstep, voffA);
;             PG8_WAIT_V(8); PG8_WAIT_L(0); PG8_BAR; PG8_MMA(0, 0, At, B0); PG8_MMA(0, 1, At, B1); PG8_BAR; PG8_SCHED;
;             PG8_LDA(At, 1, 1); PG8_STAGE(PG8_SB(1, 0), b3, voffB); PG8_STAGE(PG8_SB(1, 1), b3 + hstep, voffB); PG8_STAGE(PG8_SA(1, 0), a3, voffA);
;             PG8_WAIT_V(8); PG8_WAIT_L(0); PG8_BAR; PG8_MMA(1, 0, At, B0); PG8_MMA(1, 1, At, B1); PG8_BAR; PG8_SCHED;
	v_mfma_i32_16x16x64_i8 v[72:75], v[36:39], v[184:187], v[72:75]
	s_waitcnt lgkmcnt(6)
	v_mfma_i32_16x16x64_i8 v[72:75], v[44:47], v[188:191], v[72:75]
	s_waitcnt lgkmcnt(5)
	v_mfma_i32_16x16x64_i8 v[56:59], v[44:47], v[208:211], v[56:59]
	s_waitcnt lgkmcnt(4)
	v_mfma_i32_16x16x64_i8 v[56:59], v[36:39], v[204:207], v[56:59]
	s_waitcnt lgkmcnt(3)
	v_mfma_i32_16x16x64_i8 v[32:35], v[36:39], v[212:215], v[32:35]
	s_waitcnt lgkmcnt(2)
	v_mfma_i32_16x16x64_i8 v[32:35], v[44:47], v[216:219], v[32:35]
	s_waitcnt lgkmcnt(1)
	v_mfma_i32_16x16x64_i8 v[16:19], v[44:47], v[224:227], v[16:19]
	s_waitcnt lgkmcnt(0)
	v_mfma_i32_16x16x64_i8 v[16:19], v[36:39], v[220:223], v[16:19]
	v_mfma_i32_16x16x64_i8 v[8:11], v[140:143], v[220:223], v[8:11]
	v_mfma_i32_16x16x64_i8 v[8:11], v[144:147], v[224:227], v[8:11]
	v_mfma_i32_16x16x64_i8 v[24:27], v[144:147], v[216:219], v[24:27]
	v_mfma_i32_16x16x64_i8 v[24:27], v[140:143], v[212:215], v[24:27]
	v_mfma_i32_16x16x64_i8 v[48:51], v[140:143], v[204:207], v[48:51]
	v_mfma_i32_16x16x64_i8 v[48:51], v[144:147], v[208:211], v[48:51]
	v_mfma_i32_16x16x64_i8 v[64:67], v[144:147], v[188:191], v[64:67]
	v_mfma_i32_16x16x64_i8 v[64:67], v[140:143], v[184:187], v[64:67]
	v_mfma_i32_16x16x64_i8 v[36:39], v[160:163], v[184:187], v[68:71]
	v_mfma_i32_16x16x64_i8 v[36:39], v[172:175], v[188:191], v[36:39]
	v_mfma_i32_16x16x64_i8 v[52:55], v[172:175], v[208:211], v[52:55]
	v_mfma_i32_16x16x64_i8 v[52:55], v[160:163], v[204:207], v[52:55]
	v_mfma_i32_16x16x64_i8 v[28:31], v[160:163], v[212:215], v[28:31]
	v_mfma_i32_16x16x64_i8 v[28:31], v[172:175], v[216:219], v[28:31]
	v_mfma_i32_16x16x64_i8 v[12:15], v[172:175], v[224:227], v[12:15]
	v_mfma_i32_16x16x64_i8 v[12:15], v[160:163], v[220:223], v[12:15]
	v_mfma_i32_16x16x64_i8 v[4:7], v[176:179], v[220:223], v[4:7]
	v_mfma_i32_16x16x64_i8 v[4:7], v[180:183], v[224:227], v[4:7]
	v_mfma_i32_16x16x64_i8 v[20:23], v[180:183], v[216:219], v[20:23]
	v_mfma_i32_16x16x64_i8 v[20:23], v[176:179], v[212:215], v[20:23]
	v_mfma_i32_16x16x64_i8 v[40:43], v[176:179], v[204:207], v[40:43]
	v_mfma_i32_16x16x64_i8 v[40:43], v[180:183], v[208:211], v[40:43]
	v_mfma_i32_16x16x64_i8 v[44:47], v[180:183], v[188:191], v[60:63]
	v_mfma_i32_16x16x64_i8 v[44:47], v[176:179], v[184:187], v[44:47]
	s_barrier
	s_mov_b32 m0, s50
	s_nop 0
	global_load_lds_dwordx4 v[240:241], off
	s_mov_b32 m0, s51
	s_nop 0
	global_load_lds_dwordx4 v[242:243], off
	s_add_i32 s64, 0, 0x18000
	s_add_i32 s65, 0, 0x1c000
	v_add_u32_e32 v144, s64, v167
	v_add_u32_e32 v158, s65, v167
	ds_read_b128 v[60:63], v144
	ds_read_b128 v[184:187], v171 offset:32768
	ds_read_b128 v[68:71], v144 offset:1024
	ds_read_b128 v[188:191], v171 offset:33792
	ds_read_b128 v[208:211], v171 offset:35840
	ds_read_b128 v[204:207], v171 offset:34816
	ds_read_b128 v[212:215], v171 offset:36864
	ds_read_b128 v[216:219], v171 offset:37888
	s_add_u32 s48, s48, 0x80000
	s_addc_u32 s49, s49, 0
	s_mov_b32 m0, s52
	ds_read_b128 v[224:227], v171 offset:39936
	ds_read_b128 v[220:223], v171 offset:38912
	ds_read_b128 v[140:143], v144 offset:2048
	ds_read_b128 v[144:147], v144 offset:3072
	ds_read_b128 v[160:163], v158
	ds_read_b128 v[172:175], v158 offset:1024
	ds_read_b128 v[176:179], v158 offset:2048
	ds_read_b128 v[180:183], v158 offset:3072
	s_setprio 0
	global_load_lds_dwordx4 v152, s[48:49]
	s_mov_b32 m0, s53
	s_nop 0
	global_load_lds_dwordx4 v150, s[48:49]
	s_waitcnt vmcnt(8)
	s_waitcnt lgkmcnt(14)
	s_setprio 1
	s_barrier
; #define PG8_STAGE(bufoff, gbase, voff) do { _Pragma("unroll") for (int _i = 0; _i < 2; ++_i) \
;         __builtin_amdgcn_global_load_lds((const unsigned*)((const char*)(gbase) + (voff)[_i]), (PG8_LAS unsigned*)(lds + (bufoff) + ldsw + _i * 8192), 16, 0, 0); } while (0)
; #define PG8_LDA(dst, b, h) do { _Pragma("unroll") for (int m = 0; m < 4; ++m) _Pragma("unroll") for (int k = 0; k < 2; ++k) dst[m][k] = *(const PG8_LAS bf16x8*)(lds + PG8_SA(b, h) + aoff + m * 2048 + k * 1024); } while (0)
; #define PG8_LDB(dst, b, h) do { _Pragma("unroll") for (int n = 0; n < 2; ++n) _Pragma("unroll") for (int k = 0; k < 2; ++k) dst[n][k] = *(const PG8_LAS bf16x8*)(lds + PG8_SB(b, h) + boff + n * 2048 + k * 1024); } while (0)
; #define PG8_WAIT_V(n) asm volatile("s_waitcnt vmcnt(" #n ")" ::: "memory")
; #define PG8_WAIT_L(n) asm volatile("s_waitcnt lgkmcnt(" #n ")" ::: "memory")
; #define PG8_BAR __builtin_amdgcn_s_barrier()
; #define PG8_SCHED __builtin_amdgcn_sched_barrier(0)
; template <class Epi, class Sched, bool ALIGN_EPI = false, bool SP2 = false, bool I8 = false>
; __device__ __forceinline__ void gemm_phase(PG8_LAS unsigned char* lds, const Gemm g, const Sched& S, const Epi& E) {
;     ...
;             if constexpr (SP2) {
;             PG8_LDB(B0, 0, 0); PG8_LDB(B1, 0, 1); PG8_SCHED; PG8_LDA(At, 0, 0); PG8_STAGE(PG8_SA(1, 1), a1 + hstep, voffA);
;             PG8_WAIT_V(8); PG8_WAIT_L(0); PG8_BAR; PG8_MMA(0, 0, At, B0); PG8_MMA(0, 1, At, B1); PG8_BAR; PG8_SCHED;
;             PG8_LDA(At, 0, 1); PG8_STAGE(PG8_SB(0, 0), b2, voffB); PG8_STAGE(PG8_SB(0, 1), b2 + hstep, voffB); PG8_STAGE(PG8_SA(0, 0), a2, voffA);
;             PG8_WAIT_V(8); PG8_WAIT_L(0); PG8_BAR; PG8_MMA(1, 0, At, B0); PG8_MMA(1, 1, At, B1); PG8_BAR; PG8_SCHED;
;             PG8_LDB(B0, 1, 0); PG8_LDB(B1, 1, 1); PG8_SCHED; PG8_LDA(At, 1, 0); PG8_STAGE(PG8_SA(0, 1), a2 + hstep, voffA);
;             PG8_WAIT_V(8); PG8_WAIT_L(0); PG8_BAR; PG8_MMA(0, 0, At, B0); PG8_MMA(0, 1, At, B1); PG8_BAR; PG8_SCHED;
;             PG8_LDA(At, 1, 1); PG8_STAGE(PG8_SB(1, 0), b3, voffB); PG8_STAGE(PG8_SB(1, 1), b3 + hstep, voffB); PG8_STAGE(PG8_SA(1, 0), a3, voffA);
;             PG8_WAIT_V(8); PG8_WAIT_L(0); PG8_BAR; PG8_MMA(1, 0, At, B0); PG8_MMA(1, 1, At, B1); PG8_BAR; PG8_SCHED;
	v_mfma_i32_16x16x64_i8 v[136:139], v[60:63], v[184:187], v[136:139]
	s_waitcnt lgkmcnt(12)
	v_mfma_i32_16x16x64_i8 v[136:139], v[68:71], v[188:191], v[136:139]
	s_waitcnt lgkmcnt(11)
	v_mfma_i32_16x16x64_i8 v[120:123], v[68:71], v[208:211], v[120:123]
	s_waitcnt lgkmcnt(10)
	v_mfma_i32_16x16x64_i8 v[120:123], v[60:63], v[204:207], v[120:123]
	s_waitcnt lgkmcnt(9)
	v_mfma_i32_16x16x64_i8 v[104:107], v[60:63], v[212:215], v[104:107]
	s_waitcnt lgkmcnt(8)
	v_mfma_i32_16x16x64_i8 v[104:107], v[68:71], v[216:219], v[104:107]
	s_waitcnt lgkmcnt(7)
	v_mfma_i32_16x16x64_i8 v[88:91], v[68:71], v[224:227], v[88:91]
	s_waitcnt lgkmcnt(6)
	v_mfma_i32_16x16x64_i8 v[88:91], v[60:63], v[220:223], v[88:91]
	s_waitcnt lgkmcnt(5)
	v_mfma_i32_16x16x64_i8 v[80:83], v[140:143], v[220:223], v[80:83]
	s_waitcnt lgkmcnt(4)
	v_mfma_i32_16x16x64_i8 v[80:83], v[144:147], v[224:227], v[80:83]
	v_mfma_i32_16x16x64_i8 v[96:99], v[144:147], v[216:219], v[96:99]
	v_mfma_i32_16x16x64_i8 v[96:99], v[140:143], v[212:215], v[96:99]
	v_mfma_i32_16x16x64_i8 v[112:115], v[140:143], v[204:207], v[112:115]
	v_mfma_i32_16x16x64_i8 v[112:115], v[144:147], v[208:211], v[112:115]
	v_mfma_i32_16x16x64_i8 v[128:131], v[144:147], v[188:191], v[128:131]
	v_mfma_i32_16x16x64_i8 v[128:131], v[140:143], v[184:187], v[128:131]
	s_waitcnt lgkmcnt(3)
	v_mfma_i32_16x16x64_i8 v[132:135], v[160:163], v[184:187], v[132:135]
	s_waitcnt lgkmcnt(2)
	v_mfma_i32_16x16x64_i8 v[132:135], v[172:175], v[188:191], v[132:135]
	v_mfma_i32_16x16x64_i8 v[116:119], v[172:175], v[208:211], v[116:119]
	v_mfma_i32_16x16x64_i8 v[116:119], v[160:163], v[204:207], v[116:119]
	v_mfma_i32_16x16x64_i8 v[100:103], v[160:163], v[212:215], v[100:103]
	v_mfma_i32_16x16x64_i8 v[100:103], v[172:175], v[216:219], v[100:103]
	v_mfma_i32_16x16x64_i8 v[84:87], v[172:175], v[224:227], v[84:87]
	v_mfma_i32_16x16x64_i8 v[84:87], v[160:163], v[220:223], v[84:87]
	s_waitcnt lgkmcnt(1)
	v_mfma_i32_16x16x64_i8 v[76:79], v[176:179], v[220:223], v[76:79]
	s_waitcnt lgkmcnt(0)
	v_mfma_i32_16x16x64_i8 v[76:79], v[180:183], v[224:227], v[76:79]
	v_mfma_i32_16x16x64_i8 v[92:95], v[180:183], v[216:219], v[92:95]
	v_mfma_i32_16x16x64_i8 v[92:95], v[176:179], v[212:215], v[92:95]
	v_mfma_i32_16x16x64_i8 v[108:111], v[176:179], v[204:207], v[108:111]
	v_mfma_i32_16x16x64_i8 v[108:111], v[180:183], v[208:211], v[108:111]
	v_mfma_i32_16x16x64_i8 v[124:127], v[180:183], v[188:191], v[124:127]
	v_mfma_i32_16x16x64_i8 v[124:127], v[176:179], v[184:187], v[124:127]
	s_barrier
	s_add_i32 s48, s64, s47
	v_lshl_add_u64 v[164:165], v[164:165], 0, s[84:85]
	s_mov_b32 m0, s48
	ds_read_b128 v[184:187], v171 offset:49152
	ds_read_b128 v[188:191], v171 offset:50176
	ds_read_b128 v[208:211], v171 offset:52224
	ds_read_b128 v[204:207], v171 offset:51200
	ds_read_b128 v[212:215], v171 offset:53248
	ds_read_b128 v[216:219], v171 offset:54272
	ds_read_b128 v[224:227], v171 offset:56320
	ds_read_b128 v[220:223], v171 offset:55296
	s_setprio 0
	global_load_lds_dwordx4 v[164:165], off
	s_add_i32 m0, s48, 0x2000
	s_add_u32 s44, s44, 0x80080
	v_lshl_add_u64 v[164:165], v[228:229], 0, s[84:85]
	s_addc_u32 s45, s45, 0
	s_add_i32 s48, s65, s47
	global_load_lds_dwordx4 v[164:165], off
	s_mov_b32 m0, s48
	s_nop 0
	global_load_lds_dwordx4 v2, s[44:45]
	s_add_i32 m0, s48, 0x2000
	s_nop 0
	global_load_lds_dwordx4 v148, s[44:45]
	s_cmp_eq_u32 s61, 28
	s_cbranch_scc0 .Ldefer_1591_body
	v_lshl_add_u64 v[164:165], v[240:241], 0, s[84:85]
	s_mov_b32 m0, s54
	s_nop 0
	global_load_lds_dwordx4 v[164:165], off
	v_lshl_add_u64 v[164:165], v[242:243], 0, s[84:85]
	s_mov_b32 m0, s55
	s_nop 0
	global_load_lds_dwordx4 v[164:165], off

; #define PG8_WAIT_V(n) asm volatile("s_waitcnt vmcnt(" #n ")" ::: "memory")
; #define PG8_WAIT_L(n) asm volatile("s_waitcnt lgkmcnt(" #n ")" ::: "memory")
; #define PG8_BAR __builtin_amdgcn_s_barrier()
; template <class Epi, class Sched, bool ALIGN_EPI = false, bool SP2 = false, bool I8 = false>
; __device__ __forceinline__ void gemm_phase(PG8_LAS unsigned char* lds, const Gemm g, const Sched& S, const Epi& E) {
;     ...
;         const bool has_next = S.next(ui + 1, nxt);
;         const char* nA = has_next ? (const char*)g.A + (size_t)nxt.pm * tstep : cA; const char* nB = has_next ? (const char*)g.Bt + (size_t)nxt.pn * tstep : cB;
;         for (int t = 0; t < nt; t += 2) {
;             const bool last = (t == nt - 2);
;             const char* a1 = cA + (size_t)(t + 1) * kstep;
;             const char* a2 = last ? nA : cA + (size_t)(t + 2) * kstep; const char* b2 = last ? nB : cB + (size_t)(t + 2) * kstep;
;             const char* a3 = a2 + kstep; const char* b3 = b2 + kstep;
;             if (last && has_next) S.a_ready(nxt);
;             if constexpr (SP2) {
;             PG8_LDB(B0, 0, 0); PG8_LDB(B1, 0, 1); PG8_SCHED; PG8_LDA(At, 0, 0); PG8_STAGE(PG8_SA(1, 1), a1 + hstep, voffA);
;             PG8_WAIT_V(8); PG8_WAIT_L(0); PG8_BAR; PG8_MMA(0, 0, At, B0); PG8_MMA(0, 1, At, B1); PG8_BAR; PG8_SCHED;
;             PG8_LDA(At, 0, 1); PG8_STAGE(PG8_SB(0, 0), b2, voffB); PG8_STAGE(PG8_SB(0, 1), b2 + hstep, voffB); PG8_STAGE(PG8_SA(0, 0), a2, voffA);
;             PG8_WAIT_V(8); PG8_WAIT_L(0); PG8_BAR; PG8_MMA(1, 0, At, B0); PG8_MMA(1, 1, At, B1); PG8_BAR; PG8_SCHED;
;             PG8_LDB(B0, 1, 0); PG8_LDB(B1, 1, 1); PG8_SCHED; PG8_LDA(At, 1, 0); PG8_STAGE(PG8_SA(0, 1), a2 + hstep, voffA);
;             PG8_WAIT_V(8); PG8_WAIT_L(0); PG8_BAR; PG8_MMA(0, 0, At, B0); PG8_MMA(0, 1, At, B1); PG8_BAR; PG8_SCHED;
;             PG8_LDA(At, 1, 1); PG8_STAGE(PG8_SB(1, 0), b3, voffB); PG8_STAGE(PG8_SB(1, 1), b3 + hstep, voffB); PG8_STAGE(PG8_SA(1, 0), a3, voffA);
;             PG8_WAIT_V(8); PG8_WAIT_L(0); PG8_BAR; PG8_MMA(1, 0, At, B0); PG8_MMA(1, 1, At, B1); PG8_BAR; PG8_SCHED;
;     ...
; #pragma unroll
;         for (int a = 0; a < 2; ++a)
; #pragma unroll
;             for (int b = 0; b < 2; ++b)
; #pragma unroll
;                 for (int m = 0; m < 4; ++m)
; #pragma unroll
;                     for (int n = 0; n < 2; ++n) acc[a][b][m][n] = (acc_t){0, 0, 0, 0};
.LBB0_1621:
	v_mov_b32_e32 v127, 0
	s_andn2_b64 vcc, exec, s[26:27]
	v_mov_b32_e32 v126, v127
	v_mov_b32_e32 v125, v127
	v_mov_b32_e32 v124, v127
	v_mov_b32_e32 v131, v127
	v_mov_b32_e32 v130, v127
	v_mov_b32_e32 v129, v127
	v_mov_b32_e32 v128, v127
	v_mov_b32_e32 v115, v127
	v_mov_b32_e32 v114, v127
	v_mov_b32_e32 v113, v127
	v_mov_b32_e32 v112, v127
	v_mov_b32_e32 v111, v127
	v_mov_b32_e32 v110, v127
	v_mov_b32_e32 v109, v127
	v_mov_b32_e32 v108, v127
	v_mov_b32_e32 v99, v127
	v_mov_b32_e32 v98, v127
	v_mov_b32_e32 v97, v127
	v_mov_b32_e32 v96, v127
	v_mov_b32_e32 v95, v127
	v_mov_b32_e32 v94, v127
	v_mov_b32_e32 v93, v127
	v_mov_b32_e32 v92, v127
	v_mov_b32_e32 v83, v127
	v_mov_b32_e32 v82, v127
	v_mov_b32_e32 v81, v127
	v_mov_b32_e32 v80, v127
	v_mov_b32_e32 v79, v127
	v_mov_b32_e32 v78, v127
	v_mov_b32_e32 v77, v127
	v_mov_b32_e32 v76, v127
	v_mov_b32_e32 v123, v127
	v_mov_b32_e32 v122, v127
	v_mov_b32_e32 v121, v127
	v_mov_b32_e32 v120, v127
	v_mov_b32_e32 v119, v127
	v_mov_b32_e32 v118, v127
	v_mov_b32_e32 v117, v127
	v_mov_b32_e32 v116, v127
	v_mov_b32_e32 v107, v127
	v_mov_b32_e32 v106, v127
	v_mov_b32_e32 v105, v127
	v_mov_b32_e32 v104, v127
	v_mov_b32_e32 v103, v127
	v_mov_b32_e32 v102, v127
	v_mov_b32_e32 v101, v127
	v_mov_b32_e32 v100, v127
	v_mov_b32_e32 v91, v127
	v_mov_b32_e32 v90, v127
	v_mov_b32_e32 v89, v127
	v_mov_b32_e32 v88, v127
	v_mov_b32_e32 v87, v127
	v_mov_b32_e32 v86, v127
	v_mov_b32_e32 v85, v127
	v_mov_b32_e32 v84, v127
	v_mov_b32_e32 v75, v127
	v_mov_b32_e32 v74, v127
	v_mov_b32_e32 v73, v127
	v_mov_b32_e32 v72, v127
	v_mov_b32_e32 v71, v127
	v_mov_b32_e32 v70, v127
	v_mov_b32_e32 v69, v127
	v_mov_b32_e32 v68, v127
	v_mov_b32_e32 v67, v127
	v_mov_b32_e32 v66, v127
	v_mov_b32_e32 v65, v127
	v_mov_b32_e32 v64, v127
	v_mov_b32_e32 v63, v127
	v_mov_b32_e32 v62, v127
	v_mov_b32_e32 v61, v127
	v_mov_b32_e32 v60, v127
	v_mov_b32_e32 v51, v127
	v_mov_b32_e32 v50, v127
	v_mov_b32_e32 v49, v127
	v_mov_b32_e32 v48, v127
	v_mov_b32_e32 v47, v127
	v_mov_b32_e32 v46, v127
	v_mov_b32_e32 v45, v127
	v_mov_b32_e32 v44, v127
	v_mov_b32_e32 v35, v127
	v_mov_b32_e32 v34, v127
	v_mov_b32_e32 v33, v127
	v_mov_b32_e32 v32, v127
	v_mov_b32_e32 v31, v127
	v_mov_b32_e32 v30, v127
	v_mov_b32_e32 v29, v127
	v_mov_b32_e32 v28, v127
	v_mov_b32_e32 v19, v127
	v_mov_b32_e32 v18, v127
	v_mov_b32_e32 v17, v127
	v_mov_b32_e32 v16, v127
	v_mov_b32_e32 v15, v127
	v_mov_b32_e32 v14, v127
	v_mov_b32_e32 v13, v127
	v_mov_b32_e32 v12, v127
	v_mov_b32_e32 v59, v127
	v_mov_b32_e32 v58, v127
	v_mov_b32_e32 v57, v127
	v_mov_b32_e32 v56, v127
	v_mov_b32_e32 v55, v127
	v_mov_b32_e32 v54, v127
	v_mov_b32_e32 v53, v127
	v_mov_b32_e32 v52, v127
	v_mov_b32_e32 v43, v127
	v_mov_b32_e32 v42, v127
	v_mov_b32_e32 v41, v127
	v_mov_b32_e32 v40, v127
	v_mov_b32_e32 v39, v127
	v_mov_b32_e32 v38, v127
	v_mov_b32_e32 v37, v127
	v_mov_b32_e32 v36, v127
	v_mov_b32_e32 v27, v127
	v_mov_b32_e32 v26, v127
	v_mov_b32_e32 v25, v127
	v_mov_b32_e32 v24, v127
	v_mov_b32_e32 v23, v127
	v_mov_b32_e32 v22, v127
	v_mov_b32_e32 v21, v127
	v_mov_b32_e32 v20, v127
	v_mov_b32_e32 v11, v127
	v_mov_b32_e32 v10, v127
	v_mov_b32_e32 v9, v127
	v_mov_b32_e32 v8, v127
	v_mov_b32_e32 v7, v127
	v_mov_b32_e32 v6, v127
	v_mov_b32_e32 v5, v127
	v_mov_b32_e32 v4, v127
	s_cbranch_vccnz .LBB0_1625
	s_add_u32 s44, s44, 0x80
	s_addc_u32 s45, s45, 0
	s_add_u32 s65, s48, 0x100
	s_addc_u32 s67, s49, 0
	s_mov_b32 s48, 0
	s_add_i32 s72, s48, 2
	s_add_u32 s73, s44, 0x80
	s_addc_u32 s49, s45, 0
	s_add_i32 s86, 0, 0x10000
	s_cmp_eq_u32 s57, s48
	s_cselect_b32 s49, s13, s49
	s_cselect_b32 s48, s12, s73
	s_cselect_b32 s77, s41, s67
	s_cselect_b32 s76, s40, s65
	s_add_i32 s73, 0, 0x14000
	v_add_u32_e32 v158, s86, v143
	v_add_u32_e32 v174, s73, v143
	ds_read_b128 v[146:149], v158
	ds_read_b128 v[178:181], v145
	ds_read_b128 v[150:153], v158 offset:1024
	ds_read_b128 v[182:185], v145 offset:1024
	ds_read_b128 v[204:207], v145 offset:3072
	ds_read_b128 v[186:189], v145 offset:2048
	ds_read_b128 v[208:211], v145 offset:4096
	ds_read_b128 v[212:215], v145 offset:5120
	v_lshl_add_u64 v[190:191], s[44:45], 0, v[138:139]
	s_add_i32 m0, s47, 0xc000
	ds_read_b128 v[220:223], v145 offset:7168
	ds_read_b128 v[216:219], v145 offset:6144
	ds_read_b128 v[154:157], v158 offset:2048
	ds_read_b128 v[158:161], v158 offset:3072
	ds_read_b128 v[162:165], v174
	ds_read_b128 v[166:169], v174 offset:1024
	ds_read_b128 v[170:173], v174 offset:2048
	ds_read_b128 v[174:177], v174 offset:3072
	global_load_lds_dwordx4 v[190:191], off
	v_lshl_add_u64 v[190:191], s[44:45], 0, v[140:141]
	s_add_i32 m0, s47, 0xe000
	s_nop 0
	global_load_lds_dwordx4 v[190:191], off
	s_waitcnt vmcnt(8)
	s_waitcnt lgkmcnt(14)
	s_setprio 1
	s_barrier
; #define PG8_STAGE(bufoff, gbase, voff) do { _Pragma("unroll") for (int _i = 0; _i < 2; ++_i) \
;         __builtin_amdgcn_global_load_lds((const unsigned*)((const char*)(gbase) + (voff)[_i]), (PG8_LAS unsigned*)(lds + (bufoff) + ldsw + _i * 8192), 16, 0, 0); } while (0)
; #define PG8_LDA(dst, b, h) do { _Pragma("unroll") for (int m = 0; m < 4; ++m) _Pragma("unroll") for (int k = 0; k < 2; ++k) dst[m][k] = *(const PG8_LAS bf16x8*)(lds + PG8_SA(b, h) + aoff + m * 2048 + k * 1024); } while (0)
; #define PG8_LDB(dst, b, h) do { _Pragma("unroll") for (int n = 0; n < 2; ++n) _Pragma("unroll") for (int k = 0; k < 2; ++k) dst[n][k] = *(const PG8_LAS bf16x8*)(lds + PG8_SB(b, h) + boff + n * 2048 + k * 1024); } while (0)
; #define PG8_WAIT_V(n) asm volatile("s_waitcnt vmcnt(" #n ")" ::: "memory")
; #define PG8_WAIT_L(n) asm volatile("s_waitcnt lgkmcnt(" #n ")" ::: "memory")
; #define PG8_BAR __builtin_amdgcn_s_barrier()
; #define PG8_SCHED __builtin_amdgcn_sched_barrier(0)
; template <class Epi, class Sched, bool ALIGN_EPI = false, bool SP2 = false, bool I8 = false>
; __device__ __forceinline__ void gemm_phase(PG8_LAS unsigned char* lds, const Gemm g, const Sched& S, const Epi& E) {
;     ...
;             if constexpr (SP2) {
;             PG8_LDB(B0, 0, 0); PG8_LDB(B1, 0, 1); PG8_SCHED; PG8_LDA(At, 0, 0); PG8_STAGE(PG8_SA(1, 1), a1 + hstep, voffA);
;             PG8_WAIT_V(8); PG8_WAIT_L(0); PG8_BAR; PG8_MMA(0, 0, At, B0); PG8_MMA(0, 1, At, B1); PG8_BAR; PG8_SCHED;
;             PG8_LDA(At, 0, 1); PG8_STAGE(PG8_SB(0, 0), b2, voffB); PG8_STAGE(PG8_SB(0, 1), b2 + hstep, voffB); PG8_STAGE(PG8_SA(0, 0), a2, voffA);
;             PG8_WAIT_V(8); PG8_WAIT_L(0); PG8_BAR; PG8_MMA(1, 0, At, B0); PG8_MMA(1, 1, At, B1); PG8_BAR; PG8_SCHED;
;             PG8_LDB(B0, 1, 0); PG8_LDB(B1, 1, 1); PG8_SCHED; PG8_LDA(At, 1, 0); PG8_STAGE(PG8_SA(0, 1), a2 + hstep, voffA);
;             PG8_WAIT_V(8); PG8_WAIT_L(0); PG8_BAR; PG8_MMA(0, 0, At, B0); PG8_MMA(0, 1, At, B1); PG8_BAR; PG8_SCHED;
;             PG8_LDA(At, 1, 1); PG8_STAGE(PG8_SB(1, 0), b3, voffB); PG8_STAGE(PG8_SB(1, 1), b3 + hstep, voffB); PG8_STAGE(PG8_SA(1, 0), a3, voffA);
;             PG8_WAIT_V(8); PG8_WAIT_L(0); PG8_BAR; PG8_MMA(1, 0, At, B0); PG8_MMA(1, 1, At, B1); PG8_BAR; PG8_SCHED;
	v_mfma_f32_16x16x32_bf16 v[124:127], v[146:149], v[178:181], 0
	s_waitcnt lgkmcnt(12)
	v_mfma_f32_16x16x32_bf16 v[124:127], v[150:153], v[182:185], v[124:127]
	s_waitcnt lgkmcnt(11)
	v_mfma_f32_16x16x32_bf16 v[112:115], v[150:153], v[204:207], 0
	s_waitcnt lgkmcnt(10)
	v_mfma_f32_16x16x32_bf16 v[112:115], v[146:149], v[186:189], v[112:115]
	s_waitcnt lgkmcnt(9)
	v_mfma_f32_16x16x32_bf16 v[96:99], v[146:149], v[208:211], 0
	s_waitcnt lgkmcnt(8)
	v_mfma_f32_16x16x32_bf16 v[96:99], v[150:153], v[212:215], v[96:99]
	s_waitcnt lgkmcnt(7)
	v_mfma_f32_16x16x32_bf16 v[80:83], v[150:153], v[220:223], 0
	s_waitcnt lgkmcnt(6)
	v_mfma_f32_16x16x32_bf16 v[80:83], v[146:149], v[216:219], v[80:83]
	s_waitcnt lgkmcnt(5)
	v_mfma_f32_16x16x32_bf16 v[76:79], v[154:157], v[216:219], 0
	s_waitcnt lgkmcnt(4)
	v_mfma_f32_16x16x32_bf16 v[76:79], v[158:161], v[220:223], v[76:79]
	v_mfma_f32_16x16x32_bf16 v[92:95], v[158:161], v[212:215], 0
	v_mfma_f32_16x16x32_bf16 v[92:95], v[154:157], v[208:211], v[92:95]
	v_mfma_f32_16x16x32_bf16 v[108:111], v[154:157], v[186:189], 0
	v_mfma_f32_16x16x32_bf16 v[108:111], v[158:161], v[204:207], v[108:111]
	v_mfma_f32_16x16x32_bf16 v[128:131], v[158:161], v[182:185], 0
	v_mfma_f32_16x16x32_bf16 v[128:131], v[154:157], v[178:181], v[128:131]
	s_waitcnt lgkmcnt(3)
	v_mfma_f32_16x16x32_bf16 v[120:123], v[162:165], v[178:181], 0
	s_waitcnt lgkmcnt(2)
	v_mfma_f32_16x16x32_bf16 v[120:123], v[166:169], v[182:185], v[120:123]
	v_mfma_f32_16x16x32_bf16 v[104:107], v[166:169], v[204:207], 0
	v_mfma_f32_16x16x32_bf16 v[104:107], v[162:165], v[186:189], v[104:107]
	v_mfma_f32_16x16x32_bf16 v[88:91], v[162:165], v[208:211], 0
	v_mfma_f32_16x16x32_bf16 v[88:91], v[166:169], v[212:215], v[88:91]
	v_mfma_f32_16x16x32_bf16 v[72:75], v[166:169], v[220:223], 0
	v_mfma_f32_16x16x32_bf16 v[72:75], v[162:165], v[216:219], v[72:75]
	s_waitcnt lgkmcnt(1)
	v_mfma_f32_16x16x32_bf16 v[68:71], v[170:173], v[216:219], 0
	s_waitcnt lgkmcnt(0)
	v_mfma_f32_16x16x32_bf16 v[68:71], v[174:177], v[220:223], v[68:71]
	v_mfma_f32_16x16x32_bf16 v[84:87], v[174:177], v[212:215], 0
	v_mfma_f32_16x16x32_bf16 v[84:87], v[170:173], v[208:211], v[84:87]
	v_mfma_f32_16x16x32_bf16 v[100:103], v[170:173], v[186:189], 0
	v_mfma_f32_16x16x32_bf16 v[100:103], v[174:177], v[204:207], v[100:103]
	v_mfma_f32_16x16x32_bf16 v[116:119], v[174:177], v[182:185], 0
	v_mfma_f32_16x16x32_bf16 v[116:119], v[170:173], v[178:181], v[116:119]
	s_barrier
	s_add_i32 s86, s86, s28
	v_lshl_add_u64 v[190:191], s[76:77], 0, v[2:3]
	s_mov_b32 m0, s86
	ds_read_b128 v[178:181], v145 offset:16384
	ds_read_b128 v[182:185], v145 offset:17408
	ds_read_b128 v[204:207], v145 offset:19456
	ds_read_b128 v[186:189], v145 offset:18432
	ds_read_b128 v[208:211], v145 offset:20480
	ds_read_b128 v[212:215], v145 offset:21504
	ds_read_b128 v[220:223], v145 offset:23552
	ds_read_b128 v[216:219], v145 offset:22528
	s_setprio 0
	global_load_lds_dwordx4 v[190:191], off
	s_add_i32 m0, s86, 0x2000
	v_lshl_add_u64 v[224:225], s[76:77], 0, v[136:137]
	s_add_u32 s76, s76, s18
	s_addc_u32 s77, s77, s19
	s_add_i32 s73, s73, s28
	global_load_lds_dwordx4 v[224:225], off
	v_lshl_add_u64 v[226:227], s[76:77], 0, v[2:3]
	s_mov_b32 m0, s73
	v_lshl_add_u64 v[228:229], s[76:77], 0, v[136:137]
	global_load_lds_dwordx4 v[226:227], off
	s_add_i32 m0, s73, 0x2000
	v_lshl_add_u64 v[240:241], s[48:49], 0, v[132:133]
	global_load_lds_dwordx4 v[228:229], off
	v_lshl_add_u64 v[242:243], s[48:49], 0, v[134:135]
	s_waitcnt vmcnt(6)
	s_waitcnt lgkmcnt(7)
	s_setprio 1
	s_barrier
	v_mfma_f32_16x16x32_bf16 v[64:67], v[146:149], v[178:181], 0
	s_waitcnt lgkmcnt(6)
	v_mfma_f32_16x16x32_bf16 v[64:67], v[150:153], v[182:185], v[64:67]
	s_waitcnt lgkmcnt(5)
	v_mfma_f32_16x16x32_bf16 v[48:51], v[150:153], v[204:207], 0
	s_waitcnt lgkmcnt(4)
	v_mfma_f32_16x16x32_bf16 v[48:51], v[146:149], v[186:189], v[48:51]
	s_waitcnt lgkmcnt(3)
	v_mfma_f32_16x16x32_bf16 v[32:35], v[146:149], v[208:211], 0
	s_waitcnt lgkmcnt(2)
	v_mfma_f32_16x16x32_bf16 v[32:35], v[150:153], v[212:215], v[32:35]
	s_waitcnt lgkmcnt(1)
	v_mfma_f32_16x16x32_bf16 v[16:19], v[150:153], v[220:223], 0
	s_waitcnt lgkmcnt(0)
	v_mfma_f32_16x16x32_bf16 v[16:19], v[146:149], v[216:219], v[16:19]
	v_mfma_f32_16x16x32_bf16 v[12:15], v[154:157], v[216:219], 0
	v_mfma_f32_16x16x32_bf16 v[12:15], v[158:161], v[220:223], v[12:15]
	v_mfma_f32_16x16x32_bf16 v[28:31], v[158:161], v[212:215], 0
	v_mfma_f32_16x16x32_bf16 v[28:31], v[154:157], v[208:211], v[28:31]
	v_mfma_f32_16x16x32_bf16 v[44:47], v[154:157], v[186:189], 0
	v_mfma_f32_16x16x32_bf16 v[44:47], v[158:161], v[204:207], v[44:47]
	v_mfma_f32_16x16x32_bf16 v[60:63], v[158:161], v[182:185], 0
	v_mfma_f32_16x16x32_bf16 v[60:63], v[154:157], v[178:181], v[60:63]
	v_mfma_f32_16x16x32_bf16 v[56:59], v[162:165], v[178:181], 0
	v_mfma_f32_16x16x32_bf16 v[56:59], v[166:169], v[182:185], v[56:59]
	v_mfma_f32_16x16x32_bf16 v[40:43], v[166:169], v[204:207], 0
	v_mfma_f32_16x16x32_bf16 v[40:43], v[162:165], v[186:189], v[40:43]
	v_mfma_f32_16x16x32_bf16 v[24:27], v[162:165], v[208:211], 0
	v_mfma_f32_16x16x32_bf16 v[24:27], v[166:169], v[212:215], v[24:27]
	v_mfma_f32_16x16x32_bf16 v[8:11], v[166:169], v[220:223], 0
	v_mfma_f32_16x16x32_bf16 v[8:11], v[162:165], v[216:219], v[8:11]
	v_mfma_f32_16x16x32_bf16 v[4:7], v[170:173], v[216:219], 0
	v_mfma_f32_16x16x32_bf16 v[4:7], v[174:177], v[220:223], v[4:7]
	v_mfma_f32_16x16x32_bf16 v[20:23], v[174:177], v[212:215], 0
	v_mfma_f32_16x16x32_bf16 v[20:23], v[170:173], v[208:211], v[20:23]
	v_mfma_f32_16x16x32_bf16 v[36:39], v[170:173], v[186:189], 0
	v_mfma_f32_16x16x32_bf16 v[36:39], v[174:177], v[204:207], v[36:39]
	v_mfma_f32_16x16x32_bf16 v[52:55], v[174:177], v[182:185], 0
	v_mfma_f32_16x16x32_bf16 v[52:55], v[170:173], v[178:181], v[52:55]
	s_barrier
; #define PG8_STAGE(bufoff, gbase, voff) do { _Pragma("unroll") for (int _i = 0; _i < 2; ++_i) \
;         __builtin_amdgcn_global_load_lds((const unsigned*)((const char*)(gbase) + (voff)[_i]), (PG8_LAS unsigned*)(lds + (bufoff) + ldsw + _i * 8192), 16, 0, 0); } while (0)
; #define PG8_LDA(dst, b, h) do { _Pragma("unroll") for (int m = 0; m < 4; ++m) _Pragma("unroll") for (int k = 0; k < 2; ++k) dst[m][k] = *(const PG8_LAS bf16x8*)(lds + PG8_SA(b, h) + aoff + m * 2048 + k * 1024); } while (0)
; #define PG8_LDB(dst, b, h) do { _Pragma("unroll") for (int n = 0; n < 2; ++n) _Pragma("unroll") for (int k = 0; k < 2; ++k) dst[n][k] = *(const PG8_LAS bf16x8*)(lds + PG8_SB(b, h) + boff + n * 2048 + k * 1024); } while (0)
; #define PG8_WAIT_V(n) asm volatile("s_waitcnt vmcnt(" #n ")" ::: "memory")
; #define PG8_WAIT_L(n) asm volatile("s_waitcnt lgkmcnt(" #n ")" ::: "memory")
; #define PG8_BAR __builtin_amdgcn_s_barrier()
; #define PG8_SCHED __builtin_amdgcn_sched_barrier(0)
; template <class Epi, class Sched, bool ALIGN_EPI = false, bool SP2 = false, bool I8 = false>
; __device__ __forceinline__ void gemm_phase(PG8_LAS unsigned char* lds, const Gemm g, const Sched& S, const Epi& E) {
;     ...
;             if constexpr (SP2) {
;             PG8_LDB(B0, 0, 0); PG8_LDB(B1, 0, 1); PG8_SCHED; PG8_LDA(At, 0, 0); PG8_STAGE(PG8_SA(1, 1), a1 + hstep, voffA);
;             PG8_WAIT_V(8); PG8_WAIT_L(0); PG8_BAR; PG8_MMA(0, 0, At, B0); PG8_MMA(0, 1, At, B1); PG8_BAR; PG8_SCHED;
;             PG8_LDA(At, 0, 1); PG8_STAGE(PG8_SB(0, 0), b2, voffB); PG8_STAGE(PG8_SB(0, 1), b2 + hstep, voffB); PG8_STAGE(PG8_SA(0, 0), a2, voffA);
;             PG8_WAIT_V(8); PG8_WAIT_L(0); PG8_BAR; PG8_MMA(1, 0, At, B0); PG8_MMA(1, 1, At, B1); PG8_BAR; PG8_SCHED;
;             PG8_LDB(B0, 1, 0); PG8_LDB(B1, 1, 1); PG8_SCHED; PG8_LDA(At, 1, 0); PG8_STAGE(PG8_SA(0, 1), a2 + hstep, voffA);
;             PG8_WAIT_V(8); PG8_WAIT_L(0); PG8_BAR; PG8_MMA(0, 0, At, B0); PG8_MMA(0, 1, At, B1); PG8_BAR; PG8_SCHED;
;             PG8_LDA(At, 1, 1); PG8_STAGE(PG8_SB(1, 0), b3, voffB); PG8_STAGE(PG8_SB(1, 1), b3 + hstep, voffB); PG8_STAGE(PG8_SA(1, 0), a3, voffA);
;             PG8_WAIT_V(8); PG8_WAIT_L(0); PG8_BAR; PG8_MMA(1, 0, At, B0); PG8_MMA(1, 1, At, B1); PG8_BAR; PG8_SCHED;
	s_mov_b32 m0, s47
	s_nop 0
	global_load_lds_dwordx4 v[240:241], off
	s_mov_b32 m0, s50
	s_nop 0
	global_load_lds_dwordx4 v[242:243], off
	s_add_i32 s73, 0, 0x18000
	s_add_i32 s76, 0, 0x1c000
	v_add_u32_e32 v158, s73, v143
	v_add_u32_e32 v174, s76, v143
	ds_read_b128 v[146:149], v158
	ds_read_b128 v[178:181], v145 offset:32768
	ds_read_b128 v[150:153], v158 offset:1024
	ds_read_b128 v[182:185], v145 offset:33792
	ds_read_b128 v[204:207], v145 offset:35840
	ds_read_b128 v[186:189], v145 offset:34816
	ds_read_b128 v[208:211], v145 offset:36864
	ds_read_b128 v[212:215], v145 offset:37888
	s_add_u32 s48, s48, s18
	s_addc_u32 s49, s49, s19
	s_mov_b32 m0, s51
	ds_read_b128 v[220:223], v145 offset:39936
	ds_read_b128 v[216:219], v145 offset:38912
	ds_read_b128 v[154:157], v158 offset:2048
	ds_read_b128 v[158:161], v158 offset:3072
	ds_read_b128 v[162:165], v174
	ds_read_b128 v[166:169], v174 offset:1024
	ds_read_b128 v[170:173], v174 offset:2048
	ds_read_b128 v[174:177], v174 offset:3072
	s_setprio 0
	global_load_lds_dwordx4 v132, s[48:49]
	s_mov_b32 m0, s52
	s_nop 0
	global_load_lds_dwordx4 v134, s[48:49]
	s_waitcnt vmcnt(8)
	s_waitcnt lgkmcnt(14)
	s_setprio 1
	s_barrier
	v_mfma_f32_16x16x32_bf16 v[124:127], v[146:149], v[178:181], v[124:127]
	s_waitcnt lgkmcnt(12)
	v_mfma_f32_16x16x32_bf16 v[124:127], v[150:153], v[182:185], v[124:127]
	s_waitcnt lgkmcnt(11)
	v_mfma_f32_16x16x32_bf16 v[112:115], v[150:153], v[204:207], v[112:115]
	s_waitcnt lgkmcnt(10)
	v_mfma_f32_16x16x32_bf16 v[112:115], v[146:149], v[186:189], v[112:115]
	s_waitcnt lgkmcnt(9)
	v_mfma_f32_16x16x32_bf16 v[96:99], v[146:149], v[208:211], v[96:99]
	s_waitcnt lgkmcnt(8)
	v_mfma_f32_16x16x32_bf16 v[96:99], v[150:153], v[212:215], v[96:99]
	s_waitcnt lgkmcnt(7)
	v_mfma_f32_16x16x32_bf16 v[80:83], v[150:153], v[220:223], v[80:83]
	s_waitcnt lgkmcnt(6)
	v_mfma_f32_16x16x32_bf16 v[80:83], v[146:149], v[216:219], v[80:83]
	s_waitcnt lgkmcnt(5)
	v_mfma_f32_16x16x32_bf16 v[76:79], v[154:157], v[216:219], v[76:79]
	s_waitcnt lgkmcnt(4)
	v_mfma_f32_16x16x32_bf16 v[76:79], v[158:161], v[220:223], v[76:79]
	v_mfma_f32_16x16x32_bf16 v[92:95], v[158:161], v[212:215], v[92:95]
	v_mfma_f32_16x16x32_bf16 v[92:95], v[154:157], v[208:211], v[92:95]
	v_mfma_f32_16x16x32_bf16 v[108:111], v[154:157], v[186:189], v[108:111]
	v_mfma_f32_16x16x32_bf16 v[108:111], v[158:161], v[204:207], v[108:111]
	v_mfma_f32_16x16x32_bf16 v[128:131], v[158:161], v[182:185], v[128:131]
	v_mfma_f32_16x16x32_bf16 v[128:131], v[154:157], v[178:181], v[128:131]
	s_waitcnt lgkmcnt(3)
	v_mfma_f32_16x16x32_bf16 v[120:123], v[162:165], v[178:181], v[120:123]
	s_waitcnt lgkmcnt(2)
	v_mfma_f32_16x16x32_bf16 v[120:123], v[166:169], v[182:185], v[120:123]
	v_mfma_f32_16x16x32_bf16 v[104:107], v[166:169], v[204:207], v[104:107]
	v_mfma_f32_16x16x32_bf16 v[104:107], v[162:165], v[186:189], v[104:107]
	v_mfma_f32_16x16x32_bf16 v[88:91], v[162:165], v[208:211], v[88:91]
	v_mfma_f32_16x16x32_bf16 v[88:91], v[166:169], v[212:215], v[88:91]
	v_mfma_f32_16x16x32_bf16 v[72:75], v[166:169], v[220:223], v[72:75]
	v_mfma_f32_16x16x32_bf16 v[72:75], v[162:165], v[216:219], v[72:75]
	s_waitcnt lgkmcnt(1)
	v_mfma_f32_16x16x32_bf16 v[68:71], v[170:173], v[216:219], v[68:71]
	s_waitcnt lgkmcnt(0)
	v_mfma_f32_16x16x32_bf16 v[68:71], v[174:177], v[220:223], v[68:71]
	v_mfma_f32_16x16x32_bf16 v[84:87], v[174:177], v[212:215], v[84:87]
	v_mfma_f32_16x16x32_bf16 v[84:87], v[170:173], v[208:211], v[84:87]
	v_mfma_f32_16x16x32_bf16 v[100:103], v[170:173], v[186:189], v[100:103]
	v_mfma_f32_16x16x32_bf16 v[100:103], v[174:177], v[204:207], v[100:103]
	v_mfma_f32_16x16x32_bf16 v[116:119], v[174:177], v[182:185], v[116:119]
	v_mfma_f32_16x16x32_bf16 v[116:119], v[170:173], v[178:181], v[116:119]
	s_barrier
	s_add_i32 s48, s73, s28
	v_lshl_add_u64 v[190:191], v[190:191], 0, s[84:85]
	s_mov_b32 m0, s48
	ds_read_b128 v[178:181], v145 offset:49152
	ds_read_b128 v[182:185], v145 offset:50176
	ds_read_b128 v[204:207], v145 offset:52224
	ds_read_b128 v[186:189], v145 offset:51200
	ds_read_b128 v[208:211], v145 offset:53248
	ds_read_b128 v[212:215], v145 offset:54272
	ds_read_b128 v[220:223], v145 offset:56320
	ds_read_b128 v[216:219], v145 offset:55296
	s_setprio 0
	global_load_lds_dwordx4 v[190:191], off
	v_lshl_add_u64 v[190:191], v[224:225], 0, s[84:85]
	s_add_i32 m0, s48, 0x2000
	s_add_i32 s48, s76, s28
	global_load_lds_dwordx4 v[190:191], off
	v_lshl_add_u64 v[190:191], v[226:227], 0, s[84:85]
	s_mov_b32 m0, s48
	s_nop 0
	global_load_lds_dwordx4 v[190:191], off
	v_lshl_add_u64 v[190:191], v[228:229], 0, s[84:85]
	s_add_i32 m0, s48, 0x2000
	s_nop 0
	global_load_lds_dwordx4 v[190:191], off
	v_lshl_add_u64 v[190:191], v[240:241], 0, s[84:85]
	s_mov_b32 m0, s55
	s_nop 0
	global_load_lds_dwordx4 v[190:191], off
	v_lshl_add_u64 v[190:191], v[242:243], 0, s[84:85]
	s_mov_b32 m0, s56
	s_nop 0
	global_load_lds_dwordx4 v[190:191], off
	s_waitcnt vmcnt(8)
	s_waitcnt lgkmcnt(7)
	s_setprio 1
	s_barrier
; #define PG8_STAGE(bufoff, gbase, voff) do { _Pragma("unroll") for (int _i = 0; _i < 2; ++_i) \
;         __builtin_amdgcn_global_load_lds((const unsigned*)((const char*)(gbase) + (voff)[_i]), (PG8_LAS unsigned*)(lds + (bufoff) + ldsw + _i * 8192), 16, 0, 0); } while (0)
; #define PG8_LDA(dst, b, h) do { _Pragma("unroll") for (int m = 0; m < 4; ++m) _Pragma("unroll") for (int k = 0; k < 2; ++k) dst[m][k] = *(const PG8_LAS bf16x8*)(lds + PG8_SA(b, h) + aoff + m * 2048 + k * 1024); } while (0)
; template <class Epi, class Sched, bool ALIGN_EPI = false, bool SP2 = false, bool I8 = false>
; __device__ __forceinline__ void gemm_phase(PG8_LAS unsigned char* lds, const Gemm g, const Sched& S, const Epi& E) {
;     ...
;         const bool has_next = S.next(ui + 1, nxt);
;         const char* nA = has_next ? (const char*)g.A + (size_t)nxt.pm * tstep : cA; const char* nB = has_next ? (const char*)g.Bt + (size_t)nxt.pn * tstep : cB;
;         for (int t = 0; t < nt; t += 2) {
;             const bool last = (t == nt - 2);
;             const char* a1 = cA + (size_t)(t + 1) * kstep;
;             const char* a2 = last ? nA : cA + (size_t)(t + 2) * kstep; const char* b2 = last ? nB : cB + (size_t)(t + 2) * kstep;
;             const char* a3 = a2 + kstep; const char* b3 = b2 + kstep;
;             if (last && has_next) S.a_ready(nxt);
;             if constexpr (SP2) {
;             PG8_LDB(B0, 0, 0); PG8_LDB(B1, 0, 1); PG8_SCHED; PG8_LDA(At, 0, 0); PG8_STAGE(PG8_SA(1, 1), a1 + hstep, voffA);
;             PG8_WAIT_V(8); PG8_WAIT_L(0); PG8_BAR; PG8_MMA(0, 0, At, B0); PG8_MMA(0, 1, At, B1); PG8_BAR; PG8_SCHED;
;             PG8_LDA(At, 0, 1); PG8_STAGE(PG8_SB(0, 0), b2, voffB); PG8_STAGE(PG8_SB(0, 1), b2 + hstep, voffB); PG8_STAGE(PG8_SA(0, 0), a2, voffA);
;             PG8_WAIT_V(8); PG8_WAIT_L(0); PG8_BAR; PG8_MMA(1, 0, At, B0); PG8_MMA(1, 1, At, B1); PG8_BAR; PG8_SCHED;
;             PG8_LDB(B0, 1, 0); PG8_LDB(B1, 1, 1); PG8_SCHED; PG8_LDA(At, 1, 0); PG8_STAGE(PG8_SA(0, 1), a2 + hstep, voffA);
;             PG8_WAIT_V(8); PG8_WAIT_L(0); PG8_BAR; PG8_MMA(0, 0, At, B0); PG8_MMA(0, 1, At, B1); PG8_BAR; PG8_SCHED;
;             PG8_LDA(At, 1, 1); PG8_STAGE(PG8_SB(1, 0), b3, voffB); PG8_STAGE(PG8_SB(1, 1), b3 + hstep, voffB); PG8_STAGE(PG8_SA(1, 0), a3, voffA);
;             PG8_WAIT_V(8); PG8_WAIT_L(0); PG8_BAR; PG8_MMA(1, 0, At, B0); PG8_MMA(1, 1, At, B1); PG8_BAR; PG8_SCHED;
	v_mfma_f32_16x16x32_bf16 v[64:67], v[146:149], v[178:181], v[64:67]
	s_waitcnt lgkmcnt(6)
	v_mfma_f32_16x16x32_bf16 v[64:67], v[150:153], v[182:185], v[64:67]
	s_waitcnt lgkmcnt(5)
	v_mfma_f32_16x16x32_bf16 v[48:51], v[150:153], v[204:207], v[48:51]
	s_waitcnt lgkmcnt(4)
	v_mfma_f32_16x16x32_bf16 v[48:51], v[146:149], v[186:189], v[48:51]
	s_waitcnt lgkmcnt(3)
	v_mfma_f32_16x16x32_bf16 v[32:35], v[146:149], v[208:211], v[32:35]
	s_waitcnt lgkmcnt(2)
	v_mfma_f32_16x16x32_bf16 v[32:35], v[150:153], v[212:215], v[32:35]
	s_waitcnt lgkmcnt(1)
	v_mfma_f32_16x16x32_bf16 v[16:19], v[150:153], v[220:223], v[16:19]
	s_waitcnt lgkmcnt(0)
	v_mfma_f32_16x16x32_bf16 v[16:19], v[146:149], v[216:219], v[16:19]
	v_mfma_f32_16x16x32_bf16 v[12:15], v[154:157], v[216:219], v[12:15]
	v_mfma_f32_16x16x32_bf16 v[12:15], v[158:161], v[220:223], v[12:15]
	v_mfma_f32_16x16x32_bf16 v[28:31], v[158:161], v[212:215], v[28:31]
	v_mfma_f32_16x16x32_bf16 v[28:31], v[154:157], v[208:211], v[28:31]
	v_mfma_f32_16x16x32_bf16 v[44:47], v[154:157], v[186:189], v[44:47]
	v_mfma_f32_16x16x32_bf16 v[44:47], v[158:161], v[204:207], v[44:47]
	v_mfma_f32_16x16x32_bf16 v[60:63], v[158:161], v[182:185], v[60:63]
	v_mfma_f32_16x16x32_bf16 v[60:63], v[154:157], v[178:181], v[60:63]
	v_mfma_f32_16x16x32_bf16 v[56:59], v[162:165], v[178:181], v[56:59]
	v_mfma_f32_16x16x32_bf16 v[56:59], v[166:169], v[182:185], v[56:59]
	v_mfma_f32_16x16x32_bf16 v[40:43], v[166:169], v[204:207], v[40:43]
	v_mfma_f32_16x16x32_bf16 v[40:43], v[162:165], v[186:189], v[40:43]
	v_mfma_f32_16x16x32_bf16 v[24:27], v[162:165], v[208:211], v[24:27]
	v_mfma_f32_16x16x32_bf16 v[24:27], v[166:169], v[212:215], v[24:27]
	v_mfma_f32_16x16x32_bf16 v[8:11], v[166:169], v[220:223], v[8:11]
	v_mfma_f32_16x16x32_bf16 v[8:11], v[162:165], v[216:219], v[8:11]
	v_mfma_f32_16x16x32_bf16 v[4:7], v[170:173], v[216:219], v[4:7]
	v_mfma_f32_16x16x32_bf16 v[4:7], v[174:177], v[220:223], v[4:7]
	v_mfma_f32_16x16x32_bf16 v[20:23], v[174:177], v[212:215], v[20:23]
	v_mfma_f32_16x16x32_bf16 v[20:23], v[170:173], v[208:211], v[20:23]
	v_mfma_f32_16x16x32_bf16 v[36:39], v[170:173], v[186:189], v[36:39]
	v_mfma_f32_16x16x32_bf16 v[36:39], v[174:177], v[204:207], v[36:39]
	v_mfma_f32_16x16x32_bf16 v[52:55], v[174:177], v[182:185], v[52:55]
	v_mfma_f32_16x16x32_bf16 v[52:55], v[170:173], v[178:181], v[52:55]
	s_barrier
	s_setprio 0
	s_add_u32 s44, s44, 0x100
	s_addc_u32 s45, s45, 0
	s_add_u32 s65, s65, 0x100
	s_addc_u32 s67, s67, 0
	s_cmp_ge_i32 s72, s53
	s_mov_b32 s48, s72
	s_cbranch_scc1 .Lkloop_exit_4
.LBB0_1623:
	s_add_i32 s72, s48, 2
	s_add_u32 s73, s44, 0x80
	s_addc_u32 s49, s45, 0
	s_add_i32 s86, 0, 0x10000
	s_cmp_eq_u32 s57, s48
	s_cselect_b32 s49, s13, s49
	s_cselect_b32 s48, s12, s73
	s_cselect_b32 s77, s41, s67
	s_cselect_b32 s76, s40, s65
	s_add_i32 s73, 0, 0x14000
	v_add_u32_e32 v158, s86, v143
	v_add_u32_e32 v174, s73, v143
	ds_read_b128 v[146:149], v158
	ds_read_b128 v[178:181], v145
	ds_read_b128 v[150:153], v158 offset:1024
	ds_read_b128 v[182:185], v145 offset:1024
	ds_read_b128 v[204:207], v145 offset:3072
	ds_read_b128 v[186:189], v145 offset:2048
	ds_read_b128 v[208:211], v145 offset:4096
	ds_read_b128 v[212:215], v145 offset:5120
	v_lshl_add_u64 v[190:191], s[44:45], 0, v[138:139]
	s_add_i32 m0, s47, 0xc000
	ds_read_b128 v[220:223], v145 offset:7168
	ds_read_b128 v[216:219], v145 offset:6144
	ds_read_b128 v[154:157], v158 offset:2048
	ds_read_b128 v[158:161], v158 offset:3072
	ds_read_b128 v[162:165], v174
	ds_read_b128 v[166:169], v174 offset:1024
	ds_read_b128 v[170:173], v174 offset:2048
	ds_read_b128 v[174:177], v174 offset:3072
	global_load_lds_dwordx4 v[190:191], off
	v_lshl_add_u64 v[190:191], s[44:45], 0, v[140:141]
	s_add_i32 m0, s47, 0xe000
	s_nop 0
	global_load_lds_dwordx4 v[190:191], off
	s_waitcnt vmcnt(8)
	s_waitcnt lgkmcnt(14)
	s_setprio 1
	s_barrier
	v_mfma_f32_16x16x32_bf16 v[124:127], v[146:149], v[178:181], v[124:127]
	s_waitcnt lgkmcnt(12)
	v_mfma_f32_16x16x32_bf16 v[124:127], v[150:153], v[182:185], v[124:127]
	s_waitcnt lgkmcnt(11)
	v_mfma_f32_16x16x32_bf16 v[112:115], v[150:153], v[204:207], v[112:115]
	s_waitcnt lgkmcnt(10)
	v_mfma_f32_16x16x32_bf16 v[112:115], v[146:149], v[186:189], v[112:115]
	s_waitcnt lgkmcnt(9)
	v_mfma_f32_16x16x32_bf16 v[96:99], v[146:149], v[208:211], v[96:99]
	s_waitcnt lgkmcnt(8)
	v_mfma_f32_16x16x32_bf16 v[96:99], v[150:153], v[212:215], v[96:99]
	s_waitcnt lgkmcnt(7)
	v_mfma_f32_16x16x32_bf16 v[80:83], v[150:153], v[220:223], v[80:83]
	s_waitcnt lgkmcnt(6)
	v_mfma_f32_16x16x32_bf16 v[80:83], v[146:149], v[216:219], v[80:83]
	s_waitcnt lgkmcnt(5)
	v_mfma_f32_16x16x32_bf16 v[76:79], v[154:157], v[216:219], v[76:79]
	s_waitcnt lgkmcnt(4)
	v_mfma_f32_16x16x32_bf16 v[76:79], v[158:161], v[220:223], v[76:79]
	v_mfma_f32_16x16x32_bf16 v[92:95], v[158:161], v[212:215], v[92:95]
	v_mfma_f32_16x16x32_bf16 v[92:95], v[154:157], v[208:211], v[92:95]
	v_mfma_f32_16x16x32_bf16 v[108:111], v[154:157], v[186:189], v[108:111]
	v_mfma_f32_16x16x32_bf16 v[108:111], v[158:161], v[204:207], v[108:111]
	v_mfma_f32_16x16x32_bf16 v[128:131], v[158:161], v[182:185], v[128:131]
	v_mfma_f32_16x16x32_bf16 v[128:131], v[154:157], v[178:181], v[128:131]
	s_waitcnt lgkmcnt(3)
	v_mfma_f32_16x16x32_bf16 v[120:123], v[162:165], v[178:181], v[120:123]
	s_waitcnt lgkmcnt(2)
	v_mfma_f32_16x16x32_bf16 v[120:123], v[166:169], v[182:185], v[120:123]
	v_mfma_f32_16x16x32_bf16 v[104:107], v[166:169], v[204:207], v[104:107]
	v_mfma_f32_16x16x32_bf16 v[104:107], v[162:165], v[186:189], v[104:107]
	v_mfma_f32_16x16x32_bf16 v[88:91], v[162:165], v[208:211], v[88:91]
	v_mfma_f32_16x16x32_bf16 v[88:91], v[166:169], v[212:215], v[88:91]
	v_mfma_f32_16x16x32_bf16 v[72:75], v[166:169], v[220:223], v[72:75]
	v_mfma_f32_16x16x32_bf16 v[72:75], v[162:165], v[216:219], v[72:75]
	s_waitcnt lgkmcnt(1)
	v_mfma_f32_16x16x32_bf16 v[68:71], v[170:173], v[216:219], v[68:71]
	s_waitcnt lgkmcnt(0)
	v_mfma_f32_16x16x32_bf16 v[68:71], v[174:177], v[220:223], v[68:71]
	v_mfma_f32_16x16x32_bf16 v[84:87], v[174:177], v[212:215], v[84:87]
	v_mfma_f32_16x16x32_bf16 v[84:87], v[170:173], v[208:211], v[84:87]
	v_mfma_f32_16x16x32_bf16 v[100:103], v[170:173], v[186:189], v[100:103]
	v_mfma_f32_16x16x32_bf16 v[100:103], v[174:177], v[204:207], v[100:103]
	v_mfma_f32_16x16x32_bf16 v[116:119], v[174:177], v[182:185], v[116:119]
	v_mfma_f32_16x16x32_bf16 v[116:119], v[170:173], v[178:181], v[116:119]
	s_barrier
; #define PG8_STAGE(bufoff, gbase, voff) do { _Pragma("unroll") for (int _i = 0; _i < 2; ++_i) \
;         __builtin_amdgcn_global_load_lds((const unsigned*)((const char*)(gbase) + (voff)[_i]), (PG8_LAS unsigned*)(lds + (bufoff) + ldsw + _i * 8192), 16, 0, 0); } while (0)
; #define PG8_LDA(dst, b, h) do { _Pragma("unroll") for (int m = 0; m < 4; ++m) _Pragma("unroll") for (int k = 0; k < 2; ++k) dst[m][k] = *(const PG8_LAS bf16x8*)(lds + PG8_SA(b, h) + aoff + m * 2048 + k * 1024); } while (0)
; #define PG8_LDB(dst, b, h) do { _Pragma("unroll") for (int n = 0; n < 2; ++n) _Pragma("unroll") for (int k = 0; k < 2; ++k) dst[n][k] = *(const PG8_LAS bf16x8*)(lds + PG8_SB(b, h) + boff + n * 2048 + k * 1024); } while (0)
; #define PG8_WAIT_V(n) asm volatile("s_waitcnt vmcnt(" #n ")" ::: "memory")
; #define PG8_WAIT_L(n) asm volatile("s_waitcnt lgkmcnt(" #n ")" ::: "memory")
; #define PG8_BAR __builtin_amdgcn_s_barrier()
; #define PG8_SCHED __builtin_amdgcn_sched_barrier(0)
; template <class Epi, class Sched, bool ALIGN_EPI = false, bool SP2 = false, bool I8 = false>
; __device__ __forceinline__ void gemm_phase(PG8_LAS unsigned char* lds, const Gemm g, const Sched& S, const Epi& E) {
;     ...
;             if constexpr (SP2) {
;             PG8_LDB(B0, 0, 0); PG8_LDB(B1, 0, 1); PG8_SCHED; PG8_LDA(At, 0, 0); PG8_STAGE(PG8_SA(1, 1), a1 + hstep, voffA);
;             PG8_WAIT_V(8); PG8_WAIT_L(0); PG8_BAR; PG8_MMA(0, 0, At, B0); PG8_MMA(0, 1, At, B1); PG8_BAR; PG8_SCHED;
;             PG8_LDA(At, 0, 1); PG8_STAGE(PG8_SB(0, 0), b2, voffB); PG8_STAGE(PG8_SB(0, 1), b2 + hstep, voffB); PG8_STAGE(PG8_SA(0, 0), a2, voffA);
;             PG8_WAIT_V(8); PG8_WAIT_L(0); PG8_BAR; PG8_MMA(1, 0, At, B0); PG8_MMA(1, 1, At, B1); PG8_BAR; PG8_SCHED;
;             PG8_LDB(B0, 1, 0); PG8_LDB(B1, 1, 1); PG8_SCHED; PG8_LDA(At, 1, 0); PG8_STAGE(PG8_SA(0, 1), a2 + hstep, voffA);
;             PG8_WAIT_V(8); PG8_WAIT_L(0); PG8_BAR; PG8_MMA(0, 0, At, B0); PG8_MMA(0, 1, At, B1); PG8_BAR; PG8_SCHED;
;             PG8_LDA(At, 1, 1); PG8_STAGE(PG8_SB(1, 0), b3, voffB); PG8_STAGE(PG8_SB(1, 1), b3 + hstep, voffB); PG8_STAGE(PG8_SA(1, 0), a3, voffA);
;             PG8_WAIT_V(8); PG8_WAIT_L(0); PG8_BAR; PG8_MMA(1, 0, At, B0); PG8_MMA(1, 1, At, B1); PG8_BAR; PG8_SCHED;
	s_add_i32 s86, s86, s28
	v_lshl_add_u64 v[190:191], s[76:77], 0, v[2:3]
	s_mov_b32 m0, s86
	ds_read_b128 v[178:181], v145 offset:16384
	ds_read_b128 v[182:185], v145 offset:17408
	ds_read_b128 v[204:207], v145 offset:19456
	ds_read_b128 v[186:189], v145 offset:18432
	ds_read_b128 v[208:211], v145 offset:20480
	ds_read_b128 v[212:215], v145 offset:21504
	ds_read_b128 v[220:223], v145 offset:23552
	ds_read_b128 v[216:219], v145 offset:22528
	s_setprio 0
	global_load_lds_dwordx4 v[190:191], off
	s_add_i32 m0, s86, 0x2000
	v_lshl_add_u64 v[224:225], s[76:77], 0, v[136:137]
	s_add_u32 s76, s76, s18
	s_addc_u32 s77, s77, s19
	s_add_i32 s73, s73, s28
	global_load_lds_dwordx4 v[224:225], off
	v_lshl_add_u64 v[226:227], s[76:77], 0, v[2:3]
	s_mov_b32 m0, s73
	v_lshl_add_u64 v[228:229], s[76:77], 0, v[136:137]
	global_load_lds_dwordx4 v[226:227], off
	s_add_i32 m0, s73, 0x2000
	v_lshl_add_u64 v[240:241], s[48:49], 0, v[132:133]
	global_load_lds_dwordx4 v[228:229], off
	v_lshl_add_u64 v[242:243], s[48:49], 0, v[134:135]
	s_waitcnt vmcnt(6)
	s_waitcnt lgkmcnt(7)
	s_setprio 1
	s_barrier
	v_mfma_f32_16x16x32_bf16 v[64:67], v[146:149], v[178:181], v[64:67]
	s_waitcnt lgkmcnt(6)
	v_mfma_f32_16x16x32_bf16 v[64:67], v[150:153], v[182:185], v[64:67]
	s_waitcnt lgkmcnt(5)
	v_mfma_f32_16x16x32_bf16 v[48:51], v[150:153], v[204:207], v[48:51]
	s_waitcnt lgkmcnt(4)
	v_mfma_f32_16x16x32_bf16 v[48:51], v[146:149], v[186:189], v[48:51]
	s_waitcnt lgkmcnt(3)
	v_mfma_f32_16x16x32_bf16 v[32:35], v[146:149], v[208:211], v[32:35]
	s_waitcnt lgkmcnt(2)
	v_mfma_f32_16x16x32_bf16 v[32:35], v[150:153], v[212:215], v[32:35]
	s_waitcnt lgkmcnt(1)
	v_mfma_f32_16x16x32_bf16 v[16:19], v[150:153], v[220:223], v[16:19]
	s_waitcnt lgkmcnt(0)
	v_mfma_f32_16x16x32_bf16 v[16:19], v[146:149], v[216:219], v[16:19]
	v_mfma_f32_16x16x32_bf16 v[12:15], v[154:157], v[216:219], v[12:15]
	v_mfma_f32_16x16x32_bf16 v[12:15], v[158:161], v[220:223], v[12:15]
	v_mfma_f32_16x16x32_bf16 v[28:31], v[158:161], v[212:215], v[28:31]
	v_mfma_f32_16x16x32_bf16 v[28:31], v[154:157], v[208:211], v[28:31]
	v_mfma_f32_16x16x32_bf16 v[44:47], v[154:157], v[186:189], v[44:47]
	v_mfma_f32_16x16x32_bf16 v[44:47], v[158:161], v[204:207], v[44:47]
	v_mfma_f32_16x16x32_bf16 v[60:63], v[158:161], v[182:185], v[60:63]
	v_mfma_f32_16x16x32_bf16 v[60:63], v[154:157], v[178:181], v[60:63]
	v_mfma_f32_16x16x32_bf16 v[56:59], v[162:165], v[178:181], v[56:59]
	v_mfma_f32_16x16x32_bf16 v[56:59], v[166:169], v[182:185], v[56:59]
	v_mfma_f32_16x16x32_bf16 v[40:43], v[166:169], v[204:207], v[40:43]
	v_mfma_f32_16x16x32_bf16 v[40:43], v[162:165], v[186:189], v[40:43]
	v_mfma_f32_16x16x32_bf16 v[24:27], v[162:165], v[208:211], v[24:27]
	v_mfma_f32_16x16x32_bf16 v[24:27], v[166:169], v[212:215], v[24:27]
	v_mfma_f32_16x16x32_bf16 v[8:11], v[166:169], v[220:223], v[8:11]
	v_mfma_f32_16x16x32_bf16 v[8:11], v[162:165], v[216:219], v[8:11]
	v_mfma_f32_16x16x32_bf16 v[4:7], v[170:173], v[216:219], v[4:7]
	v_mfma_f32_16x16x32_bf16 v[4:7], v[174:177], v[220:223], v[4:7]
	v_mfma_f32_16x16x32_bf16 v[20:23], v[174:177], v[212:215], v[20:23]
	v_mfma_f32_16x16x32_bf16 v[20:23], v[170:173], v[208:211], v[20:23]
	v_mfma_f32_16x16x32_bf16 v[36:39], v[170:173], v[186:189], v[36:39]
	v_mfma_f32_16x16x32_bf16 v[36:39], v[174:177], v[204:207], v[36:39]
	v_mfma_f32_16x16x32_bf16 v[52:55], v[174:177], v[182:185], v[52:55]
	v_mfma_f32_16x16x32_bf16 v[52:55], v[170:173], v[178:181], v[52:55]
	s_barrier
	s_mov_b32 m0, s47
	s_nop 0
	global_load_lds_dwordx4 v[240:241], off
	s_mov_b32 m0, s50
	s_nop 0
	global_load_lds_dwordx4 v[242:243], off
	s_add_i32 s73, 0, 0x18000
	s_add_i32 s76, 0, 0x1c000
	v_add_u32_e32 v158, s73, v143
	v_add_u32_e32 v174, s76, v143
	ds_read_b128 v[146:149], v158
	ds_read_b128 v[178:181], v145 offset:32768
	ds_read_b128 v[150:153], v158 offset:1024
	ds_read_b128 v[182:185], v145 offset:33792
	ds_read_b128 v[204:207], v145 offset:35840
	ds_read_b128 v[186:189], v145 offset:34816
	ds_read_b128 v[208:211], v145 offset:36864
	ds_read_b128 v[212:215], v145 offset:37888
	s_add_u32 s48, s48, s18
	s_addc_u32 s49, s49, s19
	s_mov_b32 m0, s51
	ds_read_b128 v[220:223], v145 offset:39936
	ds_read_b128 v[216:219], v145 offset:38912
	ds_read_b128 v[154:157], v158 offset:2048
	ds_read_b128 v[158:161], v158 offset:3072
	ds_read_b128 v[162:165], v174
	ds_read_b128 v[166:169], v174 offset:1024
	ds_read_b128 v[170:173], v174 offset:2048
	ds_read_b128 v[174:177], v174 offset:3072
	s_setprio 0
	global_load_lds_dwordx4 v132, s[48:49]
	s_mov_b32 m0, s52
	s_nop 0
	global_load_lds_dwordx4 v134, s[48:49]
	s_waitcnt vmcnt(8)
	s_waitcnt lgkmcnt(14)
	s_setprio 1
	s_barrier
; #define PG8_STAGE(bufoff, gbase, voff) do { _Pragma("unroll") for (int _i = 0; _i < 2; ++_i) \
;         __builtin_amdgcn_global_load_lds((const unsigned*)((const char*)(gbase) + (voff)[_i]), (PG8_LAS unsigned*)(lds + (bufoff) + ldsw + _i * 8192), 16, 0, 0); } while (0)
; #define PG8_LDA(dst, b, h) do { _Pragma("unroll") for (int m = 0; m < 4; ++m) _Pragma("unroll") for (int k = 0; k < 2; ++k) dst[m][k] = *(const PG8_LAS bf16x8*)(lds + PG8_SA(b, h) + aoff + m * 2048 + k * 1024); } while (0)
; #define PG8_LDB(dst, b, h) do { _Pragma("unroll") for (int n = 0; n < 2; ++n) _Pragma("unroll") for (int k = 0; k < 2; ++k) dst[n][k] = *(const PG8_LAS bf16x8*)(lds + PG8_SB(b, h) + boff + n * 2048 + k * 1024); } while (0)
; #define PG8_WAIT_V(n) asm volatile("s_waitcnt vmcnt(" #n ")" ::: "memory")
; #define PG8_WAIT_L(n) asm volatile("s_waitcnt lgkmcnt(" #n ")" ::: "memory")
; #define PG8_BAR __builtin_amdgcn_s_barrier()
; #define PG8_SCHED __builtin_amdgcn_sched_barrier(0)
; template <class Epi, class Sched, bool ALIGN_EPI = false, bool SP2 = false, bool I8 = false>
; __device__ __forceinline__ void gemm_phase(PG8_LAS unsigned char* lds, const Gemm g, const Sched& S, const Epi& E) {
;     ...
;             if constexpr (SP2) {
;             PG8_LDB(B0, 0, 0); PG8_LDB(B1, 0, 1); PG8_SCHED; PG8_LDA(At, 0, 0); PG8_STAGE(PG8_SA(1, 1), a1 + hstep, voffA);
;             PG8_WAIT_V(8); PG8_WAIT_L(0); PG8_BAR; PG8_MMA(0, 0, At, B0); PG8_MMA(0, 1, At, B1); PG8_BAR; PG8_SCHED;
;             PG8_LDA(At, 0, 1); PG8_STAGE(PG8_SB(0, 0), b2, voffB); PG8_STAGE(PG8_SB(0, 1), b2 + hstep, voffB); PG8_STAGE(PG8_SA(0, 0), a2, voffA);
;             PG8_WAIT_V(8); PG8_WAIT_L(0); PG8_BAR; PG8_MMA(1, 0, At, B0); PG8_MMA(1, 1, At, B1); PG8_BAR; PG8_SCHED;
;             PG8_LDB(B0, 1, 0); PG8_LDB(B1, 1, 1); PG8_SCHED; PG8_LDA(At, 1, 0); PG8_STAGE(PG8_SA(0, 1), a2 + hstep, voffA);
;             PG8_WAIT_V(8); PG8_WAIT_L(0); PG8_BAR; PG8_MMA(0, 0, At, B0); PG8_MMA(0, 1, At, B1); PG8_BAR; PG8_SCHED;
;             PG8_LDA(At, 1, 1); PG8_STAGE(PG8_SB(1, 0), b3, voffB); PG8_STAGE(PG8_SB(1, 1), b3 + hstep, voffB); PG8_STAGE(PG8_SA(1, 0), a3, voffA);
;             PG8_WAIT_V(8); PG8_WAIT_L(0); PG8_BAR; PG8_MMA(1, 0, At, B0); PG8_MMA(1, 1, At, B1); PG8_BAR; PG8_SCHED;
	v_mfma_f32_16x16x32_bf16 v[124:127], v[146:149], v[178:181], v[124:127]
	s_waitcnt lgkmcnt(12)
	v_mfma_f32_16x16x32_bf16 v[124:127], v[150:153], v[182:185], v[124:127]
	s_waitcnt lgkmcnt(11)
	v_mfma_f32_16x16x32_bf16 v[112:115], v[150:153], v[204:207], v[112:115]
	s_waitcnt lgkmcnt(10)
	v_mfma_f32_16x16x32_bf16 v[112:115], v[146:149], v[186:189], v[112:115]
	s_waitcnt lgkmcnt(9)
	v_mfma_f32_16x16x32_bf16 v[96:99], v[146:149], v[208:211], v[96:99]
	s_waitcnt lgkmcnt(8)
	v_mfma_f32_16x16x32_bf16 v[96:99], v[150:153], v[212:215], v[96:99]
	s_waitcnt lgkmcnt(7)
	v_mfma_f32_16x16x32_bf16 v[80:83], v[150:153], v[220:223], v[80:83]
	s_waitcnt lgkmcnt(6)
	v_mfma_f32_16x16x32_bf16 v[80:83], v[146:149], v[216:219], v[80:83]
	s_waitcnt lgkmcnt(5)
	v_mfma_f32_16x16x32_bf16 v[76:79], v[154:157], v[216:219], v[76:79]
	s_waitcnt lgkmcnt(4)
	v_mfma_f32_16x16x32_bf16 v[76:79], v[158:161], v[220:223], v[76:79]
	v_mfma_f32_16x16x32_bf16 v[92:95], v[158:161], v[212:215], v[92:95]
	v_mfma_f32_16x16x32_bf16 v[92:95], v[154:157], v[208:211], v[92:95]
	v_mfma_f32_16x16x32_bf16 v[108:111], v[154:157], v[186:189], v[108:111]
	v_mfma_f32_16x16x32_bf16 v[108:111], v[158:161], v[204:207], v[108:111]
	v_mfma_f32_16x16x32_bf16 v[128:131], v[158:161], v[182:185], v[128:131]
	v_mfma_f32_16x16x32_bf16 v[128:131], v[154:157], v[178:181], v[128:131]
	s_waitcnt lgkmcnt(3)
	v_mfma_f32_16x16x32_bf16 v[120:123], v[162:165], v[178:181], v[120:123]
	s_waitcnt lgkmcnt(2)
	v_mfma_f32_16x16x32_bf16 v[120:123], v[166:169], v[182:185], v[120:123]
	v_mfma_f32_16x16x32_bf16 v[104:107], v[166:169], v[204:207], v[104:107]
	v_mfma_f32_16x16x32_bf16 v[104:107], v[162:165], v[186:189], v[104:107]
	v_mfma_f32_16x16x32_bf16 v[88:91], v[162:165], v[208:211], v[88:91]
	v_mfma_f32_16x16x32_bf16 v[88:91], v[166:169], v[212:215], v[88:91]
	v_mfma_f32_16x16x32_bf16 v[72:75], v[166:169], v[220:223], v[72:75]
	v_mfma_f32_16x16x32_bf16 v[72:75], v[162:165], v[216:219], v[72:75]
	s_waitcnt lgkmcnt(1)
	v_mfma_f32_16x16x32_bf16 v[68:71], v[170:173], v[216:219], v[68:71]
	s_waitcnt lgkmcnt(0)
	v_mfma_f32_16x16x32_bf16 v[68:71], v[174:177], v[220:223], v[68:71]
	v_mfma_f32_16x16x32_bf16 v[84:87], v[174:177], v[212:215], v[84:87]
	v_mfma_f32_16x16x32_bf16 v[84:87], v[170:173], v[208:211], v[84:87]
	v_mfma_f32_16x16x32_bf16 v[100:103], v[170:173], v[186:189], v[100:103]
	v_mfma_f32_16x16x32_bf16 v[100:103], v[174:177], v[204:207], v[100:103]
	v_mfma_f32_16x16x32_bf16 v[116:119], v[174:177], v[182:185], v[116:119]
	v_mfma_f32_16x16x32_bf16 v[116:119], v[170:173], v[178:181], v[116:119]
	s_barrier
	s_add_i32 s48, s73, s28
	v_lshl_add_u64 v[190:191], v[190:191], 0, s[84:85]
	s_mov_b32 m0, s48
	ds_read_b128 v[178:181], v145 offset:49152
	ds_read_b128 v[182:185], v145 offset:50176
	ds_read_b128 v[204:207], v145 offset:52224
	ds_read_b128 v[186:189], v145 offset:51200
	ds_read_b128 v[208:211], v145 offset:53248
	ds_read_b128 v[212:215], v145 offset:54272
	ds_read_b128 v[220:223], v145 offset:56320
	ds_read_b128 v[216:219], v145 offset:55296
	s_setprio 0
	global_load_lds_dwordx4 v[190:191], off
	v_lshl_add_u64 v[190:191], v[224:225], 0, s[84:85]
	s_add_i32 m0, s48, 0x2000
	s_add_i32 s48, s76, s28
	global_load_lds_dwordx4 v[190:191], off
	v_lshl_add_u64 v[190:191], v[226:227], 0, s[84:85]
	s_mov_b32 m0, s48
	s_nop 0
	global_load_lds_dwordx4 v[190:191], off
	v_lshl_add_u64 v[190:191], v[228:229], 0, s[84:85]
	s_add_i32 m0, s48, 0x2000
	s_nop 0
	global_load_lds_dwordx4 v[190:191], off
	v_lshl_add_u64 v[190:191], v[240:241], 0, s[84:85]
	s_mov_b32 m0, s55
	s_nop 0
	global_load_lds_dwordx4 v[190:191], off
	v_lshl_add_u64 v[190:191], v[242:243], 0, s[84:85]
	s_mov_b32 m0, s56
	s_nop 0
	global_load_lds_dwordx4 v[190:191], off
	s_waitcnt vmcnt(8)
	s_waitcnt lgkmcnt(7)
	s_setprio 1
	s_barrier
	v_mfma_f32_16x16x32_bf16 v[64:67], v[146:149], v[178:181], v[64:67]
	s_waitcnt lgkmcnt(6)
	v_mfma_f32_16x16x32_bf16 v[64:67], v[150:153], v[182:185], v[64:67]
	s_waitcnt lgkmcnt(5)
	v_mfma_f32_16x16x32_bf16 v[48:51], v[150:153], v[204:207], v[48:51]
	s_waitcnt lgkmcnt(4)
	v_mfma_f32_16x16x32_bf16 v[48:51], v[146:149], v[186:189], v[48:51]
	s_waitcnt lgkmcnt(3)
	v_mfma_f32_16x16x32_bf16 v[32:35], v[146:149], v[208:211], v[32:35]
	s_waitcnt lgkmcnt(2)
	v_mfma_f32_16x16x32_bf16 v[32:35], v[150:153], v[212:215], v[32:35]
	s_waitcnt lgkmcnt(1)
	v_mfma_f32_16x16x32_bf16 v[16:19], v[150:153], v[220:223], v[16:19]
	s_waitcnt lgkmcnt(0)
	v_mfma_f32_16x16x32_bf16 v[16:19], v[146:149], v[216:219], v[16:19]
	v_mfma_f32_16x16x32_bf16 v[12:15], v[154:157], v[216:219], v[12:15]
	v_mfma_f32_16x16x32_bf16 v[12:15], v[158:161], v[220:223], v[12:15]
	v_mfma_f32_16x16x32_bf16 v[28:31], v[158:161], v[212:215], v[28:31]
	v_mfma_f32_16x16x32_bf16 v[28:31], v[154:157], v[208:211], v[28:31]
	v_mfma_f32_16x16x32_bf16 v[44:47], v[154:157], v[186:189], v[44:47]
	v_mfma_f32_16x16x32_bf16 v[44:47], v[158:161], v[204:207], v[44:47]
	v_mfma_f32_16x16x32_bf16 v[60:63], v[158:161], v[182:185], v[60:63]
	v_mfma_f32_16x16x32_bf16 v[60:63], v[154:157], v[178:181], v[60:63]
	v_mfma_f32_16x16x32_bf16 v[56:59], v[162:165], v[178:181], v[56:59]
	v_mfma_f32_16x16x32_bf16 v[56:59], v[166:169], v[182:185], v[56:59]
	v_mfma_f32_16x16x32_bf16 v[40:43], v[166:169], v[204:207], v[40:43]
	v_mfma_f32_16x16x32_bf16 v[40:43], v[162:165], v[186:189], v[40:43]
	v_mfma_f32_16x16x32_bf16 v[24:27], v[162:165], v[208:211], v[24:27]
	v_mfma_f32_16x16x32_bf16 v[24:27], v[166:169], v[212:215], v[24:27]
	v_mfma_f32_16x16x32_bf16 v[8:11], v[166:169], v[220:223], v[8:11]
	v_mfma_f32_16x16x32_bf16 v[8:11], v[162:165], v[216:219], v[8:11]
	v_mfma_f32_16x16x32_bf16 v[4:7], v[170:173], v[216:219], v[4:7]
	v_mfma_f32_16x16x32_bf16 v[4:7], v[174:177], v[220:223], v[4:7]
	v_mfma_f32_16x16x32_bf16 v[20:23], v[174:177], v[212:215], v[20:23]
	v_mfma_f32_16x16x32_bf16 v[20:23], v[170:173], v[208:211], v[20:23]
	v_mfma_f32_16x16x32_bf16 v[36:39], v[170:173], v[186:189], v[36:39]
	v_mfma_f32_16x16x32_bf16 v[36:39], v[174:177], v[204:207], v[36:39]
	v_mfma_f32_16x16x32_bf16 v[52:55], v[174:177], v[182:185], v[52:55]
	v_mfma_f32_16x16x32_bf16 v[52:55], v[170:173], v[178:181], v[52:55]
	s_barrier
	s_setprio 0
	s_add_u32 s44, s44, 0x100
	s_addc_u32 s45, s45, 0
	s_add_u32 s65, s65, 0x100
	s_addc_u32 s67, s67, 0
	s_cmp_ge_i32 s72, s53
	s_mov_b32 s48, s72
	s_cbranch_scc0 .LBB0_1623

; #define PG8_STAGE(bufoff, gbase, voff) do { _Pragma("unroll") for (int _i = 0; _i < 2; ++_i) \
;         __builtin_amdgcn_global_load_lds((const unsigned*)((const char*)(gbase) + (voff)[_i]), (PG8_LAS unsigned*)(lds + (bufoff) + ldsw + _i * 8192), 16, 0, 0); } while (0)
; #define PG8_LDA(dst, b, h) do { _Pragma("unroll") for (int m = 0; m < 4; ++m) _Pragma("unroll") for (int k = 0; k < 2; ++k) dst[m][k] = *(const PG8_LAS bf16x8*)(lds + PG8_SA(b, h) + aoff + m * 2048 + k * 1024); } while (0)
; #define PG8_BAR __builtin_amdgcn_s_barrier()
; template <class Epi, class Sched, bool ALIGN_EPI = false, bool SP2 = false, bool I8 = false>
; __device__ __forceinline__ void gemm_phase(PG8_LAS unsigned char* lds, const Gemm g, const Sched& S, const Epi& E) {
;     ...
;         const char* nA = has_next ? (const char*)g.A + (size_t)nxt.pm * tstep : cA; const char* nB = has_next ? (const char*)g.Bt + (size_t)nxt.pn * tstep : cB;
;         for (int t = 0; t < nt; t += 2) {
;             const bool last = (t == nt - 2);
;             const char* a1 = cA + (size_t)(t + 1) * kstep;
;             const char* a2 = last ? nA : cA + (size_t)(t + 2) * kstep; const char* b2 = last ? nB : cB + (size_t)(t + 2) * kstep;
;             const char* a3 = a2 + kstep; const char* b3 = b2 + kstep;
;             if (last && has_next) S.a_ready(nxt);
;             if constexpr (SP2) {
;             PG8_LDB(B0, 0, 0); PG8_LDB(B1, 0, 1); PG8_SCHED; PG8_LDA(At, 0, 0); PG8_STAGE(PG8_SA(1, 1), a1 + hstep, voffA);
;             PG8_WAIT_V(8); PG8_WAIT_L(0); PG8_BAR; PG8_MMA(0, 0, At, B0); PG8_MMA(0, 1, At, B1); PG8_BAR; PG8_SCHED;
;             PG8_LDA(At, 0, 1); PG8_STAGE(PG8_SB(0, 0), b2, voffB); PG8_STAGE(PG8_SB(0, 1), b2 + hstep, voffB); PG8_STAGE(PG8_SA(0, 0), a2, voffA);
;             PG8_WAIT_V(8); PG8_WAIT_L(0); PG8_BAR; PG8_MMA(1, 0, At, B0); PG8_MMA(1, 1, At, B1); PG8_BAR; PG8_SCHED;
;             PG8_LDB(B0, 1, 0); PG8_LDB(B1, 1, 1); PG8_SCHED; PG8_LDA(At, 1, 0); PG8_STAGE(PG8_SA(0, 1), a2 + hstep, voffA);
;             PG8_WAIT_V(8); PG8_WAIT_L(0); PG8_BAR; PG8_MMA(0, 0, At, B0); PG8_MMA(0, 1, At, B1); PG8_BAR; PG8_SCHED;
;             PG8_LDA(At, 1, 1); PG8_STAGE(PG8_SB(1, 0), b3, voffB); PG8_STAGE(PG8_SB(1, 1), b3 + hstep, voffB); PG8_STAGE(PG8_SA(1, 0), a3, voffA);
;             PG8_WAIT_V(8); PG8_WAIT_L(0); PG8_BAR; PG8_MMA(1, 0, At, B0); PG8_MMA(1, 1, At, B1); PG8_BAR; PG8_SCHED;
.LBB0_1699:
	s_add_u32 s53, s24, 0x100
	s_addc_u32 s54, s25, 0
	s_mov_b32 s55, -2
	s_add_u32 s24, s22, 0x100
	s_addc_u32 s25, s23, 0
	s_add_i32 s56, 0, 0x10000
	s_cmpk_eq_i32 s55, 0xa8
	s_cselect_b32 s37, s13, s25
	s_cselect_b32 s36, s12, s24
	s_cselect_b32 s27, s21, s54
	s_cselect_b32 s26, s20, s53
	s_add_i32 s57, 0, 0x14000
	v_add_u32_e32 v144, s56, v240
	v_add_u32_e32 v160, s57, v240
	ds_read_b128 v[124:127], v144
	ds_read_b128 v[164:167], v242
	ds_read_b128 v[128:131], v144 offset:1024
	ds_read_b128 v[168:171], v242 offset:1024
	ds_read_b128 v[176:179], v242 offset:3072
	ds_read_b128 v[172:175], v242 offset:2048
	ds_read_b128 v[180:183], v242 offset:4096
	ds_read_b128 v[184:187], v242 offset:5120
	v_lshl_add_u64 v[218:219], s[22:23], 0, v[210:211]
	s_add_i32 m0, s42, 0xc000
	ds_read_b128 v[214:217], v242 offset:7168
	ds_read_b128 v[188:191], v242 offset:6144
	ds_read_b128 v[132:135], v144 offset:2048
	ds_read_b128 v[144:147], v144 offset:3072
	ds_read_b128 v[148:151], v160
	ds_read_b128 v[152:155], v160 offset:1024
	ds_read_b128 v[156:159], v160 offset:2048
	ds_read_b128 v[160:163], v160 offset:3072
	global_load_lds_dwordx4 v[218:219], off
	v_lshl_add_u64 v[218:219], s[22:23], 0, v[212:213]
	s_add_i32 m0, s42, 0xe000
	s_nop 0
	global_load_lds_dwordx4 v[218:219], off
	s_waitcnt vmcnt(8)
	s_waitcnt lgkmcnt(14)
	s_setprio 1
	s_barrier
	v_mfma_f32_16x16x32_bf16 v[140:143], v[124:127], v[164:167], 0
	s_waitcnt lgkmcnt(12)
	v_mfma_f32_16x16x32_bf16 v[140:143], v[128:131], v[168:171], v[140:143]
	s_waitcnt lgkmcnt(11)
	v_mfma_f32_16x16x32_bf16 v[112:115], v[128:131], v[176:179], 0
	s_waitcnt lgkmcnt(10)
	v_mfma_f32_16x16x32_bf16 v[112:115], v[124:127], v[172:175], v[112:115]
	s_waitcnt lgkmcnt(9)
	v_mfma_f32_16x16x32_bf16 v[96:99], v[124:127], v[180:183], 0
	s_waitcnt lgkmcnt(8)
	v_mfma_f32_16x16x32_bf16 v[96:99], v[128:131], v[184:187], v[96:99]
	s_waitcnt lgkmcnt(7)
	v_mfma_f32_16x16x32_bf16 v[80:83], v[128:131], v[214:217], 0
	s_waitcnt lgkmcnt(6)
	v_mfma_f32_16x16x32_bf16 v[80:83], v[124:127], v[188:191], v[80:83]
	s_waitcnt lgkmcnt(5)
	v_mfma_f32_16x16x32_bf16 v[76:79], v[132:135], v[188:191], 0
	s_waitcnt lgkmcnt(4)
	v_mfma_f32_16x16x32_bf16 v[76:79], v[144:147], v[214:217], v[76:79]
	v_mfma_f32_16x16x32_bf16 v[92:95], v[144:147], v[184:187], 0
	v_mfma_f32_16x16x32_bf16 v[92:95], v[132:135], v[180:183], v[92:95]
	v_mfma_f32_16x16x32_bf16 v[108:111], v[132:135], v[172:175], 0
	v_mfma_f32_16x16x32_bf16 v[108:111], v[144:147], v[176:179], v[108:111]
	v_mfma_f32_16x16x32_bf16 v[136:139], v[144:147], v[168:171], 0
	v_mfma_f32_16x16x32_bf16 v[136:139], v[132:135], v[164:167], v[136:139]
	s_waitcnt lgkmcnt(3)
	v_mfma_f32_16x16x32_bf16 v[120:123], v[148:151], v[164:167], 0
	s_waitcnt lgkmcnt(2)
	v_mfma_f32_16x16x32_bf16 v[120:123], v[152:155], v[168:171], v[120:123]
	v_mfma_f32_16x16x32_bf16 v[104:107], v[152:155], v[176:179], 0
	v_mfma_f32_16x16x32_bf16 v[104:107], v[148:151], v[172:175], v[104:107]
	v_mfma_f32_16x16x32_bf16 v[88:91], v[148:151], v[180:183], 0
	v_mfma_f32_16x16x32_bf16 v[88:91], v[152:155], v[184:187], v[88:91]
	v_mfma_f32_16x16x32_bf16 v[72:75], v[152:155], v[214:217], 0
	v_mfma_f32_16x16x32_bf16 v[72:75], v[148:151], v[188:191], v[72:75]
	s_waitcnt lgkmcnt(1)
	v_mfma_f32_16x16x32_bf16 v[68:71], v[156:159], v[188:191], 0
	s_waitcnt lgkmcnt(0)
	v_mfma_f32_16x16x32_bf16 v[68:71], v[160:163], v[214:217], v[68:71]
	v_mfma_f32_16x16x32_bf16 v[84:87], v[160:163], v[184:187], 0
	v_mfma_f32_16x16x32_bf16 v[84:87], v[156:159], v[180:183], v[84:87]
	v_mfma_f32_16x16x32_bf16 v[100:103], v[156:159], v[172:175], 0
	v_mfma_f32_16x16x32_bf16 v[100:103], v[160:163], v[176:179], v[100:103]
	v_mfma_f32_16x16x32_bf16 v[116:119], v[160:163], v[168:171], 0
	v_mfma_f32_16x16x32_bf16 v[116:119], v[156:159], v[164:167], v[116:119]
	s_barrier
	s_add_i32 s22, s56, s41
	v_lshl_add_u64 v[218:219], s[26:27], 0, v[2:3]
	s_mov_b32 m0, s22
	ds_read_b128 v[164:167], v242 offset:16384
	ds_read_b128 v[168:171], v242 offset:17408
	ds_read_b128 v[176:179], v242 offset:19456
	ds_read_b128 v[172:175], v242 offset:18432
	ds_read_b128 v[180:183], v242 offset:20480
	ds_read_b128 v[184:187], v242 offset:21504
	ds_read_b128 v[214:217], v242 offset:23552
	ds_read_b128 v[188:191], v242 offset:22528
	s_setprio 0
	global_load_lds_dwordx4 v[218:219], off
	s_add_i32 m0, s22, 0x2000
	s_add_u32 s22, s26, 0x2b0000
	v_lshl_add_u64 v[220:221], s[26:27], 0, v[204:205]
	s_addc_u32 s23, s27, 0
	s_add_i32 s56, s57, s41
	global_load_lds_dwordx4 v[220:221], off
	s_mov_b32 m0, s56
	v_lshl_add_u64 v[224:225], s[36:37], 0, v[206:207]
	global_load_lds_dwordx4 v2, s[22:23]
	s_add_i32 m0, s56, 0x2000
	s_nop 0
	global_load_lds_dwordx4 v204, s[22:23]
	v_lshl_add_u64 v[222:223], s[36:37], 0, v[208:209]
	s_waitcnt vmcnt(6)
	s_waitcnt lgkmcnt(7)
	s_setprio 1
	s_barrier
; #define PG8_STAGE(bufoff, gbase, voff) do { _Pragma("unroll") for (int _i = 0; _i < 2; ++_i) \
;         __builtin_amdgcn_global_load_lds((const unsigned*)((const char*)(gbase) + (voff)[_i]), (PG8_LAS unsigned*)(lds + (bufoff) + ldsw + _i * 8192), 16, 0, 0); } while (0)
; #define PG8_LDA(dst, b, h) do { _Pragma("unroll") for (int m = 0; m < 4; ++m) _Pragma("unroll") for (int k = 0; k < 2; ++k) dst[m][k] = *(const PG8_LAS bf16x8*)(lds + PG8_SA(b, h) + aoff + m * 2048 + k * 1024); } while (0)
; #define PG8_LDB(dst, b, h) do { _Pragma("unroll") for (int n = 0; n < 2; ++n) _Pragma("unroll") for (int k = 0; k < 2; ++k) dst[n][k] = *(const PG8_LAS bf16x8*)(lds + PG8_SB(b, h) + boff + n * 2048 + k * 1024); } while (0)
; #define PG8_WAIT_V(n) asm volatile("s_waitcnt vmcnt(" #n ")" ::: "memory")
; #define PG8_WAIT_L(n) asm volatile("s_waitcnt lgkmcnt(" #n ")" ::: "memory")
; #define PG8_BAR __builtin_amdgcn_s_barrier()
; #define PG8_SCHED __builtin_amdgcn_sched_barrier(0)
; template <class Epi, class Sched, bool ALIGN_EPI = false, bool SP2 = false, bool I8 = false>
; __device__ __forceinline__ void gemm_phase(PG8_LAS unsigned char* lds, const Gemm g, const Sched& S, const Epi& E) {
;     ...
;             if constexpr (SP2) {
;             PG8_LDB(B0, 0, 0); PG8_LDB(B1, 0, 1); PG8_SCHED; PG8_LDA(At, 0, 0); PG8_STAGE(PG8_SA(1, 1), a1 + hstep, voffA);
;             PG8_WAIT_V(8); PG8_WAIT_L(0); PG8_BAR; PG8_MMA(0, 0, At, B0); PG8_MMA(0, 1, At, B1); PG8_BAR; PG8_SCHED;
;             PG8_LDA(At, 0, 1); PG8_STAGE(PG8_SB(0, 0), b2, voffB); PG8_STAGE(PG8_SB(0, 1), b2 + hstep, voffB); PG8_STAGE(PG8_SA(0, 0), a2, voffA);
;             PG8_WAIT_V(8); PG8_WAIT_L(0); PG8_BAR; PG8_MMA(1, 0, At, B0); PG8_MMA(1, 1, At, B1); PG8_BAR; PG8_SCHED;
;             PG8_LDB(B0, 1, 0); PG8_LDB(B1, 1, 1); PG8_SCHED; PG8_LDA(At, 1, 0); PG8_STAGE(PG8_SA(0, 1), a2 + hstep, voffA);
;             PG8_WAIT_V(8); PG8_WAIT_L(0); PG8_BAR; PG8_MMA(0, 0, At, B0); PG8_MMA(0, 1, At, B1); PG8_BAR; PG8_SCHED;
;             PG8_LDA(At, 1, 1); PG8_STAGE(PG8_SB(1, 0), b3, voffB); PG8_STAGE(PG8_SB(1, 1), b3 + hstep, voffB); PG8_STAGE(PG8_SA(1, 0), a3, voffA);
;             PG8_WAIT_V(8); PG8_WAIT_L(0); PG8_BAR; PG8_MMA(1, 0, At, B0); PG8_MMA(1, 1, At, B1); PG8_BAR; PG8_SCHED;
	v_mfma_f32_16x16x32_bf16 v[64:67], v[124:127], v[164:167], 0
	s_waitcnt lgkmcnt(6)
	v_mfma_f32_16x16x32_bf16 v[64:67], v[128:131], v[168:171], v[64:67]
	s_waitcnt lgkmcnt(5)
	v_mfma_f32_16x16x32_bf16 v[48:51], v[128:131], v[176:179], 0
	s_waitcnt lgkmcnt(4)
	v_mfma_f32_16x16x32_bf16 v[48:51], v[124:127], v[172:175], v[48:51]
	s_waitcnt lgkmcnt(3)
	v_mfma_f32_16x16x32_bf16 v[32:35], v[124:127], v[180:183], 0
	s_waitcnt lgkmcnt(2)
	v_mfma_f32_16x16x32_bf16 v[32:35], v[128:131], v[184:187], v[32:35]
	s_waitcnt lgkmcnt(1)
	v_mfma_f32_16x16x32_bf16 v[16:19], v[128:131], v[214:217], 0
	s_waitcnt lgkmcnt(0)
	v_mfma_f32_16x16x32_bf16 v[16:19], v[124:127], v[188:191], v[16:19]
	v_mfma_f32_16x16x32_bf16 v[12:15], v[132:135], v[188:191], 0
	v_mfma_f32_16x16x32_bf16 v[12:15], v[144:147], v[214:217], v[12:15]
	v_mfma_f32_16x16x32_bf16 v[28:31], v[144:147], v[184:187], 0
	v_mfma_f32_16x16x32_bf16 v[28:31], v[132:135], v[180:183], v[28:31]
	v_mfma_f32_16x16x32_bf16 v[44:47], v[132:135], v[172:175], 0
	v_mfma_f32_16x16x32_bf16 v[44:47], v[144:147], v[176:179], v[44:47]
	v_mfma_f32_16x16x32_bf16 v[60:63], v[144:147], v[168:171], 0
	v_mfma_f32_16x16x32_bf16 v[60:63], v[132:135], v[164:167], v[60:63]
	v_mfma_f32_16x16x32_bf16 v[56:59], v[148:151], v[164:167], 0
	v_mfma_f32_16x16x32_bf16 v[56:59], v[152:155], v[168:171], v[56:59]
	v_mfma_f32_16x16x32_bf16 v[40:43], v[152:155], v[176:179], 0
	v_mfma_f32_16x16x32_bf16 v[40:43], v[148:151], v[172:175], v[40:43]
	v_mfma_f32_16x16x32_bf16 v[24:27], v[148:151], v[180:183], 0
	v_mfma_f32_16x16x32_bf16 v[24:27], v[152:155], v[184:187], v[24:27]
	v_mfma_f32_16x16x32_bf16 v[8:11], v[152:155], v[214:217], 0
	v_mfma_f32_16x16x32_bf16 v[8:11], v[148:151], v[188:191], v[8:11]
	v_mfma_f32_16x16x32_bf16 v[4:7], v[156:159], v[188:191], 0
	v_mfma_f32_16x16x32_bf16 v[4:7], v[160:163], v[214:217], v[4:7]
	v_mfma_f32_16x16x32_bf16 v[20:23], v[160:163], v[184:187], 0
	v_mfma_f32_16x16x32_bf16 v[20:23], v[156:159], v[180:183], v[20:23]
	v_mfma_f32_16x16x32_bf16 v[36:39], v[156:159], v[172:175], 0
	v_mfma_f32_16x16x32_bf16 v[36:39], v[160:163], v[176:179], v[36:39]
	v_mfma_f32_16x16x32_bf16 v[52:55], v[160:163], v[168:171], 0
	v_mfma_f32_16x16x32_bf16 v[52:55], v[156:159], v[164:167], v[52:55]
	s_barrier
	s_mov_b32 m0, s42
	s_nop 0
	global_load_lds_dwordx4 v[222:223], off
	s_mov_b32 m0, s43
	s_nop 0
	global_load_lds_dwordx4 v[224:225], off
	s_add_i32 s56, 0, 0x18000
	s_add_i32 s57, 0, 0x1c000
	v_add_u32_e32 v144, s56, v240
	v_add_u32_e32 v160, s57, v240
	ds_read_b128 v[124:127], v144
	ds_read_b128 v[164:167], v242 offset:32768
	ds_read_b128 v[128:131], v144 offset:1024
	ds_read_b128 v[168:171], v242 offset:33792
	ds_read_b128 v[176:179], v242 offset:35840
	ds_read_b128 v[172:175], v242 offset:34816
	ds_read_b128 v[180:183], v242 offset:36864
	ds_read_b128 v[184:187], v242 offset:37888
	s_add_u32 s22, s36, 0x2b0000
	s_addc_u32 s23, s37, 0
	s_mov_b32 m0, s44
	ds_read_b128 v[214:217], v242 offset:39936
	ds_read_b128 v[188:191], v242 offset:38912
	ds_read_b128 v[132:135], v144 offset:2048
	ds_read_b128 v[144:147], v144 offset:3072
	ds_read_b128 v[148:151], v160
	ds_read_b128 v[152:155], v160 offset:1024
	ds_read_b128 v[156:159], v160 offset:2048
	ds_read_b128 v[160:163], v160 offset:3072
	s_setprio 0
	global_load_lds_dwordx4 v208, s[22:23]
	s_mov_b32 m0, s45
	s_nop 0
	global_load_lds_dwordx4 v206, s[22:23]
	s_waitcnt vmcnt(8)
	s_waitcnt lgkmcnt(14)
	s_setprio 1
	s_barrier
; #define PG8_STAGE(bufoff, gbase, voff) do { _Pragma("unroll") for (int _i = 0; _i < 2; ++_i) \
;         __builtin_amdgcn_global_load_lds((const unsigned*)((const char*)(gbase) + (voff)[_i]), (PG8_LAS unsigned*)(lds + (bufoff) + ldsw + _i * 8192), 16, 0, 0); } while (0)
; #define PG8_LDA(dst, b, h) do { _Pragma("unroll") for (int m = 0; m < 4; ++m) _Pragma("unroll") for (int k = 0; k < 2; ++k) dst[m][k] = *(const PG8_LAS bf16x8*)(lds + PG8_SA(b, h) + aoff + m * 2048 + k * 1024); } while (0)
; #define PG8_LDB(dst, b, h) do { _Pragma("unroll") for (int n = 0; n < 2; ++n) _Pragma("unroll") for (int k = 0; k < 2; ++k) dst[n][k] = *(const PG8_LAS bf16x8*)(lds + PG8_SB(b, h) + boff + n * 2048 + k * 1024); } while (0)
; #define PG8_WAIT_V(n) asm volatile("s_waitcnt vmcnt(" #n ")" ::: "memory")
; #define PG8_WAIT_L(n) asm volatile("s_waitcnt lgkmcnt(" #n ")" ::: "memory")
; #define PG8_BAR __builtin_amdgcn_s_barrier()
; #define PG8_SCHED __builtin_amdgcn_sched_barrier(0)
; template <class Epi, class Sched, bool ALIGN_EPI = false, bool SP2 = false, bool I8 = false>
; __device__ __forceinline__ void gemm_phase(PG8_LAS unsigned char* lds, const Gemm g, const Sched& S, const Epi& E) {
;     ...
;             if constexpr (SP2) {
;             PG8_LDB(B0, 0, 0); PG8_LDB(B1, 0, 1); PG8_SCHED; PG8_LDA(At, 0, 0); PG8_STAGE(PG8_SA(1, 1), a1 + hstep, voffA);
;             PG8_WAIT_V(8); PG8_WAIT_L(0); PG8_BAR; PG8_MMA(0, 0, At, B0); PG8_MMA(0, 1, At, B1); PG8_BAR; PG8_SCHED;
;             PG8_LDA(At, 0, 1); PG8_STAGE(PG8_SB(0, 0), b2, voffB); PG8_STAGE(PG8_SB(0, 1), b2 + hstep, voffB); PG8_STAGE(PG8_SA(0, 0), a2, voffA);
;             PG8_WAIT_V(8); PG8_WAIT_L(0); PG8_BAR; PG8_MMA(1, 0, At, B0); PG8_MMA(1, 1, At, B1); PG8_BAR; PG8_SCHED;
;             PG8_LDB(B0, 1, 0); PG8_LDB(B1, 1, 1); PG8_SCHED; PG8_LDA(At, 1, 0); PG8_STAGE(PG8_SA(0, 1), a2 + hstep, voffA);
;             PG8_WAIT_V(8); PG8_WAIT_L(0); PG8_BAR; PG8_MMA(0, 0, At, B0); PG8_MMA(0, 1, At, B1); PG8_BAR; PG8_SCHED;
;             PG8_LDA(At, 1, 1); PG8_STAGE(PG8_SB(1, 0), b3, voffB); PG8_STAGE(PG8_SB(1, 1), b3 + hstep, voffB); PG8_STAGE(PG8_SA(1, 0), a3, voffA);
;             PG8_WAIT_V(8); PG8_WAIT_L(0); PG8_BAR; PG8_MMA(1, 0, At, B0); PG8_MMA(1, 1, At, B1); PG8_BAR; PG8_SCHED;
	v_mfma_f32_16x16x32_bf16 v[140:143], v[124:127], v[164:167], v[140:143]
	s_waitcnt lgkmcnt(12)
	v_mfma_f32_16x16x32_bf16 v[140:143], v[128:131], v[168:171], v[140:143]
	s_waitcnt lgkmcnt(11)
	v_mfma_f32_16x16x32_bf16 v[112:115], v[128:131], v[176:179], v[112:115]
	s_waitcnt lgkmcnt(10)
	v_mfma_f32_16x16x32_bf16 v[112:115], v[124:127], v[172:175], v[112:115]
	s_waitcnt lgkmcnt(9)
	v_mfma_f32_16x16x32_bf16 v[96:99], v[124:127], v[180:183], v[96:99]
	s_waitcnt lgkmcnt(8)
	v_mfma_f32_16x16x32_bf16 v[96:99], v[128:131], v[184:187], v[96:99]
	s_waitcnt lgkmcnt(7)
	v_mfma_f32_16x16x32_bf16 v[80:83], v[128:131], v[214:217], v[80:83]
	s_waitcnt lgkmcnt(6)
	v_mfma_f32_16x16x32_bf16 v[80:83], v[124:127], v[188:191], v[80:83]
	s_waitcnt lgkmcnt(5)
	v_mfma_f32_16x16x32_bf16 v[76:79], v[132:135], v[188:191], v[76:79]
	s_waitcnt lgkmcnt(4)
	v_mfma_f32_16x16x32_bf16 v[76:79], v[144:147], v[214:217], v[76:79]
	v_mfma_f32_16x16x32_bf16 v[92:95], v[144:147], v[184:187], v[92:95]
	v_mfma_f32_16x16x32_bf16 v[92:95], v[132:135], v[180:183], v[92:95]
	v_mfma_f32_16x16x32_bf16 v[108:111], v[132:135], v[172:175], v[108:111]
	v_mfma_f32_16x16x32_bf16 v[108:111], v[144:147], v[176:179], v[108:111]
	v_mfma_f32_16x16x32_bf16 v[136:139], v[144:147], v[168:171], v[136:139]
	v_mfma_f32_16x16x32_bf16 v[136:139], v[132:135], v[164:167], v[136:139]
	s_waitcnt lgkmcnt(3)
	v_mfma_f32_16x16x32_bf16 v[120:123], v[148:151], v[164:167], v[120:123]
	s_waitcnt lgkmcnt(2)
	v_mfma_f32_16x16x32_bf16 v[120:123], v[152:155], v[168:171], v[120:123]
	v_mfma_f32_16x16x32_bf16 v[104:107], v[152:155], v[176:179], v[104:107]
	v_mfma_f32_16x16x32_bf16 v[104:107], v[148:151], v[172:175], v[104:107]
	v_mfma_f32_16x16x32_bf16 v[88:91], v[148:151], v[180:183], v[88:91]
	v_mfma_f32_16x16x32_bf16 v[88:91], v[152:155], v[184:187], v[88:91]
	v_mfma_f32_16x16x32_bf16 v[72:75], v[152:155], v[214:217], v[72:75]
	v_mfma_f32_16x16x32_bf16 v[72:75], v[148:151], v[188:191], v[72:75]
	s_waitcnt lgkmcnt(1)
	v_mfma_f32_16x16x32_bf16 v[68:71], v[156:159], v[188:191], v[68:71]
	s_waitcnt lgkmcnt(0)
	v_mfma_f32_16x16x32_bf16 v[68:71], v[160:163], v[214:217], v[68:71]
	v_mfma_f32_16x16x32_bf16 v[84:87], v[160:163], v[184:187], v[84:87]
	v_mfma_f32_16x16x32_bf16 v[84:87], v[156:159], v[180:183], v[84:87]
	v_mfma_f32_16x16x32_bf16 v[100:103], v[156:159], v[172:175], v[100:103]
	v_mfma_f32_16x16x32_bf16 v[100:103], v[160:163], v[176:179], v[100:103]
	v_mfma_f32_16x16x32_bf16 v[116:119], v[160:163], v[168:171], v[116:119]
	v_mfma_f32_16x16x32_bf16 v[116:119], v[156:159], v[164:167], v[116:119]
	s_barrier
	s_add_i32 s22, s56, s41
	v_lshl_add_u64 v[218:219], v[218:219], 0, s[84:85]
	s_mov_b32 m0, s22
	ds_read_b128 v[164:167], v242 offset:49152
	ds_read_b128 v[168:171], v242 offset:50176
	ds_read_b128 v[176:179], v242 offset:52224
	ds_read_b128 v[172:175], v242 offset:51200
	ds_read_b128 v[180:183], v242 offset:53248
	ds_read_b128 v[184:187], v242 offset:54272
	ds_read_b128 v[214:217], v242 offset:56320
	ds_read_b128 v[188:191], v242 offset:55296
	s_setprio 0
	global_load_lds_dwordx4 v[218:219], off
	s_add_i32 m0, s22, 0x2000
	s_add_u32 s22, s26, 0x2b0080
	v_lshl_add_u64 v[218:219], v[220:221], 0, s[84:85]
	s_addc_u32 s23, s27, 0
	s_add_i32 s26, s57, s41
	global_load_lds_dwordx4 v[218:219], off
	s_mov_b32 m0, s26
	s_nop 0
	global_load_lds_dwordx4 v2, s[22:23]
	s_add_i32 m0, s26, 0x2000
	s_nop 0
	global_load_lds_dwordx4 v204, s[22:23]
	s_cmpk_eq_i32 s55, 0xa8
	s_cbranch_scc0 .Ldefer_1700_peel
	v_lshl_add_u64 v[218:219], v[222:223], 0, s[84:85]
	s_mov_b32 m0, s46
	s_nop 0
	global_load_lds_dwordx4 v[218:219], off
	v_lshl_add_u64 v[218:219], v[224:225], 0, s[84:85]
	s_mov_b32 m0, s47
	s_nop 0
	global_load_lds_dwordx4 v[218:219], off

; #define PG8_STAGE(bufoff, gbase, voff) do { _Pragma("unroll") for (int _i = 0; _i < 2; ++_i) \
;         __builtin_amdgcn_global_load_lds((const unsigned*)((const char*)(gbase) + (voff)[_i]), (PG8_LAS unsigned*)(lds + (bufoff) + ldsw + _i * 8192), 16, 0, 0); } while (0)
; #define PG8_LDA(dst, b, h) do { _Pragma("unroll") for (int m = 0; m < 4; ++m) _Pragma("unroll") for (int k = 0; k < 2; ++k) dst[m][k] = *(const PG8_LAS bf16x8*)(lds + PG8_SA(b, h) + aoff + m * 2048 + k * 1024); } while (0)
; #define PG8_LDB(dst, b, h) do { _Pragma("unroll") for (int n = 0; n < 2; ++n) _Pragma("unroll") for (int k = 0; k < 2; ++k) dst[n][k] = *(const PG8_LAS bf16x8*)(lds + PG8_SB(b, h) + boff + n * 2048 + k * 1024); } while (0)
; #define PG8_WAIT_V(n) asm volatile("s_waitcnt vmcnt(" #n ")" ::: "memory")
; #define PG8_WAIT_L(n) asm volatile("s_waitcnt lgkmcnt(" #n ")" ::: "memory")
; #define PG8_BAR __builtin_amdgcn_s_barrier()
; #define PG8_SCHED __builtin_amdgcn_sched_barrier(0)
; template <class Epi, class Sched, bool ALIGN_EPI = false, bool SP2 = false, bool I8 = false>
; __device__ __forceinline__ void gemm_phase(PG8_LAS unsigned char* lds, const Gemm g, const Sched& S, const Epi& E) {
;     ...
;             if constexpr (SP2) {
;             PG8_LDB(B0, 0, 0); PG8_LDB(B1, 0, 1); PG8_SCHED; PG8_LDA(At, 0, 0); PG8_STAGE(PG8_SA(1, 1), a1 + hstep, voffA);
;             PG8_WAIT_V(8); PG8_WAIT_L(0); PG8_BAR; PG8_MMA(0, 0, At, B0); PG8_MMA(0, 1, At, B1); PG8_BAR; PG8_SCHED;
;             PG8_LDA(At, 0, 1); PG8_STAGE(PG8_SB(0, 0), b2, voffB); PG8_STAGE(PG8_SB(0, 1), b2 + hstep, voffB); PG8_STAGE(PG8_SA(0, 0), a2, voffA);
;             PG8_WAIT_V(8); PG8_WAIT_L(0); PG8_BAR; PG8_MMA(1, 0, At, B0); PG8_MMA(1, 1, At, B1); PG8_BAR; PG8_SCHED;
;             PG8_LDB(B0, 1, 0); PG8_LDB(B1, 1, 1); PG8_SCHED; PG8_LDA(At, 1, 0); PG8_STAGE(PG8_SA(0, 1), a2 + hstep, voffA);
;             PG8_WAIT_V(8); PG8_WAIT_L(0); PG8_BAR; PG8_MMA(0, 0, At, B0); PG8_MMA(0, 1, At, B1); PG8_BAR; PG8_SCHED;
;             PG8_LDA(At, 1, 1); PG8_STAGE(PG8_SB(1, 0), b3, voffB); PG8_STAGE(PG8_SB(1, 1), b3 + hstep, voffB); PG8_STAGE(PG8_SA(1, 0), a3, voffA);
;             PG8_WAIT_V(8); PG8_WAIT_L(0); PG8_BAR; PG8_MMA(1, 0, At, B0); PG8_MMA(1, 1, At, B1); PG8_BAR; PG8_SCHED;
.LBB0_1700:
	s_add_u32 s24, s22, 0x100
	s_addc_u32 s25, s23, 0
	s_add_i32 s56, 0, 0x10000
	s_cmpk_eq_i32 s55, 0xa8
	s_cselect_b32 s37, s13, s25
	s_cselect_b32 s36, s12, s24
	s_cselect_b32 s27, s21, s54
	s_cselect_b32 s26, s20, s53
	s_add_i32 s57, 0, 0x14000
	v_add_u32_e32 v144, s56, v240
	v_add_u32_e32 v160, s57, v240
	ds_read_b128 v[124:127], v144
	ds_read_b128 v[164:167], v242
	ds_read_b128 v[128:131], v144 offset:1024
	ds_read_b128 v[168:171], v242 offset:1024
	ds_read_b128 v[176:179], v242 offset:3072
	ds_read_b128 v[172:175], v242 offset:2048
	ds_read_b128 v[180:183], v242 offset:4096
	ds_read_b128 v[184:187], v242 offset:5120
	v_lshl_add_u64 v[218:219], v[222:223], 0, s[84:85]
	s_mov_b32 m0, s46
	s_nop 0
	global_load_lds_dwordx4 v[218:219], off
	v_lshl_add_u64 v[218:219], v[224:225], 0, s[84:85]
	s_mov_b32 m0, s47
	s_nop 0
	global_load_lds_dwordx4 v[218:219], off
	v_lshl_add_u64 v[218:219], s[22:23], 0, v[210:211]
	s_add_i32 m0, s42, 0xc000
	ds_read_b128 v[214:217], v242 offset:7168
	ds_read_b128 v[188:191], v242 offset:6144
	ds_read_b128 v[132:135], v144 offset:2048
	ds_read_b128 v[144:147], v144 offset:3072
	ds_read_b128 v[148:151], v160
	ds_read_b128 v[152:155], v160 offset:1024
	ds_read_b128 v[156:159], v160 offset:2048
	ds_read_b128 v[160:163], v160 offset:3072
	global_load_lds_dwordx4 v[218:219], off
	v_lshl_add_u64 v[218:219], s[22:23], 0, v[212:213]
	s_add_i32 m0, s42, 0xe000
	s_nop 0
	global_load_lds_dwordx4 v[218:219], off
	s_waitcnt vmcnt(8)
	s_waitcnt lgkmcnt(14)
	s_setprio 1
	s_barrier
	v_mfma_f32_16x16x32_bf16 v[140:143], v[124:127], v[164:167], v[140:143]
	s_waitcnt lgkmcnt(12)
	v_mfma_f32_16x16x32_bf16 v[140:143], v[128:131], v[168:171], v[140:143]
	s_waitcnt lgkmcnt(11)
	v_mfma_f32_16x16x32_bf16 v[112:115], v[128:131], v[176:179], v[112:115]
	s_waitcnt lgkmcnt(10)
	v_mfma_f32_16x16x32_bf16 v[112:115], v[124:127], v[172:175], v[112:115]
	s_waitcnt lgkmcnt(9)
	v_mfma_f32_16x16x32_bf16 v[96:99], v[124:127], v[180:183], v[96:99]
	s_waitcnt lgkmcnt(8)
	v_mfma_f32_16x16x32_bf16 v[96:99], v[128:131], v[184:187], v[96:99]
	s_waitcnt lgkmcnt(7)
	v_mfma_f32_16x16x32_bf16 v[80:83], v[128:131], v[214:217], v[80:83]
	s_waitcnt lgkmcnt(6)
	v_mfma_f32_16x16x32_bf16 v[80:83], v[124:127], v[188:191], v[80:83]
	s_waitcnt lgkmcnt(5)
	v_mfma_f32_16x16x32_bf16 v[76:79], v[132:135], v[188:191], v[76:79]
	s_waitcnt lgkmcnt(4)
	v_mfma_f32_16x16x32_bf16 v[76:79], v[144:147], v[214:217], v[76:79]
	v_mfma_f32_16x16x32_bf16 v[92:95], v[144:147], v[184:187], v[92:95]
	v_mfma_f32_16x16x32_bf16 v[92:95], v[132:135], v[180:183], v[92:95]
	v_mfma_f32_16x16x32_bf16 v[108:111], v[132:135], v[172:175], v[108:111]
	v_mfma_f32_16x16x32_bf16 v[108:111], v[144:147], v[176:179], v[108:111]
	v_mfma_f32_16x16x32_bf16 v[136:139], v[144:147], v[168:171], v[136:139]
	v_mfma_f32_16x16x32_bf16 v[136:139], v[132:135], v[164:167], v[136:139]
	s_waitcnt lgkmcnt(3)
	v_mfma_f32_16x16x32_bf16 v[120:123], v[148:151], v[164:167], v[120:123]
	s_waitcnt lgkmcnt(2)
	v_mfma_f32_16x16x32_bf16 v[120:123], v[152:155], v[168:171], v[120:123]
	v_mfma_f32_16x16x32_bf16 v[104:107], v[152:155], v[176:179], v[104:107]
	v_mfma_f32_16x16x32_bf16 v[104:107], v[148:151], v[172:175], v[104:107]
	v_mfma_f32_16x16x32_bf16 v[88:91], v[148:151], v[180:183], v[88:91]
	v_mfma_f32_16x16x32_bf16 v[88:91], v[152:155], v[184:187], v[88:91]
	v_mfma_f32_16x16x32_bf16 v[72:75], v[152:155], v[214:217], v[72:75]
	v_mfma_f32_16x16x32_bf16 v[72:75], v[148:151], v[188:191], v[72:75]
	s_waitcnt lgkmcnt(1)
	v_mfma_f32_16x16x32_bf16 v[68:71], v[156:159], v[188:191], v[68:71]
	s_waitcnt lgkmcnt(0)
	v_mfma_f32_16x16x32_bf16 v[68:71], v[160:163], v[214:217], v[68:71]
	v_mfma_f32_16x16x32_bf16 v[84:87], v[160:163], v[184:187], v[84:87]
	v_mfma_f32_16x16x32_bf16 v[84:87], v[156:159], v[180:183], v[84:87]
	v_mfma_f32_16x16x32_bf16 v[100:103], v[156:159], v[172:175], v[100:103]
	v_mfma_f32_16x16x32_bf16 v[100:103], v[160:163], v[176:179], v[100:103]
	v_mfma_f32_16x16x32_bf16 v[116:119], v[160:163], v[168:171], v[116:119]
	v_mfma_f32_16x16x32_bf16 v[116:119], v[156:159], v[164:167], v[116:119]
	s_barrier
	s_add_i32 s22, s56, s41
	v_lshl_add_u64 v[218:219], s[26:27], 0, v[2:3]
	s_mov_b32 m0, s22
	ds_read_b128 v[164:167], v242 offset:16384
	ds_read_b128 v[168:171], v242 offset:17408
	ds_read_b128 v[176:179], v242 offset:19456
	ds_read_b128 v[172:175], v242 offset:18432
	ds_read_b128 v[180:183], v242 offset:20480
	ds_read_b128 v[184:187], v242 offset:21504
	ds_read_b128 v[214:217], v242 offset:23552
	ds_read_b128 v[188:191], v242 offset:22528
	s_setprio 0
	global_load_lds_dwordx4 v[218:219], off
	s_add_i32 m0, s22, 0x2000
	s_add_u32 s22, s26, 0x2b0000
	v_lshl_add_u64 v[220:221], s[26:27], 0, v[204:205]
	s_addc_u32 s23, s27, 0
	s_add_i32 s56, s57, s41
	global_load_lds_dwordx4 v[220:221], off
	s_mov_b32 m0, s56
	v_lshl_add_u64 v[224:225], s[36:37], 0, v[206:207]
	global_load_lds_dwordx4 v2, s[22:23]
	s_add_i32 m0, s56, 0x2000
	s_nop 0
	global_load_lds_dwordx4 v204, s[22:23]
	v_lshl_add_u64 v[222:223], s[36:37], 0, v[208:209]
	s_waitcnt vmcnt(6)
	s_waitcnt lgkmcnt(7)
	s_setprio 1
	s_barrier
; #define PG8_STAGE(bufoff, gbase, voff) do { _Pragma("unroll") for (int _i = 0; _i < 2; ++_i) \
;         __builtin_amdgcn_global_load_lds((const unsigned*)((const char*)(gbase) + (voff)[_i]), (PG8_LAS unsigned*)(lds + (bufoff) + ldsw + _i * 8192), 16, 0, 0); } while (0)
; #define PG8_LDA(dst, b, h) do { _Pragma("unroll") for (int m = 0; m < 4; ++m) _Pragma("unroll") for (int k = 0; k < 2; ++k) dst[m][k] = *(const PG8_LAS bf16x8*)(lds + PG8_SA(b, h) + aoff + m * 2048 + k * 1024); } while (0)
; #define PG8_LDB(dst, b, h) do { _Pragma("unroll") for (int n = 0; n < 2; ++n) _Pragma("unroll") for (int k = 0; k < 2; ++k) dst[n][k] = *(const PG8_LAS bf16x8*)(lds + PG8_SB(b, h) + boff + n * 2048 + k * 1024); } while (0)
; #define PG8_WAIT_V(n) asm volatile("s_waitcnt vmcnt(" #n ")" ::: "memory")
; #define PG8_WAIT_L(n) asm volatile("s_waitcnt lgkmcnt(" #n ")" ::: "memory")
; #define PG8_BAR __builtin_amdgcn_s_barrier()
; #define PG8_SCHED __builtin_amdgcn_sched_barrier(0)
; template <class Epi, class Sched, bool ALIGN_EPI = false, bool SP2 = false, bool I8 = false>
; __device__ __forceinline__ void gemm_phase(PG8_LAS unsigned char* lds, const Gemm g, const Sched& S, const Epi& E) {
;     ...
;             if constexpr (SP2) {
;             PG8_LDB(B0, 0, 0); PG8_LDB(B1, 0, 1); PG8_SCHED; PG8_LDA(At, 0, 0); PG8_STAGE(PG8_SA(1, 1), a1 + hstep, voffA);
;             PG8_WAIT_V(8); PG8_WAIT_L(0); PG8_BAR; PG8_MMA(0, 0, At, B0); PG8_MMA(0, 1, At, B1); PG8_BAR; PG8_SCHED;
;             PG8_LDA(At, 0, 1); PG8_STAGE(PG8_SB(0, 0), b2, voffB); PG8_STAGE(PG8_SB(0, 1), b2 + hstep, voffB); PG8_STAGE(PG8_SA(0, 0), a2, voffA);
;             PG8_WAIT_V(8); PG8_WAIT_L(0); PG8_BAR; PG8_MMA(1, 0, At, B0); PG8_MMA(1, 1, At, B1); PG8_BAR; PG8_SCHED;
;             PG8_LDB(B0, 1, 0); PG8_LDB(B1, 1, 1); PG8_SCHED; PG8_LDA(At, 1, 0); PG8_STAGE(PG8_SA(0, 1), a2 + hstep, voffA);
;             PG8_WAIT_V(8); PG8_WAIT_L(0); PG8_BAR; PG8_MMA(0, 0, At, B0); PG8_MMA(0, 1, At, B1); PG8_BAR; PG8_SCHED;
;             PG8_LDA(At, 1, 1); PG8_STAGE(PG8_SB(1, 0), b3, voffB); PG8_STAGE(PG8_SB(1, 1), b3 + hstep, voffB); PG8_STAGE(PG8_SA(1, 0), a3, voffA);
;             PG8_WAIT_V(8); PG8_WAIT_L(0); PG8_BAR; PG8_MMA(1, 0, At, B0); PG8_MMA(1, 1, At, B1); PG8_BAR; PG8_SCHED;
	v_mfma_f32_16x16x32_bf16 v[64:67], v[124:127], v[164:167], v[64:67]
	s_waitcnt lgkmcnt(6)
	v_mfma_f32_16x16x32_bf16 v[64:67], v[128:131], v[168:171], v[64:67]
	s_waitcnt lgkmcnt(5)
	v_mfma_f32_16x16x32_bf16 v[48:51], v[128:131], v[176:179], v[48:51]
	s_waitcnt lgkmcnt(4)
	v_mfma_f32_16x16x32_bf16 v[48:51], v[124:127], v[172:175], v[48:51]
	s_waitcnt lgkmcnt(3)
	v_mfma_f32_16x16x32_bf16 v[32:35], v[124:127], v[180:183], v[32:35]
	s_waitcnt lgkmcnt(2)
	v_mfma_f32_16x16x32_bf16 v[32:35], v[128:131], v[184:187], v[32:35]
	s_waitcnt lgkmcnt(1)
	v_mfma_f32_16x16x32_bf16 v[16:19], v[128:131], v[214:217], v[16:19]
	s_waitcnt lgkmcnt(0)
	v_mfma_f32_16x16x32_bf16 v[16:19], v[124:127], v[188:191], v[16:19]
	v_mfma_f32_16x16x32_bf16 v[12:15], v[132:135], v[188:191], v[12:15]
	v_mfma_f32_16x16x32_bf16 v[12:15], v[144:147], v[214:217], v[12:15]
	v_mfma_f32_16x16x32_bf16 v[28:31], v[144:147], v[184:187], v[28:31]
	v_mfma_f32_16x16x32_bf16 v[28:31], v[132:135], v[180:183], v[28:31]
	v_mfma_f32_16x16x32_bf16 v[44:47], v[132:135], v[172:175], v[44:47]
	v_mfma_f32_16x16x32_bf16 v[44:47], v[144:147], v[176:179], v[44:47]
	v_mfma_f32_16x16x32_bf16 v[60:63], v[144:147], v[168:171], v[60:63]
	v_mfma_f32_16x16x32_bf16 v[60:63], v[132:135], v[164:167], v[60:63]
	v_mfma_f32_16x16x32_bf16 v[56:59], v[148:151], v[164:167], v[56:59]
	v_mfma_f32_16x16x32_bf16 v[56:59], v[152:155], v[168:171], v[56:59]
	v_mfma_f32_16x16x32_bf16 v[40:43], v[152:155], v[176:179], v[40:43]
	v_mfma_f32_16x16x32_bf16 v[40:43], v[148:151], v[172:175], v[40:43]
	v_mfma_f32_16x16x32_bf16 v[24:27], v[148:151], v[180:183], v[24:27]
	v_mfma_f32_16x16x32_bf16 v[24:27], v[152:155], v[184:187], v[24:27]
	v_mfma_f32_16x16x32_bf16 v[8:11], v[152:155], v[214:217], v[8:11]
	v_mfma_f32_16x16x32_bf16 v[8:11], v[148:151], v[188:191], v[8:11]
	v_mfma_f32_16x16x32_bf16 v[4:7], v[156:159], v[188:191], v[4:7]
	v_mfma_f32_16x16x32_bf16 v[4:7], v[160:163], v[214:217], v[4:7]
	v_mfma_f32_16x16x32_bf16 v[20:23], v[160:163], v[184:187], v[20:23]
	v_mfma_f32_16x16x32_bf16 v[20:23], v[156:159], v[180:183], v[20:23]
	v_mfma_f32_16x16x32_bf16 v[36:39], v[156:159], v[172:175], v[36:39]
	v_mfma_f32_16x16x32_bf16 v[36:39], v[160:163], v[176:179], v[36:39]
	v_mfma_f32_16x16x32_bf16 v[52:55], v[160:163], v[168:171], v[52:55]
	v_mfma_f32_16x16x32_bf16 v[52:55], v[156:159], v[164:167], v[52:55]
	s_barrier
	s_mov_b32 m0, s42
	s_nop 0
	global_load_lds_dwordx4 v[222:223], off
	s_mov_b32 m0, s43
	s_nop 0
	global_load_lds_dwordx4 v[224:225], off
	s_add_i32 s56, 0, 0x18000
	s_add_i32 s57, 0, 0x1c000
	v_add_u32_e32 v144, s56, v240
	v_add_u32_e32 v160, s57, v240
	ds_read_b128 v[124:127], v144
	ds_read_b128 v[164:167], v242 offset:32768
	ds_read_b128 v[128:131], v144 offset:1024
	ds_read_b128 v[168:171], v242 offset:33792
	ds_read_b128 v[176:179], v242 offset:35840
	ds_read_b128 v[172:175], v242 offset:34816
	ds_read_b128 v[180:183], v242 offset:36864
	ds_read_b128 v[184:187], v242 offset:37888
	s_add_u32 s22, s36, 0x2b0000
	s_addc_u32 s23, s37, 0
	s_mov_b32 m0, s44
	ds_read_b128 v[214:217], v242 offset:39936
	ds_read_b128 v[188:191], v242 offset:38912
	ds_read_b128 v[132:135], v144 offset:2048
	ds_read_b128 v[144:147], v144 offset:3072
	ds_read_b128 v[148:151], v160
	ds_read_b128 v[152:155], v160 offset:1024
	ds_read_b128 v[156:159], v160 offset:2048
	ds_read_b128 v[160:163], v160 offset:3072
	s_setprio 0
	global_load_lds_dwordx4 v208, s[22:23]
	s_mov_b32 m0, s45
	s_nop 0
	global_load_lds_dwordx4 v206, s[22:23]
	s_waitcnt vmcnt(8)
	s_waitcnt lgkmcnt(14)
	s_setprio 1
	s_barrier
; #define PG8_STAGE(bufoff, gbase, voff) do { _Pragma("unroll") for (int _i = 0; _i < 2; ++_i) \
;         __builtin_amdgcn_global_load_lds((const unsigned*)((const char*)(gbase) + (voff)[_i]), (PG8_LAS unsigned*)(lds + (bufoff) + ldsw + _i * 8192), 16, 0, 0); } while (0)
; #define PG8_LDA(dst, b, h) do { _Pragma("unroll") for (int m = 0; m < 4; ++m) _Pragma("unroll") for (int k = 0; k < 2; ++k) dst[m][k] = *(const PG8_LAS bf16x8*)(lds + PG8_SA(b, h) + aoff + m * 2048 + k * 1024); } while (0)
; #define PG8_LDB(dst, b, h) do { _Pragma("unroll") for (int n = 0; n < 2; ++n) _Pragma("unroll") for (int k = 0; k < 2; ++k) dst[n][k] = *(const PG8_LAS bf16x8*)(lds + PG8_SB(b, h) + boff + n * 2048 + k * 1024); } while (0)
; #define PG8_WAIT_V(n) asm volatile("s_waitcnt vmcnt(" #n ")" ::: "memory")
; #define PG8_WAIT_L(n) asm volatile("s_waitcnt lgkmcnt(" #n ")" ::: "memory")
; #define PG8_BAR __builtin_amdgcn_s_barrier()
; #define PG8_SCHED __builtin_amdgcn_sched_barrier(0)
; template <class Epi, class Sched, bool ALIGN_EPI = false, bool SP2 = false, bool I8 = false>
; __device__ __forceinline__ void gemm_phase(PG8_LAS unsigned char* lds, const Gemm g, const Sched& S, const Epi& E) {
;     ...
;             if constexpr (SP2) {
;             PG8_LDB(B0, 0, 0); PG8_LDB(B1, 0, 1); PG8_SCHED; PG8_LDA(At, 0, 0); PG8_STAGE(PG8_SA(1, 1), a1 + hstep, voffA);
;             PG8_WAIT_V(8); PG8_WAIT_L(0); PG8_BAR; PG8_MMA(0, 0, At, B0); PG8_MMA(0, 1, At, B1); PG8_BAR; PG8_SCHED;
;             PG8_LDA(At, 0, 1); PG8_STAGE(PG8_SB(0, 0), b2, voffB); PG8_STAGE(PG8_SB(0, 1), b2 + hstep, voffB); PG8_STAGE(PG8_SA(0, 0), a2, voffA);
;             PG8_WAIT_V(8); PG8_WAIT_L(0); PG8_BAR; PG8_MMA(1, 0, At, B0); PG8_MMA(1, 1, At, B1); PG8_BAR; PG8_SCHED;
;             PG8_LDB(B0, 1, 0); PG8_LDB(B1, 1, 1); PG8_SCHED; PG8_LDA(At, 1, 0); PG8_STAGE(PG8_SA(0, 1), a2 + hstep, voffA);
;             PG8_WAIT_V(8); PG8_WAIT_L(0); PG8_BAR; PG8_MMA(0, 0, At, B0); PG8_MMA(0, 1, At, B1); PG8_BAR; PG8_SCHED;
;             PG8_LDA(At, 1, 1); PG8_STAGE(PG8_SB(1, 0), b3, voffB); PG8_STAGE(PG8_SB(1, 1), b3 + hstep, voffB); PG8_STAGE(PG8_SA(1, 0), a3, voffA);
;             PG8_WAIT_V(8); PG8_WAIT_L(0); PG8_BAR; PG8_MMA(1, 0, At, B0); PG8_MMA(1, 1, At, B1); PG8_BAR; PG8_SCHED;
	v_mfma_f32_16x16x32_bf16 v[140:143], v[124:127], v[164:167], v[140:143]
	s_waitcnt lgkmcnt(12)
	v_mfma_f32_16x16x32_bf16 v[140:143], v[128:131], v[168:171], v[140:143]
	s_waitcnt lgkmcnt(11)
	v_mfma_f32_16x16x32_bf16 v[112:115], v[128:131], v[176:179], v[112:115]
	s_waitcnt lgkmcnt(10)
	v_mfma_f32_16x16x32_bf16 v[112:115], v[124:127], v[172:175], v[112:115]
	s_waitcnt lgkmcnt(9)
	v_mfma_f32_16x16x32_bf16 v[96:99], v[124:127], v[180:183], v[96:99]
	s_waitcnt lgkmcnt(8)
	v_mfma_f32_16x16x32_bf16 v[96:99], v[128:131], v[184:187], v[96:99]
	s_waitcnt lgkmcnt(7)
	v_mfma_f32_16x16x32_bf16 v[80:83], v[128:131], v[214:217], v[80:83]
	s_waitcnt lgkmcnt(6)
	v_mfma_f32_16x16x32_bf16 v[80:83], v[124:127], v[188:191], v[80:83]
	s_waitcnt lgkmcnt(5)
	v_mfma_f32_16x16x32_bf16 v[76:79], v[132:135], v[188:191], v[76:79]
	s_waitcnt lgkmcnt(4)
	v_mfma_f32_16x16x32_bf16 v[76:79], v[144:147], v[214:217], v[76:79]
	v_mfma_f32_16x16x32_bf16 v[92:95], v[144:147], v[184:187], v[92:95]
	v_mfma_f32_16x16x32_bf16 v[92:95], v[132:135], v[180:183], v[92:95]
	v_mfma_f32_16x16x32_bf16 v[108:111], v[132:135], v[172:175], v[108:111]
	v_mfma_f32_16x16x32_bf16 v[108:111], v[144:147], v[176:179], v[108:111]
	v_mfma_f32_16x16x32_bf16 v[136:139], v[144:147], v[168:171], v[136:139]
	v_mfma_f32_16x16x32_bf16 v[136:139], v[132:135], v[164:167], v[136:139]
	s_waitcnt lgkmcnt(3)
	v_mfma_f32_16x16x32_bf16 v[120:123], v[148:151], v[164:167], v[120:123]
	s_waitcnt lgkmcnt(2)
	v_mfma_f32_16x16x32_bf16 v[120:123], v[152:155], v[168:171], v[120:123]
	v_mfma_f32_16x16x32_bf16 v[104:107], v[152:155], v[176:179], v[104:107]
	v_mfma_f32_16x16x32_bf16 v[104:107], v[148:151], v[172:175], v[104:107]
	v_mfma_f32_16x16x32_bf16 v[88:91], v[148:151], v[180:183], v[88:91]
	v_mfma_f32_16x16x32_bf16 v[88:91], v[152:155], v[184:187], v[88:91]
	v_mfma_f32_16x16x32_bf16 v[72:75], v[152:155], v[214:217], v[72:75]
	v_mfma_f32_16x16x32_bf16 v[72:75], v[148:151], v[188:191], v[72:75]
	s_waitcnt lgkmcnt(1)
	v_mfma_f32_16x16x32_bf16 v[68:71], v[156:159], v[188:191], v[68:71]
	s_waitcnt lgkmcnt(0)
	v_mfma_f32_16x16x32_bf16 v[68:71], v[160:163], v[214:217], v[68:71]
	v_mfma_f32_16x16x32_bf16 v[84:87], v[160:163], v[184:187], v[84:87]
	v_mfma_f32_16x16x32_bf16 v[84:87], v[156:159], v[180:183], v[84:87]
	v_mfma_f32_16x16x32_bf16 v[100:103], v[156:159], v[172:175], v[100:103]
	v_mfma_f32_16x16x32_bf16 v[100:103], v[160:163], v[176:179], v[100:103]
	v_mfma_f32_16x16x32_bf16 v[116:119], v[160:163], v[168:171], v[116:119]
	v_mfma_f32_16x16x32_bf16 v[116:119], v[156:159], v[164:167], v[116:119]
	s_barrier
	s_add_i32 s22, s56, s41
	v_lshl_add_u64 v[218:219], v[218:219], 0, s[84:85]
	s_mov_b32 m0, s22
	ds_read_b128 v[164:167], v242 offset:49152
	ds_read_b128 v[168:171], v242 offset:50176
	ds_read_b128 v[176:179], v242 offset:52224
	ds_read_b128 v[172:175], v242 offset:51200
	ds_read_b128 v[180:183], v242 offset:53248
	ds_read_b128 v[184:187], v242 offset:54272
	ds_read_b128 v[214:217], v242 offset:56320
	ds_read_b128 v[188:191], v242 offset:55296
	s_setprio 0
	global_load_lds_dwordx4 v[218:219], off
	s_add_i32 m0, s22, 0x2000
	s_add_u32 s22, s26, 0x2b0080
	v_lshl_add_u64 v[218:219], v[220:221], 0, s[84:85]
	s_addc_u32 s23, s27, 0
	s_add_i32 s26, s57, s41
	global_load_lds_dwordx4 v[218:219], off
	s_mov_b32 m0, s26
	s_nop 0
	global_load_lds_dwordx4 v2, s[22:23]
	s_add_i32 m0, s26, 0x2000
	s_nop 0
	global_load_lds_dwordx4 v204, s[22:23]
	s_cmpk_eq_i32 s55, 0xa8
	s_cbranch_scc0 .Ldefer_1700_body
	v_lshl_add_u64 v[218:219], v[222:223], 0, s[84:85]
	s_mov_b32 m0, s46
	s_nop 0
	global_load_lds_dwordx4 v[218:219], off
	v_lshl_add_u64 v[218:219], v[224:225], 0, s[84:85]
	s_mov_b32 m0, s47
	s_nop 0
	global_load_lds_dwordx4 v[218:219], off

; #define PG8_STAGE(bufoff, gbase, voff) do { _Pragma("unroll") for (int _i = 0; _i < 2; ++_i) \
;         __builtin_amdgcn_global_load_lds((const unsigned*)((const char*)(gbase) + (voff)[_i]), (PG8_LAS unsigned*)(lds + (bufoff) + ldsw + _i * 8192), 16, 0, 0); } while (0)
; #define PG8_LDA(dst, b, h) do { _Pragma("unroll") for (int m = 0; m < 4; ++m) _Pragma("unroll") for (int k = 0; k < 2; ++k) dst[m][k] = *(const PG8_LAS bf16x8*)(lds + PG8_SA(b, h) + aoff + m * 2048 + k * 1024); } while (0)
; template <class Epi, class Sched, bool ALIGN_EPI = false, bool SP2 = false, bool I8 = false>
; __device__ __forceinline__ void gemm_phase(PG8_LAS unsigned char* lds, const Gemm g, const Sched& S, const Epi& E) {
;     ...
;         const bool has_next = S.next(ui + 1, nxt);
;         const char* nA = has_next ? (const char*)g.A + (size_t)nxt.pm * tstep : cA; const char* nB = has_next ? (const char*)g.Bt + (size_t)nxt.pn * tstep : cB;
;         for (int t = 0; t < nt; t += 2) {
;             const bool last = (t == nt - 2);
;             const char* a1 = cA + (size_t)(t + 1) * kstep;
;             const char* a2 = last ? nA : cA + (size_t)(t + 2) * kstep; const char* b2 = last ? nB : cB + (size_t)(t + 2) * kstep;
;             const char* a3 = a2 + kstep; const char* b3 = b2 + kstep;
;             if (last && has_next) S.a_ready(nxt);
;             if constexpr (SP2) {
;             PG8_LDB(B0, 0, 0); PG8_LDB(B1, 0, 1); PG8_SCHED; PG8_LDA(At, 0, 0); PG8_STAGE(PG8_SA(1, 1), a1 + hstep, voffA);
;             PG8_WAIT_V(8); PG8_WAIT_L(0); PG8_BAR; PG8_MMA(0, 0, At, B0); PG8_MMA(0, 1, At, B1); PG8_BAR; PG8_SCHED;
;             PG8_LDA(At, 0, 1); PG8_STAGE(PG8_SB(0, 0), b2, voffB); PG8_STAGE(PG8_SB(0, 1), b2 + hstep, voffB); PG8_STAGE(PG8_SA(0, 0), a2, voffA);
;             PG8_WAIT_V(8); PG8_WAIT_L(0); PG8_BAR; PG8_MMA(1, 0, At, B0); PG8_MMA(1, 1, At, B1); PG8_BAR; PG8_SCHED;
;             PG8_LDB(B0, 1, 0); PG8_LDB(B1, 1, 1); PG8_SCHED; PG8_LDA(At, 1, 0); PG8_STAGE(PG8_SA(0, 1), a2 + hstep, voffA);
;             PG8_WAIT_V(8); PG8_WAIT_L(0); PG8_BAR; PG8_MMA(0, 0, At, B0); PG8_MMA(0, 1, At, B1); PG8_BAR; PG8_SCHED;
;             PG8_LDA(At, 1, 1); PG8_STAGE(PG8_SB(1, 0), b3, voffB); PG8_STAGE(PG8_SB(1, 1), b3 + hstep, voffB); PG8_STAGE(PG8_SA(1, 0), a3, voffA);
;             PG8_WAIT_V(8); PG8_WAIT_L(0); PG8_BAR; PG8_MMA(1, 0, At, B0); PG8_MMA(1, 1, At, B1); PG8_BAR; PG8_SCHED;
.LBB0_1842:
	s_ashr_i32 s45, s44, 31
	s_lshl_b64 s[34:35], s[44:45], 20
	s_add_u32 s50, s47, s34
	s_addc_u32 s51, s52, s35
	s_and_b64 s[34:35], s[8:9], exec
	s_cselect_b32 s11, s51, s55
	s_cselect_b32 s13, s50, s54
	s_ashr_i32 s49, s48, 31
	s_lshl_b64 s[34:35], s[48:49], 20
	s_add_u32 s56, s53, s34
	s_addc_u32 s57, s64, s35
	s_and_b64 s[34:35], s[8:9], exec
	s_cselect_b32 s34, s57, s59
	s_cselect_b32 s35, s56, s58
	s_add_u32 s54, s54, 0x80080
	s_addc_u32 s55, s55, 0
	s_add_u32 s45, s58, 0x100
	s_addc_u32 s49, s59, 0
	s_mov_b32 s86, -2
	s_waitcnt lgkmcnt(0)
	s_add_u32 s58, s54, 0xfff80080
	s_addc_u32 s59, s55, -1
	s_add_i32 s87, 0, 0x10000
	s_cmp_eq_u32 s86, 28
	s_cselect_b32 s61, s11, s59
	s_cselect_b32 s60, s13, s58
	s_cselect_b32 s59, s34, s49
	s_cselect_b32 s58, s35, s45
	s_add_i32 vcc_lo, 0, 0x14000
	v_add_u32_e32 v40, s87, v217
	v_add_u32_e32 v160, vcc_lo, v217
	ds_read_b128 v[28:31], v40
	ds_read_b128 v[164:167], v219
	ds_read_b128 v[32:35], v40 offset:1024
	ds_read_b128 v[168:171], v219 offset:1024
	ds_read_b128 v[176:179], v219 offset:3072
	ds_read_b128 v[172:175], v219 offset:2048
	ds_read_b128 v[204:207], v219 offset:4096
	ds_read_b128 v[208:211], v219 offset:5120
	s_add_i32 m0, s65, 0xc000
	ds_read_b128 v[220:223], v219 offset:7168
	ds_read_b128 v[212:215], v219 offset:6144
	ds_read_b128 v[36:39], v40 offset:2048
	ds_read_b128 v[40:43], v40 offset:3072
	ds_read_b128 v[140:143], v160
	ds_read_b128 v[144:147], v160 offset:1024
	ds_read_b128 v[156:159], v160 offset:2048
	ds_read_b128 v[160:163], v160 offset:3072
	global_load_lds_dwordx4 v186, s[54:55]
	s_add_i32 m0, s65, 0xe000
	s_nop 0
	global_load_lds_dwordx4 v188, s[54:55]
	s_waitcnt vmcnt(8)
	s_waitcnt lgkmcnt(14)
	s_setprio 1
	s_barrier
	v_mfma_i32_16x16x64_i8 v[152:155], v[28:31], v[164:167], 0
	s_waitcnt lgkmcnt(12)
	v_mfma_i32_16x16x64_i8 v[152:155], v[32:35], v[168:171], v[152:155]
	s_waitcnt lgkmcnt(11)
	v_mfma_i32_16x16x64_i8 v[128:131], v[32:35], v[176:179], 0
	s_waitcnt lgkmcnt(10)
	v_mfma_i32_16x16x64_i8 v[128:131], v[28:31], v[172:175], v[128:131]
	s_waitcnt lgkmcnt(9)
	v_mfma_i32_16x16x64_i8 v[112:115], v[28:31], v[204:207], 0
	s_waitcnt lgkmcnt(8)
	v_mfma_i32_16x16x64_i8 v[112:115], v[32:35], v[208:211], v[112:115]
	s_waitcnt lgkmcnt(7)
	v_mfma_i32_16x16x64_i8 v[96:99], v[32:35], v[220:223], 0
	s_waitcnt lgkmcnt(6)
	v_mfma_i32_16x16x64_i8 v[96:99], v[28:31], v[212:215], v[96:99]
	s_waitcnt lgkmcnt(5)
	v_mfma_i32_16x16x64_i8 v[92:95], v[36:39], v[212:215], 0
	s_waitcnt lgkmcnt(4)
	v_mfma_i32_16x16x64_i8 v[92:95], v[40:43], v[220:223], v[92:95]
	v_mfma_i32_16x16x64_i8 v[108:111], v[40:43], v[208:211], 0
	v_mfma_i32_16x16x64_i8 v[108:111], v[36:39], v[204:207], v[108:111]
	v_mfma_i32_16x16x64_i8 v[124:127], v[36:39], v[172:175], 0
	v_mfma_i32_16x16x64_i8 v[124:127], v[40:43], v[176:179], v[124:127]
	v_mfma_i32_16x16x64_i8 v[148:151], v[40:43], v[168:171], 0
	v_mfma_i32_16x16x64_i8 v[148:151], v[36:39], v[164:167], v[148:151]
	s_waitcnt lgkmcnt(3)
	v_mfma_i32_16x16x64_i8 v[136:139], v[140:143], v[164:167], 0
	s_waitcnt lgkmcnt(2)
	v_mfma_i32_16x16x64_i8 v[136:139], v[144:147], v[168:171], v[136:139]
	v_mfma_i32_16x16x64_i8 v[120:123], v[144:147], v[176:179], 0
	v_mfma_i32_16x16x64_i8 v[120:123], v[140:143], v[172:175], v[120:123]
	v_mfma_i32_16x16x64_i8 v[104:107], v[140:143], v[204:207], 0
	v_mfma_i32_16x16x64_i8 v[104:107], v[144:147], v[208:211], v[104:107]
	v_mfma_i32_16x16x64_i8 v[88:91], v[144:147], v[220:223], 0
	v_mfma_i32_16x16x64_i8 v[88:91], v[140:143], v[212:215], v[88:91]
	s_waitcnt lgkmcnt(1)
	v_mfma_i32_16x16x64_i8 v[84:87], v[156:159], v[212:215], 0
	s_waitcnt lgkmcnt(0)
	v_mfma_i32_16x16x64_i8 v[84:87], v[160:163], v[220:223], v[84:87]
	v_mfma_i32_16x16x64_i8 v[100:103], v[160:163], v[208:211], 0
	v_mfma_i32_16x16x64_i8 v[100:103], v[156:159], v[204:207], v[100:103]
	v_mfma_i32_16x16x64_i8 v[116:119], v[156:159], v[172:175], 0
	v_mfma_i32_16x16x64_i8 v[116:119], v[160:163], v[176:179], v[116:119]
	v_mfma_i32_16x16x64_i8 v[132:135], v[160:163], v[168:171], 0
	v_mfma_i32_16x16x64_i8 v[132:135], v[156:159], v[164:167], v[132:135]
	s_barrier
	s_add_i32 s87, s87, s46
	v_lshl_add_u64 v[190:191], s[58:59], 0, v[2:3]
	s_mov_b32 m0, s87
	ds_read_b128 v[164:167], v219 offset:16384
	ds_read_b128 v[168:171], v219 offset:17408
	ds_read_b128 v[176:179], v219 offset:19456
	ds_read_b128 v[172:175], v219 offset:18432
	ds_read_b128 v[204:207], v219 offset:20480
	ds_read_b128 v[208:211], v219 offset:21504
	ds_read_b128 v[220:223], v219 offset:23552
	ds_read_b128 v[212:215], v219 offset:22528
	s_setprio 0
	global_load_lds_dwordx4 v[190:191], off
	s_add_i32 m0, s87, 0x2000
	s_add_u32 s96, s58, 0x80000
	v_lshl_add_u64 v[224:225], s[58:59], 0, v[184:185]
	s_addc_u32 s97, s59, 0
	s_add_i32 s87, vcc_lo, s46
	global_load_lds_dwordx4 v[224:225], off
	s_mov_b32 m0, s87
	v_lshl_add_u64 v[228:229], s[60:61], 0, v[182:183]
	global_load_lds_dwordx4 v2, s[96:97]
	s_add_i32 m0, s87, 0x2000
	s_nop 0
	global_load_lds_dwordx4 v184, s[96:97]
	v_lshl_add_u64 v[226:227], s[60:61], 0, v[180:181]
	s_waitcnt vmcnt(6)
	s_waitcnt lgkmcnt(7)
	s_setprio 1
	s_barrier
; #define PG8_STAGE(bufoff, gbase, voff) do { _Pragma("unroll") for (int _i = 0; _i < 2; ++_i) \
;         __builtin_amdgcn_global_load_lds((const unsigned*)((const char*)(gbase) + (voff)[_i]), (PG8_LAS unsigned*)(lds + (bufoff) + ldsw + _i * 8192), 16, 0, 0); } while (0)
; #define PG8_LDA(dst, b, h) do { _Pragma("unroll") for (int m = 0; m < 4; ++m) _Pragma("unroll") for (int k = 0; k < 2; ++k) dst[m][k] = *(const PG8_LAS bf16x8*)(lds + PG8_SA(b, h) + aoff + m * 2048 + k * 1024); } while (0)
; #define PG8_LDB(dst, b, h) do { _Pragma("unroll") for (int n = 0; n < 2; ++n) _Pragma("unroll") for (int k = 0; k < 2; ++k) dst[n][k] = *(const PG8_LAS bf16x8*)(lds + PG8_SB(b, h) + boff + n * 2048 + k * 1024); } while (0)
; #define PG8_WAIT_V(n) asm volatile("s_waitcnt vmcnt(" #n ")" ::: "memory")
; #define PG8_WAIT_L(n) asm volatile("s_waitcnt lgkmcnt(" #n ")" ::: "memory")
; #define PG8_BAR __builtin_amdgcn_s_barrier()
; #define PG8_SCHED __builtin_amdgcn_sched_barrier(0)
; template <class Epi, class Sched, bool ALIGN_EPI = false, bool SP2 = false, bool I8 = false>
; __device__ __forceinline__ void gemm_phase(PG8_LAS unsigned char* lds, const Gemm g, const Sched& S, const Epi& E) {
;     ...
;             if constexpr (SP2) {
;             PG8_LDB(B0, 0, 0); PG8_LDB(B1, 0, 1); PG8_SCHED; PG8_LDA(At, 0, 0); PG8_STAGE(PG8_SA(1, 1), a1 + hstep, voffA);
;             PG8_WAIT_V(8); PG8_WAIT_L(0); PG8_BAR; PG8_MMA(0, 0, At, B0); PG8_MMA(0, 1, At, B1); PG8_BAR; PG8_SCHED;
;             PG8_LDA(At, 0, 1); PG8_STAGE(PG8_SB(0, 0), b2, voffB); PG8_STAGE(PG8_SB(0, 1), b2 + hstep, voffB); PG8_STAGE(PG8_SA(0, 0), a2, voffA);
;             PG8_WAIT_V(8); PG8_WAIT_L(0); PG8_BAR; PG8_MMA(1, 0, At, B0); PG8_MMA(1, 1, At, B1); PG8_BAR; PG8_SCHED;
;             PG8_LDB(B0, 1, 0); PG8_LDB(B1, 1, 1); PG8_SCHED; PG8_LDA(At, 1, 0); PG8_STAGE(PG8_SA(0, 1), a2 + hstep, voffA);
;             PG8_WAIT_V(8); PG8_WAIT_L(0); PG8_BAR; PG8_MMA(0, 0, At, B0); PG8_MMA(0, 1, At, B1); PG8_BAR; PG8_SCHED;
;             PG8_LDA(At, 1, 1); PG8_STAGE(PG8_SB(1, 0), b3, voffB); PG8_STAGE(PG8_SB(1, 1), b3 + hstep, voffB); PG8_STAGE(PG8_SA(1, 0), a3, voffA);
;             PG8_WAIT_V(8); PG8_WAIT_L(0); PG8_BAR; PG8_MMA(1, 0, At, B0); PG8_MMA(1, 1, At, B1); PG8_BAR; PG8_SCHED;
	v_mfma_i32_16x16x64_i8 v[80:83], v[28:31], v[164:167], 0
	s_waitcnt lgkmcnt(6)
	v_mfma_i32_16x16x64_i8 v[80:83], v[32:35], v[168:171], v[80:83]
	s_waitcnt lgkmcnt(5)
	v_mfma_i32_16x16x64_i8 v[64:67], v[32:35], v[176:179], 0
	s_waitcnt lgkmcnt(4)
	v_mfma_i32_16x16x64_i8 v[64:67], v[28:31], v[172:175], v[64:67]
	s_waitcnt lgkmcnt(3)
	v_mfma_i32_16x16x64_i8 v[48:51], v[28:31], v[204:207], 0
	s_waitcnt lgkmcnt(2)
	v_mfma_i32_16x16x64_i8 v[48:51], v[32:35], v[208:211], v[48:51]
	s_waitcnt lgkmcnt(1)
	v_mfma_i32_16x16x64_i8 v[16:19], v[32:35], v[220:223], 0
	s_waitcnt lgkmcnt(0)
	v_mfma_i32_16x16x64_i8 v[16:19], v[28:31], v[212:215], v[16:19]
	v_mfma_i32_16x16x64_i8 v[12:15], v[36:39], v[212:215], 0
	v_mfma_i32_16x16x64_i8 v[12:15], v[40:43], v[220:223], v[12:15]
	v_mfma_i32_16x16x64_i8 v[44:47], v[40:43], v[208:211], 0
	v_mfma_i32_16x16x64_i8 v[44:47], v[36:39], v[204:207], v[44:47]
	v_mfma_i32_16x16x64_i8 v[60:63], v[36:39], v[172:175], 0
	v_mfma_i32_16x16x64_i8 v[60:63], v[40:43], v[176:179], v[60:63]
	v_mfma_i32_16x16x64_i8 v[76:79], v[40:43], v[168:171], 0
	v_mfma_i32_16x16x64_i8 v[76:79], v[36:39], v[164:167], v[76:79]
	v_mfma_i32_16x16x64_i8 v[28:31], v[140:143], v[164:167], 0
	v_mfma_i32_16x16x64_i8 v[28:31], v[144:147], v[168:171], v[28:31]
	v_mfma_i32_16x16x64_i8 v[36:39], v[144:147], v[176:179], 0
	v_mfma_i32_16x16x64_i8 v[36:39], v[140:143], v[172:175], v[36:39]
	v_mfma_i32_16x16x64_i8 v[24:27], v[140:143], v[204:207], 0
	v_mfma_i32_16x16x64_i8 v[24:27], v[144:147], v[208:211], v[24:27]
	v_mfma_i32_16x16x64_i8 v[8:11], v[144:147], v[220:223], 0
	v_mfma_i32_16x16x64_i8 v[8:11], v[140:143], v[212:215], v[8:11]
	v_mfma_i32_16x16x64_i8 v[4:7], v[156:159], v[212:215], 0
	v_mfma_i32_16x16x64_i8 v[4:7], v[160:163], v[220:223], v[4:7]
	v_mfma_i32_16x16x64_i8 v[20:23], v[160:163], v[208:211], 0
	v_mfma_i32_16x16x64_i8 v[20:23], v[156:159], v[204:207], v[20:23]
	v_mfma_i32_16x16x64_i8 v[40:43], v[156:159], v[172:175], 0
	v_mfma_i32_16x16x64_i8 v[40:43], v[160:163], v[176:179], v[40:43]
	v_mfma_i32_16x16x64_i8 v[32:35], v[160:163], v[168:171], 0
	v_mfma_i32_16x16x64_i8 v[32:35], v[156:159], v[164:167], v[32:35]
	s_barrier
	s_mov_b32 m0, s65
	s_nop 0
	global_load_lds_dwordx4 v[226:227], off
	s_mov_b32 m0, s67
	s_nop 0
	global_load_lds_dwordx4 v[228:229], off
	s_add_i32 s87, 0, 0x18000
	s_add_i32 s96, 0, 0x1c000
	v_add_u32_e32 v72, s87, v217
	v_add_u32_e32 v160, s96, v217
	ds_read_b128 v[52:55], v72
	ds_read_b128 v[164:167], v219 offset:32768
	ds_read_b128 v[56:59], v72 offset:1024
	ds_read_b128 v[168:171], v219 offset:33792
	ds_read_b128 v[176:179], v219 offset:35840
	ds_read_b128 v[172:175], v219 offset:34816
	ds_read_b128 v[204:207], v219 offset:36864
	ds_read_b128 v[208:211], v219 offset:37888
	s_add_u32 s60, s60, 0x80000
	s_addc_u32 s61, s61, 0
	s_mov_b32 m0, s72
	ds_read_b128 v[220:223], v219 offset:39936
	ds_read_b128 v[212:215], v219 offset:38912
	ds_read_b128 v[68:71], v72 offset:2048
	ds_read_b128 v[72:75], v72 offset:3072
	ds_read_b128 v[140:143], v160
	ds_read_b128 v[144:147], v160 offset:1024
	ds_read_b128 v[156:159], v160 offset:2048
	ds_read_b128 v[160:163], v160 offset:3072
	s_setprio 0
	global_load_lds_dwordx4 v180, s[60:61]
	s_mov_b32 m0, s73
	s_nop 0
	global_load_lds_dwordx4 v182, s[60:61]
	s_waitcnt vmcnt(8)
	s_waitcnt lgkmcnt(14)
	s_setprio 1
	s_barrier
	v_mfma_i32_16x16x64_i8 v[152:155], v[52:55], v[164:167], v[152:155]
	s_waitcnt lgkmcnt(12)
	v_mfma_i32_16x16x64_i8 v[152:155], v[56:59], v[168:171], v[152:155]
	s_waitcnt lgkmcnt(11)
	v_mfma_i32_16x16x64_i8 v[128:131], v[56:59], v[176:179], v[128:131]
	s_waitcnt lgkmcnt(10)
	v_mfma_i32_16x16x64_i8 v[128:131], v[52:55], v[172:175], v[128:131]
	s_waitcnt lgkmcnt(9)
	v_mfma_i32_16x16x64_i8 v[112:115], v[52:55], v[204:207], v[112:115]
	s_waitcnt lgkmcnt(8)
	v_mfma_i32_16x16x64_i8 v[112:115], v[56:59], v[208:211], v[112:115]
	s_waitcnt lgkmcnt(7)
	v_mfma_i32_16x16x64_i8 v[96:99], v[56:59], v[220:223], v[96:99]
	s_waitcnt lgkmcnt(6)
	v_mfma_i32_16x16x64_i8 v[96:99], v[52:55], v[212:215], v[96:99]
	s_waitcnt lgkmcnt(5)
	v_mfma_i32_16x16x64_i8 v[92:95], v[68:71], v[212:215], v[92:95]
	s_waitcnt lgkmcnt(4)
	v_mfma_i32_16x16x64_i8 v[92:95], v[72:75], v[220:223], v[92:95]
	v_mfma_i32_16x16x64_i8 v[108:111], v[72:75], v[208:211], v[108:111]
	v_mfma_i32_16x16x64_i8 v[108:111], v[68:71], v[204:207], v[108:111]
	v_mfma_i32_16x16x64_i8 v[124:127], v[68:71], v[172:175], v[124:127]
	v_mfma_i32_16x16x64_i8 v[124:127], v[72:75], v[176:179], v[124:127]
	v_mfma_i32_16x16x64_i8 v[148:151], v[72:75], v[168:171], v[148:151]
	v_mfma_i32_16x16x64_i8 v[148:151], v[68:71], v[164:167], v[148:151]
	s_waitcnt lgkmcnt(3)
	v_mfma_i32_16x16x64_i8 v[136:139], v[140:143], v[164:167], v[136:139]
	s_waitcnt lgkmcnt(2)
	v_mfma_i32_16x16x64_i8 v[136:139], v[144:147], v[168:171], v[136:139]
	v_mfma_i32_16x16x64_i8 v[120:123], v[144:147], v[176:179], v[120:123]
	v_mfma_i32_16x16x64_i8 v[120:123], v[140:143], v[172:175], v[120:123]
	v_mfma_i32_16x16x64_i8 v[104:107], v[140:143], v[204:207], v[104:107]
	v_mfma_i32_16x16x64_i8 v[104:107], v[144:147], v[208:211], v[104:107]
	v_mfma_i32_16x16x64_i8 v[88:91], v[144:147], v[220:223], v[88:91]
	v_mfma_i32_16x16x64_i8 v[88:91], v[140:143], v[212:215], v[88:91]
	s_waitcnt lgkmcnt(1)
	v_mfma_i32_16x16x64_i8 v[84:87], v[156:159], v[212:215], v[84:87]
	s_waitcnt lgkmcnt(0)
	v_mfma_i32_16x16x64_i8 v[84:87], v[160:163], v[220:223], v[84:87]
	v_mfma_i32_16x16x64_i8 v[100:103], v[160:163], v[208:211], v[100:103]
	v_mfma_i32_16x16x64_i8 v[100:103], v[156:159], v[204:207], v[100:103]
	v_mfma_i32_16x16x64_i8 v[116:119], v[156:159], v[172:175], v[116:119]
	v_mfma_i32_16x16x64_i8 v[116:119], v[160:163], v[176:179], v[116:119]
	v_mfma_i32_16x16x64_i8 v[132:135], v[160:163], v[168:171], v[132:135]
	v_mfma_i32_16x16x64_i8 v[132:135], v[156:159], v[164:167], v[132:135]
	s_barrier
	s_add_i32 s60, s87, s46
	v_lshl_add_u64 v[190:191], v[190:191], 0, s[84:85]
	s_mov_b32 m0, s60
	ds_read_b128 v[164:167], v219 offset:49152
	ds_read_b128 v[168:171], v219 offset:50176
	ds_read_b128 v[176:179], v219 offset:52224
	ds_read_b128 v[172:175], v219 offset:51200
	ds_read_b128 v[204:207], v219 offset:53248
	ds_read_b128 v[208:211], v219 offset:54272
	ds_read_b128 v[220:223], v219 offset:56320
	ds_read_b128 v[212:215], v219 offset:55296
	s_setprio 0
	global_load_lds_dwordx4 v[190:191], off
	s_add_i32 m0, s60, 0x2000
	s_add_u32 s58, s58, 0x80080
	v_lshl_add_u64 v[190:191], v[224:225], 0, s[84:85]
	s_addc_u32 s59, s59, 0
	s_add_i32 s60, s96, s46
	global_load_lds_dwordx4 v[190:191], off
	s_mov_b32 m0, s60
	s_nop 0
	global_load_lds_dwordx4 v2, s[58:59]
	s_add_i32 m0, s60, 0x2000
	s_nop 0
	global_load_lds_dwordx4 v184, s[58:59]
	s_cmp_eq_u32 s86, 28
	s_cbranch_scc0 .Ldefer_1843_peel
	v_lshl_add_u64 v[190:191], v[226:227], 0, s[84:85]
	s_mov_b32 m0, s28
	s_nop 0
	global_load_lds_dwordx4 v[190:191], off
	v_lshl_add_u64 v[190:191], v[228:229], 0, s[84:85]
	s_mov_b32 m0, s77
	s_nop 0
	global_load_lds_dwordx4 v[190:191], off

; #define PG8_STAGE(bufoff, gbase, voff) do { _Pragma("unroll") for (int _i = 0; _i < 2; ++_i) \
;         __builtin_amdgcn_global_load_lds((const unsigned*)((const char*)(gbase) + (voff)[_i]), (PG8_LAS unsigned*)(lds + (bufoff) + ldsw + _i * 8192), 16, 0, 0); } while (0)
; #define PG8_LDA(dst, b, h) do { _Pragma("unroll") for (int m = 0; m < 4; ++m) _Pragma("unroll") for (int k = 0; k < 2; ++k) dst[m][k] = *(const PG8_LAS bf16x8*)(lds + PG8_SA(b, h) + aoff + m * 2048 + k * 1024); } while (0)
; #define PG8_LDB(dst, b, h) do { _Pragma("unroll") for (int n = 0; n < 2; ++n) _Pragma("unroll") for (int k = 0; k < 2; ++k) dst[n][k] = *(const PG8_LAS bf16x8*)(lds + PG8_SB(b, h) + boff + n * 2048 + k * 1024); } while (0)
; #define PG8_WAIT_V(n) asm volatile("s_waitcnt vmcnt(" #n ")" ::: "memory")
; #define PG8_WAIT_L(n) asm volatile("s_waitcnt lgkmcnt(" #n ")" ::: "memory")
; #define PG8_BAR __builtin_amdgcn_s_barrier()
; #define PG8_SCHED __builtin_amdgcn_sched_barrier(0)
; template <class Epi, class Sched, bool ALIGN_EPI = false, bool SP2 = false, bool I8 = false>
; __device__ __forceinline__ void gemm_phase(PG8_LAS unsigned char* lds, const Gemm g, const Sched& S, const Epi& E) {
;     ...
;             if constexpr (SP2) {
;             PG8_LDB(B0, 0, 0); PG8_LDB(B1, 0, 1); PG8_SCHED; PG8_LDA(At, 0, 0); PG8_STAGE(PG8_SA(1, 1), a1 + hstep, voffA);
;             PG8_WAIT_V(8); PG8_WAIT_L(0); PG8_BAR; PG8_MMA(0, 0, At, B0); PG8_MMA(0, 1, At, B1); PG8_BAR; PG8_SCHED;
;             PG8_LDA(At, 0, 1); PG8_STAGE(PG8_SB(0, 0), b2, voffB); PG8_STAGE(PG8_SB(0, 1), b2 + hstep, voffB); PG8_STAGE(PG8_SA(0, 0), a2, voffA);
;             PG8_WAIT_V(8); PG8_WAIT_L(0); PG8_BAR; PG8_MMA(1, 0, At, B0); PG8_MMA(1, 1, At, B1); PG8_BAR; PG8_SCHED;
;             PG8_LDB(B0, 1, 0); PG8_LDB(B1, 1, 1); PG8_SCHED; PG8_LDA(At, 1, 0); PG8_STAGE(PG8_SA(0, 1), a2 + hstep, voffA);
;             PG8_WAIT_V(8); PG8_WAIT_L(0); PG8_BAR; PG8_MMA(0, 0, At, B0); PG8_MMA(0, 1, At, B1); PG8_BAR; PG8_SCHED;
;             PG8_LDA(At, 1, 1); PG8_STAGE(PG8_SB(1, 0), b3, voffB); PG8_STAGE(PG8_SB(1, 1), b3 + hstep, voffB); PG8_STAGE(PG8_SA(1, 0), a3, voffA);
;             PG8_WAIT_V(8); PG8_WAIT_L(0); PG8_BAR; PG8_MMA(1, 0, At, B0); PG8_MMA(1, 1, At, B1); PG8_BAR; PG8_SCHED;
.LBB0_1843:
	s_add_u32 s58, s54, 0xfff80080
	s_addc_u32 s59, s55, -1
	s_add_i32 s87, 0, 0x10000
	s_cmp_eq_u32 s86, 28
	s_cselect_b32 s61, s11, s59
	s_cselect_b32 s60, s13, s58
	s_cselect_b32 s59, s34, s49
	s_cselect_b32 s58, s35, s45
	s_add_i32 vcc_lo, 0, 0x14000
	v_add_u32_e32 v40, s87, v217
	v_add_u32_e32 v160, vcc_lo, v217
	ds_read_b128 v[28:31], v40
	ds_read_b128 v[164:167], v219
	ds_read_b128 v[32:35], v40 offset:1024
	ds_read_b128 v[168:171], v219 offset:1024
	ds_read_b128 v[176:179], v219 offset:3072
	ds_read_b128 v[172:175], v219 offset:2048
	ds_read_b128 v[204:207], v219 offset:4096
	ds_read_b128 v[208:211], v219 offset:5120
	v_lshl_add_u64 v[190:191], v[226:227], 0, s[84:85]
	s_mov_b32 m0, s28
	s_nop 0
	global_load_lds_dwordx4 v[190:191], off
	v_lshl_add_u64 v[190:191], v[228:229], 0, s[84:85]
	s_mov_b32 m0, s77
	s_nop 0
	global_load_lds_dwordx4 v[190:191], off
	s_add_i32 m0, s65, 0xc000
	ds_read_b128 v[220:223], v219 offset:7168
	ds_read_b128 v[212:215], v219 offset:6144
	ds_read_b128 v[36:39], v40 offset:2048
	ds_read_b128 v[40:43], v40 offset:3072
	ds_read_b128 v[140:143], v160
	ds_read_b128 v[144:147], v160 offset:1024
	ds_read_b128 v[156:159], v160 offset:2048
	ds_read_b128 v[160:163], v160 offset:3072
	global_load_lds_dwordx4 v186, s[54:55]
	s_add_i32 m0, s65, 0xe000
	s_nop 0
	global_load_lds_dwordx4 v188, s[54:55]
	s_waitcnt vmcnt(8)
	s_waitcnt lgkmcnt(14)
	s_setprio 1
	s_barrier
	v_mfma_i32_16x16x64_i8 v[152:155], v[28:31], v[164:167], v[152:155]
	s_waitcnt lgkmcnt(12)
	v_mfma_i32_16x16x64_i8 v[152:155], v[32:35], v[168:171], v[152:155]
	s_waitcnt lgkmcnt(11)
	v_mfma_i32_16x16x64_i8 v[128:131], v[32:35], v[176:179], v[128:131]
	s_waitcnt lgkmcnt(10)
	v_mfma_i32_16x16x64_i8 v[128:131], v[28:31], v[172:175], v[128:131]
	s_waitcnt lgkmcnt(9)
	v_mfma_i32_16x16x64_i8 v[112:115], v[28:31], v[204:207], v[112:115]
	s_waitcnt lgkmcnt(8)
	v_mfma_i32_16x16x64_i8 v[112:115], v[32:35], v[208:211], v[112:115]
	s_waitcnt lgkmcnt(7)
	v_mfma_i32_16x16x64_i8 v[96:99], v[32:35], v[220:223], v[96:99]
	s_waitcnt lgkmcnt(6)
	v_mfma_i32_16x16x64_i8 v[96:99], v[28:31], v[212:215], v[96:99]
	s_waitcnt lgkmcnt(5)
	v_mfma_i32_16x16x64_i8 v[92:95], v[36:39], v[212:215], v[92:95]
	s_waitcnt lgkmcnt(4)
	v_mfma_i32_16x16x64_i8 v[92:95], v[40:43], v[220:223], v[92:95]
	v_mfma_i32_16x16x64_i8 v[108:111], v[40:43], v[208:211], v[108:111]
	v_mfma_i32_16x16x64_i8 v[108:111], v[36:39], v[204:207], v[108:111]
	v_mfma_i32_16x16x64_i8 v[124:127], v[36:39], v[172:175], v[124:127]
	v_mfma_i32_16x16x64_i8 v[124:127], v[40:43], v[176:179], v[124:127]
	v_mfma_i32_16x16x64_i8 v[148:151], v[40:43], v[168:171], v[148:151]
	v_mfma_i32_16x16x64_i8 v[148:151], v[36:39], v[164:167], v[148:151]
	s_waitcnt lgkmcnt(3)
	v_mfma_i32_16x16x64_i8 v[136:139], v[140:143], v[164:167], v[136:139]
	s_waitcnt lgkmcnt(2)
	v_mfma_i32_16x16x64_i8 v[136:139], v[144:147], v[168:171], v[136:139]
	v_mfma_i32_16x16x64_i8 v[120:123], v[144:147], v[176:179], v[120:123]
	v_mfma_i32_16x16x64_i8 v[120:123], v[140:143], v[172:175], v[120:123]
	v_mfma_i32_16x16x64_i8 v[104:107], v[140:143], v[204:207], v[104:107]
	v_mfma_i32_16x16x64_i8 v[104:107], v[144:147], v[208:211], v[104:107]
	v_mfma_i32_16x16x64_i8 v[88:91], v[144:147], v[220:223], v[88:91]
	v_mfma_i32_16x16x64_i8 v[88:91], v[140:143], v[212:215], v[88:91]
	s_waitcnt lgkmcnt(1)
	v_mfma_i32_16x16x64_i8 v[84:87], v[156:159], v[212:215], v[84:87]
	s_waitcnt lgkmcnt(0)
	v_mfma_i32_16x16x64_i8 v[84:87], v[160:163], v[220:223], v[84:87]
	v_mfma_i32_16x16x64_i8 v[100:103], v[160:163], v[208:211], v[100:103]
	v_mfma_i32_16x16x64_i8 v[100:103], v[156:159], v[204:207], v[100:103]
	v_mfma_i32_16x16x64_i8 v[116:119], v[156:159], v[172:175], v[116:119]
	v_mfma_i32_16x16x64_i8 v[116:119], v[160:163], v[176:179], v[116:119]
	v_mfma_i32_16x16x64_i8 v[132:135], v[160:163], v[168:171], v[132:135]
	v_mfma_i32_16x16x64_i8 v[132:135], v[156:159], v[164:167], v[132:135]
	s_barrier
	s_add_i32 s87, s87, s46
	v_lshl_add_u64 v[190:191], s[58:59], 0, v[2:3]
	s_mov_b32 m0, s87
	ds_read_b128 v[164:167], v219 offset:16384
	ds_read_b128 v[168:171], v219 offset:17408
	ds_read_b128 v[176:179], v219 offset:19456
	ds_read_b128 v[172:175], v219 offset:18432
	ds_read_b128 v[204:207], v219 offset:20480
	ds_read_b128 v[208:211], v219 offset:21504
	ds_read_b128 v[220:223], v219 offset:23552
	ds_read_b128 v[212:215], v219 offset:22528
	s_setprio 0
	global_load_lds_dwordx4 v[190:191], off
	s_add_i32 m0, s87, 0x2000
	s_add_u32 s96, s58, 0x80000
	v_lshl_add_u64 v[224:225], s[58:59], 0, v[184:185]
	s_addc_u32 s97, s59, 0
	s_add_i32 s87, vcc_lo, s46
	global_load_lds_dwordx4 v[224:225], off
	s_mov_b32 m0, s87
	v_lshl_add_u64 v[228:229], s[60:61], 0, v[182:183]
	global_load_lds_dwordx4 v2, s[96:97]
	s_add_i32 m0, s87, 0x2000
	s_nop 0
	global_load_lds_dwordx4 v184, s[96:97]
	v_lshl_add_u64 v[226:227], s[60:61], 0, v[180:181]
	s_waitcnt vmcnt(6)
	s_waitcnt lgkmcnt(7)
	s_setprio 1
	s_barrier
; #define PG8_STAGE(bufoff, gbase, voff) do { _Pragma("unroll") for (int _i = 0; _i < 2; ++_i) \
;         __builtin_amdgcn_global_load_lds((const unsigned*)((const char*)(gbase) + (voff)[_i]), (PG8_LAS unsigned*)(lds + (bufoff) + ldsw + _i * 8192), 16, 0, 0); } while (0)
; #define PG8_LDA(dst, b, h) do { _Pragma("unroll") for (int m = 0; m < 4; ++m) _Pragma("unroll") for (int k = 0; k < 2; ++k) dst[m][k] = *(const PG8_LAS bf16x8*)(lds + PG8_SA(b, h) + aoff + m * 2048 + k * 1024); } while (0)
; #define PG8_LDB(dst, b, h) do { _Pragma("unroll") for (int n = 0; n < 2; ++n) _Pragma("unroll") for (int k = 0; k < 2; ++k) dst[n][k] = *(const PG8_LAS bf16x8*)(lds + PG8_SB(b, h) + boff + n * 2048 + k * 1024); } while (0)
; #define PG8_WAIT_V(n) asm volatile("s_waitcnt vmcnt(" #n ")" ::: "memory")
; #define PG8_WAIT_L(n) asm volatile("s_waitcnt lgkmcnt(" #n ")" ::: "memory")
; #define PG8_BAR __builtin_amdgcn_s_barrier()
; #define PG8_SCHED __builtin_amdgcn_sched_barrier(0)
; template <class Epi, class Sched, bool ALIGN_EPI = false, bool SP2 = false, bool I8 = false>
; __device__ __forceinline__ void gemm_phase(PG8_LAS unsigned char* lds, const Gemm g, const Sched& S, const Epi& E) {
;     ...
;             if constexpr (SP2) {
;             PG8_LDB(B0, 0, 0); PG8_LDB(B1, 0, 1); PG8_SCHED; PG8_LDA(At, 0, 0); PG8_STAGE(PG8_SA(1, 1), a1 + hstep, voffA);
;             PG8_WAIT_V(8); PG8_WAIT_L(0); PG8_BAR; PG8_MMA(0, 0, At, B0); PG8_MMA(0, 1, At, B1); PG8_BAR; PG8_SCHED;
;             PG8_LDA(At, 0, 1); PG8_STAGE(PG8_SB(0, 0), b2, voffB); PG8_STAGE(PG8_SB(0, 1), b2 + hstep, voffB); PG8_STAGE(PG8_SA(0, 0), a2, voffA);
;             PG8_WAIT_V(8); PG8_WAIT_L(0); PG8_BAR; PG8_MMA(1, 0, At, B0); PG8_MMA(1, 1, At, B1); PG8_BAR; PG8_SCHED;
;             PG8_LDB(B0, 1, 0); PG8_LDB(B1, 1, 1); PG8_SCHED; PG8_LDA(At, 1, 0); PG8_STAGE(PG8_SA(0, 1), a2 + hstep, voffA);
;             PG8_WAIT_V(8); PG8_WAIT_L(0); PG8_BAR; PG8_MMA(0, 0, At, B0); PG8_MMA(0, 1, At, B1); PG8_BAR; PG8_SCHED;
;             PG8_LDA(At, 1, 1); PG8_STAGE(PG8_SB(1, 0), b3, voffB); PG8_STAGE(PG8_SB(1, 1), b3 + hstep, voffB); PG8_STAGE(PG8_SA(1, 0), a3, voffA);
;             PG8_WAIT_V(8); PG8_WAIT_L(0); PG8_BAR; PG8_MMA(1, 0, At, B0); PG8_MMA(1, 1, At, B1); PG8_BAR; PG8_SCHED;
	v_mfma_i32_16x16x64_i8 v[80:83], v[28:31], v[164:167], v[80:83]
	s_waitcnt lgkmcnt(6)
	v_mfma_i32_16x16x64_i8 v[80:83], v[32:35], v[168:171], v[80:83]
	s_waitcnt lgkmcnt(5)
	v_mfma_i32_16x16x64_i8 v[64:67], v[32:35], v[176:179], v[64:67]
	s_waitcnt lgkmcnt(4)
	v_mfma_i32_16x16x64_i8 v[64:67], v[28:31], v[172:175], v[64:67]
	s_waitcnt lgkmcnt(3)
	v_mfma_i32_16x16x64_i8 v[48:51], v[28:31], v[204:207], v[48:51]
	s_waitcnt lgkmcnt(2)
	v_mfma_i32_16x16x64_i8 v[48:51], v[32:35], v[208:211], v[48:51]
	s_waitcnt lgkmcnt(1)
	v_mfma_i32_16x16x64_i8 v[16:19], v[32:35], v[220:223], v[16:19]
	s_waitcnt lgkmcnt(0)
	v_mfma_i32_16x16x64_i8 v[16:19], v[28:31], v[212:215], v[16:19]
	v_mfma_i32_16x16x64_i8 v[12:15], v[36:39], v[212:215], v[12:15]
	v_mfma_i32_16x16x64_i8 v[12:15], v[40:43], v[220:223], v[12:15]
	v_mfma_i32_16x16x64_i8 v[44:47], v[40:43], v[208:211], v[44:47]
	v_mfma_i32_16x16x64_i8 v[44:47], v[36:39], v[204:207], v[44:47]
	v_mfma_i32_16x16x64_i8 v[60:63], v[36:39], v[172:175], v[60:63]
	v_mfma_i32_16x16x64_i8 v[60:63], v[40:43], v[176:179], v[60:63]
	v_mfma_i32_16x16x64_i8 v[76:79], v[40:43], v[168:171], v[76:79]
	v_mfma_i32_16x16x64_i8 v[76:79], v[36:39], v[164:167], v[76:79]
	v_mfma_i32_16x16x64_i8 v[28:31], v[140:143], v[164:167], v[72:75]
	v_mfma_i32_16x16x64_i8 v[28:31], v[144:147], v[168:171], v[28:31]
	v_mfma_i32_16x16x64_i8 v[36:39], v[144:147], v[176:179], v[56:59]
	v_mfma_i32_16x16x64_i8 v[36:39], v[140:143], v[172:175], v[36:39]
	v_mfma_i32_16x16x64_i8 v[24:27], v[140:143], v[204:207], v[24:27]
	v_mfma_i32_16x16x64_i8 v[24:27], v[144:147], v[208:211], v[24:27]
	v_mfma_i32_16x16x64_i8 v[8:11], v[144:147], v[220:223], v[8:11]
	v_mfma_i32_16x16x64_i8 v[8:11], v[140:143], v[212:215], v[8:11]
	v_mfma_i32_16x16x64_i8 v[4:7], v[156:159], v[212:215], v[4:7]
	v_mfma_i32_16x16x64_i8 v[4:7], v[160:163], v[220:223], v[4:7]
	v_mfma_i32_16x16x64_i8 v[20:23], v[160:163], v[208:211], v[20:23]
	v_mfma_i32_16x16x64_i8 v[20:23], v[156:159], v[204:207], v[20:23]
	v_mfma_i32_16x16x64_i8 v[40:43], v[156:159], v[172:175], v[52:55]
	v_mfma_i32_16x16x64_i8 v[40:43], v[160:163], v[176:179], v[40:43]
	v_mfma_i32_16x16x64_i8 v[32:35], v[160:163], v[168:171], v[68:71]
	v_mfma_i32_16x16x64_i8 v[32:35], v[156:159], v[164:167], v[32:35]
	s_barrier
	s_mov_b32 m0, s65
	s_nop 0
	global_load_lds_dwordx4 v[226:227], off
	s_mov_b32 m0, s67
	s_nop 0
	global_load_lds_dwordx4 v[228:229], off
	s_add_i32 s87, 0, 0x18000
	s_add_i32 s96, 0, 0x1c000
	v_add_u32_e32 v72, s87, v217
	v_add_u32_e32 v160, s96, v217
	ds_read_b128 v[52:55], v72
	ds_read_b128 v[164:167], v219 offset:32768
	ds_read_b128 v[56:59], v72 offset:1024
	ds_read_b128 v[168:171], v219 offset:33792
	ds_read_b128 v[176:179], v219 offset:35840
	ds_read_b128 v[172:175], v219 offset:34816
	ds_read_b128 v[204:207], v219 offset:36864
	ds_read_b128 v[208:211], v219 offset:37888
	s_add_u32 s60, s60, 0x80000
	s_addc_u32 s61, s61, 0
	s_mov_b32 m0, s72
	ds_read_b128 v[220:223], v219 offset:39936
	ds_read_b128 v[212:215], v219 offset:38912
	ds_read_b128 v[68:71], v72 offset:2048
	ds_read_b128 v[72:75], v72 offset:3072
	ds_read_b128 v[140:143], v160
	ds_read_b128 v[144:147], v160 offset:1024
	ds_read_b128 v[156:159], v160 offset:2048
	ds_read_b128 v[160:163], v160 offset:3072
	s_setprio 0
	global_load_lds_dwordx4 v180, s[60:61]
	s_mov_b32 m0, s73
	s_nop 0
	global_load_lds_dwordx4 v182, s[60:61]
	s_waitcnt vmcnt(8)
	s_waitcnt lgkmcnt(14)
	s_setprio 1
	s_barrier
; #define PG8_STAGE(bufoff, gbase, voff) do { _Pragma("unroll") for (int _i = 0; _i < 2; ++_i) \
;         __builtin_amdgcn_global_load_lds((const unsigned*)((const char*)(gbase) + (voff)[_i]), (PG8_LAS unsigned*)(lds + (bufoff) + ldsw + _i * 8192), 16, 0, 0); } while (0)
; #define PG8_LDA(dst, b, h) do { _Pragma("unroll") for (int m = 0; m < 4; ++m) _Pragma("unroll") for (int k = 0; k < 2; ++k) dst[m][k] = *(const PG8_LAS bf16x8*)(lds + PG8_SA(b, h) + aoff + m * 2048 + k * 1024); } while (0)
; #define PG8_LDB(dst, b, h) do { _Pragma("unroll") for (int n = 0; n < 2; ++n) _Pragma("unroll") for (int k = 0; k < 2; ++k) dst[n][k] = *(const PG8_LAS bf16x8*)(lds + PG8_SB(b, h) + boff + n * 2048 + k * 1024); } while (0)
; template <class Epi, class Sched, bool ALIGN_EPI = false, bool SP2 = false, bool I8 = false>
; __device__ __forceinline__ void gemm_phase(PG8_LAS unsigned char* lds, const Gemm g, const Sched& S, const Epi& E) {
;     ...
;             const bool last = (t == nt - 2);
;             const char* a1 = cA + (size_t)(t + 1) * kstep;
;             const char* a2 = last ? nA : cA + (size_t)(t + 2) * kstep; const char* b2 = last ? nB : cB + (size_t)(t + 2) * kstep;
;             const char* a3 = a2 + kstep; const char* b3 = b2 + kstep;
;             if (last && has_next) S.a_ready(nxt);
;             if constexpr (SP2) {
;             PG8_LDB(B0, 0, 0); PG8_LDB(B1, 0, 1); PG8_SCHED; PG8_LDA(At, 0, 0); PG8_STAGE(PG8_SA(1, 1), a1 + hstep, voffA);
;             PG8_WAIT_V(8); PG8_WAIT_L(0); PG8_BAR; PG8_MMA(0, 0, At, B0); PG8_MMA(0, 1, At, B1); PG8_BAR; PG8_SCHED;
;             PG8_LDA(At, 0, 1); PG8_STAGE(PG8_SB(0, 0), b2, voffB); PG8_STAGE(PG8_SB(0, 1), b2 + hstep, voffB); PG8_STAGE(PG8_SA(0, 0), a2, voffA);
;             PG8_WAIT_V(8); PG8_WAIT_L(0); PG8_BAR; PG8_MMA(1, 0, At, B0); PG8_MMA(1, 1, At, B1); PG8_BAR; PG8_SCHED;
;             PG8_LDB(B0, 1, 0); PG8_LDB(B1, 1, 1); PG8_SCHED; PG8_LDA(At, 1, 0); PG8_STAGE(PG8_SA(0, 1), a2 + hstep, voffA);
;             PG8_WAIT_V(8); PG8_WAIT_L(0); PG8_BAR; PG8_MMA(0, 0, At, B0); PG8_MMA(0, 1, At, B1); PG8_BAR; PG8_SCHED;
;             PG8_LDA(At, 1, 1); PG8_STAGE(PG8_SB(1, 0), b3, voffB); PG8_STAGE(PG8_SB(1, 1), b3 + hstep, voffB); PG8_STAGE(PG8_SA(1, 0), a3, voffA);
;             PG8_WAIT_V(8); PG8_WAIT_L(0); PG8_BAR; PG8_MMA(1, 0, At, B0); PG8_MMA(1, 1, At, B1); PG8_BAR; PG8_SCHED;
	v_mfma_i32_16x16x64_i8 v[152:155], v[52:55], v[164:167], v[152:155]
	s_waitcnt lgkmcnt(12)
	v_mfma_i32_16x16x64_i8 v[152:155], v[56:59], v[168:171], v[152:155]
	s_waitcnt lgkmcnt(11)
	v_mfma_i32_16x16x64_i8 v[128:131], v[56:59], v[176:179], v[128:131]
	s_waitcnt lgkmcnt(10)
	v_mfma_i32_16x16x64_i8 v[128:131], v[52:55], v[172:175], v[128:131]
	s_waitcnt lgkmcnt(9)
	v_mfma_i32_16x16x64_i8 v[112:115], v[52:55], v[204:207], v[112:115]
	s_waitcnt lgkmcnt(8)
	v_mfma_i32_16x16x64_i8 v[112:115], v[56:59], v[208:211], v[112:115]
	s_waitcnt lgkmcnt(7)
	v_mfma_i32_16x16x64_i8 v[96:99], v[56:59], v[220:223], v[96:99]
	s_waitcnt lgkmcnt(6)
	v_mfma_i32_16x16x64_i8 v[96:99], v[52:55], v[212:215], v[96:99]
	s_waitcnt lgkmcnt(5)
	v_mfma_i32_16x16x64_i8 v[92:95], v[68:71], v[212:215], v[92:95]
	s_waitcnt lgkmcnt(4)
	v_mfma_i32_16x16x64_i8 v[92:95], v[72:75], v[220:223], v[92:95]
	v_mfma_i32_16x16x64_i8 v[108:111], v[72:75], v[208:211], v[108:111]
	v_mfma_i32_16x16x64_i8 v[108:111], v[68:71], v[204:207], v[108:111]
	v_mfma_i32_16x16x64_i8 v[124:127], v[68:71], v[172:175], v[124:127]
	v_mfma_i32_16x16x64_i8 v[124:127], v[72:75], v[176:179], v[124:127]
	v_mfma_i32_16x16x64_i8 v[148:151], v[72:75], v[168:171], v[148:151]
	v_mfma_i32_16x16x64_i8 v[148:151], v[68:71], v[164:167], v[148:151]
	s_waitcnt lgkmcnt(3)
	v_mfma_i32_16x16x64_i8 v[136:139], v[140:143], v[164:167], v[136:139]
	s_waitcnt lgkmcnt(2)
	v_mfma_i32_16x16x64_i8 v[136:139], v[144:147], v[168:171], v[136:139]
	v_mfma_i32_16x16x64_i8 v[120:123], v[144:147], v[176:179], v[120:123]
	v_mfma_i32_16x16x64_i8 v[120:123], v[140:143], v[172:175], v[120:123]
	v_mfma_i32_16x16x64_i8 v[104:107], v[140:143], v[204:207], v[104:107]
	v_mfma_i32_16x16x64_i8 v[104:107], v[144:147], v[208:211], v[104:107]
	v_mfma_i32_16x16x64_i8 v[88:91], v[144:147], v[220:223], v[88:91]
	v_mfma_i32_16x16x64_i8 v[88:91], v[140:143], v[212:215], v[88:91]
	s_waitcnt lgkmcnt(1)
	v_mfma_i32_16x16x64_i8 v[84:87], v[156:159], v[212:215], v[84:87]
	s_waitcnt lgkmcnt(0)
	v_mfma_i32_16x16x64_i8 v[84:87], v[160:163], v[220:223], v[84:87]
	v_mfma_i32_16x16x64_i8 v[100:103], v[160:163], v[208:211], v[100:103]
	v_mfma_i32_16x16x64_i8 v[100:103], v[156:159], v[204:207], v[100:103]
	v_mfma_i32_16x16x64_i8 v[116:119], v[156:159], v[172:175], v[116:119]
	v_mfma_i32_16x16x64_i8 v[116:119], v[160:163], v[176:179], v[116:119]
	v_mfma_i32_16x16x64_i8 v[132:135], v[160:163], v[168:171], v[132:135]
	v_mfma_i32_16x16x64_i8 v[132:135], v[156:159], v[164:167], v[132:135]
	s_barrier
	s_add_i32 s60, s87, s46
	v_lshl_add_u64 v[190:191], v[190:191], 0, s[84:85]
	s_mov_b32 m0, s60
	ds_read_b128 v[164:167], v219 offset:49152
	ds_read_b128 v[168:171], v219 offset:50176
	ds_read_b128 v[176:179], v219 offset:52224
	ds_read_b128 v[172:175], v219 offset:51200
	ds_read_b128 v[204:207], v219 offset:53248
	ds_read_b128 v[208:211], v219 offset:54272
	ds_read_b128 v[220:223], v219 offset:56320
	ds_read_b128 v[212:215], v219 offset:55296
	s_setprio 0
	global_load_lds_dwordx4 v[190:191], off
	s_add_i32 m0, s60, 0x2000
	s_add_u32 s58, s58, 0x80080
	v_lshl_add_u64 v[190:191], v[224:225], 0, s[84:85]
	s_addc_u32 s59, s59, 0
	s_add_i32 s60, s96, s46
	global_load_lds_dwordx4 v[190:191], off
	s_mov_b32 m0, s60
	s_nop 0
	global_load_lds_dwordx4 v2, s[58:59]
	s_add_i32 m0, s60, 0x2000
	s_nop 0
	global_load_lds_dwordx4 v184, s[58:59]
	s_cmp_eq_u32 s86, 28
	s_cbranch_scc0 .Ldefer_1843_body
	v_lshl_add_u64 v[190:191], v[226:227], 0, s[84:85]
	s_mov_b32 m0, s28
	s_nop 0
	global_load_lds_dwordx4 v[190:191], off
	v_lshl_add_u64 v[190:191], v[228:229], 0, s[84:85]
	s_mov_b32 m0, s77
	s_nop 0
	global_load_lds_dwordx4 v[190:191], off
